# MFMA order: each accumulator's k0,k1 MFMAs issued back-to-back (dependent chain, C forwarded) in all GEMM K-loops and peels; plus peel, decode simplification, attention pipeline edits
# speedup vs baseline: 1.0040x; 1.0040x over previous
.LBB0_183:
	s_ashr_i32 s13, s12, 31
	s_lshl_b64 s[24:25], s[12:13], 19
	s_add_u32 s24, s80, s24
	s_addc_u32 s25, s81, s25
	s_and_b64 s[30:31], s[4:5], exec
	s_cselect_b32 s13, s25, s45
	s_cselect_b32 s66, s24, s44
	s_ashr_i32 s11, s10, 31
	s_lshl_b64 s[30:31], s[10:11], 19
	s_add_u32 s30, s52, s30
	s_addc_u32 s31, s53, s31
	s_and_b64 s[48:49], s[4:5], exec
	s_cselect_b32 s11, s31, s47
	s_cselect_b32 s67, s30, s46
	s_add_u32 s44, s44, 0x40080
	s_addc_u32 s45, s45, 0
	s_add_u32 s68, s46, 0x100
	s_addc_u32 s69, s47, 0
	s_mov_b32 s70, -2
	ds_read_b128 v[140:143], v147
	ds_read_b128 v[150:153], v147 offset:1024
	ds_read_b128 v[154:157], v147 offset:2048
	ds_read_b128 v[158:161], v147 offset:3072
	ds_read_b128 v[162:165], v148
	ds_read_b128 v[166:169], v148 offset:1024
	ds_read_b128 v[170:173], v148 offset:2048
	ds_read_b128 v[174:177], v148 offset:3072
	s_add_u32 s18, s44, 0xfffc0080
	s_addc_u32 s19, s45, -1
	s_cmp_eq_u32 s70, 12
	s_cselect_b32 s49, s13, s19
	s_cselect_b32 s48, s66, s18
	s_cselect_b32 s47, s11, s69
	s_cselect_b32 s46, s67, s68
	v_lshl_add_u64 v[178:179], s[44:45], 0, v[132:133]
	s_add_i32 m0, s37, 0xc000
	ds_read_b128 v[184:187], v149
	ds_read_b128 v[188:191], v149 offset:1024
	ds_read_b128 v[192:195], v149 offset:2048
	ds_read_b128 v[196:199], v149 offset:3072
	ds_read_b128 v[200:203], v149 offset:4096
	ds_read_b128 v[204:207], v149 offset:5120
	ds_read_b128 v[208:211], v149 offset:6144
	ds_read_b128 v[212:215], v149 offset:7168
	global_load_lds_dwordx4 v[178:179], off
	v_lshl_add_u64 v[178:179], s[44:45], 0, v[134:135]
	s_add_i32 m0, s37, 0xe000
	s_nop 0
	global_load_lds_dwordx4 v[178:179], off
	s_waitcnt vmcnt(8)
	s_waitcnt lgkmcnt(0)
	s_barrier
	s_setprio 1
	s_waitcnt lgkmcnt(0)
	v_mfma_f32_16x16x32_bf16 v[124:127], v[140:143], v[184:187], 0
	v_mfma_f32_16x16x32_bf16 v[124:127], v[150:153], v[188:191], v[124:127]
	v_mfma_f32_16x16x32_bf16 v[120:123], v[154:157], v[184:187], 0
	v_mfma_f32_16x16x32_bf16 v[120:123], v[158:161], v[188:191], v[120:123]
	v_mfma_f32_16x16x32_bf16 v[108:111], v[140:143], v[192:195], 0
	v_mfma_f32_16x16x32_bf16 v[108:111], v[150:153], v[196:199], v[108:111]
	v_mfma_f32_16x16x32_bf16 v[104:107], v[154:157], v[192:195], 0
	v_mfma_f32_16x16x32_bf16 v[104:107], v[158:161], v[196:199], v[104:107]
	v_mfma_f32_16x16x32_bf16 v[92:95], v[140:143], v[200:203], 0
	v_mfma_f32_16x16x32_bf16 v[92:95], v[150:153], v[204:207], v[92:95]
	v_mfma_f32_16x16x32_bf16 v[88:91], v[154:157], v[200:203], 0
	v_mfma_f32_16x16x32_bf16 v[88:91], v[158:161], v[204:207], v[88:91]
	v_mfma_f32_16x16x32_bf16 v[76:79], v[140:143], v[208:211], 0
	v_mfma_f32_16x16x32_bf16 v[76:79], v[150:153], v[212:215], v[76:79]
	v_mfma_f32_16x16x32_bf16 v[72:75], v[154:157], v[208:211], 0
	v_mfma_f32_16x16x32_bf16 v[72:75], v[158:161], v[212:215], v[72:75]
	s_setprio 0
	s_setprio 1
	v_mfma_f32_16x16x32_bf16 v[116:119], v[162:165], v[184:187], 0
	v_mfma_f32_16x16x32_bf16 v[116:119], v[166:169], v[188:191], v[116:119]
	v_mfma_f32_16x16x32_bf16 v[112:115], v[170:173], v[184:187], 0
	v_mfma_f32_16x16x32_bf16 v[112:115], v[174:177], v[188:191], v[112:115]
	v_mfma_f32_16x16x32_bf16 v[100:103], v[162:165], v[192:195], 0
	v_mfma_f32_16x16x32_bf16 v[100:103], v[166:169], v[196:199], v[100:103]
	v_mfma_f32_16x16x32_bf16 v[96:99], v[170:173], v[192:195], 0
	v_mfma_f32_16x16x32_bf16 v[96:99], v[174:177], v[196:199], v[96:99]
	v_mfma_f32_16x16x32_bf16 v[84:87], v[162:165], v[200:203], 0
	v_mfma_f32_16x16x32_bf16 v[84:87], v[166:169], v[204:207], v[84:87]
	v_mfma_f32_16x16x32_bf16 v[80:83], v[170:173], v[200:203], 0
	v_mfma_f32_16x16x32_bf16 v[80:83], v[174:177], v[204:207], v[80:83]
	v_mfma_f32_16x16x32_bf16 v[68:71], v[162:165], v[208:211], 0
	v_mfma_f32_16x16x32_bf16 v[68:71], v[166:169], v[212:215], v[68:71]
	v_mfma_f32_16x16x32_bf16 v[64:67], v[170:173], v[208:211], 0
	v_mfma_f32_16x16x32_bf16 v[64:67], v[174:177], v[212:215], v[64:67]
	s_setprio 0
	s_barrier
	s_add_i32 s18, s62, s54
	v_lshl_add_u64 v[178:179], s[46:47], 0, v[130:131]
	s_mov_b32 m0, s18
	ds_read_b128 v[184:187], v149 offset:16384
	ds_read_b128 v[188:191], v149 offset:17408
	ds_read_b128 v[192:195], v149 offset:18432
	ds_read_b128 v[196:199], v149 offset:19456
	ds_read_b128 v[200:203], v149 offset:20480
	ds_read_b128 v[204:207], v149 offset:21504
	ds_read_b128 v[208:211], v149 offset:22528
	ds_read_b128 v[212:215], v149 offset:23552
	global_load_lds_dwordx4 v[178:179], off
	s_add_i32 m0, s18, 0x2000
	s_add_u32 s72, s46, 0x40000
	v_lshl_add_u64 v[216:217], s[46:47], 0, v[128:129]
	s_addc_u32 s73, s47, 0
	s_add_i32 s18, s63, s54
	global_load_lds_dwordx4 v[216:217], off
	v_lshl_add_u64 v[218:219], s[72:73], 0, v[130:131]
	s_mov_b32 m0, s18
	v_lshl_add_u64 v[220:221], s[48:49], 0, v[128:129]
	global_load_lds_dwordx4 v[218:219], off
	v_lshl_add_u64 v[218:219], s[72:73], 0, v[128:129]
	s_add_i32 m0, s18, 0x2000
	s_nop 0
	global_load_lds_dwordx4 v[218:219], off
	v_lshl_add_u64 v[218:219], s[48:49], 0, v[130:131]
	s_mov_b32 m0, s37
	s_nop 0
	global_load_lds_dwordx4 v[218:219], off
	s_mov_b32 m0, s56
	s_nop 0
	global_load_lds_dwordx4 v[220:221], off
	s_waitcnt vmcnt(8)
	s_waitcnt lgkmcnt(0)
	s_barrier
	s_setprio 1
	s_waitcnt lgkmcnt(0)
	v_mfma_f32_16x16x32_bf16 v[60:63], v[140:143], v[184:187], 0
	v_mfma_f32_16x16x32_bf16 v[60:63], v[150:153], v[188:191], v[60:63]
	v_mfma_f32_16x16x32_bf16 v[56:59], v[154:157], v[184:187], 0
	v_mfma_f32_16x16x32_bf16 v[56:59], v[158:161], v[188:191], v[56:59]
	v_mfma_f32_16x16x32_bf16 v[44:47], v[140:143], v[192:195], 0
	v_mfma_f32_16x16x32_bf16 v[44:47], v[150:153], v[196:199], v[44:47]
	v_mfma_f32_16x16x32_bf16 v[40:43], v[154:157], v[192:195], 0
	v_mfma_f32_16x16x32_bf16 v[40:43], v[158:161], v[196:199], v[40:43]
	v_mfma_f32_16x16x32_bf16 v[28:31], v[140:143], v[200:203], 0
	v_mfma_f32_16x16x32_bf16 v[28:31], v[150:153], v[204:207], v[28:31]
	v_mfma_f32_16x16x32_bf16 v[24:27], v[154:157], v[200:203], 0
	v_mfma_f32_16x16x32_bf16 v[24:27], v[158:161], v[204:207], v[24:27]
	v_mfma_f32_16x16x32_bf16 v[12:15], v[140:143], v[208:211], 0
	v_mfma_f32_16x16x32_bf16 v[12:15], v[150:153], v[212:215], v[12:15]
	v_mfma_f32_16x16x32_bf16 v[8:11], v[154:157], v[208:211], 0
	v_mfma_f32_16x16x32_bf16 v[8:11], v[158:161], v[212:215], v[8:11]
	s_setprio 0
	s_setprio 1
	v_mfma_f32_16x16x32_bf16 v[52:55], v[162:165], v[184:187], 0
	v_mfma_f32_16x16x32_bf16 v[52:55], v[166:169], v[188:191], v[52:55]
	v_mfma_f32_16x16x32_bf16 v[48:51], v[170:173], v[184:187], 0
	v_mfma_f32_16x16x32_bf16 v[48:51], v[174:177], v[188:191], v[48:51]
	v_mfma_f32_16x16x32_bf16 v[36:39], v[162:165], v[192:195], 0
	v_mfma_f32_16x16x32_bf16 v[36:39], v[166:169], v[196:199], v[36:39]
	v_mfma_f32_16x16x32_bf16 v[32:35], v[170:173], v[192:195], 0
	v_mfma_f32_16x16x32_bf16 v[32:35], v[174:177], v[196:199], v[32:35]
	v_mfma_f32_16x16x32_bf16 v[20:23], v[162:165], v[200:203], 0
	v_mfma_f32_16x16x32_bf16 v[20:23], v[166:169], v[204:207], v[20:23]
	v_mfma_f32_16x16x32_bf16 v[16:19], v[170:173], v[200:203], 0
	v_mfma_f32_16x16x32_bf16 v[16:19], v[174:177], v[204:207], v[16:19]
	v_mfma_f32_16x16x32_bf16 v[4:7], v[162:165], v[208:211], 0
	v_mfma_f32_16x16x32_bf16 v[4:7], v[166:169], v[212:215], v[4:7]
	v_mfma_f32_16x16x32_bf16 v[0:3], v[170:173], v[208:211], 0
	v_mfma_f32_16x16x32_bf16 v[0:3], v[174:177], v[212:215], v[0:3]
	s_setprio 0
	s_barrier
	s_branch .Lmid_gemm0
.LBB0_184:
	ds_read_b128 v[140:143], v147
	ds_read_b128 v[150:153], v147 offset:1024
	ds_read_b128 v[154:157], v147 offset:2048
	ds_read_b128 v[158:161], v147 offset:3072
	ds_read_b128 v[162:165], v148
	ds_read_b128 v[166:169], v148 offset:1024
	ds_read_b128 v[170:173], v148 offset:2048
	ds_read_b128 v[174:177], v148 offset:3072
	s_add_u32 s18, s44, 0xfffc0080
	s_addc_u32 s19, s45, -1
	s_cmp_eq_u32 s70, 12
	s_cselect_b32 s49, s13, s19
	s_cselect_b32 s48, s66, s18
	s_cselect_b32 s47, s11, s69
	s_cselect_b32 s46, s67, s68
	v_lshl_add_u64 v[178:179], s[44:45], 0, v[132:133]
	s_add_i32 m0, s37, 0xc000
	ds_read_b128 v[184:187], v149
	ds_read_b128 v[188:191], v149 offset:1024
	ds_read_b128 v[192:195], v149 offset:2048
	ds_read_b128 v[196:199], v149 offset:3072
	ds_read_b128 v[200:203], v149 offset:4096
	ds_read_b128 v[204:207], v149 offset:5120
	ds_read_b128 v[208:211], v149 offset:6144
	ds_read_b128 v[212:215], v149 offset:7168
	global_load_lds_dwordx4 v[178:179], off
	v_lshl_add_u64 v[178:179], s[44:45], 0, v[134:135]
	s_add_i32 m0, s37, 0xe000
	s_nop 0
	global_load_lds_dwordx4 v[178:179], off
	s_waitcnt vmcnt(8)
	s_waitcnt lgkmcnt(0)
	s_barrier
	s_setprio 1
	s_waitcnt lgkmcnt(0)
	v_mfma_f32_16x16x32_bf16 v[124:127], v[140:143], v[184:187], v[124:127]
	v_mfma_f32_16x16x32_bf16 v[124:127], v[150:153], v[188:191], v[124:127]
	v_mfma_f32_16x16x32_bf16 v[120:123], v[154:157], v[184:187], v[120:123]
	v_mfma_f32_16x16x32_bf16 v[120:123], v[158:161], v[188:191], v[120:123]
	v_mfma_f32_16x16x32_bf16 v[108:111], v[140:143], v[192:195], v[108:111]
	v_mfma_f32_16x16x32_bf16 v[108:111], v[150:153], v[196:199], v[108:111]
	v_mfma_f32_16x16x32_bf16 v[104:107], v[154:157], v[192:195], v[104:107]
	v_mfma_f32_16x16x32_bf16 v[104:107], v[158:161], v[196:199], v[104:107]
	v_mfma_f32_16x16x32_bf16 v[92:95], v[140:143], v[200:203], v[92:95]
	v_mfma_f32_16x16x32_bf16 v[92:95], v[150:153], v[204:207], v[92:95]
	v_mfma_f32_16x16x32_bf16 v[88:91], v[154:157], v[200:203], v[88:91]
	v_mfma_f32_16x16x32_bf16 v[88:91], v[158:161], v[204:207], v[88:91]
	v_mfma_f32_16x16x32_bf16 v[76:79], v[140:143], v[208:211], v[76:79]
	v_mfma_f32_16x16x32_bf16 v[76:79], v[150:153], v[212:215], v[76:79]
	v_mfma_f32_16x16x32_bf16 v[72:75], v[154:157], v[208:211], v[72:75]
	v_mfma_f32_16x16x32_bf16 v[72:75], v[158:161], v[212:215], v[72:75]
	s_setprio 0
	s_setprio 1
	v_mfma_f32_16x16x32_bf16 v[116:119], v[162:165], v[184:187], v[116:119]
	v_mfma_f32_16x16x32_bf16 v[116:119], v[166:169], v[188:191], v[116:119]
	v_mfma_f32_16x16x32_bf16 v[112:115], v[170:173], v[184:187], v[112:115]
	v_mfma_f32_16x16x32_bf16 v[112:115], v[174:177], v[188:191], v[112:115]
	v_mfma_f32_16x16x32_bf16 v[100:103], v[162:165], v[192:195], v[100:103]
	v_mfma_f32_16x16x32_bf16 v[100:103], v[166:169], v[196:199], v[100:103]
	v_mfma_f32_16x16x32_bf16 v[96:99], v[170:173], v[192:195], v[96:99]
	v_mfma_f32_16x16x32_bf16 v[96:99], v[174:177], v[196:199], v[96:99]
	v_mfma_f32_16x16x32_bf16 v[84:87], v[162:165], v[200:203], v[84:87]
	v_mfma_f32_16x16x32_bf16 v[84:87], v[166:169], v[204:207], v[84:87]
	v_mfma_f32_16x16x32_bf16 v[80:83], v[170:173], v[200:203], v[80:83]
	v_mfma_f32_16x16x32_bf16 v[80:83], v[174:177], v[204:207], v[80:83]
	v_mfma_f32_16x16x32_bf16 v[68:71], v[162:165], v[208:211], v[68:71]
	v_mfma_f32_16x16x32_bf16 v[68:71], v[166:169], v[212:215], v[68:71]
	v_mfma_f32_16x16x32_bf16 v[64:67], v[170:173], v[208:211], v[64:67]
	v_mfma_f32_16x16x32_bf16 v[64:67], v[174:177], v[212:215], v[64:67]
	s_setprio 0
	s_barrier
	s_add_i32 s18, s62, s54
	v_lshl_add_u64 v[178:179], s[46:47], 0, v[130:131]
	s_mov_b32 m0, s18
	ds_read_b128 v[184:187], v149 offset:16384
	ds_read_b128 v[188:191], v149 offset:17408
	ds_read_b128 v[192:195], v149 offset:18432
	ds_read_b128 v[196:199], v149 offset:19456
	ds_read_b128 v[200:203], v149 offset:20480
	ds_read_b128 v[204:207], v149 offset:21504
	ds_read_b128 v[208:211], v149 offset:22528
	ds_read_b128 v[212:215], v149 offset:23552
	global_load_lds_dwordx4 v[178:179], off
	s_add_i32 m0, s18, 0x2000
	s_add_u32 s72, s46, 0x40000
	v_lshl_add_u64 v[216:217], s[46:47], 0, v[128:129]
	s_addc_u32 s73, s47, 0
	s_add_i32 s18, s63, s54
	global_load_lds_dwordx4 v[216:217], off
	v_lshl_add_u64 v[218:219], s[72:73], 0, v[130:131]
	s_mov_b32 m0, s18
	v_lshl_add_u64 v[220:221], s[48:49], 0, v[128:129]
	global_load_lds_dwordx4 v[218:219], off
	v_lshl_add_u64 v[218:219], s[72:73], 0, v[128:129]
	s_add_i32 m0, s18, 0x2000
	s_nop 0
	global_load_lds_dwordx4 v[218:219], off
	v_lshl_add_u64 v[218:219], s[48:49], 0, v[130:131]
	s_mov_b32 m0, s37
	s_nop 0
	global_load_lds_dwordx4 v[218:219], off
	s_mov_b32 m0, s56
	s_nop 0
	global_load_lds_dwordx4 v[220:221], off
	s_waitcnt vmcnt(8)
	s_waitcnt lgkmcnt(0)
	s_barrier
	s_setprio 1
	s_waitcnt lgkmcnt(0)
	v_mfma_f32_16x16x32_bf16 v[60:63], v[140:143], v[184:187], v[60:63]
	v_mfma_f32_16x16x32_bf16 v[60:63], v[150:153], v[188:191], v[60:63]
	v_mfma_f32_16x16x32_bf16 v[56:59], v[154:157], v[184:187], v[56:59]
	v_mfma_f32_16x16x32_bf16 v[56:59], v[158:161], v[188:191], v[56:59]
	v_mfma_f32_16x16x32_bf16 v[44:47], v[140:143], v[192:195], v[44:47]
	v_mfma_f32_16x16x32_bf16 v[44:47], v[150:153], v[196:199], v[44:47]
	v_mfma_f32_16x16x32_bf16 v[40:43], v[154:157], v[192:195], v[40:43]
	v_mfma_f32_16x16x32_bf16 v[40:43], v[158:161], v[196:199], v[40:43]
	v_mfma_f32_16x16x32_bf16 v[28:31], v[140:143], v[200:203], v[28:31]
	v_mfma_f32_16x16x32_bf16 v[28:31], v[150:153], v[204:207], v[28:31]
	v_mfma_f32_16x16x32_bf16 v[24:27], v[154:157], v[200:203], v[24:27]
	v_mfma_f32_16x16x32_bf16 v[24:27], v[158:161], v[204:207], v[24:27]
	v_mfma_f32_16x16x32_bf16 v[12:15], v[140:143], v[208:211], v[12:15]
	v_mfma_f32_16x16x32_bf16 v[12:15], v[150:153], v[212:215], v[12:15]
	v_mfma_f32_16x16x32_bf16 v[8:11], v[154:157], v[208:211], v[8:11]
	v_mfma_f32_16x16x32_bf16 v[8:11], v[158:161], v[212:215], v[8:11]
	s_setprio 0
	s_setprio 1
	v_mfma_f32_16x16x32_bf16 v[52:55], v[162:165], v[184:187], v[52:55]
	v_mfma_f32_16x16x32_bf16 v[52:55], v[166:169], v[188:191], v[52:55]
	v_mfma_f32_16x16x32_bf16 v[48:51], v[170:173], v[184:187], v[48:51]
	v_mfma_f32_16x16x32_bf16 v[48:51], v[174:177], v[188:191], v[48:51]
	v_mfma_f32_16x16x32_bf16 v[36:39], v[162:165], v[192:195], v[36:39]
	v_mfma_f32_16x16x32_bf16 v[36:39], v[166:169], v[196:199], v[36:39]
	v_mfma_f32_16x16x32_bf16 v[32:35], v[170:173], v[192:195], v[32:35]
	v_mfma_f32_16x16x32_bf16 v[32:35], v[174:177], v[196:199], v[32:35]
	v_mfma_f32_16x16x32_bf16 v[20:23], v[162:165], v[200:203], v[20:23]
	v_mfma_f32_16x16x32_bf16 v[20:23], v[166:169], v[204:207], v[20:23]
	v_mfma_f32_16x16x32_bf16 v[16:19], v[170:173], v[200:203], v[16:19]
	v_mfma_f32_16x16x32_bf16 v[16:19], v[174:177], v[204:207], v[16:19]
	v_mfma_f32_16x16x32_bf16 v[4:7], v[162:165], v[208:211], v[4:7]
	v_mfma_f32_16x16x32_bf16 v[4:7], v[166:169], v[212:215], v[4:7]
	v_mfma_f32_16x16x32_bf16 v[0:3], v[170:173], v[208:211], v[0:3]
	v_mfma_f32_16x16x32_bf16 v[0:3], v[174:177], v[212:215], v[0:3]
	s_setprio 0
	s_barrier
.Lmid_gemm0:
	s_add_i32 s18, 0, 0x18000
	s_add_i32 s19, 0, 0x1c000
	v_add_u32_e32 v158, s18, v145
	v_add_u32_e32 v174, s19, v145
	ds_read_b128 v[140:143], v158
	ds_read_b128 v[150:153], v158 offset:1024
	ds_read_b128 v[154:157], v158 offset:2048
	ds_read_b128 v[158:161], v158 offset:3072
	ds_read_b128 v[162:165], v174
	ds_read_b128 v[166:169], v174 offset:1024
	ds_read_b128 v[170:173], v174 offset:2048
	ds_read_b128 v[174:177], v174 offset:3072
	s_add_u32 s48, s48, 0x40000
	s_addc_u32 s49, s49, 0
	s_mov_b32 m0, s57
	v_lshl_add_u64 v[222:223], s[48:49], 0, v[130:131]
	ds_read_b128 v[184:187], v149 offset:32768
	ds_read_b128 v[188:191], v149 offset:33792
	ds_read_b128 v[192:195], v149 offset:34816
	ds_read_b128 v[196:199], v149 offset:35840
	ds_read_b128 v[200:203], v149 offset:36864
	ds_read_b128 v[204:207], v149 offset:37888
	ds_read_b128 v[208:211], v149 offset:38912
	ds_read_b128 v[212:215], v149 offset:39936
	global_load_lds_dwordx4 v[222:223], off
	v_lshl_add_u64 v[222:223], s[48:49], 0, v[128:129]
	s_mov_b32 m0, s58
	s_nop 0
	global_load_lds_dwordx4 v[222:223], off
	s_waitcnt vmcnt(8)
	s_waitcnt lgkmcnt(0)
	s_barrier
	s_setprio 1
	s_waitcnt lgkmcnt(0)
	v_mfma_f32_16x16x32_bf16 v[124:127], v[140:143], v[184:187], v[124:127]
	v_mfma_f32_16x16x32_bf16 v[124:127], v[150:153], v[188:191], v[124:127]
	v_mfma_f32_16x16x32_bf16 v[120:123], v[154:157], v[184:187], v[120:123]
	v_mfma_f32_16x16x32_bf16 v[120:123], v[158:161], v[188:191], v[120:123]
	v_mfma_f32_16x16x32_bf16 v[108:111], v[140:143], v[192:195], v[108:111]
	v_mfma_f32_16x16x32_bf16 v[108:111], v[150:153], v[196:199], v[108:111]
	v_mfma_f32_16x16x32_bf16 v[104:107], v[154:157], v[192:195], v[104:107]
	v_mfma_f32_16x16x32_bf16 v[104:107], v[158:161], v[196:199], v[104:107]
	v_mfma_f32_16x16x32_bf16 v[92:95], v[140:143], v[200:203], v[92:95]
	v_mfma_f32_16x16x32_bf16 v[92:95], v[150:153], v[204:207], v[92:95]
	v_mfma_f32_16x16x32_bf16 v[88:91], v[154:157], v[200:203], v[88:91]
	v_mfma_f32_16x16x32_bf16 v[88:91], v[158:161], v[204:207], v[88:91]
	v_mfma_f32_16x16x32_bf16 v[76:79], v[140:143], v[208:211], v[76:79]
	v_mfma_f32_16x16x32_bf16 v[76:79], v[150:153], v[212:215], v[76:79]
	v_mfma_f32_16x16x32_bf16 v[72:75], v[154:157], v[208:211], v[72:75]
	v_mfma_f32_16x16x32_bf16 v[72:75], v[158:161], v[212:215], v[72:75]
	s_setprio 0
	s_setprio 1
	v_mfma_f32_16x16x32_bf16 v[116:119], v[162:165], v[184:187], v[116:119]
	v_mfma_f32_16x16x32_bf16 v[116:119], v[166:169], v[188:191], v[116:119]
	v_mfma_f32_16x16x32_bf16 v[112:115], v[170:173], v[184:187], v[112:115]
	v_mfma_f32_16x16x32_bf16 v[112:115], v[174:177], v[188:191], v[112:115]
	v_mfma_f32_16x16x32_bf16 v[100:103], v[162:165], v[192:195], v[100:103]
	v_mfma_f32_16x16x32_bf16 v[100:103], v[166:169], v[196:199], v[100:103]
	v_mfma_f32_16x16x32_bf16 v[96:99], v[170:173], v[192:195], v[96:99]
	v_mfma_f32_16x16x32_bf16 v[96:99], v[174:177], v[196:199], v[96:99]
	v_mfma_f32_16x16x32_bf16 v[84:87], v[162:165], v[200:203], v[84:87]
	v_mfma_f32_16x16x32_bf16 v[84:87], v[166:169], v[204:207], v[84:87]
	v_mfma_f32_16x16x32_bf16 v[80:83], v[170:173], v[200:203], v[80:83]
	v_mfma_f32_16x16x32_bf16 v[80:83], v[174:177], v[204:207], v[80:83]
	v_mfma_f32_16x16x32_bf16 v[68:71], v[162:165], v[208:211], v[68:71]
	v_mfma_f32_16x16x32_bf16 v[68:71], v[166:169], v[212:215], v[68:71]
	v_mfma_f32_16x16x32_bf16 v[64:67], v[170:173], v[208:211], v[64:67]
	v_mfma_f32_16x16x32_bf16 v[64:67], v[174:177], v[212:215], v[64:67]
	s_setprio 0
	s_barrier
	s_add_i32 s18, s18, s54
	v_lshl_add_u64 v[178:179], v[178:179], 0, s[6:7]
	s_mov_b32 m0, s18
	ds_read_b128 v[184:187], v149 offset:49152
	ds_read_b128 v[188:191], v149 offset:50176
	ds_read_b128 v[192:195], v149 offset:51200
	ds_read_b128 v[196:199], v149 offset:52224
	ds_read_b128 v[200:203], v149 offset:53248
	ds_read_b128 v[204:207], v149 offset:54272
	ds_read_b128 v[208:211], v149 offset:55296
	ds_read_b128 v[212:215], v149 offset:56320
	global_load_lds_dwordx4 v[178:179], off
	s_add_i32 m0, s18, 0x2000
	s_add_u32 s46, s46, 0x40080
	v_lshl_add_u64 v[178:179], v[216:217], 0, s[6:7]
	s_addc_u32 s47, s47, 0
	s_add_i32 s18, s19, s54
	global_load_lds_dwordx4 v[178:179], off
	v_lshl_add_u64 v[178:179], s[46:47], 0, v[130:131]
	s_mov_b32 m0, s18
	s_nop 0
	global_load_lds_dwordx4 v[178:179], off
	v_lshl_add_u64 v[178:179], s[46:47], 0, v[128:129]
	s_add_i32 m0, s18, 0x2000
	s_nop 0
	global_load_lds_dwordx4 v[178:179], off
	v_lshl_add_u64 v[178:179], v[218:219], 0, s[6:7]
	s_mov_b32 m0, s60
	s_nop 0
	global_load_lds_dwordx4 v[178:179], off
	v_lshl_add_u64 v[178:179], v[220:221], 0, s[6:7]
	s_mov_b32 m0, s61
	s_nop 0
	global_load_lds_dwordx4 v[178:179], off
	s_waitcnt vmcnt(8)
	s_waitcnt lgkmcnt(0)
	s_barrier
	s_setprio 1
	s_waitcnt lgkmcnt(0)
	v_mfma_f32_16x16x32_bf16 v[60:63], v[140:143], v[184:187], v[60:63]
	v_mfma_f32_16x16x32_bf16 v[60:63], v[150:153], v[188:191], v[60:63]
	v_mfma_f32_16x16x32_bf16 v[56:59], v[154:157], v[184:187], v[56:59]
	v_mfma_f32_16x16x32_bf16 v[56:59], v[158:161], v[188:191], v[56:59]
	v_mfma_f32_16x16x32_bf16 v[44:47], v[140:143], v[192:195], v[44:47]
	v_mfma_f32_16x16x32_bf16 v[44:47], v[150:153], v[196:199], v[44:47]
	v_mfma_f32_16x16x32_bf16 v[40:43], v[154:157], v[192:195], v[40:43]
	v_mfma_f32_16x16x32_bf16 v[40:43], v[158:161], v[196:199], v[40:43]
	v_mfma_f32_16x16x32_bf16 v[28:31], v[140:143], v[200:203], v[28:31]
	v_mfma_f32_16x16x32_bf16 v[28:31], v[150:153], v[204:207], v[28:31]
	v_mfma_f32_16x16x32_bf16 v[24:27], v[154:157], v[200:203], v[24:27]
	v_mfma_f32_16x16x32_bf16 v[24:27], v[158:161], v[204:207], v[24:27]
	v_mfma_f32_16x16x32_bf16 v[12:15], v[140:143], v[208:211], v[12:15]
	v_mfma_f32_16x16x32_bf16 v[12:15], v[150:153], v[212:215], v[12:15]
	v_mfma_f32_16x16x32_bf16 v[8:11], v[154:157], v[208:211], v[8:11]
	v_mfma_f32_16x16x32_bf16 v[8:11], v[158:161], v[212:215], v[8:11]
	s_setprio 0
	s_setprio 1
	v_mfma_f32_16x16x32_bf16 v[52:55], v[162:165], v[184:187], v[52:55]
	v_mfma_f32_16x16x32_bf16 v[52:55], v[166:169], v[188:191], v[52:55]
	v_mfma_f32_16x16x32_bf16 v[48:51], v[170:173], v[184:187], v[48:51]
	v_mfma_f32_16x16x32_bf16 v[48:51], v[174:177], v[188:191], v[48:51]
	v_mfma_f32_16x16x32_bf16 v[36:39], v[162:165], v[192:195], v[36:39]
	v_mfma_f32_16x16x32_bf16 v[36:39], v[166:169], v[196:199], v[36:39]
	v_mfma_f32_16x16x32_bf16 v[32:35], v[170:173], v[192:195], v[32:35]
	v_mfma_f32_16x16x32_bf16 v[32:35], v[174:177], v[196:199], v[32:35]
	v_mfma_f32_16x16x32_bf16 v[20:23], v[162:165], v[200:203], v[20:23]
	v_mfma_f32_16x16x32_bf16 v[20:23], v[166:169], v[204:207], v[20:23]
	v_mfma_f32_16x16x32_bf16 v[16:19], v[170:173], v[200:203], v[16:19]
	v_mfma_f32_16x16x32_bf16 v[16:19], v[174:177], v[204:207], v[16:19]
	v_mfma_f32_16x16x32_bf16 v[4:7], v[162:165], v[208:211], v[4:7]
	v_mfma_f32_16x16x32_bf16 v[4:7], v[166:169], v[212:215], v[4:7]
	v_mfma_f32_16x16x32_bf16 v[0:3], v[170:173], v[208:211], v[0:3]
	v_mfma_f32_16x16x32_bf16 v[0:3], v[174:177], v[212:215], v[0:3]
	s_setprio 0
	s_barrier
	s_add_i32 s70, s70, 2
	s_add_u32 s44, s44, 0x100
	s_addc_u32 s45, s45, 0
	s_add_u32 s68, s68, 0x100
	s_addc_u32 s69, s69, 0
	s_cmp_gt_u32 s70, 13
	s_cbranch_scc0 .LBB0_184
	s_and_b64 vcc, exec, s[8:9]
	s_cbranch_vccz .LBB0_187
	s_barrier

.LBB0_263:
	s_add_u32 s84, s54, 0x100
	s_addc_u32 s85, s55, 0
	s_mov_b32 s86, -2
	ds_read_b128 v[152:155], v149
	ds_read_b128 v[156:159], v149 offset:1024
	ds_read_b128 v[160:163], v149 offset:2048
	ds_read_b128 v[164:167], v149 offset:3072
	ds_read_b128 v[168:171], v150
	ds_read_b128 v[172:175], v150 offset:1024
	ds_read_b128 v[176:179], v150 offset:2048
	ds_read_b128 v[184:187], v150 offset:3072
	s_add_u32 s54, s52, 0x100
	s_addc_u32 s55, s53, 0
	s_cmp_eq_u32 s86, 40
	s_cselect_b32 s59, s7, s55
	s_cselect_b32 s58, s6, s54
	s_cselect_b32 s57, s49, s85
	s_cselect_b32 s56, s48, s84
	v_lshl_add_u64 v[144:145], s[52:53], 0, v[136:137]
	s_add_i32 m0, s63, 0xc000
	ds_read_b128 v[188:191], v151
	ds_read_b128 v[192:195], v151 offset:1024
	ds_read_b128 v[196:199], v151 offset:2048
	ds_read_b128 v[200:203], v151 offset:3072
	ds_read_b128 v[204:207], v151 offset:4096
	ds_read_b128 v[208:211], v151 offset:5120
	ds_read_b128 v[212:215], v151 offset:6144
	ds_read_b128 v[216:219], v151 offset:7168
	global_load_lds_dwordx4 v[144:145], off
	v_lshl_add_u64 v[144:145], s[52:53], 0, v[138:139]
	s_add_i32 m0, s63, 0xe000
	s_nop 0
	global_load_lds_dwordx4 v[144:145], off
	s_waitcnt vmcnt(8)
	s_waitcnt lgkmcnt(0)
	s_barrier
	s_setprio 1
	s_waitcnt lgkmcnt(0)
	v_mfma_f32_16x16x32_bf16 v[124:127], v[152:155], v[188:191], 0
	v_mfma_f32_16x16x32_bf16 v[124:127], v[156:159], v[192:195], v[124:127]
	v_mfma_f32_16x16x32_bf16 v[120:123], v[160:163], v[188:191], 0
	v_mfma_f32_16x16x32_bf16 v[120:123], v[164:167], v[192:195], v[120:123]
	v_mfma_f32_16x16x32_bf16 v[116:119], v[152:155], v[196:199], 0
	v_mfma_f32_16x16x32_bf16 v[116:119], v[156:159], v[200:203], v[116:119]
	v_mfma_f32_16x16x32_bf16 v[108:111], v[160:163], v[196:199], 0
	v_mfma_f32_16x16x32_bf16 v[108:111], v[164:167], v[200:203], v[108:111]
	v_mfma_f32_16x16x32_bf16 v[100:103], v[152:155], v[204:207], 0
	v_mfma_f32_16x16x32_bf16 v[100:103], v[156:159], v[208:211], v[100:103]
	v_mfma_f32_16x16x32_bf16 v[92:95], v[160:163], v[204:207], 0
	v_mfma_f32_16x16x32_bf16 v[92:95], v[164:167], v[208:211], v[92:95]
	v_mfma_f32_16x16x32_bf16 v[84:87], v[152:155], v[212:215], 0
	v_mfma_f32_16x16x32_bf16 v[84:87], v[156:159], v[216:219], v[84:87]
	v_mfma_f32_16x16x32_bf16 v[76:79], v[160:163], v[212:215], 0
	v_mfma_f32_16x16x32_bf16 v[76:79], v[164:167], v[216:219], v[76:79]
	s_setprio 0
	s_setprio 1
	v_mfma_f32_16x16x32_bf16 v[112:115], v[168:171], v[188:191], 0
	v_mfma_f32_16x16x32_bf16 v[112:115], v[172:175], v[192:195], v[112:115]
	v_mfma_f32_16x16x32_bf16 v[104:107], v[176:179], v[188:191], 0
	v_mfma_f32_16x16x32_bf16 v[104:107], v[184:187], v[192:195], v[104:107]
	v_mfma_f32_16x16x32_bf16 v[96:99], v[168:171], v[196:199], 0
	v_mfma_f32_16x16x32_bf16 v[96:99], v[172:175], v[200:203], v[96:99]
	v_mfma_f32_16x16x32_bf16 v[88:91], v[176:179], v[196:199], 0
	v_mfma_f32_16x16x32_bf16 v[88:91], v[184:187], v[200:203], v[88:91]
	v_mfma_f32_16x16x32_bf16 v[80:83], v[168:171], v[204:207], 0
	v_mfma_f32_16x16x32_bf16 v[80:83], v[172:175], v[208:211], v[80:83]
	v_mfma_f32_16x16x32_bf16 v[72:75], v[176:179], v[204:207], 0
	v_mfma_f32_16x16x32_bf16 v[72:75], v[184:187], v[208:211], v[72:75]
	v_mfma_f32_16x16x32_bf16 v[68:71], v[168:171], v[212:215], 0
	v_mfma_f32_16x16x32_bf16 v[68:71], v[172:175], v[216:219], v[68:71]
	v_mfma_f32_16x16x32_bf16 v[64:67], v[176:179], v[212:215], 0
	v_mfma_f32_16x16x32_bf16 v[64:67], v[184:187], v[216:219], v[64:67]
	s_setprio 0
	s_barrier
	s_add_i32 s18, s70, s62
	v_lshl_add_u64 v[144:145], s[56:57], 0, v[130:131]
	s_mov_b32 m0, s18
	ds_read_b128 v[188:191], v151 offset:16384
	ds_read_b128 v[192:195], v151 offset:17408
	ds_read_b128 v[196:199], v151 offset:18432
	ds_read_b128 v[200:203], v151 offset:19456
	ds_read_b128 v[204:207], v151 offset:20480
	ds_read_b128 v[208:211], v151 offset:21504
	ds_read_b128 v[212:215], v151 offset:22528
	ds_read_b128 v[216:219], v151 offset:23552
	global_load_lds_dwordx4 v[144:145], off
	s_add_i32 m0, s18, 0x2000
	s_add_u32 s52, s56, 0xb0000
	v_lshl_add_u64 v[220:221], s[56:57], 0, v[134:135]
	s_addc_u32 s53, s57, 0
	s_add_i32 s18, s71, s62
	global_load_lds_dwordx4 v[220:221], off
	v_lshl_add_u64 v[222:223], s[52:53], 0, v[130:131]
	s_mov_b32 m0, s18
	v_lshl_add_u64 v[224:225], s[58:59], 0, v[132:133]
	global_load_lds_dwordx4 v[222:223], off
	v_lshl_add_u64 v[222:223], s[52:53], 0, v[134:135]
	s_add_i32 m0, s18, 0x2000
	s_nop 0
	global_load_lds_dwordx4 v[222:223], off
	v_lshl_add_u64 v[222:223], s[58:59], 0, v[128:129]
	s_mov_b32 m0, s63
	s_nop 0
	global_load_lds_dwordx4 v[222:223], off
	s_mov_b32 m0, s64
	s_nop 0
	global_load_lds_dwordx4 v[224:225], off
	s_waitcnt vmcnt(8)
	s_waitcnt lgkmcnt(0)
	s_barrier
	s_setprio 1
	s_waitcnt lgkmcnt(0)
	v_mfma_f32_16x16x32_bf16 v[60:63], v[152:155], v[188:191], 0
	v_mfma_f32_16x16x32_bf16 v[60:63], v[156:159], v[192:195], v[60:63]
	v_mfma_f32_16x16x32_bf16 v[56:59], v[160:163], v[188:191], 0
	v_mfma_f32_16x16x32_bf16 v[56:59], v[164:167], v[192:195], v[56:59]
	v_mfma_f32_16x16x32_bf16 v[52:55], v[152:155], v[196:199], 0
	v_mfma_f32_16x16x32_bf16 v[52:55], v[156:159], v[200:203], v[52:55]
	v_mfma_f32_16x16x32_bf16 v[44:47], v[160:163], v[196:199], 0
	v_mfma_f32_16x16x32_bf16 v[44:47], v[164:167], v[200:203], v[44:47]
	v_mfma_f32_16x16x32_bf16 v[36:39], v[152:155], v[204:207], 0
	v_mfma_f32_16x16x32_bf16 v[36:39], v[156:159], v[208:211], v[36:39]
	v_mfma_f32_16x16x32_bf16 v[28:31], v[160:163], v[204:207], 0
	v_mfma_f32_16x16x32_bf16 v[28:31], v[164:167], v[208:211], v[28:31]
	v_mfma_f32_16x16x32_bf16 v[20:23], v[152:155], v[212:215], 0
	v_mfma_f32_16x16x32_bf16 v[20:23], v[156:159], v[216:219], v[20:23]
	v_mfma_f32_16x16x32_bf16 v[12:15], v[160:163], v[212:215], 0
	v_mfma_f32_16x16x32_bf16 v[12:15], v[164:167], v[216:219], v[12:15]
	s_setprio 0
	s_setprio 1
	v_mfma_f32_16x16x32_bf16 v[48:51], v[168:171], v[188:191], 0
	v_mfma_f32_16x16x32_bf16 v[48:51], v[172:175], v[192:195], v[48:51]
	v_mfma_f32_16x16x32_bf16 v[40:43], v[176:179], v[188:191], 0
	v_mfma_f32_16x16x32_bf16 v[40:43], v[184:187], v[192:195], v[40:43]
	v_mfma_f32_16x16x32_bf16 v[32:35], v[168:171], v[196:199], 0
	v_mfma_f32_16x16x32_bf16 v[32:35], v[172:175], v[200:203], v[32:35]
	v_mfma_f32_16x16x32_bf16 v[24:27], v[176:179], v[196:199], 0
	v_mfma_f32_16x16x32_bf16 v[24:27], v[184:187], v[200:203], v[24:27]
	v_mfma_f32_16x16x32_bf16 v[16:19], v[168:171], v[204:207], 0
	v_mfma_f32_16x16x32_bf16 v[16:19], v[172:175], v[208:211], v[16:19]
	v_mfma_f32_16x16x32_bf16 v[8:11], v[176:179], v[204:207], 0
	v_mfma_f32_16x16x32_bf16 v[8:11], v[184:187], v[208:211], v[8:11]
	v_mfma_f32_16x16x32_bf16 v[4:7], v[168:171], v[212:215], 0
	v_mfma_f32_16x16x32_bf16 v[4:7], v[172:175], v[216:219], v[4:7]
	v_mfma_f32_16x16x32_bf16 v[0:3], v[176:179], v[212:215], 0
	v_mfma_f32_16x16x32_bf16 v[0:3], v[184:187], v[216:219], v[0:3]
	s_setprio 0
	s_barrier
	s_branch .Lmid_gemm1
.LBB0_264:
	ds_read_b128 v[152:155], v149
	ds_read_b128 v[156:159], v149 offset:1024
	ds_read_b128 v[160:163], v149 offset:2048
	ds_read_b128 v[164:167], v149 offset:3072
	ds_read_b128 v[168:171], v150
	ds_read_b128 v[172:175], v150 offset:1024
	ds_read_b128 v[176:179], v150 offset:2048
	ds_read_b128 v[184:187], v150 offset:3072
	s_add_u32 s54, s52, 0x100
	s_addc_u32 s55, s53, 0
	s_cmp_eq_u32 s86, 40
	s_cselect_b32 s59, s7, s55
	s_cselect_b32 s58, s6, s54
	s_cselect_b32 s57, s49, s85
	s_cselect_b32 s56, s48, s84
	v_lshl_add_u64 v[144:145], s[52:53], 0, v[136:137]
	s_add_i32 m0, s63, 0xc000
	ds_read_b128 v[188:191], v151
	ds_read_b128 v[192:195], v151 offset:1024
	ds_read_b128 v[196:199], v151 offset:2048
	ds_read_b128 v[200:203], v151 offset:3072
	ds_read_b128 v[204:207], v151 offset:4096
	ds_read_b128 v[208:211], v151 offset:5120
	ds_read_b128 v[212:215], v151 offset:6144
	ds_read_b128 v[216:219], v151 offset:7168
	global_load_lds_dwordx4 v[144:145], off
	v_lshl_add_u64 v[144:145], s[52:53], 0, v[138:139]
	s_add_i32 m0, s63, 0xe000
	s_nop 0
	global_load_lds_dwordx4 v[144:145], off
	s_waitcnt vmcnt(8)
	s_waitcnt lgkmcnt(0)
	s_barrier
	s_setprio 1
	s_waitcnt lgkmcnt(0)
	v_mfma_f32_16x16x32_bf16 v[124:127], v[152:155], v[188:191], v[124:127]
	v_mfma_f32_16x16x32_bf16 v[124:127], v[156:159], v[192:195], v[124:127]
	v_mfma_f32_16x16x32_bf16 v[120:123], v[160:163], v[188:191], v[120:123]
	v_mfma_f32_16x16x32_bf16 v[120:123], v[164:167], v[192:195], v[120:123]
	v_mfma_f32_16x16x32_bf16 v[116:119], v[152:155], v[196:199], v[116:119]
	v_mfma_f32_16x16x32_bf16 v[116:119], v[156:159], v[200:203], v[116:119]
	v_mfma_f32_16x16x32_bf16 v[108:111], v[160:163], v[196:199], v[108:111]
	v_mfma_f32_16x16x32_bf16 v[108:111], v[164:167], v[200:203], v[108:111]
	v_mfma_f32_16x16x32_bf16 v[100:103], v[152:155], v[204:207], v[100:103]
	v_mfma_f32_16x16x32_bf16 v[100:103], v[156:159], v[208:211], v[100:103]
	v_mfma_f32_16x16x32_bf16 v[92:95], v[160:163], v[204:207], v[92:95]
	v_mfma_f32_16x16x32_bf16 v[92:95], v[164:167], v[208:211], v[92:95]
	v_mfma_f32_16x16x32_bf16 v[84:87], v[152:155], v[212:215], v[84:87]
	v_mfma_f32_16x16x32_bf16 v[84:87], v[156:159], v[216:219], v[84:87]
	v_mfma_f32_16x16x32_bf16 v[76:79], v[160:163], v[212:215], v[76:79]
	v_mfma_f32_16x16x32_bf16 v[76:79], v[164:167], v[216:219], v[76:79]
	s_setprio 0
	s_setprio 1
	v_mfma_f32_16x16x32_bf16 v[112:115], v[168:171], v[188:191], v[112:115]
	v_mfma_f32_16x16x32_bf16 v[112:115], v[172:175], v[192:195], v[112:115]
	v_mfma_f32_16x16x32_bf16 v[104:107], v[176:179], v[188:191], v[104:107]
	v_mfma_f32_16x16x32_bf16 v[104:107], v[184:187], v[192:195], v[104:107]
	v_mfma_f32_16x16x32_bf16 v[96:99], v[168:171], v[196:199], v[96:99]
	v_mfma_f32_16x16x32_bf16 v[96:99], v[172:175], v[200:203], v[96:99]
	v_mfma_f32_16x16x32_bf16 v[88:91], v[176:179], v[196:199], v[88:91]
	v_mfma_f32_16x16x32_bf16 v[88:91], v[184:187], v[200:203], v[88:91]
	v_mfma_f32_16x16x32_bf16 v[80:83], v[168:171], v[204:207], v[80:83]
	v_mfma_f32_16x16x32_bf16 v[80:83], v[172:175], v[208:211], v[80:83]
	v_mfma_f32_16x16x32_bf16 v[72:75], v[176:179], v[204:207], v[72:75]
	v_mfma_f32_16x16x32_bf16 v[72:75], v[184:187], v[208:211], v[72:75]
	v_mfma_f32_16x16x32_bf16 v[68:71], v[168:171], v[212:215], v[68:71]
	v_mfma_f32_16x16x32_bf16 v[68:71], v[172:175], v[216:219], v[68:71]
	v_mfma_f32_16x16x32_bf16 v[64:67], v[176:179], v[212:215], v[64:67]
	v_mfma_f32_16x16x32_bf16 v[64:67], v[184:187], v[216:219], v[64:67]
	s_setprio 0
	s_barrier
	s_add_i32 s18, s70, s62
	v_lshl_add_u64 v[144:145], s[56:57], 0, v[130:131]
	s_mov_b32 m0, s18
	ds_read_b128 v[188:191], v151 offset:16384
	ds_read_b128 v[192:195], v151 offset:17408
	ds_read_b128 v[196:199], v151 offset:18432
	ds_read_b128 v[200:203], v151 offset:19456
	ds_read_b128 v[204:207], v151 offset:20480
	ds_read_b128 v[208:211], v151 offset:21504
	ds_read_b128 v[212:215], v151 offset:22528
	ds_read_b128 v[216:219], v151 offset:23552
	global_load_lds_dwordx4 v[144:145], off
	s_add_i32 m0, s18, 0x2000
	s_add_u32 s52, s56, 0xb0000
	v_lshl_add_u64 v[220:221], s[56:57], 0, v[134:135]
	s_addc_u32 s53, s57, 0
	s_add_i32 s18, s71, s62
	global_load_lds_dwordx4 v[220:221], off
	v_lshl_add_u64 v[222:223], s[52:53], 0, v[130:131]
	s_mov_b32 m0, s18
	v_lshl_add_u64 v[224:225], s[58:59], 0, v[132:133]
	global_load_lds_dwordx4 v[222:223], off
	v_lshl_add_u64 v[222:223], s[52:53], 0, v[134:135]
	s_add_i32 m0, s18, 0x2000
	s_nop 0
	global_load_lds_dwordx4 v[222:223], off
	v_lshl_add_u64 v[222:223], s[58:59], 0, v[128:129]
	s_mov_b32 m0, s63
	s_nop 0
	global_load_lds_dwordx4 v[222:223], off
	s_mov_b32 m0, s64
	s_nop 0
	global_load_lds_dwordx4 v[224:225], off
	s_waitcnt vmcnt(8)
	s_waitcnt lgkmcnt(0)
	s_barrier
	s_setprio 1
	s_waitcnt lgkmcnt(0)
	v_mfma_f32_16x16x32_bf16 v[60:63], v[152:155], v[188:191], v[60:63]
	v_mfma_f32_16x16x32_bf16 v[60:63], v[156:159], v[192:195], v[60:63]
	v_mfma_f32_16x16x32_bf16 v[56:59], v[160:163], v[188:191], v[56:59]
	v_mfma_f32_16x16x32_bf16 v[56:59], v[164:167], v[192:195], v[56:59]
	v_mfma_f32_16x16x32_bf16 v[52:55], v[152:155], v[196:199], v[52:55]
	v_mfma_f32_16x16x32_bf16 v[52:55], v[156:159], v[200:203], v[52:55]
	v_mfma_f32_16x16x32_bf16 v[44:47], v[160:163], v[196:199], v[44:47]
	v_mfma_f32_16x16x32_bf16 v[44:47], v[164:167], v[200:203], v[44:47]
	v_mfma_f32_16x16x32_bf16 v[36:39], v[152:155], v[204:207], v[36:39]
	v_mfma_f32_16x16x32_bf16 v[36:39], v[156:159], v[208:211], v[36:39]
	v_mfma_f32_16x16x32_bf16 v[28:31], v[160:163], v[204:207], v[28:31]
	v_mfma_f32_16x16x32_bf16 v[28:31], v[164:167], v[208:211], v[28:31]
	v_mfma_f32_16x16x32_bf16 v[20:23], v[152:155], v[212:215], v[20:23]
	v_mfma_f32_16x16x32_bf16 v[20:23], v[156:159], v[216:219], v[20:23]
	v_mfma_f32_16x16x32_bf16 v[12:15], v[160:163], v[212:215], v[12:15]
	v_mfma_f32_16x16x32_bf16 v[12:15], v[164:167], v[216:219], v[12:15]
	s_setprio 0
	s_setprio 1
	v_mfma_f32_16x16x32_bf16 v[48:51], v[168:171], v[188:191], v[48:51]
	v_mfma_f32_16x16x32_bf16 v[48:51], v[172:175], v[192:195], v[48:51]
	v_mfma_f32_16x16x32_bf16 v[40:43], v[176:179], v[188:191], v[40:43]
	v_mfma_f32_16x16x32_bf16 v[40:43], v[184:187], v[192:195], v[40:43]
	v_mfma_f32_16x16x32_bf16 v[32:35], v[168:171], v[196:199], v[32:35]
	v_mfma_f32_16x16x32_bf16 v[32:35], v[172:175], v[200:203], v[32:35]
	v_mfma_f32_16x16x32_bf16 v[24:27], v[176:179], v[196:199], v[24:27]
	v_mfma_f32_16x16x32_bf16 v[24:27], v[184:187], v[200:203], v[24:27]
	v_mfma_f32_16x16x32_bf16 v[16:19], v[168:171], v[204:207], v[16:19]
	v_mfma_f32_16x16x32_bf16 v[16:19], v[172:175], v[208:211], v[16:19]
	v_mfma_f32_16x16x32_bf16 v[8:11], v[176:179], v[204:207], v[8:11]
	v_mfma_f32_16x16x32_bf16 v[8:11], v[184:187], v[208:211], v[8:11]
	v_mfma_f32_16x16x32_bf16 v[4:7], v[168:171], v[212:215], v[4:7]
	v_mfma_f32_16x16x32_bf16 v[4:7], v[172:175], v[216:219], v[4:7]
	v_mfma_f32_16x16x32_bf16 v[0:3], v[176:179], v[212:215], v[0:3]
	v_mfma_f32_16x16x32_bf16 v[0:3], v[184:187], v[216:219], v[0:3]
	s_setprio 0
	s_barrier
.Lmid_gemm1:
	s_add_i32 s18, 0, 0x18000
	s_add_i32 s19, 0, 0x1c000
	v_add_u32_e32 v164, s18, v147
	v_add_u32_e32 v181, s19, v147
	ds_read_b128 v[152:155], v164
	ds_read_b128 v[156:159], v164 offset:1024
	ds_read_b128 v[160:163], v164 offset:2048
	ds_read_b128 v[164:167], v164 offset:3072
	ds_read_b128 v[168:171], v181
	ds_read_b128 v[172:175], v181 offset:1024
	ds_read_b128 v[176:179], v181 offset:2048
	ds_read_b128 v[184:187], v181 offset:3072
	s_add_u32 s52, s58, 0xb0000
	s_addc_u32 s53, s59, 0
	s_mov_b32 m0, s65
	v_lshl_add_u64 v[226:227], s[52:53], 0, v[128:129]
	ds_read_b128 v[188:191], v151 offset:32768
	ds_read_b128 v[192:195], v151 offset:33792
	ds_read_b128 v[196:199], v151 offset:34816
	ds_read_b128 v[200:203], v151 offset:35840
	ds_read_b128 v[204:207], v151 offset:36864
	ds_read_b128 v[208:211], v151 offset:37888
	ds_read_b128 v[212:215], v151 offset:38912
	ds_read_b128 v[216:219], v151 offset:39936
	global_load_lds_dwordx4 v[226:227], off
	v_lshl_add_u64 v[226:227], s[52:53], 0, v[132:133]
	s_mov_b32 m0, s66
	s_nop 0
	global_load_lds_dwordx4 v[226:227], off
	s_waitcnt vmcnt(8)
	s_waitcnt lgkmcnt(0)
	s_barrier
	s_setprio 1
	s_waitcnt lgkmcnt(0)
	v_mfma_f32_16x16x32_bf16 v[124:127], v[152:155], v[188:191], v[124:127]
	v_mfma_f32_16x16x32_bf16 v[124:127], v[156:159], v[192:195], v[124:127]
	v_mfma_f32_16x16x32_bf16 v[120:123], v[160:163], v[188:191], v[120:123]
	v_mfma_f32_16x16x32_bf16 v[120:123], v[164:167], v[192:195], v[120:123]
	v_mfma_f32_16x16x32_bf16 v[116:119], v[152:155], v[196:199], v[116:119]
	v_mfma_f32_16x16x32_bf16 v[116:119], v[156:159], v[200:203], v[116:119]
	v_mfma_f32_16x16x32_bf16 v[108:111], v[160:163], v[196:199], v[108:111]
	v_mfma_f32_16x16x32_bf16 v[108:111], v[164:167], v[200:203], v[108:111]
	v_mfma_f32_16x16x32_bf16 v[100:103], v[152:155], v[204:207], v[100:103]
	v_mfma_f32_16x16x32_bf16 v[100:103], v[156:159], v[208:211], v[100:103]
	v_mfma_f32_16x16x32_bf16 v[92:95], v[160:163], v[204:207], v[92:95]
	v_mfma_f32_16x16x32_bf16 v[92:95], v[164:167], v[208:211], v[92:95]
	v_mfma_f32_16x16x32_bf16 v[84:87], v[152:155], v[212:215], v[84:87]
	v_mfma_f32_16x16x32_bf16 v[84:87], v[156:159], v[216:219], v[84:87]
	v_mfma_f32_16x16x32_bf16 v[76:79], v[160:163], v[212:215], v[76:79]
	v_mfma_f32_16x16x32_bf16 v[76:79], v[164:167], v[216:219], v[76:79]
	s_setprio 0
	s_setprio 1
	v_mfma_f32_16x16x32_bf16 v[112:115], v[168:171], v[188:191], v[112:115]
	v_mfma_f32_16x16x32_bf16 v[112:115], v[172:175], v[192:195], v[112:115]
	v_mfma_f32_16x16x32_bf16 v[104:107], v[176:179], v[188:191], v[104:107]
	v_mfma_f32_16x16x32_bf16 v[104:107], v[184:187], v[192:195], v[104:107]
	v_mfma_f32_16x16x32_bf16 v[96:99], v[168:171], v[196:199], v[96:99]
	v_mfma_f32_16x16x32_bf16 v[96:99], v[172:175], v[200:203], v[96:99]
	v_mfma_f32_16x16x32_bf16 v[88:91], v[176:179], v[196:199], v[88:91]
	v_mfma_f32_16x16x32_bf16 v[88:91], v[184:187], v[200:203], v[88:91]
	v_mfma_f32_16x16x32_bf16 v[80:83], v[168:171], v[204:207], v[80:83]
	v_mfma_f32_16x16x32_bf16 v[80:83], v[172:175], v[208:211], v[80:83]
	v_mfma_f32_16x16x32_bf16 v[72:75], v[176:179], v[204:207], v[72:75]
	v_mfma_f32_16x16x32_bf16 v[72:75], v[184:187], v[208:211], v[72:75]
	v_mfma_f32_16x16x32_bf16 v[68:71], v[168:171], v[212:215], v[68:71]
	v_mfma_f32_16x16x32_bf16 v[68:71], v[172:175], v[216:219], v[68:71]
	v_mfma_f32_16x16x32_bf16 v[64:67], v[176:179], v[212:215], v[64:67]
	v_mfma_f32_16x16x32_bf16 v[64:67], v[184:187], v[216:219], v[64:67]
	s_setprio 0
	s_barrier
	s_add_i32 s18, s18, s62
	v_lshl_add_u64 v[144:145], v[144:145], 0, s[8:9]
	s_mov_b32 m0, s18
	ds_read_b128 v[188:191], v151 offset:49152
	ds_read_b128 v[192:195], v151 offset:50176
	ds_read_b128 v[196:199], v151 offset:51200
	ds_read_b128 v[200:203], v151 offset:52224
	ds_read_b128 v[204:207], v151 offset:53248
	ds_read_b128 v[208:211], v151 offset:54272
	ds_read_b128 v[212:215], v151 offset:55296
	ds_read_b128 v[216:219], v151 offset:56320
	global_load_lds_dwordx4 v[144:145], off
	s_add_i32 m0, s18, 0x2000
	s_add_u32 s52, s56, 0xb0080
	v_lshl_add_u64 v[144:145], v[220:221], 0, s[8:9]
	s_addc_u32 s53, s57, 0
	s_add_i32 s18, s19, s62
	global_load_lds_dwordx4 v[144:145], off
	v_lshl_add_u64 v[144:145], s[52:53], 0, v[130:131]
	s_mov_b32 m0, s18
	s_nop 0
	global_load_lds_dwordx4 v[144:145], off
	v_lshl_add_u64 v[144:145], s[52:53], 0, v[134:135]
	s_add_i32 m0, s18, 0x2000
	s_nop 0
	global_load_lds_dwordx4 v[144:145], off
	v_lshl_add_u64 v[144:145], v[222:223], 0, s[8:9]
	s_mov_b32 m0, s68
	s_nop 0
	global_load_lds_dwordx4 v[144:145], off
	v_lshl_add_u64 v[144:145], v[224:225], 0, s[8:9]
	s_mov_b32 m0, s69
	s_nop 0
	global_load_lds_dwordx4 v[144:145], off
	s_waitcnt vmcnt(8)
	s_waitcnt lgkmcnt(0)
	s_barrier
	s_setprio 1
	s_waitcnt lgkmcnt(0)
	v_mfma_f32_16x16x32_bf16 v[60:63], v[152:155], v[188:191], v[60:63]
	v_mfma_f32_16x16x32_bf16 v[60:63], v[156:159], v[192:195], v[60:63]
	v_mfma_f32_16x16x32_bf16 v[56:59], v[160:163], v[188:191], v[56:59]
	v_mfma_f32_16x16x32_bf16 v[56:59], v[164:167], v[192:195], v[56:59]
	v_mfma_f32_16x16x32_bf16 v[52:55], v[152:155], v[196:199], v[52:55]
	v_mfma_f32_16x16x32_bf16 v[52:55], v[156:159], v[200:203], v[52:55]
	v_mfma_f32_16x16x32_bf16 v[44:47], v[160:163], v[196:199], v[44:47]
	v_mfma_f32_16x16x32_bf16 v[44:47], v[164:167], v[200:203], v[44:47]
	v_mfma_f32_16x16x32_bf16 v[36:39], v[152:155], v[204:207], v[36:39]
	v_mfma_f32_16x16x32_bf16 v[36:39], v[156:159], v[208:211], v[36:39]
	v_mfma_f32_16x16x32_bf16 v[28:31], v[160:163], v[204:207], v[28:31]
	v_mfma_f32_16x16x32_bf16 v[28:31], v[164:167], v[208:211], v[28:31]
	v_mfma_f32_16x16x32_bf16 v[20:23], v[152:155], v[212:215], v[20:23]
	v_mfma_f32_16x16x32_bf16 v[20:23], v[156:159], v[216:219], v[20:23]
	v_mfma_f32_16x16x32_bf16 v[12:15], v[160:163], v[212:215], v[12:15]
	v_mfma_f32_16x16x32_bf16 v[12:15], v[164:167], v[216:219], v[12:15]
	s_setprio 0
	s_setprio 1
	v_mfma_f32_16x16x32_bf16 v[48:51], v[168:171], v[188:191], v[48:51]
	v_mfma_f32_16x16x32_bf16 v[48:51], v[172:175], v[192:195], v[48:51]
	v_mfma_f32_16x16x32_bf16 v[40:43], v[176:179], v[188:191], v[40:43]
	v_mfma_f32_16x16x32_bf16 v[40:43], v[184:187], v[192:195], v[40:43]
	v_mfma_f32_16x16x32_bf16 v[32:35], v[168:171], v[196:199], v[32:35]
	v_mfma_f32_16x16x32_bf16 v[32:35], v[172:175], v[200:203], v[32:35]
	v_mfma_f32_16x16x32_bf16 v[24:27], v[176:179], v[196:199], v[24:27]
	v_mfma_f32_16x16x32_bf16 v[24:27], v[184:187], v[200:203], v[24:27]
	v_mfma_f32_16x16x32_bf16 v[16:19], v[168:171], v[204:207], v[16:19]
	v_mfma_f32_16x16x32_bf16 v[16:19], v[172:175], v[208:211], v[16:19]
	v_mfma_f32_16x16x32_bf16 v[8:11], v[176:179], v[204:207], v[8:11]
	v_mfma_f32_16x16x32_bf16 v[8:11], v[184:187], v[208:211], v[8:11]
	v_mfma_f32_16x16x32_bf16 v[4:7], v[168:171], v[212:215], v[4:7]
	v_mfma_f32_16x16x32_bf16 v[4:7], v[172:175], v[216:219], v[4:7]
	v_mfma_f32_16x16x32_bf16 v[0:3], v[176:179], v[212:215], v[0:3]
	v_mfma_f32_16x16x32_bf16 v[0:3], v[184:187], v[216:219], v[0:3]
	s_setprio 0
	s_barrier
	s_add_i32 s86, s86, 2
	s_add_u32 s84, s84, 0x100
	s_addc_u32 s85, s85, 0
	s_cmp_gt_u32 s86, 41
	s_mov_b64 s[52:53], s[54:55]
	s_cbranch_scc0 .LBB0_264
	s_and_b64 vcc, exec, s[10:11]
	s_cbranch_vccz .LBB0_267
	s_barrier

.LBB0_386:
	s_ashr_i32 s49, s48, 31
	s_lshl_b64 s[52:53], s[48:49], 19
	s_add_u32 s52, s80, s52
	s_addc_u32 s53, s81, s53
	s_and_b64 s[54:55], s[4:5], exec
	s_cselect_b32 s49, s53, s59
	s_cselect_b32 s82, s52, s58
	s_ashr_i32 s47, s46, 31
	s_lshl_b64 s[54:55], s[46:47], 19
	s_add_u32 s54, s64, s54
	s_addc_u32 s55, s65, s55
	s_and_b64 s[62:63], s[4:5], exec
	s_cselect_b32 s47, s55, s61
	s_cselect_b32 s83, s54, s60
	s_add_u32 s58, s58, 0x40080
	s_addc_u32 s59, s59, 0
	s_add_u32 s84, s60, 0x100
	s_addc_u32 s85, s61, 0
	s_mov_b32 s86, -2
	ds_read_b128 v[152:155], v148
	ds_read_b128 v[156:159], v148 offset:1024
	ds_read_b128 v[160:163], v148 offset:2048
	ds_read_b128 v[164:167], v148 offset:3072
	ds_read_b128 v[168:171], v149
	ds_read_b128 v[172:175], v149 offset:1024
	ds_read_b128 v[176:179], v149 offset:2048
	ds_read_b128 v[184:187], v149 offset:3072
	s_add_u32 s18, s58, 0xfffc0080
	s_addc_u32 s19, s59, -1
	s_cmp_eq_u32 s86, 12
	s_cselect_b32 s63, s49, s19
	s_cselect_b32 s62, s82, s18
	s_cselect_b32 s61, s47, s85
	s_cselect_b32 s60, s83, s84
	v_lshl_add_u64 v[220:221], s[58:59], 0, v[138:139]
	s_add_i32 m0, s68, 0xc000
	ds_read_b128 v[188:191], v150
	ds_read_b128 v[192:195], v150 offset:1024
	ds_read_b128 v[196:199], v150 offset:2048
	ds_read_b128 v[200:203], v150 offset:3072
	ds_read_b128 v[204:207], v150 offset:4096
	ds_read_b128 v[208:211], v150 offset:5120
	ds_read_b128 v[212:215], v150 offset:6144
	ds_read_b128 v[216:219], v150 offset:7168
	global_load_lds_dwordx4 v[220:221], off
	v_lshl_add_u64 v[220:221], s[58:59], 0, v[140:141]
	s_add_i32 m0, s68, 0xe000
	s_nop 0
	global_load_lds_dwordx4 v[220:221], off
	s_waitcnt vmcnt(8)
	s_waitcnt lgkmcnt(0)
	s_barrier
	s_setprio 1
	s_waitcnt lgkmcnt(0)
	v_mfma_f32_16x16x32_bf16 v[124:127], v[152:155], v[188:191], 0
	v_mfma_f32_16x16x32_bf16 v[124:127], v[156:159], v[192:195], v[124:127]
	v_mfma_f32_16x16x32_bf16 v[120:123], v[160:163], v[188:191], 0
	v_mfma_f32_16x16x32_bf16 v[120:123], v[164:167], v[192:195], v[120:123]
	v_mfma_f32_16x16x32_bf16 v[116:119], v[152:155], v[196:199], 0
	v_mfma_f32_16x16x32_bf16 v[116:119], v[156:159], v[200:203], v[116:119]
	v_mfma_f32_16x16x32_bf16 v[112:115], v[160:163], v[196:199], 0
	v_mfma_f32_16x16x32_bf16 v[112:115], v[164:167], v[200:203], v[112:115]
	v_mfma_f32_16x16x32_bf16 v[108:111], v[152:155], v[204:207], 0
	v_mfma_f32_16x16x32_bf16 v[108:111], v[156:159], v[208:211], v[108:111]
	v_mfma_f32_16x16x32_bf16 v[104:107], v[160:163], v[204:207], 0
	v_mfma_f32_16x16x32_bf16 v[104:107], v[164:167], v[208:211], v[104:107]
	v_mfma_f32_16x16x32_bf16 v[100:103], v[152:155], v[212:215], 0
	v_mfma_f32_16x16x32_bf16 v[100:103], v[156:159], v[216:219], v[100:103]
	v_mfma_f32_16x16x32_bf16 v[96:99], v[160:163], v[212:215], 0
	v_mfma_f32_16x16x32_bf16 v[96:99], v[164:167], v[216:219], v[96:99]
	s_setprio 0
	s_setprio 1
	v_mfma_f32_16x16x32_bf16 v[68:71], v[168:171], v[188:191], 0
	v_mfma_f32_16x16x32_bf16 v[68:71], v[172:175], v[192:195], v[68:71]
	v_mfma_f32_16x16x32_bf16 v[64:67], v[176:179], v[188:191], 0
	v_mfma_f32_16x16x32_bf16 v[64:67], v[184:187], v[192:195], v[64:67]
	v_mfma_f32_16x16x32_bf16 v[52:55], v[168:171], v[196:199], 0
	v_mfma_f32_16x16x32_bf16 v[52:55], v[172:175], v[200:203], v[52:55]
	v_mfma_f32_16x16x32_bf16 v[48:51], v[176:179], v[196:199], 0
	v_mfma_f32_16x16x32_bf16 v[48:51], v[184:187], v[200:203], v[48:51]
	v_mfma_f32_16x16x32_bf16 v[44:47], v[168:171], v[204:207], 0
	v_mfma_f32_16x16x32_bf16 v[44:47], v[172:175], v[208:211], v[44:47]
	v_mfma_f32_16x16x32_bf16 v[40:43], v[176:179], v[204:207], 0
	v_mfma_f32_16x16x32_bf16 v[40:43], v[184:187], v[208:211], v[40:43]
	v_mfma_f32_16x16x32_bf16 v[36:39], v[168:171], v[212:215], 0
	v_mfma_f32_16x16x32_bf16 v[36:39], v[172:175], v[216:219], v[36:39]
	v_mfma_f32_16x16x32_bf16 v[32:35], v[176:179], v[212:215], 0
	v_mfma_f32_16x16x32_bf16 v[32:35], v[184:187], v[216:219], v[32:35]
	s_setprio 0
	s_barrier
	s_add_i32 s18, s76, s66
	v_lshl_add_u64 v[220:221], s[60:61], 0, v[132:133]
	s_mov_b32 m0, s18
	ds_read_b128 v[188:191], v150 offset:16384
	ds_read_b128 v[192:195], v150 offset:17408
	ds_read_b128 v[196:199], v150 offset:18432
	ds_read_b128 v[200:203], v150 offset:19456
	ds_read_b128 v[204:207], v150 offset:20480
	ds_read_b128 v[208:211], v150 offset:21504
	ds_read_b128 v[212:215], v150 offset:22528
	ds_read_b128 v[216:219], v150 offset:23552
	global_load_lds_dwordx4 v[220:221], off
	s_add_i32 m0, s18, 0x2000
	s_add_u32 s88, s60, 0x40000
	v_lshl_add_u64 v[222:223], s[60:61], 0, v[128:129]
	s_addc_u32 s89, s61, 0
	s_add_i32 s18, s77, s66
	global_load_lds_dwordx4 v[222:223], off
	v_lshl_add_u64 v[224:225], s[88:89], 0, v[132:133]
	s_mov_b32 m0, s18
	v_lshl_add_u64 v[226:227], s[62:63], 0, v[130:131]
	global_load_lds_dwordx4 v[224:225], off
	v_lshl_add_u64 v[224:225], s[88:89], 0, v[128:129]
	s_add_i32 m0, s18, 0x2000
	s_nop 0
	global_load_lds_dwordx4 v[224:225], off
	v_lshl_add_u64 v[224:225], s[62:63], 0, v[134:135]
	s_mov_b32 m0, s68
	s_nop 0
	global_load_lds_dwordx4 v[224:225], off
	s_mov_b32 m0, s69
	s_nop 0
	global_load_lds_dwordx4 v[226:227], off
	s_waitcnt vmcnt(8)
	s_waitcnt lgkmcnt(0)
	s_barrier
	s_setprio 1
	s_waitcnt lgkmcnt(0)
	v_mfma_f32_16x16x32_bf16 v[92:95], v[152:155], v[188:191], 0
	v_mfma_f32_16x16x32_bf16 v[92:95], v[156:159], v[192:195], v[92:95]
	v_mfma_f32_16x16x32_bf16 v[88:91], v[160:163], v[188:191], 0
	v_mfma_f32_16x16x32_bf16 v[88:91], v[164:167], v[192:195], v[88:91]
	v_mfma_f32_16x16x32_bf16 v[84:87], v[152:155], v[196:199], 0
	v_mfma_f32_16x16x32_bf16 v[84:87], v[156:159], v[200:203], v[84:87]
	v_mfma_f32_16x16x32_bf16 v[80:83], v[160:163], v[196:199], 0
	v_mfma_f32_16x16x32_bf16 v[80:83], v[164:167], v[200:203], v[80:83]
	v_mfma_f32_16x16x32_bf16 v[76:79], v[152:155], v[204:207], 0
	v_mfma_f32_16x16x32_bf16 v[76:79], v[156:159], v[208:211], v[76:79]
	v_mfma_f32_16x16x32_bf16 v[72:75], v[160:163], v[204:207], 0
	v_mfma_f32_16x16x32_bf16 v[72:75], v[164:167], v[208:211], v[72:75]
	v_mfma_f32_16x16x32_bf16 v[60:63], v[152:155], v[212:215], 0
	v_mfma_f32_16x16x32_bf16 v[60:63], v[156:159], v[216:219], v[60:63]
	v_mfma_f32_16x16x32_bf16 v[56:59], v[160:163], v[212:215], 0
	v_mfma_f32_16x16x32_bf16 v[56:59], v[164:167], v[216:219], v[56:59]
	s_setprio 0
	s_setprio 1
	v_mfma_f32_16x16x32_bf16 v[28:31], v[168:171], v[188:191], 0
	v_mfma_f32_16x16x32_bf16 v[28:31], v[172:175], v[192:195], v[28:31]
	v_mfma_f32_16x16x32_bf16 v[24:27], v[176:179], v[188:191], 0
	v_mfma_f32_16x16x32_bf16 v[24:27], v[184:187], v[192:195], v[24:27]
	v_mfma_f32_16x16x32_bf16 v[20:23], v[168:171], v[196:199], 0
	v_mfma_f32_16x16x32_bf16 v[20:23], v[172:175], v[200:203], v[20:23]
	v_mfma_f32_16x16x32_bf16 v[16:19], v[176:179], v[196:199], 0
	v_mfma_f32_16x16x32_bf16 v[16:19], v[184:187], v[200:203], v[16:19]
	v_mfma_f32_16x16x32_bf16 v[12:15], v[168:171], v[204:207], 0
	v_mfma_f32_16x16x32_bf16 v[12:15], v[172:175], v[208:211], v[12:15]
	v_mfma_f32_16x16x32_bf16 v[8:11], v[176:179], v[204:207], 0
	v_mfma_f32_16x16x32_bf16 v[8:11], v[184:187], v[208:211], v[8:11]
	v_mfma_f32_16x16x32_bf16 v[4:7], v[168:171], v[212:215], 0
	v_mfma_f32_16x16x32_bf16 v[4:7], v[172:175], v[216:219], v[4:7]
	v_mfma_f32_16x16x32_bf16 v[0:3], v[176:179], v[212:215], 0
	v_mfma_f32_16x16x32_bf16 v[0:3], v[184:187], v[216:219], v[0:3]
	s_setprio 0
	s_barrier
	s_branch .Lmid_gemm2
.LBB0_387:
	ds_read_b128 v[152:155], v148
	ds_read_b128 v[156:159], v148 offset:1024
	ds_read_b128 v[160:163], v148 offset:2048
	ds_read_b128 v[164:167], v148 offset:3072
	ds_read_b128 v[168:171], v149
	ds_read_b128 v[172:175], v149 offset:1024
	ds_read_b128 v[176:179], v149 offset:2048
	ds_read_b128 v[184:187], v149 offset:3072
	s_add_u32 s18, s58, 0xfffc0080
	s_addc_u32 s19, s59, -1
	s_cmp_eq_u32 s86, 12
	s_cselect_b32 s63, s49, s19
	s_cselect_b32 s62, s82, s18
	s_cselect_b32 s61, s47, s85
	s_cselect_b32 s60, s83, s84
	v_lshl_add_u64 v[220:221], s[58:59], 0, v[138:139]
	s_add_i32 m0, s68, 0xc000
	ds_read_b128 v[188:191], v150
	ds_read_b128 v[192:195], v150 offset:1024
	ds_read_b128 v[196:199], v150 offset:2048
	ds_read_b128 v[200:203], v150 offset:3072
	ds_read_b128 v[204:207], v150 offset:4096
	ds_read_b128 v[208:211], v150 offset:5120
	ds_read_b128 v[212:215], v150 offset:6144
	ds_read_b128 v[216:219], v150 offset:7168
	global_load_lds_dwordx4 v[220:221], off
	v_lshl_add_u64 v[220:221], s[58:59], 0, v[140:141]
	s_add_i32 m0, s68, 0xe000
	s_nop 0
	global_load_lds_dwordx4 v[220:221], off
	s_waitcnt vmcnt(8)
	s_waitcnt lgkmcnt(0)
	s_barrier
	s_setprio 1
	s_waitcnt lgkmcnt(0)
	v_mfma_f32_16x16x32_bf16 v[124:127], v[152:155], v[188:191], v[124:127]
	v_mfma_f32_16x16x32_bf16 v[124:127], v[156:159], v[192:195], v[124:127]
	v_mfma_f32_16x16x32_bf16 v[120:123], v[160:163], v[188:191], v[120:123]
	v_mfma_f32_16x16x32_bf16 v[120:123], v[164:167], v[192:195], v[120:123]
	v_mfma_f32_16x16x32_bf16 v[116:119], v[152:155], v[196:199], v[116:119]
	v_mfma_f32_16x16x32_bf16 v[116:119], v[156:159], v[200:203], v[116:119]
	v_mfma_f32_16x16x32_bf16 v[112:115], v[160:163], v[196:199], v[112:115]
	v_mfma_f32_16x16x32_bf16 v[112:115], v[164:167], v[200:203], v[112:115]
	v_mfma_f32_16x16x32_bf16 v[108:111], v[152:155], v[204:207], v[108:111]
	v_mfma_f32_16x16x32_bf16 v[108:111], v[156:159], v[208:211], v[108:111]
	v_mfma_f32_16x16x32_bf16 v[104:107], v[160:163], v[204:207], v[104:107]
	v_mfma_f32_16x16x32_bf16 v[104:107], v[164:167], v[208:211], v[104:107]
	v_mfma_f32_16x16x32_bf16 v[100:103], v[152:155], v[212:215], v[100:103]
	v_mfma_f32_16x16x32_bf16 v[100:103], v[156:159], v[216:219], v[100:103]
	v_mfma_f32_16x16x32_bf16 v[96:99], v[160:163], v[212:215], v[96:99]
	v_mfma_f32_16x16x32_bf16 v[96:99], v[164:167], v[216:219], v[96:99]
	s_setprio 0
	s_setprio 1
	v_mfma_f32_16x16x32_bf16 v[68:71], v[168:171], v[188:191], v[68:71]
	v_mfma_f32_16x16x32_bf16 v[68:71], v[172:175], v[192:195], v[68:71]
	v_mfma_f32_16x16x32_bf16 v[64:67], v[176:179], v[188:191], v[64:67]
	v_mfma_f32_16x16x32_bf16 v[64:67], v[184:187], v[192:195], v[64:67]
	v_mfma_f32_16x16x32_bf16 v[52:55], v[168:171], v[196:199], v[52:55]
	v_mfma_f32_16x16x32_bf16 v[52:55], v[172:175], v[200:203], v[52:55]
	v_mfma_f32_16x16x32_bf16 v[48:51], v[176:179], v[196:199], v[48:51]
	v_mfma_f32_16x16x32_bf16 v[48:51], v[184:187], v[200:203], v[48:51]
	v_mfma_f32_16x16x32_bf16 v[44:47], v[168:171], v[204:207], v[44:47]
	v_mfma_f32_16x16x32_bf16 v[44:47], v[172:175], v[208:211], v[44:47]
	v_mfma_f32_16x16x32_bf16 v[40:43], v[176:179], v[204:207], v[40:43]
	v_mfma_f32_16x16x32_bf16 v[40:43], v[184:187], v[208:211], v[40:43]
	v_mfma_f32_16x16x32_bf16 v[36:39], v[168:171], v[212:215], v[36:39]
	v_mfma_f32_16x16x32_bf16 v[36:39], v[172:175], v[216:219], v[36:39]
	v_mfma_f32_16x16x32_bf16 v[32:35], v[176:179], v[212:215], v[32:35]
	v_mfma_f32_16x16x32_bf16 v[32:35], v[184:187], v[216:219], v[32:35]
	s_setprio 0
	s_barrier
	s_add_i32 s18, s76, s66
	v_lshl_add_u64 v[220:221], s[60:61], 0, v[132:133]
	s_mov_b32 m0, s18
	ds_read_b128 v[188:191], v150 offset:16384
	ds_read_b128 v[192:195], v150 offset:17408
	ds_read_b128 v[196:199], v150 offset:18432
	ds_read_b128 v[200:203], v150 offset:19456
	ds_read_b128 v[204:207], v150 offset:20480
	ds_read_b128 v[208:211], v150 offset:21504
	ds_read_b128 v[212:215], v150 offset:22528
	ds_read_b128 v[216:219], v150 offset:23552
	global_load_lds_dwordx4 v[220:221], off
	s_add_i32 m0, s18, 0x2000
	s_add_u32 s88, s60, 0x40000
	v_lshl_add_u64 v[222:223], s[60:61], 0, v[128:129]
	s_addc_u32 s89, s61, 0
	s_add_i32 s18, s77, s66
	global_load_lds_dwordx4 v[222:223], off
	v_lshl_add_u64 v[224:225], s[88:89], 0, v[132:133]
	s_mov_b32 m0, s18
	v_lshl_add_u64 v[226:227], s[62:63], 0, v[130:131]
	global_load_lds_dwordx4 v[224:225], off
	v_lshl_add_u64 v[224:225], s[88:89], 0, v[128:129]
	s_add_i32 m0, s18, 0x2000
	s_nop 0
	global_load_lds_dwordx4 v[224:225], off
	v_lshl_add_u64 v[224:225], s[62:63], 0, v[134:135]
	s_mov_b32 m0, s68
	s_nop 0
	global_load_lds_dwordx4 v[224:225], off
	s_mov_b32 m0, s69
	s_nop 0
	global_load_lds_dwordx4 v[226:227], off
	s_waitcnt vmcnt(8)
	s_waitcnt lgkmcnt(0)
	s_barrier
	s_setprio 1
	s_waitcnt lgkmcnt(0)
	v_mfma_f32_16x16x32_bf16 v[92:95], v[152:155], v[188:191], v[92:95]
	v_mfma_f32_16x16x32_bf16 v[92:95], v[156:159], v[192:195], v[92:95]
	v_mfma_f32_16x16x32_bf16 v[88:91], v[160:163], v[188:191], v[88:91]
	v_mfma_f32_16x16x32_bf16 v[88:91], v[164:167], v[192:195], v[88:91]
	v_mfma_f32_16x16x32_bf16 v[84:87], v[152:155], v[196:199], v[84:87]
	v_mfma_f32_16x16x32_bf16 v[84:87], v[156:159], v[200:203], v[84:87]
	v_mfma_f32_16x16x32_bf16 v[80:83], v[160:163], v[196:199], v[80:83]
	v_mfma_f32_16x16x32_bf16 v[80:83], v[164:167], v[200:203], v[80:83]
	v_mfma_f32_16x16x32_bf16 v[76:79], v[152:155], v[204:207], v[76:79]
	v_mfma_f32_16x16x32_bf16 v[76:79], v[156:159], v[208:211], v[76:79]
	v_mfma_f32_16x16x32_bf16 v[72:75], v[160:163], v[204:207], v[72:75]
	v_mfma_f32_16x16x32_bf16 v[72:75], v[164:167], v[208:211], v[72:75]
	v_mfma_f32_16x16x32_bf16 v[60:63], v[152:155], v[212:215], v[60:63]
	v_mfma_f32_16x16x32_bf16 v[60:63], v[156:159], v[216:219], v[60:63]
	v_mfma_f32_16x16x32_bf16 v[56:59], v[160:163], v[212:215], v[56:59]
	v_mfma_f32_16x16x32_bf16 v[56:59], v[164:167], v[216:219], v[56:59]
	s_setprio 0
	s_setprio 1
	v_mfma_f32_16x16x32_bf16 v[28:31], v[168:171], v[188:191], v[28:31]
	v_mfma_f32_16x16x32_bf16 v[28:31], v[172:175], v[192:195], v[28:31]
	v_mfma_f32_16x16x32_bf16 v[24:27], v[176:179], v[188:191], v[24:27]
	v_mfma_f32_16x16x32_bf16 v[24:27], v[184:187], v[192:195], v[24:27]
	v_mfma_f32_16x16x32_bf16 v[20:23], v[168:171], v[196:199], v[20:23]
	v_mfma_f32_16x16x32_bf16 v[20:23], v[172:175], v[200:203], v[20:23]
	v_mfma_f32_16x16x32_bf16 v[16:19], v[176:179], v[196:199], v[16:19]
	v_mfma_f32_16x16x32_bf16 v[16:19], v[184:187], v[200:203], v[16:19]
	v_mfma_f32_16x16x32_bf16 v[12:15], v[168:171], v[204:207], v[12:15]
	v_mfma_f32_16x16x32_bf16 v[12:15], v[172:175], v[208:211], v[12:15]
	v_mfma_f32_16x16x32_bf16 v[8:11], v[176:179], v[204:207], v[8:11]
	v_mfma_f32_16x16x32_bf16 v[8:11], v[184:187], v[208:211], v[8:11]
	v_mfma_f32_16x16x32_bf16 v[4:7], v[168:171], v[212:215], v[4:7]
	v_mfma_f32_16x16x32_bf16 v[4:7], v[172:175], v[216:219], v[4:7]
	v_mfma_f32_16x16x32_bf16 v[0:3], v[176:179], v[212:215], v[0:3]
	v_mfma_f32_16x16x32_bf16 v[0:3], v[184:187], v[216:219], v[0:3]
	s_setprio 0
	s_barrier
.Lmid_gemm2:
	s_add_i32 s18, 0, 0x18000
	s_add_i32 s19, 0, 0x1c000
	v_add_u32_e32 v164, s18, v147
	v_add_u32_e32 v181, s19, v147
	ds_read_b128 v[152:155], v164
	ds_read_b128 v[156:159], v164 offset:1024
	ds_read_b128 v[160:163], v164 offset:2048
	ds_read_b128 v[164:167], v164 offset:3072
	ds_read_b128 v[168:171], v181
	ds_read_b128 v[172:175], v181 offset:1024
	ds_read_b128 v[176:179], v181 offset:2048
	ds_read_b128 v[184:187], v181 offset:3072
	s_add_u32 s62, s62, 0x40000
	s_addc_u32 s63, s63, 0
	s_mov_b32 m0, s70
	v_lshl_add_u64 v[228:229], s[62:63], 0, v[134:135]
	ds_read_b128 v[188:191], v150 offset:32768
	ds_read_b128 v[192:195], v150 offset:33792
	ds_read_b128 v[196:199], v150 offset:34816
	ds_read_b128 v[200:203], v150 offset:35840
	ds_read_b128 v[204:207], v150 offset:36864
	ds_read_b128 v[208:211], v150 offset:37888
	ds_read_b128 v[212:215], v150 offset:38912
	ds_read_b128 v[216:219], v150 offset:39936
	global_load_lds_dwordx4 v[228:229], off
	v_lshl_add_u64 v[228:229], s[62:63], 0, v[130:131]
	s_mov_b32 m0, s71
	s_nop 0
	global_load_lds_dwordx4 v[228:229], off
	s_waitcnt vmcnt(8)
	s_waitcnt lgkmcnt(0)
	s_barrier
	s_setprio 1
	s_waitcnt lgkmcnt(0)
	v_mfma_f32_16x16x32_bf16 v[124:127], v[152:155], v[188:191], v[124:127]
	v_mfma_f32_16x16x32_bf16 v[124:127], v[156:159], v[192:195], v[124:127]
	v_mfma_f32_16x16x32_bf16 v[120:123], v[160:163], v[188:191], v[120:123]
	v_mfma_f32_16x16x32_bf16 v[120:123], v[164:167], v[192:195], v[120:123]
	v_mfma_f32_16x16x32_bf16 v[116:119], v[152:155], v[196:199], v[116:119]
	v_mfma_f32_16x16x32_bf16 v[116:119], v[156:159], v[200:203], v[116:119]
	v_mfma_f32_16x16x32_bf16 v[112:115], v[160:163], v[196:199], v[112:115]
	v_mfma_f32_16x16x32_bf16 v[112:115], v[164:167], v[200:203], v[112:115]
	v_mfma_f32_16x16x32_bf16 v[108:111], v[152:155], v[204:207], v[108:111]
	v_mfma_f32_16x16x32_bf16 v[108:111], v[156:159], v[208:211], v[108:111]
	v_mfma_f32_16x16x32_bf16 v[104:107], v[160:163], v[204:207], v[104:107]
	v_mfma_f32_16x16x32_bf16 v[104:107], v[164:167], v[208:211], v[104:107]
	v_mfma_f32_16x16x32_bf16 v[100:103], v[152:155], v[212:215], v[100:103]
	v_mfma_f32_16x16x32_bf16 v[100:103], v[156:159], v[216:219], v[100:103]
	v_mfma_f32_16x16x32_bf16 v[96:99], v[160:163], v[212:215], v[96:99]
	v_mfma_f32_16x16x32_bf16 v[96:99], v[164:167], v[216:219], v[96:99]
	s_setprio 0
	s_setprio 1
	v_mfma_f32_16x16x32_bf16 v[68:71], v[168:171], v[188:191], v[68:71]
	v_mfma_f32_16x16x32_bf16 v[68:71], v[172:175], v[192:195], v[68:71]
	v_mfma_f32_16x16x32_bf16 v[64:67], v[176:179], v[188:191], v[64:67]
	v_mfma_f32_16x16x32_bf16 v[64:67], v[184:187], v[192:195], v[64:67]
	v_mfma_f32_16x16x32_bf16 v[52:55], v[168:171], v[196:199], v[52:55]
	v_mfma_f32_16x16x32_bf16 v[52:55], v[172:175], v[200:203], v[52:55]
	v_mfma_f32_16x16x32_bf16 v[48:51], v[176:179], v[196:199], v[48:51]
	v_mfma_f32_16x16x32_bf16 v[48:51], v[184:187], v[200:203], v[48:51]
	v_mfma_f32_16x16x32_bf16 v[44:47], v[168:171], v[204:207], v[44:47]
	v_mfma_f32_16x16x32_bf16 v[44:47], v[172:175], v[208:211], v[44:47]
	v_mfma_f32_16x16x32_bf16 v[40:43], v[176:179], v[204:207], v[40:43]
	v_mfma_f32_16x16x32_bf16 v[40:43], v[184:187], v[208:211], v[40:43]
	v_mfma_f32_16x16x32_bf16 v[36:39], v[168:171], v[212:215], v[36:39]
	v_mfma_f32_16x16x32_bf16 v[36:39], v[172:175], v[216:219], v[36:39]
	v_mfma_f32_16x16x32_bf16 v[32:35], v[176:179], v[212:215], v[32:35]
	v_mfma_f32_16x16x32_bf16 v[32:35], v[184:187], v[216:219], v[32:35]
	s_setprio 0
	s_barrier
	s_add_i32 s18, s18, s66
	v_lshl_add_u64 v[220:221], v[220:221], 0, s[6:7]
	s_mov_b32 m0, s18
	ds_read_b128 v[188:191], v150 offset:49152
	ds_read_b128 v[192:195], v150 offset:50176
	ds_read_b128 v[196:199], v150 offset:51200
	ds_read_b128 v[200:203], v150 offset:52224
	ds_read_b128 v[204:207], v150 offset:53248
	ds_read_b128 v[208:211], v150 offset:54272
	ds_read_b128 v[212:215], v150 offset:55296
	ds_read_b128 v[216:219], v150 offset:56320
	global_load_lds_dwordx4 v[220:221], off
	s_add_i32 m0, s18, 0x2000
	s_add_u32 s60, s60, 0x40080
	v_lshl_add_u64 v[220:221], v[222:223], 0, s[6:7]
	s_addc_u32 s61, s61, 0
	s_add_i32 s18, s19, s66
	global_load_lds_dwordx4 v[220:221], off
	v_lshl_add_u64 v[220:221], s[60:61], 0, v[132:133]
	s_mov_b32 m0, s18
	s_nop 0
	global_load_lds_dwordx4 v[220:221], off
	v_lshl_add_u64 v[220:221], s[60:61], 0, v[128:129]
	s_add_i32 m0, s18, 0x2000
	s_nop 0
	global_load_lds_dwordx4 v[220:221], off
	v_lshl_add_u64 v[220:221], v[224:225], 0, s[6:7]
	s_mov_b32 m0, s74
	s_nop 0
	global_load_lds_dwordx4 v[220:221], off
	v_lshl_add_u64 v[220:221], v[226:227], 0, s[6:7]
	s_mov_b32 m0, s75
	s_nop 0
	global_load_lds_dwordx4 v[220:221], off
	s_waitcnt vmcnt(8)
	s_waitcnt lgkmcnt(0)
	s_barrier
	s_setprio 1
	s_waitcnt lgkmcnt(0)
	v_mfma_f32_16x16x32_bf16 v[92:95], v[152:155], v[188:191], v[92:95]
	v_mfma_f32_16x16x32_bf16 v[92:95], v[156:159], v[192:195], v[92:95]
	v_mfma_f32_16x16x32_bf16 v[88:91], v[160:163], v[188:191], v[88:91]
	v_mfma_f32_16x16x32_bf16 v[88:91], v[164:167], v[192:195], v[88:91]
	v_mfma_f32_16x16x32_bf16 v[84:87], v[152:155], v[196:199], v[84:87]
	v_mfma_f32_16x16x32_bf16 v[84:87], v[156:159], v[200:203], v[84:87]
	v_mfma_f32_16x16x32_bf16 v[80:83], v[160:163], v[196:199], v[80:83]
	v_mfma_f32_16x16x32_bf16 v[80:83], v[164:167], v[200:203], v[80:83]
	v_mfma_f32_16x16x32_bf16 v[76:79], v[152:155], v[204:207], v[76:79]
	v_mfma_f32_16x16x32_bf16 v[76:79], v[156:159], v[208:211], v[76:79]
	v_mfma_f32_16x16x32_bf16 v[72:75], v[160:163], v[204:207], v[72:75]
	v_mfma_f32_16x16x32_bf16 v[72:75], v[164:167], v[208:211], v[72:75]
	v_mfma_f32_16x16x32_bf16 v[60:63], v[152:155], v[212:215], v[60:63]
	v_mfma_f32_16x16x32_bf16 v[60:63], v[156:159], v[216:219], v[60:63]
	v_mfma_f32_16x16x32_bf16 v[56:59], v[160:163], v[212:215], v[56:59]
	v_mfma_f32_16x16x32_bf16 v[56:59], v[164:167], v[216:219], v[56:59]
	s_setprio 0
	s_setprio 1
	v_mfma_f32_16x16x32_bf16 v[28:31], v[168:171], v[188:191], v[28:31]
	v_mfma_f32_16x16x32_bf16 v[28:31], v[172:175], v[192:195], v[28:31]
	v_mfma_f32_16x16x32_bf16 v[24:27], v[176:179], v[188:191], v[24:27]
	v_mfma_f32_16x16x32_bf16 v[24:27], v[184:187], v[192:195], v[24:27]
	v_mfma_f32_16x16x32_bf16 v[20:23], v[168:171], v[196:199], v[20:23]
	v_mfma_f32_16x16x32_bf16 v[20:23], v[172:175], v[200:203], v[20:23]
	v_mfma_f32_16x16x32_bf16 v[16:19], v[176:179], v[196:199], v[16:19]
	v_mfma_f32_16x16x32_bf16 v[16:19], v[184:187], v[200:203], v[16:19]
	v_mfma_f32_16x16x32_bf16 v[12:15], v[168:171], v[204:207], v[12:15]
	v_mfma_f32_16x16x32_bf16 v[12:15], v[172:175], v[208:211], v[12:15]
	v_mfma_f32_16x16x32_bf16 v[8:11], v[176:179], v[204:207], v[8:11]
	v_mfma_f32_16x16x32_bf16 v[8:11], v[184:187], v[208:211], v[8:11]
	v_mfma_f32_16x16x32_bf16 v[4:7], v[168:171], v[212:215], v[4:7]
	v_mfma_f32_16x16x32_bf16 v[4:7], v[172:175], v[216:219], v[4:7]
	v_mfma_f32_16x16x32_bf16 v[0:3], v[176:179], v[212:215], v[0:3]
	v_mfma_f32_16x16x32_bf16 v[0:3], v[184:187], v[216:219], v[0:3]
	s_setprio 0
	s_barrier
	s_add_i32 s86, s86, 2
	s_add_u32 s58, s58, 0x100
	s_addc_u32 s59, s59, 0
	s_add_u32 s84, s84, 0x100
	s_addc_u32 s85, s85, 0
	s_cmp_gt_u32 s86, 13
	s_cbranch_scc0 .LBB0_387
	s_and_b64 vcc, exec, s[8:9]
	s_cbranch_vccz .LBB0_390
	s_barrier

.LBB0_600:
	s_ashr_i32 s49, s48, 31
	s_lshl_b64 s[18:19], s[48:49], 19
	s_add_u32 s52, s38, s18
	s_addc_u32 s53, s39, s19
	s_and_b64 s[18:19], s[4:5], exec
	s_cselect_b32 s49, s53, s59
	s_cselect_b32 s84, s52, s58
	s_ashr_i32 s47, s46, 31
	s_lshl_b64 s[18:19], s[46:47], 19
	s_add_u32 s54, s64, s18
	s_addc_u32 s55, s65, s19
	s_and_b64 s[18:19], s[4:5], exec
	s_cselect_b32 s47, s55, s61
	s_cselect_b32 s85, s54, s60
	s_add_u32 s58, s58, 0x40080
	s_addc_u32 s59, s59, 0
	s_add_u32 s86, s60, 0x100
	s_addc_u32 s87, s61, 0
	s_mov_b32 s88, -2
	ds_read_b128 v[152:155], v149
	ds_read_b128 v[156:159], v149 offset:1024
	ds_read_b128 v[160:163], v149 offset:2048
	ds_read_b128 v[164:167], v149 offset:3072
	ds_read_b128 v[168:171], v150
	ds_read_b128 v[172:175], v150 offset:1024
	ds_read_b128 v[176:179], v150 offset:2048
	ds_read_b128 v[184:187], v150 offset:3072
	s_add_u32 s18, s58, 0xfffc0080
	s_addc_u32 s19, s59, -1
	s_cmp_eq_u32 s88, 12
	s_cselect_b32 s63, s49, s19
	s_cselect_b32 s62, s84, s18
	s_cselect_b32 s61, s47, s87
	s_cselect_b32 s60, s85, s86
	v_lshl_add_u64 v[144:145], s[58:59], 0, v[136:137]
	s_add_i32 m0, s57, 0xc000
	ds_read_b128 v[188:191], v151
	ds_read_b128 v[192:195], v151 offset:1024
	ds_read_b128 v[196:199], v151 offset:2048
	ds_read_b128 v[200:203], v151 offset:3072
	ds_read_b128 v[204:207], v151 offset:4096
	ds_read_b128 v[208:211], v151 offset:5120
	ds_read_b128 v[212:215], v151 offset:6144
	ds_read_b128 v[216:219], v151 offset:7168
	global_load_lds_dwordx4 v[144:145], off
	v_lshl_add_u64 v[144:145], s[58:59], 0, v[138:139]
	s_add_i32 m0, s57, 0xe000
	s_nop 0
	global_load_lds_dwordx4 v[144:145], off
	s_waitcnt vmcnt(8)
	s_waitcnt lgkmcnt(0)
	s_barrier
	s_setprio 1
	s_waitcnt lgkmcnt(0)
	v_mfma_f32_16x16x32_bf16 v[124:127], v[152:155], v[188:191], 0
	v_mfma_f32_16x16x32_bf16 v[124:127], v[156:159], v[192:195], v[124:127]
	v_mfma_f32_16x16x32_bf16 v[120:123], v[160:163], v[188:191], 0
	v_mfma_f32_16x16x32_bf16 v[120:123], v[164:167], v[192:195], v[120:123]
	v_mfma_f32_16x16x32_bf16 v[116:119], v[152:155], v[196:199], 0
	v_mfma_f32_16x16x32_bf16 v[116:119], v[156:159], v[200:203], v[116:119]
	v_mfma_f32_16x16x32_bf16 v[108:111], v[160:163], v[196:199], 0
	v_mfma_f32_16x16x32_bf16 v[108:111], v[164:167], v[200:203], v[108:111]
	v_mfma_f32_16x16x32_bf16 v[100:103], v[152:155], v[204:207], 0
	v_mfma_f32_16x16x32_bf16 v[100:103], v[156:159], v[208:211], v[100:103]
	v_mfma_f32_16x16x32_bf16 v[92:95], v[160:163], v[204:207], 0
	v_mfma_f32_16x16x32_bf16 v[92:95], v[164:167], v[208:211], v[92:95]
	v_mfma_f32_16x16x32_bf16 v[84:87], v[152:155], v[212:215], 0
	v_mfma_f32_16x16x32_bf16 v[84:87], v[156:159], v[216:219], v[84:87]
	v_mfma_f32_16x16x32_bf16 v[76:79], v[160:163], v[212:215], 0
	v_mfma_f32_16x16x32_bf16 v[76:79], v[164:167], v[216:219], v[76:79]
	s_setprio 0
	s_setprio 1
	v_mfma_f32_16x16x32_bf16 v[112:115], v[168:171], v[188:191], 0
	v_mfma_f32_16x16x32_bf16 v[112:115], v[172:175], v[192:195], v[112:115]
	v_mfma_f32_16x16x32_bf16 v[104:107], v[176:179], v[188:191], 0
	v_mfma_f32_16x16x32_bf16 v[104:107], v[184:187], v[192:195], v[104:107]
	v_mfma_f32_16x16x32_bf16 v[96:99], v[168:171], v[196:199], 0
	v_mfma_f32_16x16x32_bf16 v[96:99], v[172:175], v[200:203], v[96:99]
	v_mfma_f32_16x16x32_bf16 v[88:91], v[176:179], v[196:199], 0
	v_mfma_f32_16x16x32_bf16 v[88:91], v[184:187], v[200:203], v[88:91]
	v_mfma_f32_16x16x32_bf16 v[80:83], v[168:171], v[204:207], 0
	v_mfma_f32_16x16x32_bf16 v[80:83], v[172:175], v[208:211], v[80:83]
	v_mfma_f32_16x16x32_bf16 v[72:75], v[176:179], v[204:207], 0
	v_mfma_f32_16x16x32_bf16 v[72:75], v[184:187], v[208:211], v[72:75]
	v_mfma_f32_16x16x32_bf16 v[68:71], v[168:171], v[212:215], 0
	v_mfma_f32_16x16x32_bf16 v[68:71], v[172:175], v[216:219], v[68:71]
	v_mfma_f32_16x16x32_bf16 v[64:67], v[176:179], v[212:215], 0
	v_mfma_f32_16x16x32_bf16 v[64:67], v[184:187], v[216:219], v[64:67]
	s_setprio 0
	s_barrier
	s_add_i32 s18, s73, s66
	v_lshl_add_u64 v[144:145], s[60:61], 0, v[130:131]
	s_mov_b32 m0, s18
	ds_read_b128 v[188:191], v151 offset:16384
	ds_read_b128 v[192:195], v151 offset:17408
	ds_read_b128 v[196:199], v151 offset:18432
	ds_read_b128 v[200:203], v151 offset:19456
	ds_read_b128 v[204:207], v151 offset:20480
	ds_read_b128 v[208:211], v151 offset:21504
	ds_read_b128 v[212:215], v151 offset:22528
	ds_read_b128 v[216:219], v151 offset:23552
	global_load_lds_dwordx4 v[144:145], off
	s_add_i32 m0, s18, 0x2000
	s_add_u32 s18, s60, 0x40000
	v_lshl_add_u64 v[220:221], s[60:61], 0, v[134:135]
	s_addc_u32 s19, s61, 0
	s_add_i32 s79, s74, s66
	global_load_lds_dwordx4 v[220:221], off
	v_lshl_add_u64 v[222:223], s[18:19], 0, v[130:131]
	s_mov_b32 m0, s79
	v_lshl_add_u64 v[224:225], s[62:63], 0, v[132:133]
	global_load_lds_dwordx4 v[222:223], off
	v_lshl_add_u64 v[222:223], s[18:19], 0, v[134:135]
	s_add_i32 m0, s79, 0x2000
	s_nop 0
	global_load_lds_dwordx4 v[222:223], off
	v_lshl_add_u64 v[222:223], s[62:63], 0, v[128:129]
	s_mov_b32 m0, s57
	s_nop 0
	global_load_lds_dwordx4 v[222:223], off
	s_mov_b32 m0, s67
	s_nop 0
	global_load_lds_dwordx4 v[224:225], off
	s_waitcnt vmcnt(8)
	s_waitcnt lgkmcnt(0)
	s_barrier
	s_setprio 1
	s_waitcnt lgkmcnt(0)
	v_mfma_f32_16x16x32_bf16 v[60:63], v[152:155], v[188:191], 0
	v_mfma_f32_16x16x32_bf16 v[60:63], v[156:159], v[192:195], v[60:63]
	v_mfma_f32_16x16x32_bf16 v[56:59], v[160:163], v[188:191], 0
	v_mfma_f32_16x16x32_bf16 v[56:59], v[164:167], v[192:195], v[56:59]
	v_mfma_f32_16x16x32_bf16 v[52:55], v[152:155], v[196:199], 0
	v_mfma_f32_16x16x32_bf16 v[52:55], v[156:159], v[200:203], v[52:55]
	v_mfma_f32_16x16x32_bf16 v[44:47], v[160:163], v[196:199], 0
	v_mfma_f32_16x16x32_bf16 v[44:47], v[164:167], v[200:203], v[44:47]
	v_mfma_f32_16x16x32_bf16 v[36:39], v[152:155], v[204:207], 0
	v_mfma_f32_16x16x32_bf16 v[36:39], v[156:159], v[208:211], v[36:39]
	v_mfma_f32_16x16x32_bf16 v[28:31], v[160:163], v[204:207], 0
	v_mfma_f32_16x16x32_bf16 v[28:31], v[164:167], v[208:211], v[28:31]
	v_mfma_f32_16x16x32_bf16 v[20:23], v[152:155], v[212:215], 0
	v_mfma_f32_16x16x32_bf16 v[20:23], v[156:159], v[216:219], v[20:23]
	v_mfma_f32_16x16x32_bf16 v[12:15], v[160:163], v[212:215], 0
	v_mfma_f32_16x16x32_bf16 v[12:15], v[164:167], v[216:219], v[12:15]
	s_setprio 0
	s_setprio 1
	v_mfma_f32_16x16x32_bf16 v[48:51], v[168:171], v[188:191], 0
	v_mfma_f32_16x16x32_bf16 v[48:51], v[172:175], v[192:195], v[48:51]
	v_mfma_f32_16x16x32_bf16 v[40:43], v[176:179], v[188:191], 0
	v_mfma_f32_16x16x32_bf16 v[40:43], v[184:187], v[192:195], v[40:43]
	v_mfma_f32_16x16x32_bf16 v[32:35], v[168:171], v[196:199], 0
	v_mfma_f32_16x16x32_bf16 v[32:35], v[172:175], v[200:203], v[32:35]
	v_mfma_f32_16x16x32_bf16 v[24:27], v[176:179], v[196:199], 0
	v_mfma_f32_16x16x32_bf16 v[24:27], v[184:187], v[200:203], v[24:27]
	v_mfma_f32_16x16x32_bf16 v[16:19], v[168:171], v[204:207], 0
	v_mfma_f32_16x16x32_bf16 v[16:19], v[172:175], v[208:211], v[16:19]
	v_mfma_f32_16x16x32_bf16 v[8:11], v[176:179], v[204:207], 0
	v_mfma_f32_16x16x32_bf16 v[8:11], v[184:187], v[208:211], v[8:11]
	v_mfma_f32_16x16x32_bf16 v[4:7], v[168:171], v[212:215], 0
	v_mfma_f32_16x16x32_bf16 v[4:7], v[172:175], v[216:219], v[4:7]
	v_mfma_f32_16x16x32_bf16 v[0:3], v[176:179], v[212:215], 0
	v_mfma_f32_16x16x32_bf16 v[0:3], v[184:187], v[216:219], v[0:3]
	s_setprio 0
	s_barrier
	s_branch .Lmid_gemm3
.LBB0_601:
	ds_read_b128 v[152:155], v149
	ds_read_b128 v[156:159], v149 offset:1024
	ds_read_b128 v[160:163], v149 offset:2048
	ds_read_b128 v[164:167], v149 offset:3072
	ds_read_b128 v[168:171], v150
	ds_read_b128 v[172:175], v150 offset:1024
	ds_read_b128 v[176:179], v150 offset:2048
	ds_read_b128 v[184:187], v150 offset:3072
	s_add_u32 s18, s58, 0xfffc0080
	s_addc_u32 s19, s59, -1
	s_cmp_eq_u32 s88, 12
	s_cselect_b32 s63, s49, s19
	s_cselect_b32 s62, s84, s18
	s_cselect_b32 s61, s47, s87
	s_cselect_b32 s60, s85, s86
	v_lshl_add_u64 v[144:145], s[58:59], 0, v[136:137]
	s_add_i32 m0, s57, 0xc000
	ds_read_b128 v[188:191], v151
	ds_read_b128 v[192:195], v151 offset:1024
	ds_read_b128 v[196:199], v151 offset:2048
	ds_read_b128 v[200:203], v151 offset:3072
	ds_read_b128 v[204:207], v151 offset:4096
	ds_read_b128 v[208:211], v151 offset:5120
	ds_read_b128 v[212:215], v151 offset:6144
	ds_read_b128 v[216:219], v151 offset:7168
	global_load_lds_dwordx4 v[144:145], off
	v_lshl_add_u64 v[144:145], s[58:59], 0, v[138:139]
	s_add_i32 m0, s57, 0xe000
	s_nop 0
	global_load_lds_dwordx4 v[144:145], off
	s_waitcnt vmcnt(8)
	s_waitcnt lgkmcnt(0)
	s_barrier
	s_setprio 1
	s_waitcnt lgkmcnt(0)
	v_mfma_f32_16x16x32_bf16 v[124:127], v[152:155], v[188:191], v[124:127]
	v_mfma_f32_16x16x32_bf16 v[124:127], v[156:159], v[192:195], v[124:127]
	v_mfma_f32_16x16x32_bf16 v[120:123], v[160:163], v[188:191], v[120:123]
	v_mfma_f32_16x16x32_bf16 v[120:123], v[164:167], v[192:195], v[120:123]
	v_mfma_f32_16x16x32_bf16 v[116:119], v[152:155], v[196:199], v[116:119]
	v_mfma_f32_16x16x32_bf16 v[116:119], v[156:159], v[200:203], v[116:119]
	v_mfma_f32_16x16x32_bf16 v[108:111], v[160:163], v[196:199], v[108:111]
	v_mfma_f32_16x16x32_bf16 v[108:111], v[164:167], v[200:203], v[108:111]
	v_mfma_f32_16x16x32_bf16 v[100:103], v[152:155], v[204:207], v[100:103]
	v_mfma_f32_16x16x32_bf16 v[100:103], v[156:159], v[208:211], v[100:103]
	v_mfma_f32_16x16x32_bf16 v[92:95], v[160:163], v[204:207], v[92:95]
	v_mfma_f32_16x16x32_bf16 v[92:95], v[164:167], v[208:211], v[92:95]
	v_mfma_f32_16x16x32_bf16 v[84:87], v[152:155], v[212:215], v[84:87]
	v_mfma_f32_16x16x32_bf16 v[84:87], v[156:159], v[216:219], v[84:87]
	v_mfma_f32_16x16x32_bf16 v[76:79], v[160:163], v[212:215], v[76:79]
	v_mfma_f32_16x16x32_bf16 v[76:79], v[164:167], v[216:219], v[76:79]
	s_setprio 0
	s_setprio 1
	v_mfma_f32_16x16x32_bf16 v[112:115], v[168:171], v[188:191], v[112:115]
	v_mfma_f32_16x16x32_bf16 v[112:115], v[172:175], v[192:195], v[112:115]
	v_mfma_f32_16x16x32_bf16 v[104:107], v[176:179], v[188:191], v[104:107]
	v_mfma_f32_16x16x32_bf16 v[104:107], v[184:187], v[192:195], v[104:107]
	v_mfma_f32_16x16x32_bf16 v[96:99], v[168:171], v[196:199], v[96:99]
	v_mfma_f32_16x16x32_bf16 v[96:99], v[172:175], v[200:203], v[96:99]
	v_mfma_f32_16x16x32_bf16 v[88:91], v[176:179], v[196:199], v[88:91]
	v_mfma_f32_16x16x32_bf16 v[88:91], v[184:187], v[200:203], v[88:91]
	v_mfma_f32_16x16x32_bf16 v[80:83], v[168:171], v[204:207], v[80:83]
	v_mfma_f32_16x16x32_bf16 v[80:83], v[172:175], v[208:211], v[80:83]
	v_mfma_f32_16x16x32_bf16 v[72:75], v[176:179], v[204:207], v[72:75]
	v_mfma_f32_16x16x32_bf16 v[72:75], v[184:187], v[208:211], v[72:75]
	v_mfma_f32_16x16x32_bf16 v[68:71], v[168:171], v[212:215], v[68:71]
	v_mfma_f32_16x16x32_bf16 v[68:71], v[172:175], v[216:219], v[68:71]
	v_mfma_f32_16x16x32_bf16 v[64:67], v[176:179], v[212:215], v[64:67]
	v_mfma_f32_16x16x32_bf16 v[64:67], v[184:187], v[216:219], v[64:67]
	s_setprio 0
	s_barrier
	s_add_i32 s18, s73, s66
	v_lshl_add_u64 v[144:145], s[60:61], 0, v[130:131]
	s_mov_b32 m0, s18
	ds_read_b128 v[188:191], v151 offset:16384
	ds_read_b128 v[192:195], v151 offset:17408
	ds_read_b128 v[196:199], v151 offset:18432
	ds_read_b128 v[200:203], v151 offset:19456
	ds_read_b128 v[204:207], v151 offset:20480
	ds_read_b128 v[208:211], v151 offset:21504
	ds_read_b128 v[212:215], v151 offset:22528
	ds_read_b128 v[216:219], v151 offset:23552
	global_load_lds_dwordx4 v[144:145], off
	s_add_i32 m0, s18, 0x2000
	s_add_u32 s18, s60, 0x40000
	v_lshl_add_u64 v[220:221], s[60:61], 0, v[134:135]
	s_addc_u32 s19, s61, 0
	s_add_i32 s79, s74, s66
	global_load_lds_dwordx4 v[220:221], off
	v_lshl_add_u64 v[222:223], s[18:19], 0, v[130:131]
	s_mov_b32 m0, s79
	v_lshl_add_u64 v[224:225], s[62:63], 0, v[132:133]
	global_load_lds_dwordx4 v[222:223], off
	v_lshl_add_u64 v[222:223], s[18:19], 0, v[134:135]
	s_add_i32 m0, s79, 0x2000
	s_nop 0
	global_load_lds_dwordx4 v[222:223], off
	v_lshl_add_u64 v[222:223], s[62:63], 0, v[128:129]
	s_mov_b32 m0, s57
	s_nop 0
	global_load_lds_dwordx4 v[222:223], off
	s_mov_b32 m0, s67
	s_nop 0
	global_load_lds_dwordx4 v[224:225], off
	s_waitcnt vmcnt(8)
	s_waitcnt lgkmcnt(0)
	s_barrier
	s_setprio 1
	s_waitcnt lgkmcnt(0)
	v_mfma_f32_16x16x32_bf16 v[60:63], v[152:155], v[188:191], v[60:63]
	v_mfma_f32_16x16x32_bf16 v[60:63], v[156:159], v[192:195], v[60:63]
	v_mfma_f32_16x16x32_bf16 v[56:59], v[160:163], v[188:191], v[56:59]
	v_mfma_f32_16x16x32_bf16 v[56:59], v[164:167], v[192:195], v[56:59]
	v_mfma_f32_16x16x32_bf16 v[52:55], v[152:155], v[196:199], v[52:55]
	v_mfma_f32_16x16x32_bf16 v[52:55], v[156:159], v[200:203], v[52:55]
	v_mfma_f32_16x16x32_bf16 v[44:47], v[160:163], v[196:199], v[44:47]
	v_mfma_f32_16x16x32_bf16 v[44:47], v[164:167], v[200:203], v[44:47]
	v_mfma_f32_16x16x32_bf16 v[36:39], v[152:155], v[204:207], v[36:39]
	v_mfma_f32_16x16x32_bf16 v[36:39], v[156:159], v[208:211], v[36:39]
	v_mfma_f32_16x16x32_bf16 v[28:31], v[160:163], v[204:207], v[28:31]
	v_mfma_f32_16x16x32_bf16 v[28:31], v[164:167], v[208:211], v[28:31]
	v_mfma_f32_16x16x32_bf16 v[20:23], v[152:155], v[212:215], v[20:23]
	v_mfma_f32_16x16x32_bf16 v[20:23], v[156:159], v[216:219], v[20:23]
	v_mfma_f32_16x16x32_bf16 v[12:15], v[160:163], v[212:215], v[12:15]
	v_mfma_f32_16x16x32_bf16 v[12:15], v[164:167], v[216:219], v[12:15]
	s_setprio 0
	s_setprio 1
	v_mfma_f32_16x16x32_bf16 v[48:51], v[168:171], v[188:191], v[48:51]
	v_mfma_f32_16x16x32_bf16 v[48:51], v[172:175], v[192:195], v[48:51]
	v_mfma_f32_16x16x32_bf16 v[40:43], v[176:179], v[188:191], v[40:43]
	v_mfma_f32_16x16x32_bf16 v[40:43], v[184:187], v[192:195], v[40:43]
	v_mfma_f32_16x16x32_bf16 v[32:35], v[168:171], v[196:199], v[32:35]
	v_mfma_f32_16x16x32_bf16 v[32:35], v[172:175], v[200:203], v[32:35]
	v_mfma_f32_16x16x32_bf16 v[24:27], v[176:179], v[196:199], v[24:27]
	v_mfma_f32_16x16x32_bf16 v[24:27], v[184:187], v[200:203], v[24:27]
	v_mfma_f32_16x16x32_bf16 v[16:19], v[168:171], v[204:207], v[16:19]
	v_mfma_f32_16x16x32_bf16 v[16:19], v[172:175], v[208:211], v[16:19]
	v_mfma_f32_16x16x32_bf16 v[8:11], v[176:179], v[204:207], v[8:11]
	v_mfma_f32_16x16x32_bf16 v[8:11], v[184:187], v[208:211], v[8:11]
	v_mfma_f32_16x16x32_bf16 v[4:7], v[168:171], v[212:215], v[4:7]
	v_mfma_f32_16x16x32_bf16 v[4:7], v[172:175], v[216:219], v[4:7]
	v_mfma_f32_16x16x32_bf16 v[0:3], v[176:179], v[212:215], v[0:3]
	v_mfma_f32_16x16x32_bf16 v[0:3], v[184:187], v[216:219], v[0:3]
	s_setprio 0
	s_barrier
.Lmid_gemm3:
	s_add_i32 s79, 0, 0x18000
	s_add_i32 s89, 0, 0x1c000
	v_add_u32_e32 v164, s79, v147
	v_add_u32_e32 v181, s89, v147
	ds_read_b128 v[152:155], v164
	ds_read_b128 v[156:159], v164 offset:1024
	ds_read_b128 v[160:163], v164 offset:2048
	ds_read_b128 v[164:167], v164 offset:3072
	ds_read_b128 v[168:171], v181
	ds_read_b128 v[172:175], v181 offset:1024
	ds_read_b128 v[176:179], v181 offset:2048
	ds_read_b128 v[184:187], v181 offset:3072
	s_add_u32 s18, s62, 0x40000
	s_addc_u32 s19, s63, 0
	s_mov_b32 m0, s68
	v_lshl_add_u64 v[226:227], s[18:19], 0, v[128:129]
	ds_read_b128 v[188:191], v151 offset:32768
	ds_read_b128 v[192:195], v151 offset:33792
	ds_read_b128 v[196:199], v151 offset:34816
	ds_read_b128 v[200:203], v151 offset:35840
	ds_read_b128 v[204:207], v151 offset:36864
	ds_read_b128 v[208:211], v151 offset:37888
	ds_read_b128 v[212:215], v151 offset:38912
	ds_read_b128 v[216:219], v151 offset:39936
	global_load_lds_dwordx4 v[226:227], off
	v_lshl_add_u64 v[226:227], s[18:19], 0, v[132:133]
	s_mov_b32 m0, s69
	s_nop 0
	global_load_lds_dwordx4 v[226:227], off
	s_waitcnt vmcnt(8)
	s_waitcnt lgkmcnt(0)
	s_barrier
	s_setprio 1
	s_waitcnt lgkmcnt(0)
	v_mfma_f32_16x16x32_bf16 v[124:127], v[152:155], v[188:191], v[124:127]
	v_mfma_f32_16x16x32_bf16 v[124:127], v[156:159], v[192:195], v[124:127]
	v_mfma_f32_16x16x32_bf16 v[120:123], v[160:163], v[188:191], v[120:123]
	v_mfma_f32_16x16x32_bf16 v[120:123], v[164:167], v[192:195], v[120:123]
	v_mfma_f32_16x16x32_bf16 v[116:119], v[152:155], v[196:199], v[116:119]
	v_mfma_f32_16x16x32_bf16 v[116:119], v[156:159], v[200:203], v[116:119]
	v_mfma_f32_16x16x32_bf16 v[108:111], v[160:163], v[196:199], v[108:111]
	v_mfma_f32_16x16x32_bf16 v[108:111], v[164:167], v[200:203], v[108:111]
	v_mfma_f32_16x16x32_bf16 v[100:103], v[152:155], v[204:207], v[100:103]
	v_mfma_f32_16x16x32_bf16 v[100:103], v[156:159], v[208:211], v[100:103]
	v_mfma_f32_16x16x32_bf16 v[92:95], v[160:163], v[204:207], v[92:95]
	v_mfma_f32_16x16x32_bf16 v[92:95], v[164:167], v[208:211], v[92:95]
	v_mfma_f32_16x16x32_bf16 v[84:87], v[152:155], v[212:215], v[84:87]
	v_mfma_f32_16x16x32_bf16 v[84:87], v[156:159], v[216:219], v[84:87]
	v_mfma_f32_16x16x32_bf16 v[76:79], v[160:163], v[212:215], v[76:79]
	v_mfma_f32_16x16x32_bf16 v[76:79], v[164:167], v[216:219], v[76:79]
	s_setprio 0
	s_setprio 1
	v_mfma_f32_16x16x32_bf16 v[112:115], v[168:171], v[188:191], v[112:115]
	v_mfma_f32_16x16x32_bf16 v[112:115], v[172:175], v[192:195], v[112:115]
	v_mfma_f32_16x16x32_bf16 v[104:107], v[176:179], v[188:191], v[104:107]
	v_mfma_f32_16x16x32_bf16 v[104:107], v[184:187], v[192:195], v[104:107]
	v_mfma_f32_16x16x32_bf16 v[96:99], v[168:171], v[196:199], v[96:99]
	v_mfma_f32_16x16x32_bf16 v[96:99], v[172:175], v[200:203], v[96:99]
	v_mfma_f32_16x16x32_bf16 v[88:91], v[176:179], v[196:199], v[88:91]
	v_mfma_f32_16x16x32_bf16 v[88:91], v[184:187], v[200:203], v[88:91]
	v_mfma_f32_16x16x32_bf16 v[80:83], v[168:171], v[204:207], v[80:83]
	v_mfma_f32_16x16x32_bf16 v[80:83], v[172:175], v[208:211], v[80:83]
	v_mfma_f32_16x16x32_bf16 v[72:75], v[176:179], v[204:207], v[72:75]
	v_mfma_f32_16x16x32_bf16 v[72:75], v[184:187], v[208:211], v[72:75]
	v_mfma_f32_16x16x32_bf16 v[68:71], v[168:171], v[212:215], v[68:71]
	v_mfma_f32_16x16x32_bf16 v[68:71], v[172:175], v[216:219], v[68:71]
	v_mfma_f32_16x16x32_bf16 v[64:67], v[176:179], v[212:215], v[64:67]
	v_mfma_f32_16x16x32_bf16 v[64:67], v[184:187], v[216:219], v[64:67]
	s_setprio 0
	s_barrier
	s_add_i32 s18, s79, s66
	v_lshl_add_u64 v[144:145], v[144:145], 0, s[10:11]
	s_mov_b32 m0, s18
	ds_read_b128 v[188:191], v151 offset:49152
	ds_read_b128 v[192:195], v151 offset:50176
	ds_read_b128 v[196:199], v151 offset:51200
	ds_read_b128 v[200:203], v151 offset:52224
	ds_read_b128 v[204:207], v151 offset:53248
	ds_read_b128 v[208:211], v151 offset:54272
	ds_read_b128 v[212:215], v151 offset:55296
	ds_read_b128 v[216:219], v151 offset:56320
	global_load_lds_dwordx4 v[144:145], off
	s_add_i32 m0, s18, 0x2000
	s_add_u32 s18, s60, 0x40080
	v_lshl_add_u64 v[144:145], v[220:221], 0, s[10:11]
	s_addc_u32 s19, s61, 0
	s_add_i32 s60, s89, s66
	global_load_lds_dwordx4 v[144:145], off
	v_lshl_add_u64 v[144:145], s[18:19], 0, v[130:131]
	s_mov_b32 m0, s60
	s_nop 0
	global_load_lds_dwordx4 v[144:145], off
	v_lshl_add_u64 v[144:145], s[18:19], 0, v[134:135]
	s_add_i32 m0, s60, 0x2000
	s_nop 0
	global_load_lds_dwordx4 v[144:145], off
	v_lshl_add_u64 v[144:145], v[222:223], 0, s[10:11]
	s_mov_b32 m0, s71
	s_nop 0
	global_load_lds_dwordx4 v[144:145], off
	v_lshl_add_u64 v[144:145], v[224:225], 0, s[10:11]
	s_mov_b32 m0, s72
	s_nop 0
	global_load_lds_dwordx4 v[144:145], off
	s_waitcnt vmcnt(8)
	s_waitcnt lgkmcnt(0)
	s_barrier
	s_setprio 1
	s_waitcnt lgkmcnt(0)
	v_mfma_f32_16x16x32_bf16 v[60:63], v[152:155], v[188:191], v[60:63]
	v_mfma_f32_16x16x32_bf16 v[60:63], v[156:159], v[192:195], v[60:63]
	v_mfma_f32_16x16x32_bf16 v[56:59], v[160:163], v[188:191], v[56:59]
	v_mfma_f32_16x16x32_bf16 v[56:59], v[164:167], v[192:195], v[56:59]
	v_mfma_f32_16x16x32_bf16 v[52:55], v[152:155], v[196:199], v[52:55]
	v_mfma_f32_16x16x32_bf16 v[52:55], v[156:159], v[200:203], v[52:55]
	v_mfma_f32_16x16x32_bf16 v[44:47], v[160:163], v[196:199], v[44:47]
	v_mfma_f32_16x16x32_bf16 v[44:47], v[164:167], v[200:203], v[44:47]
	v_mfma_f32_16x16x32_bf16 v[36:39], v[152:155], v[204:207], v[36:39]
	v_mfma_f32_16x16x32_bf16 v[36:39], v[156:159], v[208:211], v[36:39]
	v_mfma_f32_16x16x32_bf16 v[28:31], v[160:163], v[204:207], v[28:31]
	v_mfma_f32_16x16x32_bf16 v[28:31], v[164:167], v[208:211], v[28:31]
	v_mfma_f32_16x16x32_bf16 v[20:23], v[152:155], v[212:215], v[20:23]
	v_mfma_f32_16x16x32_bf16 v[20:23], v[156:159], v[216:219], v[20:23]
	v_mfma_f32_16x16x32_bf16 v[12:15], v[160:163], v[212:215], v[12:15]
	v_mfma_f32_16x16x32_bf16 v[12:15], v[164:167], v[216:219], v[12:15]
	s_setprio 0
	s_setprio 1
	v_mfma_f32_16x16x32_bf16 v[48:51], v[168:171], v[188:191], v[48:51]
	v_mfma_f32_16x16x32_bf16 v[48:51], v[172:175], v[192:195], v[48:51]
	v_mfma_f32_16x16x32_bf16 v[40:43], v[176:179], v[188:191], v[40:43]
	v_mfma_f32_16x16x32_bf16 v[40:43], v[184:187], v[192:195], v[40:43]
	v_mfma_f32_16x16x32_bf16 v[32:35], v[168:171], v[196:199], v[32:35]
	v_mfma_f32_16x16x32_bf16 v[32:35], v[172:175], v[200:203], v[32:35]
	v_mfma_f32_16x16x32_bf16 v[24:27], v[176:179], v[196:199], v[24:27]
	v_mfma_f32_16x16x32_bf16 v[24:27], v[184:187], v[200:203], v[24:27]
	v_mfma_f32_16x16x32_bf16 v[16:19], v[168:171], v[204:207], v[16:19]
	v_mfma_f32_16x16x32_bf16 v[16:19], v[172:175], v[208:211], v[16:19]
	v_mfma_f32_16x16x32_bf16 v[8:11], v[176:179], v[204:207], v[8:11]
	v_mfma_f32_16x16x32_bf16 v[8:11], v[184:187], v[208:211], v[8:11]
	v_mfma_f32_16x16x32_bf16 v[4:7], v[168:171], v[212:215], v[4:7]
	v_mfma_f32_16x16x32_bf16 v[4:7], v[172:175], v[216:219], v[4:7]
	v_mfma_f32_16x16x32_bf16 v[0:3], v[176:179], v[212:215], v[0:3]
	v_mfma_f32_16x16x32_bf16 v[0:3], v[184:187], v[216:219], v[0:3]
	s_setprio 0
	s_barrier
	s_add_i32 s88, s88, 2
	s_add_u32 s58, s58, 0x100
	s_addc_u32 s59, s59, 0
	s_add_u32 s86, s86, 0x100
	s_addc_u32 s87, s87, 0
	s_cmp_gt_u32 s88, 13
	s_cbranch_scc0 .LBB0_601
	s_and_b64 vcc, exec, s[12:13]
	s_cbranch_vccz .LBB0_604
	s_barrier

.LBB0_723:
	s_ashr_i32 s31, s30, 31
	s_lshl_b64 s[36:37], s[30:31], 19
	s_add_u32 s36, s80, s36
	s_addc_u32 s37, s81, s37
	s_and_b64 s[44:45], s[10:11], exec
	s_cselect_b32 s31, s37, s49
	s_cselect_b32 s70, s36, s48
	s_ashr_i32 s19, s18, 31
	s_lshl_b64 s[44:45], s[18:19], 19
	s_add_u32 s44, s56, s44
	s_addc_u32 s45, s57, s45
	s_and_b64 s[54:55], s[10:11], exec
	s_cselect_b32 s19, s45, s53
	s_cselect_b32 s71, s44, s52
	s_add_u32 s48, s48, 0x40080
	s_addc_u32 s49, s49, 0
	s_add_u32 s72, s52, 0x100
	s_addc_u32 s73, s53, 0
	s_mov_b32 s74, -2
	ds_read_b128 v[140:143], v147
	ds_read_b128 v[150:153], v147 offset:1024
	ds_read_b128 v[154:157], v147 offset:2048
	ds_read_b128 v[158:161], v147 offset:3072
	ds_read_b128 v[162:165], v148
	ds_read_b128 v[166:169], v148 offset:1024
	ds_read_b128 v[170:173], v148 offset:2048
	ds_read_b128 v[174:177], v148 offset:3072
	s_add_u32 s52, s48, 0xfffc0080
	s_addc_u32 s53, s49, -1
	s_cmp_eq_u32 s74, 12
	s_cselect_b32 s55, s31, s53
	s_cselect_b32 s54, s70, s52
	s_cselect_b32 s53, s19, s73
	s_cselect_b32 s52, s71, s72
	v_lshl_add_u64 v[178:179], s[48:49], 0, v[132:133]
	s_add_i32 m0, s47, 0xc000
	ds_read_b128 v[184:187], v149
	ds_read_b128 v[188:191], v149 offset:1024
	ds_read_b128 v[192:195], v149 offset:2048
	ds_read_b128 v[196:199], v149 offset:3072
	ds_read_b128 v[200:203], v149 offset:4096
	ds_read_b128 v[204:207], v149 offset:5120
	ds_read_b128 v[208:211], v149 offset:6144
	ds_read_b128 v[212:215], v149 offset:7168
	global_load_lds_dwordx4 v[178:179], off
	v_lshl_add_u64 v[178:179], s[48:49], 0, v[134:135]
	s_add_i32 m0, s47, 0xe000
	s_nop 0
	global_load_lds_dwordx4 v[178:179], off
	s_waitcnt vmcnt(8)
	s_waitcnt lgkmcnt(0)
	s_barrier
	s_setprio 1
	s_waitcnt lgkmcnt(0)
	v_mfma_f32_16x16x32_bf16 v[124:127], v[140:143], v[184:187], 0
	v_mfma_f32_16x16x32_bf16 v[124:127], v[150:153], v[188:191], v[124:127]
	v_mfma_f32_16x16x32_bf16 v[120:123], v[154:157], v[184:187], 0
	v_mfma_f32_16x16x32_bf16 v[120:123], v[158:161], v[188:191], v[120:123]
	v_mfma_f32_16x16x32_bf16 v[108:111], v[140:143], v[192:195], 0
	v_mfma_f32_16x16x32_bf16 v[108:111], v[150:153], v[196:199], v[108:111]
	v_mfma_f32_16x16x32_bf16 v[104:107], v[154:157], v[192:195], 0
	v_mfma_f32_16x16x32_bf16 v[104:107], v[158:161], v[196:199], v[104:107]
	v_mfma_f32_16x16x32_bf16 v[92:95], v[140:143], v[200:203], 0
	v_mfma_f32_16x16x32_bf16 v[92:95], v[150:153], v[204:207], v[92:95]
	v_mfma_f32_16x16x32_bf16 v[88:91], v[154:157], v[200:203], 0
	v_mfma_f32_16x16x32_bf16 v[88:91], v[158:161], v[204:207], v[88:91]
	v_mfma_f32_16x16x32_bf16 v[76:79], v[140:143], v[208:211], 0
	v_mfma_f32_16x16x32_bf16 v[76:79], v[150:153], v[212:215], v[76:79]
	v_mfma_f32_16x16x32_bf16 v[72:75], v[154:157], v[208:211], 0
	v_mfma_f32_16x16x32_bf16 v[72:75], v[158:161], v[212:215], v[72:75]
	s_setprio 0
	s_setprio 1
	v_mfma_f32_16x16x32_bf16 v[116:119], v[162:165], v[184:187], 0
	v_mfma_f32_16x16x32_bf16 v[116:119], v[166:169], v[188:191], v[116:119]
	v_mfma_f32_16x16x32_bf16 v[112:115], v[170:173], v[184:187], 0
	v_mfma_f32_16x16x32_bf16 v[112:115], v[174:177], v[188:191], v[112:115]
	v_mfma_f32_16x16x32_bf16 v[100:103], v[162:165], v[192:195], 0
	v_mfma_f32_16x16x32_bf16 v[100:103], v[166:169], v[196:199], v[100:103]
	v_mfma_f32_16x16x32_bf16 v[96:99], v[170:173], v[192:195], 0
	v_mfma_f32_16x16x32_bf16 v[96:99], v[174:177], v[196:199], v[96:99]
	v_mfma_f32_16x16x32_bf16 v[84:87], v[162:165], v[200:203], 0
	v_mfma_f32_16x16x32_bf16 v[84:87], v[166:169], v[204:207], v[84:87]
	v_mfma_f32_16x16x32_bf16 v[80:83], v[170:173], v[200:203], 0
	v_mfma_f32_16x16x32_bf16 v[80:83], v[174:177], v[204:207], v[80:83]
	v_mfma_f32_16x16x32_bf16 v[68:71], v[162:165], v[208:211], 0
	v_mfma_f32_16x16x32_bf16 v[68:71], v[166:169], v[212:215], v[68:71]
	v_mfma_f32_16x16x32_bf16 v[64:67], v[170:173], v[208:211], 0
	v_mfma_f32_16x16x32_bf16 v[64:67], v[174:177], v[212:215], v[64:67]
	s_setprio 0
	s_barrier
	s_add_i32 s75, s66, s58
	v_lshl_add_u64 v[178:179], s[52:53], 0, v[130:131]
	s_mov_b32 m0, s75
	ds_read_b128 v[184:187], v149 offset:16384
	ds_read_b128 v[188:191], v149 offset:17408
	ds_read_b128 v[192:195], v149 offset:18432
	ds_read_b128 v[196:199], v149 offset:19456
	ds_read_b128 v[200:203], v149 offset:20480
	ds_read_b128 v[204:207], v149 offset:21504
	ds_read_b128 v[208:211], v149 offset:22528
	ds_read_b128 v[212:215], v149 offset:23552
	global_load_lds_dwordx4 v[178:179], off
	s_add_i32 m0, s75, 0x2000
	s_add_u32 s76, s52, 0x40000
	v_lshl_add_u64 v[216:217], s[52:53], 0, v[128:129]
	s_addc_u32 s77, s53, 0
	s_add_i32 s75, s67, s58
	global_load_lds_dwordx4 v[216:217], off
	v_lshl_add_u64 v[218:219], s[76:77], 0, v[130:131]
	s_mov_b32 m0, s75
	v_lshl_add_u64 v[220:221], s[54:55], 0, v[128:129]
	global_load_lds_dwordx4 v[218:219], off
	v_lshl_add_u64 v[218:219], s[76:77], 0, v[128:129]
	s_add_i32 m0, s75, 0x2000
	s_nop 0
	global_load_lds_dwordx4 v[218:219], off
	v_lshl_add_u64 v[218:219], s[54:55], 0, v[130:131]
	s_mov_b32 m0, s47
	s_nop 0
	global_load_lds_dwordx4 v[218:219], off
	s_mov_b32 m0, s60
	s_nop 0
	global_load_lds_dwordx4 v[220:221], off
	s_waitcnt vmcnt(8)
	s_waitcnt lgkmcnt(0)
	s_barrier
	s_setprio 1
	s_waitcnt lgkmcnt(0)
	v_mfma_f32_16x16x32_bf16 v[60:63], v[140:143], v[184:187], 0
	v_mfma_f32_16x16x32_bf16 v[60:63], v[150:153], v[188:191], v[60:63]
	v_mfma_f32_16x16x32_bf16 v[56:59], v[154:157], v[184:187], 0
	v_mfma_f32_16x16x32_bf16 v[56:59], v[158:161], v[188:191], v[56:59]
	v_mfma_f32_16x16x32_bf16 v[44:47], v[140:143], v[192:195], 0
	v_mfma_f32_16x16x32_bf16 v[44:47], v[150:153], v[196:199], v[44:47]
	v_mfma_f32_16x16x32_bf16 v[40:43], v[154:157], v[192:195], 0
	v_mfma_f32_16x16x32_bf16 v[40:43], v[158:161], v[196:199], v[40:43]
	v_mfma_f32_16x16x32_bf16 v[28:31], v[140:143], v[200:203], 0
	v_mfma_f32_16x16x32_bf16 v[28:31], v[150:153], v[204:207], v[28:31]
	v_mfma_f32_16x16x32_bf16 v[24:27], v[154:157], v[200:203], 0
	v_mfma_f32_16x16x32_bf16 v[24:27], v[158:161], v[204:207], v[24:27]
	v_mfma_f32_16x16x32_bf16 v[12:15], v[140:143], v[208:211], 0
	v_mfma_f32_16x16x32_bf16 v[12:15], v[150:153], v[212:215], v[12:15]
	v_mfma_f32_16x16x32_bf16 v[8:11], v[154:157], v[208:211], 0
	v_mfma_f32_16x16x32_bf16 v[8:11], v[158:161], v[212:215], v[8:11]
	s_setprio 0
	s_setprio 1
	v_mfma_f32_16x16x32_bf16 v[52:55], v[162:165], v[184:187], 0
	v_mfma_f32_16x16x32_bf16 v[52:55], v[166:169], v[188:191], v[52:55]
	v_mfma_f32_16x16x32_bf16 v[48:51], v[170:173], v[184:187], 0
	v_mfma_f32_16x16x32_bf16 v[48:51], v[174:177], v[188:191], v[48:51]
	v_mfma_f32_16x16x32_bf16 v[36:39], v[162:165], v[192:195], 0
	v_mfma_f32_16x16x32_bf16 v[36:39], v[166:169], v[196:199], v[36:39]
	v_mfma_f32_16x16x32_bf16 v[32:35], v[170:173], v[192:195], 0
	v_mfma_f32_16x16x32_bf16 v[32:35], v[174:177], v[196:199], v[32:35]
	v_mfma_f32_16x16x32_bf16 v[20:23], v[162:165], v[200:203], 0
	v_mfma_f32_16x16x32_bf16 v[20:23], v[166:169], v[204:207], v[20:23]
	v_mfma_f32_16x16x32_bf16 v[16:19], v[170:173], v[200:203], 0
	v_mfma_f32_16x16x32_bf16 v[16:19], v[174:177], v[204:207], v[16:19]
	v_mfma_f32_16x16x32_bf16 v[4:7], v[162:165], v[208:211], 0
	v_mfma_f32_16x16x32_bf16 v[4:7], v[166:169], v[212:215], v[4:7]
	v_mfma_f32_16x16x32_bf16 v[0:3], v[170:173], v[208:211], 0
	v_mfma_f32_16x16x32_bf16 v[0:3], v[174:177], v[212:215], v[0:3]
	s_setprio 0
	s_barrier
	s_branch .Lmid_gemm4
.LBB0_724:
	ds_read_b128 v[140:143], v147
	ds_read_b128 v[150:153], v147 offset:1024
	ds_read_b128 v[154:157], v147 offset:2048
	ds_read_b128 v[158:161], v147 offset:3072
	ds_read_b128 v[162:165], v148
	ds_read_b128 v[166:169], v148 offset:1024
	ds_read_b128 v[170:173], v148 offset:2048
	ds_read_b128 v[174:177], v148 offset:3072
	s_add_u32 s52, s48, 0xfffc0080
	s_addc_u32 s53, s49, -1
	s_cmp_eq_u32 s74, 12
	s_cselect_b32 s55, s31, s53
	s_cselect_b32 s54, s70, s52
	s_cselect_b32 s53, s19, s73
	s_cselect_b32 s52, s71, s72
	v_lshl_add_u64 v[178:179], s[48:49], 0, v[132:133]
	s_add_i32 m0, s47, 0xc000
	ds_read_b128 v[184:187], v149
	ds_read_b128 v[188:191], v149 offset:1024
	ds_read_b128 v[192:195], v149 offset:2048
	ds_read_b128 v[196:199], v149 offset:3072
	ds_read_b128 v[200:203], v149 offset:4096
	ds_read_b128 v[204:207], v149 offset:5120
	ds_read_b128 v[208:211], v149 offset:6144
	ds_read_b128 v[212:215], v149 offset:7168
	global_load_lds_dwordx4 v[178:179], off
	v_lshl_add_u64 v[178:179], s[48:49], 0, v[134:135]
	s_add_i32 m0, s47, 0xe000
	s_nop 0
	global_load_lds_dwordx4 v[178:179], off
	s_waitcnt vmcnt(8)
	s_waitcnt lgkmcnt(0)
	s_barrier
	s_setprio 1
	s_waitcnt lgkmcnt(0)
	v_mfma_f32_16x16x32_bf16 v[124:127], v[140:143], v[184:187], v[124:127]
	v_mfma_f32_16x16x32_bf16 v[124:127], v[150:153], v[188:191], v[124:127]
	v_mfma_f32_16x16x32_bf16 v[120:123], v[154:157], v[184:187], v[120:123]
	v_mfma_f32_16x16x32_bf16 v[120:123], v[158:161], v[188:191], v[120:123]
	v_mfma_f32_16x16x32_bf16 v[108:111], v[140:143], v[192:195], v[108:111]
	v_mfma_f32_16x16x32_bf16 v[108:111], v[150:153], v[196:199], v[108:111]
	v_mfma_f32_16x16x32_bf16 v[104:107], v[154:157], v[192:195], v[104:107]
	v_mfma_f32_16x16x32_bf16 v[104:107], v[158:161], v[196:199], v[104:107]
	v_mfma_f32_16x16x32_bf16 v[92:95], v[140:143], v[200:203], v[92:95]
	v_mfma_f32_16x16x32_bf16 v[92:95], v[150:153], v[204:207], v[92:95]
	v_mfma_f32_16x16x32_bf16 v[88:91], v[154:157], v[200:203], v[88:91]
	v_mfma_f32_16x16x32_bf16 v[88:91], v[158:161], v[204:207], v[88:91]
	v_mfma_f32_16x16x32_bf16 v[76:79], v[140:143], v[208:211], v[76:79]
	v_mfma_f32_16x16x32_bf16 v[76:79], v[150:153], v[212:215], v[76:79]
	v_mfma_f32_16x16x32_bf16 v[72:75], v[154:157], v[208:211], v[72:75]
	v_mfma_f32_16x16x32_bf16 v[72:75], v[158:161], v[212:215], v[72:75]
	s_setprio 0
	s_setprio 1
	v_mfma_f32_16x16x32_bf16 v[116:119], v[162:165], v[184:187], v[116:119]
	v_mfma_f32_16x16x32_bf16 v[116:119], v[166:169], v[188:191], v[116:119]
	v_mfma_f32_16x16x32_bf16 v[112:115], v[170:173], v[184:187], v[112:115]
	v_mfma_f32_16x16x32_bf16 v[112:115], v[174:177], v[188:191], v[112:115]
	v_mfma_f32_16x16x32_bf16 v[100:103], v[162:165], v[192:195], v[100:103]
	v_mfma_f32_16x16x32_bf16 v[100:103], v[166:169], v[196:199], v[100:103]
	v_mfma_f32_16x16x32_bf16 v[96:99], v[170:173], v[192:195], v[96:99]
	v_mfma_f32_16x16x32_bf16 v[96:99], v[174:177], v[196:199], v[96:99]
	v_mfma_f32_16x16x32_bf16 v[84:87], v[162:165], v[200:203], v[84:87]
	v_mfma_f32_16x16x32_bf16 v[84:87], v[166:169], v[204:207], v[84:87]
	v_mfma_f32_16x16x32_bf16 v[80:83], v[170:173], v[200:203], v[80:83]
	v_mfma_f32_16x16x32_bf16 v[80:83], v[174:177], v[204:207], v[80:83]
	v_mfma_f32_16x16x32_bf16 v[68:71], v[162:165], v[208:211], v[68:71]
	v_mfma_f32_16x16x32_bf16 v[68:71], v[166:169], v[212:215], v[68:71]
	v_mfma_f32_16x16x32_bf16 v[64:67], v[170:173], v[208:211], v[64:67]
	v_mfma_f32_16x16x32_bf16 v[64:67], v[174:177], v[212:215], v[64:67]
	s_setprio 0
	s_barrier
	s_add_i32 s75, s66, s58
	v_lshl_add_u64 v[178:179], s[52:53], 0, v[130:131]
	s_mov_b32 m0, s75
	ds_read_b128 v[184:187], v149 offset:16384
	ds_read_b128 v[188:191], v149 offset:17408
	ds_read_b128 v[192:195], v149 offset:18432
	ds_read_b128 v[196:199], v149 offset:19456
	ds_read_b128 v[200:203], v149 offset:20480
	ds_read_b128 v[204:207], v149 offset:21504
	ds_read_b128 v[208:211], v149 offset:22528
	ds_read_b128 v[212:215], v149 offset:23552
	global_load_lds_dwordx4 v[178:179], off
	s_add_i32 m0, s75, 0x2000
	s_add_u32 s76, s52, 0x40000
	v_lshl_add_u64 v[216:217], s[52:53], 0, v[128:129]
	s_addc_u32 s77, s53, 0
	s_add_i32 s75, s67, s58
	global_load_lds_dwordx4 v[216:217], off
	v_lshl_add_u64 v[218:219], s[76:77], 0, v[130:131]
	s_mov_b32 m0, s75
	v_lshl_add_u64 v[220:221], s[54:55], 0, v[128:129]
	global_load_lds_dwordx4 v[218:219], off
	v_lshl_add_u64 v[218:219], s[76:77], 0, v[128:129]
	s_add_i32 m0, s75, 0x2000
	s_nop 0
	global_load_lds_dwordx4 v[218:219], off
	v_lshl_add_u64 v[218:219], s[54:55], 0, v[130:131]
	s_mov_b32 m0, s47
	s_nop 0
	global_load_lds_dwordx4 v[218:219], off
	s_mov_b32 m0, s60
	s_nop 0
	global_load_lds_dwordx4 v[220:221], off
	s_waitcnt vmcnt(8)
	s_waitcnt lgkmcnt(0)
	s_barrier
	s_setprio 1
	s_waitcnt lgkmcnt(0)
	v_mfma_f32_16x16x32_bf16 v[60:63], v[140:143], v[184:187], v[60:63]
	v_mfma_f32_16x16x32_bf16 v[60:63], v[150:153], v[188:191], v[60:63]
	v_mfma_f32_16x16x32_bf16 v[56:59], v[154:157], v[184:187], v[56:59]
	v_mfma_f32_16x16x32_bf16 v[56:59], v[158:161], v[188:191], v[56:59]
	v_mfma_f32_16x16x32_bf16 v[44:47], v[140:143], v[192:195], v[44:47]
	v_mfma_f32_16x16x32_bf16 v[44:47], v[150:153], v[196:199], v[44:47]
	v_mfma_f32_16x16x32_bf16 v[40:43], v[154:157], v[192:195], v[40:43]
	v_mfma_f32_16x16x32_bf16 v[40:43], v[158:161], v[196:199], v[40:43]
	v_mfma_f32_16x16x32_bf16 v[28:31], v[140:143], v[200:203], v[28:31]
	v_mfma_f32_16x16x32_bf16 v[28:31], v[150:153], v[204:207], v[28:31]
	v_mfma_f32_16x16x32_bf16 v[24:27], v[154:157], v[200:203], v[24:27]
	v_mfma_f32_16x16x32_bf16 v[24:27], v[158:161], v[204:207], v[24:27]
	v_mfma_f32_16x16x32_bf16 v[12:15], v[140:143], v[208:211], v[12:15]
	v_mfma_f32_16x16x32_bf16 v[12:15], v[150:153], v[212:215], v[12:15]
	v_mfma_f32_16x16x32_bf16 v[8:11], v[154:157], v[208:211], v[8:11]
	v_mfma_f32_16x16x32_bf16 v[8:11], v[158:161], v[212:215], v[8:11]
	s_setprio 0
	s_setprio 1
	v_mfma_f32_16x16x32_bf16 v[52:55], v[162:165], v[184:187], v[52:55]
	v_mfma_f32_16x16x32_bf16 v[52:55], v[166:169], v[188:191], v[52:55]
	v_mfma_f32_16x16x32_bf16 v[48:51], v[170:173], v[184:187], v[48:51]
	v_mfma_f32_16x16x32_bf16 v[48:51], v[174:177], v[188:191], v[48:51]
	v_mfma_f32_16x16x32_bf16 v[36:39], v[162:165], v[192:195], v[36:39]
	v_mfma_f32_16x16x32_bf16 v[36:39], v[166:169], v[196:199], v[36:39]
	v_mfma_f32_16x16x32_bf16 v[32:35], v[170:173], v[192:195], v[32:35]
	v_mfma_f32_16x16x32_bf16 v[32:35], v[174:177], v[196:199], v[32:35]
	v_mfma_f32_16x16x32_bf16 v[20:23], v[162:165], v[200:203], v[20:23]
	v_mfma_f32_16x16x32_bf16 v[20:23], v[166:169], v[204:207], v[20:23]
	v_mfma_f32_16x16x32_bf16 v[16:19], v[170:173], v[200:203], v[16:19]
	v_mfma_f32_16x16x32_bf16 v[16:19], v[174:177], v[204:207], v[16:19]
	v_mfma_f32_16x16x32_bf16 v[4:7], v[162:165], v[208:211], v[4:7]
	v_mfma_f32_16x16x32_bf16 v[4:7], v[166:169], v[212:215], v[4:7]
	v_mfma_f32_16x16x32_bf16 v[0:3], v[170:173], v[208:211], v[0:3]
	v_mfma_f32_16x16x32_bf16 v[0:3], v[174:177], v[212:215], v[0:3]
	s_setprio 0
	s_barrier
.Lmid_gemm4:
	s_add_i32 s75, 0, 0x18000
	s_add_i32 s76, 0, 0x1c000
	v_add_u32_e32 v158, s75, v145
	v_add_u32_e32 v174, s76, v145
	ds_read_b128 v[140:143], v158
	ds_read_b128 v[150:153], v158 offset:1024
	ds_read_b128 v[154:157], v158 offset:2048
	ds_read_b128 v[158:161], v158 offset:3072
	ds_read_b128 v[162:165], v174
	ds_read_b128 v[166:169], v174 offset:1024
	ds_read_b128 v[170:173], v174 offset:2048
	ds_read_b128 v[174:177], v174 offset:3072
	s_add_u32 s54, s54, 0x40000
	s_addc_u32 s55, s55, 0
	s_mov_b32 m0, s61
	v_lshl_add_u64 v[222:223], s[54:55], 0, v[130:131]
	ds_read_b128 v[184:187], v149 offset:32768
	ds_read_b128 v[188:191], v149 offset:33792
	ds_read_b128 v[192:195], v149 offset:34816
	ds_read_b128 v[196:199], v149 offset:35840
	ds_read_b128 v[200:203], v149 offset:36864
	ds_read_b128 v[204:207], v149 offset:37888
	ds_read_b128 v[208:211], v149 offset:38912
	ds_read_b128 v[212:215], v149 offset:39936
	global_load_lds_dwordx4 v[222:223], off
	v_lshl_add_u64 v[222:223], s[54:55], 0, v[128:129]
	s_mov_b32 m0, s62
	s_nop 0
	global_load_lds_dwordx4 v[222:223], off
	s_waitcnt vmcnt(8)
	s_waitcnt lgkmcnt(0)
	s_barrier
	s_setprio 1
	s_waitcnt lgkmcnt(0)
	v_mfma_f32_16x16x32_bf16 v[124:127], v[140:143], v[184:187], v[124:127]
	v_mfma_f32_16x16x32_bf16 v[124:127], v[150:153], v[188:191], v[124:127]
	v_mfma_f32_16x16x32_bf16 v[120:123], v[154:157], v[184:187], v[120:123]
	v_mfma_f32_16x16x32_bf16 v[120:123], v[158:161], v[188:191], v[120:123]
	v_mfma_f32_16x16x32_bf16 v[108:111], v[140:143], v[192:195], v[108:111]
	v_mfma_f32_16x16x32_bf16 v[108:111], v[150:153], v[196:199], v[108:111]
	v_mfma_f32_16x16x32_bf16 v[104:107], v[154:157], v[192:195], v[104:107]
	v_mfma_f32_16x16x32_bf16 v[104:107], v[158:161], v[196:199], v[104:107]
	v_mfma_f32_16x16x32_bf16 v[92:95], v[140:143], v[200:203], v[92:95]
	v_mfma_f32_16x16x32_bf16 v[92:95], v[150:153], v[204:207], v[92:95]
	v_mfma_f32_16x16x32_bf16 v[88:91], v[154:157], v[200:203], v[88:91]
	v_mfma_f32_16x16x32_bf16 v[88:91], v[158:161], v[204:207], v[88:91]
	v_mfma_f32_16x16x32_bf16 v[76:79], v[140:143], v[208:211], v[76:79]
	v_mfma_f32_16x16x32_bf16 v[76:79], v[150:153], v[212:215], v[76:79]
	v_mfma_f32_16x16x32_bf16 v[72:75], v[154:157], v[208:211], v[72:75]
	v_mfma_f32_16x16x32_bf16 v[72:75], v[158:161], v[212:215], v[72:75]
	s_setprio 0
	s_setprio 1
	v_mfma_f32_16x16x32_bf16 v[116:119], v[162:165], v[184:187], v[116:119]
	v_mfma_f32_16x16x32_bf16 v[116:119], v[166:169], v[188:191], v[116:119]
	v_mfma_f32_16x16x32_bf16 v[112:115], v[170:173], v[184:187], v[112:115]
	v_mfma_f32_16x16x32_bf16 v[112:115], v[174:177], v[188:191], v[112:115]
	v_mfma_f32_16x16x32_bf16 v[100:103], v[162:165], v[192:195], v[100:103]
	v_mfma_f32_16x16x32_bf16 v[100:103], v[166:169], v[196:199], v[100:103]
	v_mfma_f32_16x16x32_bf16 v[96:99], v[170:173], v[192:195], v[96:99]
	v_mfma_f32_16x16x32_bf16 v[96:99], v[174:177], v[196:199], v[96:99]
	v_mfma_f32_16x16x32_bf16 v[84:87], v[162:165], v[200:203], v[84:87]
	v_mfma_f32_16x16x32_bf16 v[84:87], v[166:169], v[204:207], v[84:87]
	v_mfma_f32_16x16x32_bf16 v[80:83], v[170:173], v[200:203], v[80:83]
	v_mfma_f32_16x16x32_bf16 v[80:83], v[174:177], v[204:207], v[80:83]
	v_mfma_f32_16x16x32_bf16 v[68:71], v[162:165], v[208:211], v[68:71]
	v_mfma_f32_16x16x32_bf16 v[68:71], v[166:169], v[212:215], v[68:71]
	v_mfma_f32_16x16x32_bf16 v[64:67], v[170:173], v[208:211], v[64:67]
	v_mfma_f32_16x16x32_bf16 v[64:67], v[174:177], v[212:215], v[64:67]
	s_setprio 0
	s_barrier
	s_add_i32 s54, s75, s58
	v_lshl_add_u64 v[178:179], v[178:179], 0, s[12:13]
	s_mov_b32 m0, s54
	ds_read_b128 v[184:187], v149 offset:49152
	ds_read_b128 v[188:191], v149 offset:50176
	ds_read_b128 v[192:195], v149 offset:51200
	ds_read_b128 v[196:199], v149 offset:52224
	ds_read_b128 v[200:203], v149 offset:53248
	ds_read_b128 v[204:207], v149 offset:54272
	ds_read_b128 v[208:211], v149 offset:55296
	ds_read_b128 v[212:215], v149 offset:56320
	global_load_lds_dwordx4 v[178:179], off
	s_add_i32 m0, s54, 0x2000
	s_add_u32 s52, s52, 0x40080
	v_lshl_add_u64 v[178:179], v[216:217], 0, s[12:13]
	s_addc_u32 s53, s53, 0
	s_add_i32 s54, s76, s58
	global_load_lds_dwordx4 v[178:179], off
	v_lshl_add_u64 v[178:179], s[52:53], 0, v[130:131]
	s_mov_b32 m0, s54
	s_nop 0
	global_load_lds_dwordx4 v[178:179], off
	v_lshl_add_u64 v[178:179], s[52:53], 0, v[128:129]
	s_add_i32 m0, s54, 0x2000
	s_nop 0
	global_load_lds_dwordx4 v[178:179], off
	v_lshl_add_u64 v[178:179], v[218:219], 0, s[12:13]
	s_mov_b32 m0, s64
	s_nop 0
	global_load_lds_dwordx4 v[178:179], off
	v_lshl_add_u64 v[178:179], v[220:221], 0, s[12:13]
	s_mov_b32 m0, s65
	s_nop 0
	global_load_lds_dwordx4 v[178:179], off
	s_waitcnt vmcnt(8)
	s_waitcnt lgkmcnt(0)
	s_barrier
	s_setprio 1
	s_waitcnt lgkmcnt(0)
	v_mfma_f32_16x16x32_bf16 v[60:63], v[140:143], v[184:187], v[60:63]
	v_mfma_f32_16x16x32_bf16 v[60:63], v[150:153], v[188:191], v[60:63]
	v_mfma_f32_16x16x32_bf16 v[56:59], v[154:157], v[184:187], v[56:59]
	v_mfma_f32_16x16x32_bf16 v[56:59], v[158:161], v[188:191], v[56:59]
	v_mfma_f32_16x16x32_bf16 v[44:47], v[140:143], v[192:195], v[44:47]
	v_mfma_f32_16x16x32_bf16 v[44:47], v[150:153], v[196:199], v[44:47]
	v_mfma_f32_16x16x32_bf16 v[40:43], v[154:157], v[192:195], v[40:43]
	v_mfma_f32_16x16x32_bf16 v[40:43], v[158:161], v[196:199], v[40:43]
	v_mfma_f32_16x16x32_bf16 v[28:31], v[140:143], v[200:203], v[28:31]
	v_mfma_f32_16x16x32_bf16 v[28:31], v[150:153], v[204:207], v[28:31]
	v_mfma_f32_16x16x32_bf16 v[24:27], v[154:157], v[200:203], v[24:27]
	v_mfma_f32_16x16x32_bf16 v[24:27], v[158:161], v[204:207], v[24:27]
	v_mfma_f32_16x16x32_bf16 v[12:15], v[140:143], v[208:211], v[12:15]
	v_mfma_f32_16x16x32_bf16 v[12:15], v[150:153], v[212:215], v[12:15]
	v_mfma_f32_16x16x32_bf16 v[8:11], v[154:157], v[208:211], v[8:11]
	v_mfma_f32_16x16x32_bf16 v[8:11], v[158:161], v[212:215], v[8:11]
	s_setprio 0
	s_setprio 1
	v_mfma_f32_16x16x32_bf16 v[52:55], v[162:165], v[184:187], v[52:55]
	v_mfma_f32_16x16x32_bf16 v[52:55], v[166:169], v[188:191], v[52:55]
	v_mfma_f32_16x16x32_bf16 v[48:51], v[170:173], v[184:187], v[48:51]
	v_mfma_f32_16x16x32_bf16 v[48:51], v[174:177], v[188:191], v[48:51]
	v_mfma_f32_16x16x32_bf16 v[36:39], v[162:165], v[192:195], v[36:39]
	v_mfma_f32_16x16x32_bf16 v[36:39], v[166:169], v[196:199], v[36:39]
	v_mfma_f32_16x16x32_bf16 v[32:35], v[170:173], v[192:195], v[32:35]
	v_mfma_f32_16x16x32_bf16 v[32:35], v[174:177], v[196:199], v[32:35]
	v_mfma_f32_16x16x32_bf16 v[20:23], v[162:165], v[200:203], v[20:23]
	v_mfma_f32_16x16x32_bf16 v[20:23], v[166:169], v[204:207], v[20:23]
	v_mfma_f32_16x16x32_bf16 v[16:19], v[170:173], v[200:203], v[16:19]
	v_mfma_f32_16x16x32_bf16 v[16:19], v[174:177], v[204:207], v[16:19]
	v_mfma_f32_16x16x32_bf16 v[4:7], v[162:165], v[208:211], v[4:7]
	v_mfma_f32_16x16x32_bf16 v[4:7], v[166:169], v[212:215], v[4:7]
	v_mfma_f32_16x16x32_bf16 v[0:3], v[170:173], v[208:211], v[0:3]
	v_mfma_f32_16x16x32_bf16 v[0:3], v[174:177], v[212:215], v[0:3]
	s_setprio 0
	s_barrier
	s_add_i32 s74, s74, 2
	s_add_u32 s48, s48, 0x100
	s_addc_u32 s49, s49, 0
	s_add_u32 s72, s72, 0x100
	s_addc_u32 s73, s73, 0
	s_cmp_gt_u32 s74, 13
	s_cbranch_scc0 .LBB0_724
	s_and_b64 vcc, exec, s[16:17]
	s_cbranch_vccz .LBB0_727
	s_barrier

.LBB0_803:
	s_add_u32 s84, s54, 0x100
	s_addc_u32 s85, s55, 0
	s_mov_b32 s86, -2
	ds_read_b128 v[152:155], v149
	ds_read_b128 v[156:159], v149 offset:1024
	ds_read_b128 v[160:163], v149 offset:2048
	ds_read_b128 v[164:167], v149 offset:3072
	ds_read_b128 v[168:171], v150
	ds_read_b128 v[172:175], v150 offset:1024
	ds_read_b128 v[176:179], v150 offset:2048
	ds_read_b128 v[184:187], v150 offset:3072
	s_add_u32 s54, s52, 0x100
	s_addc_u32 s55, s53, 0
	s_cmp_eq_u32 s86, 40
	s_cselect_b32 s59, s13, s55
	s_cselect_b32 s58, s12, s54
	s_cselect_b32 s57, s49, s85
	s_cselect_b32 s56, s48, s84
	v_lshl_add_u64 v[144:145], s[52:53], 0, v[136:137]
	s_add_i32 m0, s63, 0xc000
	ds_read_b128 v[188:191], v151
	ds_read_b128 v[192:195], v151 offset:1024
	ds_read_b128 v[196:199], v151 offset:2048
	ds_read_b128 v[200:203], v151 offset:3072
	ds_read_b128 v[204:207], v151 offset:4096
	ds_read_b128 v[208:211], v151 offset:5120
	ds_read_b128 v[212:215], v151 offset:6144
	ds_read_b128 v[216:219], v151 offset:7168
	global_load_lds_dwordx4 v[144:145], off
	v_lshl_add_u64 v[144:145], s[52:53], 0, v[138:139]
	s_add_i32 m0, s63, 0xe000
	s_nop 0
	global_load_lds_dwordx4 v[144:145], off
	s_waitcnt vmcnt(8)
	s_waitcnt lgkmcnt(0)
	s_barrier
	s_setprio 1
	s_waitcnt lgkmcnt(0)
	v_mfma_f32_16x16x32_bf16 v[124:127], v[152:155], v[188:191], 0
	v_mfma_f32_16x16x32_bf16 v[124:127], v[156:159], v[192:195], v[124:127]
	v_mfma_f32_16x16x32_bf16 v[120:123], v[160:163], v[188:191], 0
	v_mfma_f32_16x16x32_bf16 v[120:123], v[164:167], v[192:195], v[120:123]
	v_mfma_f32_16x16x32_bf16 v[116:119], v[152:155], v[196:199], 0
	v_mfma_f32_16x16x32_bf16 v[116:119], v[156:159], v[200:203], v[116:119]
	v_mfma_f32_16x16x32_bf16 v[108:111], v[160:163], v[196:199], 0
	v_mfma_f32_16x16x32_bf16 v[108:111], v[164:167], v[200:203], v[108:111]
	v_mfma_f32_16x16x32_bf16 v[100:103], v[152:155], v[204:207], 0
	v_mfma_f32_16x16x32_bf16 v[100:103], v[156:159], v[208:211], v[100:103]
	v_mfma_f32_16x16x32_bf16 v[92:95], v[160:163], v[204:207], 0
	v_mfma_f32_16x16x32_bf16 v[92:95], v[164:167], v[208:211], v[92:95]
	v_mfma_f32_16x16x32_bf16 v[84:87], v[152:155], v[212:215], 0
	v_mfma_f32_16x16x32_bf16 v[84:87], v[156:159], v[216:219], v[84:87]
	v_mfma_f32_16x16x32_bf16 v[76:79], v[160:163], v[212:215], 0
	v_mfma_f32_16x16x32_bf16 v[76:79], v[164:167], v[216:219], v[76:79]
	s_setprio 0
	s_setprio 1
	v_mfma_f32_16x16x32_bf16 v[112:115], v[168:171], v[188:191], 0
	v_mfma_f32_16x16x32_bf16 v[112:115], v[172:175], v[192:195], v[112:115]
	v_mfma_f32_16x16x32_bf16 v[104:107], v[176:179], v[188:191], 0
	v_mfma_f32_16x16x32_bf16 v[104:107], v[184:187], v[192:195], v[104:107]
	v_mfma_f32_16x16x32_bf16 v[96:99], v[168:171], v[196:199], 0
	v_mfma_f32_16x16x32_bf16 v[96:99], v[172:175], v[200:203], v[96:99]
	v_mfma_f32_16x16x32_bf16 v[88:91], v[176:179], v[196:199], 0
	v_mfma_f32_16x16x32_bf16 v[88:91], v[184:187], v[200:203], v[88:91]
	v_mfma_f32_16x16x32_bf16 v[80:83], v[168:171], v[204:207], 0
	v_mfma_f32_16x16x32_bf16 v[80:83], v[172:175], v[208:211], v[80:83]
	v_mfma_f32_16x16x32_bf16 v[72:75], v[176:179], v[204:207], 0
	v_mfma_f32_16x16x32_bf16 v[72:75], v[184:187], v[208:211], v[72:75]
	v_mfma_f32_16x16x32_bf16 v[68:71], v[168:171], v[212:215], 0
	v_mfma_f32_16x16x32_bf16 v[68:71], v[172:175], v[216:219], v[68:71]
	v_mfma_f32_16x16x32_bf16 v[64:67], v[176:179], v[212:215], 0
	v_mfma_f32_16x16x32_bf16 v[64:67], v[184:187], v[216:219], v[64:67]
	s_setprio 0
	s_barrier
	s_add_i32 s52, s70, s62
	v_lshl_add_u64 v[144:145], s[56:57], 0, v[130:131]
	s_mov_b32 m0, s52
	ds_read_b128 v[188:191], v151 offset:16384
	ds_read_b128 v[192:195], v151 offset:17408
	ds_read_b128 v[196:199], v151 offset:18432
	ds_read_b128 v[200:203], v151 offset:19456
	ds_read_b128 v[204:207], v151 offset:20480
	ds_read_b128 v[208:211], v151 offset:21504
	ds_read_b128 v[212:215], v151 offset:22528
	ds_read_b128 v[216:219], v151 offset:23552
	global_load_lds_dwordx4 v[144:145], off
	s_add_i32 m0, s52, 0x2000
	s_add_u32 s52, s56, 0xb0000
	v_lshl_add_u64 v[220:221], s[56:57], 0, v[134:135]
	s_addc_u32 s53, s57, 0
	s_add_i32 s79, s71, s62
	global_load_lds_dwordx4 v[220:221], off
	v_lshl_add_u64 v[222:223], s[52:53], 0, v[130:131]
	s_mov_b32 m0, s79
	v_lshl_add_u64 v[224:225], s[58:59], 0, v[132:133]
	global_load_lds_dwordx4 v[222:223], off
	v_lshl_add_u64 v[222:223], s[52:53], 0, v[134:135]
	s_add_i32 m0, s79, 0x2000
	s_nop 0
	global_load_lds_dwordx4 v[222:223], off
	v_lshl_add_u64 v[222:223], s[58:59], 0, v[128:129]
	s_mov_b32 m0, s63
	s_nop 0
	global_load_lds_dwordx4 v[222:223], off
	s_mov_b32 m0, s64
	s_nop 0
	global_load_lds_dwordx4 v[224:225], off
	s_waitcnt vmcnt(8)
	s_waitcnt lgkmcnt(0)
	s_barrier
	s_setprio 1
	s_waitcnt lgkmcnt(0)
	v_mfma_f32_16x16x32_bf16 v[60:63], v[152:155], v[188:191], 0
	v_mfma_f32_16x16x32_bf16 v[60:63], v[156:159], v[192:195], v[60:63]
	v_mfma_f32_16x16x32_bf16 v[56:59], v[160:163], v[188:191], 0
	v_mfma_f32_16x16x32_bf16 v[56:59], v[164:167], v[192:195], v[56:59]
	v_mfma_f32_16x16x32_bf16 v[52:55], v[152:155], v[196:199], 0
	v_mfma_f32_16x16x32_bf16 v[52:55], v[156:159], v[200:203], v[52:55]
	v_mfma_f32_16x16x32_bf16 v[44:47], v[160:163], v[196:199], 0
	v_mfma_f32_16x16x32_bf16 v[44:47], v[164:167], v[200:203], v[44:47]
	v_mfma_f32_16x16x32_bf16 v[36:39], v[152:155], v[204:207], 0
	v_mfma_f32_16x16x32_bf16 v[36:39], v[156:159], v[208:211], v[36:39]
	v_mfma_f32_16x16x32_bf16 v[28:31], v[160:163], v[204:207], 0
	v_mfma_f32_16x16x32_bf16 v[28:31], v[164:167], v[208:211], v[28:31]
	v_mfma_f32_16x16x32_bf16 v[20:23], v[152:155], v[212:215], 0
	v_mfma_f32_16x16x32_bf16 v[20:23], v[156:159], v[216:219], v[20:23]
	v_mfma_f32_16x16x32_bf16 v[12:15], v[160:163], v[212:215], 0
	v_mfma_f32_16x16x32_bf16 v[12:15], v[164:167], v[216:219], v[12:15]
	s_setprio 0
	s_setprio 1
	v_mfma_f32_16x16x32_bf16 v[48:51], v[168:171], v[188:191], 0
	v_mfma_f32_16x16x32_bf16 v[48:51], v[172:175], v[192:195], v[48:51]
	v_mfma_f32_16x16x32_bf16 v[40:43], v[176:179], v[188:191], 0
	v_mfma_f32_16x16x32_bf16 v[40:43], v[184:187], v[192:195], v[40:43]
	v_mfma_f32_16x16x32_bf16 v[32:35], v[168:171], v[196:199], 0
	v_mfma_f32_16x16x32_bf16 v[32:35], v[172:175], v[200:203], v[32:35]
	v_mfma_f32_16x16x32_bf16 v[24:27], v[176:179], v[196:199], 0
	v_mfma_f32_16x16x32_bf16 v[24:27], v[184:187], v[200:203], v[24:27]
	v_mfma_f32_16x16x32_bf16 v[16:19], v[168:171], v[204:207], 0
	v_mfma_f32_16x16x32_bf16 v[16:19], v[172:175], v[208:211], v[16:19]
	v_mfma_f32_16x16x32_bf16 v[8:11], v[176:179], v[204:207], 0
	v_mfma_f32_16x16x32_bf16 v[8:11], v[184:187], v[208:211], v[8:11]
	v_mfma_f32_16x16x32_bf16 v[4:7], v[168:171], v[212:215], 0
	v_mfma_f32_16x16x32_bf16 v[4:7], v[172:175], v[216:219], v[4:7]
	v_mfma_f32_16x16x32_bf16 v[0:3], v[176:179], v[212:215], 0
	v_mfma_f32_16x16x32_bf16 v[0:3], v[184:187], v[216:219], v[0:3]
	s_setprio 0
	s_barrier
	s_branch .Lmid_gemm5
.LBB0_804:
	ds_read_b128 v[152:155], v149
	ds_read_b128 v[156:159], v149 offset:1024
	ds_read_b128 v[160:163], v149 offset:2048
	ds_read_b128 v[164:167], v149 offset:3072
	ds_read_b128 v[168:171], v150
	ds_read_b128 v[172:175], v150 offset:1024
	ds_read_b128 v[176:179], v150 offset:2048
	ds_read_b128 v[184:187], v150 offset:3072
	s_add_u32 s54, s52, 0x100
	s_addc_u32 s55, s53, 0
	s_cmp_eq_u32 s86, 40
	s_cselect_b32 s59, s13, s55
	s_cselect_b32 s58, s12, s54
	s_cselect_b32 s57, s49, s85
	s_cselect_b32 s56, s48, s84
	v_lshl_add_u64 v[144:145], s[52:53], 0, v[136:137]
	s_add_i32 m0, s63, 0xc000
	ds_read_b128 v[188:191], v151
	ds_read_b128 v[192:195], v151 offset:1024
	ds_read_b128 v[196:199], v151 offset:2048
	ds_read_b128 v[200:203], v151 offset:3072
	ds_read_b128 v[204:207], v151 offset:4096
	ds_read_b128 v[208:211], v151 offset:5120
	ds_read_b128 v[212:215], v151 offset:6144
	ds_read_b128 v[216:219], v151 offset:7168
	global_load_lds_dwordx4 v[144:145], off
	v_lshl_add_u64 v[144:145], s[52:53], 0, v[138:139]
	s_add_i32 m0, s63, 0xe000
	s_nop 0
	global_load_lds_dwordx4 v[144:145], off
	s_waitcnt vmcnt(8)
	s_waitcnt lgkmcnt(0)
	s_barrier
	s_setprio 1
	s_waitcnt lgkmcnt(0)
	v_mfma_f32_16x16x32_bf16 v[124:127], v[152:155], v[188:191], v[124:127]
	v_mfma_f32_16x16x32_bf16 v[124:127], v[156:159], v[192:195], v[124:127]
	v_mfma_f32_16x16x32_bf16 v[120:123], v[160:163], v[188:191], v[120:123]
	v_mfma_f32_16x16x32_bf16 v[120:123], v[164:167], v[192:195], v[120:123]
	v_mfma_f32_16x16x32_bf16 v[116:119], v[152:155], v[196:199], v[116:119]
	v_mfma_f32_16x16x32_bf16 v[116:119], v[156:159], v[200:203], v[116:119]
	v_mfma_f32_16x16x32_bf16 v[108:111], v[160:163], v[196:199], v[108:111]
	v_mfma_f32_16x16x32_bf16 v[108:111], v[164:167], v[200:203], v[108:111]
	v_mfma_f32_16x16x32_bf16 v[100:103], v[152:155], v[204:207], v[100:103]
	v_mfma_f32_16x16x32_bf16 v[100:103], v[156:159], v[208:211], v[100:103]
	v_mfma_f32_16x16x32_bf16 v[92:95], v[160:163], v[204:207], v[92:95]
	v_mfma_f32_16x16x32_bf16 v[92:95], v[164:167], v[208:211], v[92:95]
	v_mfma_f32_16x16x32_bf16 v[84:87], v[152:155], v[212:215], v[84:87]
	v_mfma_f32_16x16x32_bf16 v[84:87], v[156:159], v[216:219], v[84:87]
	v_mfma_f32_16x16x32_bf16 v[76:79], v[160:163], v[212:215], v[76:79]
	v_mfma_f32_16x16x32_bf16 v[76:79], v[164:167], v[216:219], v[76:79]
	s_setprio 0
	s_setprio 1
	v_mfma_f32_16x16x32_bf16 v[112:115], v[168:171], v[188:191], v[112:115]
	v_mfma_f32_16x16x32_bf16 v[112:115], v[172:175], v[192:195], v[112:115]
	v_mfma_f32_16x16x32_bf16 v[104:107], v[176:179], v[188:191], v[104:107]
	v_mfma_f32_16x16x32_bf16 v[104:107], v[184:187], v[192:195], v[104:107]
	v_mfma_f32_16x16x32_bf16 v[96:99], v[168:171], v[196:199], v[96:99]
	v_mfma_f32_16x16x32_bf16 v[96:99], v[172:175], v[200:203], v[96:99]
	v_mfma_f32_16x16x32_bf16 v[88:91], v[176:179], v[196:199], v[88:91]
	v_mfma_f32_16x16x32_bf16 v[88:91], v[184:187], v[200:203], v[88:91]
	v_mfma_f32_16x16x32_bf16 v[80:83], v[168:171], v[204:207], v[80:83]
	v_mfma_f32_16x16x32_bf16 v[80:83], v[172:175], v[208:211], v[80:83]
	v_mfma_f32_16x16x32_bf16 v[72:75], v[176:179], v[204:207], v[72:75]
	v_mfma_f32_16x16x32_bf16 v[72:75], v[184:187], v[208:211], v[72:75]
	v_mfma_f32_16x16x32_bf16 v[68:71], v[168:171], v[212:215], v[68:71]
	v_mfma_f32_16x16x32_bf16 v[68:71], v[172:175], v[216:219], v[68:71]
	v_mfma_f32_16x16x32_bf16 v[64:67], v[176:179], v[212:215], v[64:67]
	v_mfma_f32_16x16x32_bf16 v[64:67], v[184:187], v[216:219], v[64:67]
	s_setprio 0
	s_barrier
	s_add_i32 s52, s70, s62
	v_lshl_add_u64 v[144:145], s[56:57], 0, v[130:131]
	s_mov_b32 m0, s52
	ds_read_b128 v[188:191], v151 offset:16384
	ds_read_b128 v[192:195], v151 offset:17408
	ds_read_b128 v[196:199], v151 offset:18432
	ds_read_b128 v[200:203], v151 offset:19456
	ds_read_b128 v[204:207], v151 offset:20480
	ds_read_b128 v[208:211], v151 offset:21504
	ds_read_b128 v[212:215], v151 offset:22528
	ds_read_b128 v[216:219], v151 offset:23552
	global_load_lds_dwordx4 v[144:145], off
	s_add_i32 m0, s52, 0x2000
	s_add_u32 s52, s56, 0xb0000
	v_lshl_add_u64 v[220:221], s[56:57], 0, v[134:135]
	s_addc_u32 s53, s57, 0
	s_add_i32 s79, s71, s62
	global_load_lds_dwordx4 v[220:221], off
	v_lshl_add_u64 v[222:223], s[52:53], 0, v[130:131]
	s_mov_b32 m0, s79
	v_lshl_add_u64 v[224:225], s[58:59], 0, v[132:133]
	global_load_lds_dwordx4 v[222:223], off
	v_lshl_add_u64 v[222:223], s[52:53], 0, v[134:135]
	s_add_i32 m0, s79, 0x2000
	s_nop 0
	global_load_lds_dwordx4 v[222:223], off
	v_lshl_add_u64 v[222:223], s[58:59], 0, v[128:129]
	s_mov_b32 m0, s63
	s_nop 0
	global_load_lds_dwordx4 v[222:223], off
	s_mov_b32 m0, s64
	s_nop 0
	global_load_lds_dwordx4 v[224:225], off
	s_waitcnt vmcnt(8)
	s_waitcnt lgkmcnt(0)
	s_barrier
	s_setprio 1
	s_waitcnt lgkmcnt(0)
	v_mfma_f32_16x16x32_bf16 v[60:63], v[152:155], v[188:191], v[60:63]
	v_mfma_f32_16x16x32_bf16 v[60:63], v[156:159], v[192:195], v[60:63]
	v_mfma_f32_16x16x32_bf16 v[56:59], v[160:163], v[188:191], v[56:59]
	v_mfma_f32_16x16x32_bf16 v[56:59], v[164:167], v[192:195], v[56:59]
	v_mfma_f32_16x16x32_bf16 v[52:55], v[152:155], v[196:199], v[52:55]
	v_mfma_f32_16x16x32_bf16 v[52:55], v[156:159], v[200:203], v[52:55]
	v_mfma_f32_16x16x32_bf16 v[44:47], v[160:163], v[196:199], v[44:47]
	v_mfma_f32_16x16x32_bf16 v[44:47], v[164:167], v[200:203], v[44:47]
	v_mfma_f32_16x16x32_bf16 v[36:39], v[152:155], v[204:207], v[36:39]
	v_mfma_f32_16x16x32_bf16 v[36:39], v[156:159], v[208:211], v[36:39]
	v_mfma_f32_16x16x32_bf16 v[28:31], v[160:163], v[204:207], v[28:31]
	v_mfma_f32_16x16x32_bf16 v[28:31], v[164:167], v[208:211], v[28:31]
	v_mfma_f32_16x16x32_bf16 v[20:23], v[152:155], v[212:215], v[20:23]
	v_mfma_f32_16x16x32_bf16 v[20:23], v[156:159], v[216:219], v[20:23]
	v_mfma_f32_16x16x32_bf16 v[12:15], v[160:163], v[212:215], v[12:15]
	v_mfma_f32_16x16x32_bf16 v[12:15], v[164:167], v[216:219], v[12:15]
	s_setprio 0
	s_setprio 1
	v_mfma_f32_16x16x32_bf16 v[48:51], v[168:171], v[188:191], v[48:51]
	v_mfma_f32_16x16x32_bf16 v[48:51], v[172:175], v[192:195], v[48:51]
	v_mfma_f32_16x16x32_bf16 v[40:43], v[176:179], v[188:191], v[40:43]
	v_mfma_f32_16x16x32_bf16 v[40:43], v[184:187], v[192:195], v[40:43]
	v_mfma_f32_16x16x32_bf16 v[32:35], v[168:171], v[196:199], v[32:35]
	v_mfma_f32_16x16x32_bf16 v[32:35], v[172:175], v[200:203], v[32:35]
	v_mfma_f32_16x16x32_bf16 v[24:27], v[176:179], v[196:199], v[24:27]
	v_mfma_f32_16x16x32_bf16 v[24:27], v[184:187], v[200:203], v[24:27]
	v_mfma_f32_16x16x32_bf16 v[16:19], v[168:171], v[204:207], v[16:19]
	v_mfma_f32_16x16x32_bf16 v[16:19], v[172:175], v[208:211], v[16:19]
	v_mfma_f32_16x16x32_bf16 v[8:11], v[176:179], v[204:207], v[8:11]
	v_mfma_f32_16x16x32_bf16 v[8:11], v[184:187], v[208:211], v[8:11]
	v_mfma_f32_16x16x32_bf16 v[4:7], v[168:171], v[212:215], v[4:7]
	v_mfma_f32_16x16x32_bf16 v[4:7], v[172:175], v[216:219], v[4:7]
	v_mfma_f32_16x16x32_bf16 v[0:3], v[176:179], v[212:215], v[0:3]
	v_mfma_f32_16x16x32_bf16 v[0:3], v[184:187], v[216:219], v[0:3]
	s_setprio 0
	s_barrier
.Lmid_gemm5:
	s_add_i32 s79, 0, 0x18000
	s_add_i32 s87, 0, 0x1c000
	v_add_u32_e32 v164, s79, v147
	v_add_u32_e32 v181, s87, v147
	ds_read_b128 v[152:155], v164
	ds_read_b128 v[156:159], v164 offset:1024
	ds_read_b128 v[160:163], v164 offset:2048
	ds_read_b128 v[164:167], v164 offset:3072
	ds_read_b128 v[168:171], v181
	ds_read_b128 v[172:175], v181 offset:1024
	ds_read_b128 v[176:179], v181 offset:2048
	ds_read_b128 v[184:187], v181 offset:3072
	s_add_u32 s52, s58, 0xb0000
	s_addc_u32 s53, s59, 0
	s_mov_b32 m0, s65
	v_lshl_add_u64 v[226:227], s[52:53], 0, v[128:129]
	ds_read_b128 v[188:191], v151 offset:32768
	ds_read_b128 v[192:195], v151 offset:33792
	ds_read_b128 v[196:199], v151 offset:34816
	ds_read_b128 v[200:203], v151 offset:35840
	ds_read_b128 v[204:207], v151 offset:36864
	ds_read_b128 v[208:211], v151 offset:37888
	ds_read_b128 v[212:215], v151 offset:38912
	ds_read_b128 v[216:219], v151 offset:39936
	global_load_lds_dwordx4 v[226:227], off
	v_lshl_add_u64 v[226:227], s[52:53], 0, v[132:133]
	s_mov_b32 m0, s66
	s_nop 0
	global_load_lds_dwordx4 v[226:227], off
	s_waitcnt vmcnt(8)
	s_waitcnt lgkmcnt(0)
	s_barrier
	s_setprio 1
	s_waitcnt lgkmcnt(0)
	v_mfma_f32_16x16x32_bf16 v[124:127], v[152:155], v[188:191], v[124:127]
	v_mfma_f32_16x16x32_bf16 v[124:127], v[156:159], v[192:195], v[124:127]
	v_mfma_f32_16x16x32_bf16 v[120:123], v[160:163], v[188:191], v[120:123]
	v_mfma_f32_16x16x32_bf16 v[120:123], v[164:167], v[192:195], v[120:123]
	v_mfma_f32_16x16x32_bf16 v[116:119], v[152:155], v[196:199], v[116:119]
	v_mfma_f32_16x16x32_bf16 v[116:119], v[156:159], v[200:203], v[116:119]
	v_mfma_f32_16x16x32_bf16 v[108:111], v[160:163], v[196:199], v[108:111]
	v_mfma_f32_16x16x32_bf16 v[108:111], v[164:167], v[200:203], v[108:111]
	v_mfma_f32_16x16x32_bf16 v[100:103], v[152:155], v[204:207], v[100:103]
	v_mfma_f32_16x16x32_bf16 v[100:103], v[156:159], v[208:211], v[100:103]
	v_mfma_f32_16x16x32_bf16 v[92:95], v[160:163], v[204:207], v[92:95]
	v_mfma_f32_16x16x32_bf16 v[92:95], v[164:167], v[208:211], v[92:95]
	v_mfma_f32_16x16x32_bf16 v[84:87], v[152:155], v[212:215], v[84:87]
	v_mfma_f32_16x16x32_bf16 v[84:87], v[156:159], v[216:219], v[84:87]
	v_mfma_f32_16x16x32_bf16 v[76:79], v[160:163], v[212:215], v[76:79]
	v_mfma_f32_16x16x32_bf16 v[76:79], v[164:167], v[216:219], v[76:79]
	s_setprio 0
	s_setprio 1
	v_mfma_f32_16x16x32_bf16 v[112:115], v[168:171], v[188:191], v[112:115]
	v_mfma_f32_16x16x32_bf16 v[112:115], v[172:175], v[192:195], v[112:115]
	v_mfma_f32_16x16x32_bf16 v[104:107], v[176:179], v[188:191], v[104:107]
	v_mfma_f32_16x16x32_bf16 v[104:107], v[184:187], v[192:195], v[104:107]
	v_mfma_f32_16x16x32_bf16 v[96:99], v[168:171], v[196:199], v[96:99]
	v_mfma_f32_16x16x32_bf16 v[96:99], v[172:175], v[200:203], v[96:99]
	v_mfma_f32_16x16x32_bf16 v[88:91], v[176:179], v[196:199], v[88:91]
	v_mfma_f32_16x16x32_bf16 v[88:91], v[184:187], v[200:203], v[88:91]
	v_mfma_f32_16x16x32_bf16 v[80:83], v[168:171], v[204:207], v[80:83]
	v_mfma_f32_16x16x32_bf16 v[80:83], v[172:175], v[208:211], v[80:83]
	v_mfma_f32_16x16x32_bf16 v[72:75], v[176:179], v[204:207], v[72:75]
	v_mfma_f32_16x16x32_bf16 v[72:75], v[184:187], v[208:211], v[72:75]
	v_mfma_f32_16x16x32_bf16 v[68:71], v[168:171], v[212:215], v[68:71]
	v_mfma_f32_16x16x32_bf16 v[68:71], v[172:175], v[216:219], v[68:71]
	v_mfma_f32_16x16x32_bf16 v[64:67], v[176:179], v[212:215], v[64:67]
	v_mfma_f32_16x16x32_bf16 v[64:67], v[184:187], v[216:219], v[64:67]
	s_setprio 0
	s_barrier
	s_add_i32 s52, s79, s62
	v_lshl_add_u64 v[144:145], v[144:145], 0, s[16:17]
	s_mov_b32 m0, s52
	ds_read_b128 v[188:191], v151 offset:49152
	ds_read_b128 v[192:195], v151 offset:50176
	ds_read_b128 v[196:199], v151 offset:51200
	ds_read_b128 v[200:203], v151 offset:52224
	ds_read_b128 v[204:207], v151 offset:53248
	ds_read_b128 v[208:211], v151 offset:54272
	ds_read_b128 v[212:215], v151 offset:55296
	ds_read_b128 v[216:219], v151 offset:56320
	global_load_lds_dwordx4 v[144:145], off
	s_add_i32 m0, s52, 0x2000
	s_add_u32 s52, s56, 0xb0080
	v_lshl_add_u64 v[144:145], v[220:221], 0, s[16:17]
	s_addc_u32 s53, s57, 0
	s_add_i32 s56, s87, s62
	global_load_lds_dwordx4 v[144:145], off
	v_lshl_add_u64 v[144:145], s[52:53], 0, v[130:131]
	s_mov_b32 m0, s56
	s_nop 0
	global_load_lds_dwordx4 v[144:145], off
	v_lshl_add_u64 v[144:145], s[52:53], 0, v[134:135]
	s_add_i32 m0, s56, 0x2000
	s_nop 0
	global_load_lds_dwordx4 v[144:145], off
	v_lshl_add_u64 v[144:145], v[222:223], 0, s[16:17]
	s_mov_b32 m0, s68
	s_nop 0
	global_load_lds_dwordx4 v[144:145], off
	v_lshl_add_u64 v[144:145], v[224:225], 0, s[16:17]
	s_mov_b32 m0, s69
	s_nop 0
	global_load_lds_dwordx4 v[144:145], off
	s_waitcnt vmcnt(8)
	s_waitcnt lgkmcnt(0)
	s_barrier
	s_setprio 1
	s_waitcnt lgkmcnt(0)
	v_mfma_f32_16x16x32_bf16 v[60:63], v[152:155], v[188:191], v[60:63]
	v_mfma_f32_16x16x32_bf16 v[60:63], v[156:159], v[192:195], v[60:63]
	v_mfma_f32_16x16x32_bf16 v[56:59], v[160:163], v[188:191], v[56:59]
	v_mfma_f32_16x16x32_bf16 v[56:59], v[164:167], v[192:195], v[56:59]
	v_mfma_f32_16x16x32_bf16 v[52:55], v[152:155], v[196:199], v[52:55]
	v_mfma_f32_16x16x32_bf16 v[52:55], v[156:159], v[200:203], v[52:55]
	v_mfma_f32_16x16x32_bf16 v[44:47], v[160:163], v[196:199], v[44:47]
	v_mfma_f32_16x16x32_bf16 v[44:47], v[164:167], v[200:203], v[44:47]
	v_mfma_f32_16x16x32_bf16 v[36:39], v[152:155], v[204:207], v[36:39]
	v_mfma_f32_16x16x32_bf16 v[36:39], v[156:159], v[208:211], v[36:39]
	v_mfma_f32_16x16x32_bf16 v[28:31], v[160:163], v[204:207], v[28:31]
	v_mfma_f32_16x16x32_bf16 v[28:31], v[164:167], v[208:211], v[28:31]
	v_mfma_f32_16x16x32_bf16 v[20:23], v[152:155], v[212:215], v[20:23]
	v_mfma_f32_16x16x32_bf16 v[20:23], v[156:159], v[216:219], v[20:23]
	v_mfma_f32_16x16x32_bf16 v[12:15], v[160:163], v[212:215], v[12:15]
	v_mfma_f32_16x16x32_bf16 v[12:15], v[164:167], v[216:219], v[12:15]
	s_setprio 0
	s_setprio 1
	v_mfma_f32_16x16x32_bf16 v[48:51], v[168:171], v[188:191], v[48:51]
	v_mfma_f32_16x16x32_bf16 v[48:51], v[172:175], v[192:195], v[48:51]
	v_mfma_f32_16x16x32_bf16 v[40:43], v[176:179], v[188:191], v[40:43]
	v_mfma_f32_16x16x32_bf16 v[40:43], v[184:187], v[192:195], v[40:43]
	v_mfma_f32_16x16x32_bf16 v[32:35], v[168:171], v[196:199], v[32:35]
	v_mfma_f32_16x16x32_bf16 v[32:35], v[172:175], v[200:203], v[32:35]
	v_mfma_f32_16x16x32_bf16 v[24:27], v[176:179], v[196:199], v[24:27]
	v_mfma_f32_16x16x32_bf16 v[24:27], v[184:187], v[200:203], v[24:27]
	v_mfma_f32_16x16x32_bf16 v[16:19], v[168:171], v[204:207], v[16:19]
	v_mfma_f32_16x16x32_bf16 v[16:19], v[172:175], v[208:211], v[16:19]
	v_mfma_f32_16x16x32_bf16 v[8:11], v[176:179], v[204:207], v[8:11]
	v_mfma_f32_16x16x32_bf16 v[8:11], v[184:187], v[208:211], v[8:11]
	v_mfma_f32_16x16x32_bf16 v[4:7], v[168:171], v[212:215], v[4:7]
	v_mfma_f32_16x16x32_bf16 v[4:7], v[172:175], v[216:219], v[4:7]
	v_mfma_f32_16x16x32_bf16 v[0:3], v[176:179], v[212:215], v[0:3]
	v_mfma_f32_16x16x32_bf16 v[0:3], v[184:187], v[216:219], v[0:3]
	s_setprio 0
	s_barrier
	s_add_i32 s86, s86, 2
	s_add_u32 s84, s84, 0x100
	s_addc_u32 s85, s85, 0
	s_cmp_gt_u32 s86, 41
	s_mov_b64 s[52:53], s[54:55]
	s_cbranch_scc0 .LBB0_804
	s_and_b64 vcc, exec, s[18:19]
	s_cbranch_vccz .LBB0_807
	s_barrier

.LBB0_934:
	s_ashr_i32 s53, s52, 31
	s_lshl_b64 s[54:55], s[52:53], 19
	s_add_u32 s54, s80, s54
	s_addc_u32 s55, s81, s55
	s_and_b64 s[56:57], s[10:11], exec
	s_cselect_b32 s53, s55, s61
	s_cselect_b32 s83, s54, s60
	s_ashr_i32 s49, s48, 31
	s_lshl_b64 s[56:57], s[48:49], 19
	s_add_u32 s56, s66, s56
	s_addc_u32 s57, s67, s57
	s_and_b64 s[64:65], s[10:11], exec
	s_cselect_b32 s49, s57, s63
	s_cselect_b32 s84, s56, s62
	s_add_u32 s60, s60, 0x40080
	s_addc_u32 s61, s61, 0
	s_add_u32 s85, s62, 0x100
	s_addc_u32 s86, s63, 0
	s_mov_b32 s87, -2
	ds_read_b128 v[152:155], v148
	ds_read_b128 v[156:159], v148 offset:1024
	ds_read_b128 v[160:163], v148 offset:2048
	ds_read_b128 v[164:167], v148 offset:3072
	ds_read_b128 v[168:171], v149
	ds_read_b128 v[172:175], v149 offset:1024
	ds_read_b128 v[176:179], v149 offset:2048
	ds_read_b128 v[184:187], v149 offset:3072
	s_add_u32 s62, s60, 0xfffc0080
	s_addc_u32 s63, s61, -1
	s_cmp_eq_u32 s87, 12
	s_cselect_b32 s65, s53, s63
	s_cselect_b32 s64, s83, s62
	s_cselect_b32 s63, s49, s86
	s_cselect_b32 s62, s84, s85
	v_lshl_add_u64 v[220:221], s[60:61], 0, v[138:139]
	s_add_i32 m0, s69, 0xc000
	ds_read_b128 v[188:191], v150
	ds_read_b128 v[192:195], v150 offset:1024
	ds_read_b128 v[196:199], v150 offset:2048
	ds_read_b128 v[200:203], v150 offset:3072
	ds_read_b128 v[204:207], v150 offset:4096
	ds_read_b128 v[208:211], v150 offset:5120
	ds_read_b128 v[212:215], v150 offset:6144
	ds_read_b128 v[216:219], v150 offset:7168
	global_load_lds_dwordx4 v[220:221], off
	v_lshl_add_u64 v[220:221], s[60:61], 0, v[140:141]
	s_add_i32 m0, s69, 0xe000
	s_nop 0
	global_load_lds_dwordx4 v[220:221], off
	s_waitcnt vmcnt(8)
	s_waitcnt lgkmcnt(0)
	s_barrier
	s_setprio 1
	s_waitcnt lgkmcnt(0)
	v_mfma_f32_16x16x32_bf16 v[124:127], v[152:155], v[188:191], 0
	v_mfma_f32_16x16x32_bf16 v[124:127], v[156:159], v[192:195], v[124:127]
	v_mfma_f32_16x16x32_bf16 v[120:123], v[160:163], v[188:191], 0
	v_mfma_f32_16x16x32_bf16 v[120:123], v[164:167], v[192:195], v[120:123]
	v_mfma_f32_16x16x32_bf16 v[116:119], v[152:155], v[196:199], 0
	v_mfma_f32_16x16x32_bf16 v[116:119], v[156:159], v[200:203], v[116:119]
	v_mfma_f32_16x16x32_bf16 v[112:115], v[160:163], v[196:199], 0
	v_mfma_f32_16x16x32_bf16 v[112:115], v[164:167], v[200:203], v[112:115]
	v_mfma_f32_16x16x32_bf16 v[108:111], v[152:155], v[204:207], 0
	v_mfma_f32_16x16x32_bf16 v[108:111], v[156:159], v[208:211], v[108:111]
	v_mfma_f32_16x16x32_bf16 v[104:107], v[160:163], v[204:207], 0
	v_mfma_f32_16x16x32_bf16 v[104:107], v[164:167], v[208:211], v[104:107]
	v_mfma_f32_16x16x32_bf16 v[100:103], v[152:155], v[212:215], 0
	v_mfma_f32_16x16x32_bf16 v[100:103], v[156:159], v[216:219], v[100:103]
	v_mfma_f32_16x16x32_bf16 v[96:99], v[160:163], v[212:215], 0
	v_mfma_f32_16x16x32_bf16 v[96:99], v[164:167], v[216:219], v[96:99]
	s_setprio 0
	s_setprio 1
	v_mfma_f32_16x16x32_bf16 v[76:79], v[168:171], v[188:191], 0
	v_mfma_f32_16x16x32_bf16 v[76:79], v[172:175], v[192:195], v[76:79]
	v_mfma_f32_16x16x32_bf16 v[68:71], v[176:179], v[188:191], 0
	v_mfma_f32_16x16x32_bf16 v[68:71], v[184:187], v[192:195], v[68:71]
	v_mfma_f32_16x16x32_bf16 v[60:63], v[168:171], v[196:199], 0
	v_mfma_f32_16x16x32_bf16 v[60:63], v[172:175], v[200:203], v[60:63]
	v_mfma_f32_16x16x32_bf16 v[52:55], v[176:179], v[196:199], 0
	v_mfma_f32_16x16x32_bf16 v[52:55], v[184:187], v[200:203], v[52:55]
	v_mfma_f32_16x16x32_bf16 v[44:47], v[168:171], v[204:207], 0
	v_mfma_f32_16x16x32_bf16 v[44:47], v[172:175], v[208:211], v[44:47]
	v_mfma_f32_16x16x32_bf16 v[40:43], v[176:179], v[204:207], 0
	v_mfma_f32_16x16x32_bf16 v[40:43], v[184:187], v[208:211], v[40:43]
	v_mfma_f32_16x16x32_bf16 v[36:39], v[168:171], v[212:215], 0
	v_mfma_f32_16x16x32_bf16 v[36:39], v[172:175], v[216:219], v[36:39]
	v_mfma_f32_16x16x32_bf16 v[32:35], v[176:179], v[212:215], 0
	v_mfma_f32_16x16x32_bf16 v[32:35], v[184:187], v[216:219], v[32:35]
	s_setprio 0
	s_barrier
	s_add_i32 s79, s77, s68
	v_lshl_add_u64 v[220:221], s[62:63], 0, v[130:131]
	s_mov_b32 m0, s79
	ds_read_b128 v[188:191], v150 offset:16384
	ds_read_b128 v[192:195], v150 offset:17408
	ds_read_b128 v[196:199], v150 offset:18432
	ds_read_b128 v[200:203], v150 offset:19456
	ds_read_b128 v[204:207], v150 offset:20480
	ds_read_b128 v[208:211], v150 offset:21504
	ds_read_b128 v[212:215], v150 offset:22528
	ds_read_b128 v[216:219], v150 offset:23552
	global_load_lds_dwordx4 v[220:221], off
	s_add_i32 m0, s79, 0x2000
	s_add_u32 s88, s62, 0x40000
	v_lshl_add_u64 v[222:223], s[62:63], 0, v[134:135]
	s_addc_u32 s89, s63, 0
	s_add_i32 s79, s82, s68
	global_load_lds_dwordx4 v[222:223], off
	v_lshl_add_u64 v[224:225], s[88:89], 0, v[130:131]
	s_mov_b32 m0, s79
	v_lshl_add_u64 v[226:227], s[64:65], 0, v[132:133]
	global_load_lds_dwordx4 v[224:225], off
	v_lshl_add_u64 v[224:225], s[88:89], 0, v[134:135]
	s_add_i32 m0, s79, 0x2000
	s_nop 0
	global_load_lds_dwordx4 v[224:225], off
	v_lshl_add_u64 v[224:225], s[64:65], 0, v[128:129]
	s_mov_b32 m0, s69
	s_nop 0
	global_load_lds_dwordx4 v[224:225], off
	s_mov_b32 m0, s70
	s_nop 0
	global_load_lds_dwordx4 v[226:227], off
	s_waitcnt vmcnt(8)
	s_waitcnt lgkmcnt(0)
	s_barrier
	s_setprio 1
	s_waitcnt lgkmcnt(0)
	v_mfma_f32_16x16x32_bf16 v[92:95], v[152:155], v[188:191], 0
	v_mfma_f32_16x16x32_bf16 v[92:95], v[156:159], v[192:195], v[92:95]
	v_mfma_f32_16x16x32_bf16 v[88:91], v[160:163], v[188:191], 0
	v_mfma_f32_16x16x32_bf16 v[88:91], v[164:167], v[192:195], v[88:91]
	v_mfma_f32_16x16x32_bf16 v[84:87], v[152:155], v[196:199], 0
	v_mfma_f32_16x16x32_bf16 v[84:87], v[156:159], v[200:203], v[84:87]
	v_mfma_f32_16x16x32_bf16 v[80:83], v[160:163], v[196:199], 0
	v_mfma_f32_16x16x32_bf16 v[80:83], v[164:167], v[200:203], v[80:83]
	v_mfma_f32_16x16x32_bf16 v[72:75], v[152:155], v[204:207], 0
	v_mfma_f32_16x16x32_bf16 v[72:75], v[156:159], v[208:211], v[72:75]
	v_mfma_f32_16x16x32_bf16 v[64:67], v[160:163], v[204:207], 0
	v_mfma_f32_16x16x32_bf16 v[64:67], v[164:167], v[208:211], v[64:67]
	v_mfma_f32_16x16x32_bf16 v[56:59], v[152:155], v[212:215], 0
	v_mfma_f32_16x16x32_bf16 v[56:59], v[156:159], v[216:219], v[56:59]
	v_mfma_f32_16x16x32_bf16 v[48:51], v[160:163], v[212:215], 0
	v_mfma_f32_16x16x32_bf16 v[48:51], v[164:167], v[216:219], v[48:51]
	s_setprio 0
	s_setprio 1
	v_mfma_f32_16x16x32_bf16 v[28:31], v[168:171], v[188:191], 0
	v_mfma_f32_16x16x32_bf16 v[28:31], v[172:175], v[192:195], v[28:31]
	v_mfma_f32_16x16x32_bf16 v[24:27], v[176:179], v[188:191], 0
	v_mfma_f32_16x16x32_bf16 v[24:27], v[184:187], v[192:195], v[24:27]
	v_mfma_f32_16x16x32_bf16 v[20:23], v[168:171], v[196:199], 0
	v_mfma_f32_16x16x32_bf16 v[20:23], v[172:175], v[200:203], v[20:23]
	v_mfma_f32_16x16x32_bf16 v[16:19], v[176:179], v[196:199], 0
	v_mfma_f32_16x16x32_bf16 v[16:19], v[184:187], v[200:203], v[16:19]
	v_mfma_f32_16x16x32_bf16 v[12:15], v[168:171], v[204:207], 0
	v_mfma_f32_16x16x32_bf16 v[12:15], v[172:175], v[208:211], v[12:15]
	v_mfma_f32_16x16x32_bf16 v[8:11], v[176:179], v[204:207], 0
	v_mfma_f32_16x16x32_bf16 v[8:11], v[184:187], v[208:211], v[8:11]
	v_mfma_f32_16x16x32_bf16 v[4:7], v[168:171], v[212:215], 0
	v_mfma_f32_16x16x32_bf16 v[4:7], v[172:175], v[216:219], v[4:7]
	v_mfma_f32_16x16x32_bf16 v[0:3], v[176:179], v[212:215], 0
	v_mfma_f32_16x16x32_bf16 v[0:3], v[184:187], v[216:219], v[0:3]
	s_setprio 0
	s_barrier
	s_branch .Lmid_gemm6
.LBB0_935:
	ds_read_b128 v[152:155], v148
	ds_read_b128 v[156:159], v148 offset:1024
	ds_read_b128 v[160:163], v148 offset:2048
	ds_read_b128 v[164:167], v148 offset:3072
	ds_read_b128 v[168:171], v149
	ds_read_b128 v[172:175], v149 offset:1024
	ds_read_b128 v[176:179], v149 offset:2048
	ds_read_b128 v[184:187], v149 offset:3072
	s_add_u32 s62, s60, 0xfffc0080
	s_addc_u32 s63, s61, -1
	s_cmp_eq_u32 s87, 12
	s_cselect_b32 s65, s53, s63
	s_cselect_b32 s64, s83, s62
	s_cselect_b32 s63, s49, s86
	s_cselect_b32 s62, s84, s85
	v_lshl_add_u64 v[220:221], s[60:61], 0, v[138:139]
	s_add_i32 m0, s69, 0xc000
	ds_read_b128 v[188:191], v150
	ds_read_b128 v[192:195], v150 offset:1024
	ds_read_b128 v[196:199], v150 offset:2048
	ds_read_b128 v[200:203], v150 offset:3072
	ds_read_b128 v[204:207], v150 offset:4096
	ds_read_b128 v[208:211], v150 offset:5120
	ds_read_b128 v[212:215], v150 offset:6144
	ds_read_b128 v[216:219], v150 offset:7168
	global_load_lds_dwordx4 v[220:221], off
	v_lshl_add_u64 v[220:221], s[60:61], 0, v[140:141]
	s_add_i32 m0, s69, 0xe000
	s_nop 0
	global_load_lds_dwordx4 v[220:221], off
	s_waitcnt vmcnt(8)
	s_waitcnt lgkmcnt(0)
	s_barrier
	s_setprio 1
	s_waitcnt lgkmcnt(0)
	v_mfma_f32_16x16x32_bf16 v[124:127], v[152:155], v[188:191], v[124:127]
	v_mfma_f32_16x16x32_bf16 v[124:127], v[156:159], v[192:195], v[124:127]
	v_mfma_f32_16x16x32_bf16 v[120:123], v[160:163], v[188:191], v[120:123]
	v_mfma_f32_16x16x32_bf16 v[120:123], v[164:167], v[192:195], v[120:123]
	v_mfma_f32_16x16x32_bf16 v[116:119], v[152:155], v[196:199], v[116:119]
	v_mfma_f32_16x16x32_bf16 v[116:119], v[156:159], v[200:203], v[116:119]
	v_mfma_f32_16x16x32_bf16 v[112:115], v[160:163], v[196:199], v[112:115]
	v_mfma_f32_16x16x32_bf16 v[112:115], v[164:167], v[200:203], v[112:115]
	v_mfma_f32_16x16x32_bf16 v[108:111], v[152:155], v[204:207], v[108:111]
	v_mfma_f32_16x16x32_bf16 v[108:111], v[156:159], v[208:211], v[108:111]
	v_mfma_f32_16x16x32_bf16 v[104:107], v[160:163], v[204:207], v[104:107]
	v_mfma_f32_16x16x32_bf16 v[104:107], v[164:167], v[208:211], v[104:107]
	v_mfma_f32_16x16x32_bf16 v[100:103], v[152:155], v[212:215], v[100:103]
	v_mfma_f32_16x16x32_bf16 v[100:103], v[156:159], v[216:219], v[100:103]
	v_mfma_f32_16x16x32_bf16 v[96:99], v[160:163], v[212:215], v[96:99]
	v_mfma_f32_16x16x32_bf16 v[96:99], v[164:167], v[216:219], v[96:99]
	s_setprio 0
	s_setprio 1
	v_mfma_f32_16x16x32_bf16 v[76:79], v[168:171], v[188:191], v[76:79]
	v_mfma_f32_16x16x32_bf16 v[76:79], v[172:175], v[192:195], v[76:79]
	v_mfma_f32_16x16x32_bf16 v[68:71], v[176:179], v[188:191], v[68:71]
	v_mfma_f32_16x16x32_bf16 v[68:71], v[184:187], v[192:195], v[68:71]
	v_mfma_f32_16x16x32_bf16 v[60:63], v[168:171], v[196:199], v[60:63]
	v_mfma_f32_16x16x32_bf16 v[60:63], v[172:175], v[200:203], v[60:63]
	v_mfma_f32_16x16x32_bf16 v[52:55], v[176:179], v[196:199], v[52:55]
	v_mfma_f32_16x16x32_bf16 v[52:55], v[184:187], v[200:203], v[52:55]
	v_mfma_f32_16x16x32_bf16 v[44:47], v[168:171], v[204:207], v[44:47]
	v_mfma_f32_16x16x32_bf16 v[44:47], v[172:175], v[208:211], v[44:47]
	v_mfma_f32_16x16x32_bf16 v[40:43], v[176:179], v[204:207], v[40:43]
	v_mfma_f32_16x16x32_bf16 v[40:43], v[184:187], v[208:211], v[40:43]
	v_mfma_f32_16x16x32_bf16 v[36:39], v[168:171], v[212:215], v[36:39]
	v_mfma_f32_16x16x32_bf16 v[36:39], v[172:175], v[216:219], v[36:39]
	v_mfma_f32_16x16x32_bf16 v[32:35], v[176:179], v[212:215], v[32:35]
	v_mfma_f32_16x16x32_bf16 v[32:35], v[184:187], v[216:219], v[32:35]
	s_setprio 0
	s_barrier
	s_add_i32 s79, s77, s68
	v_lshl_add_u64 v[220:221], s[62:63], 0, v[130:131]
	s_mov_b32 m0, s79
	ds_read_b128 v[188:191], v150 offset:16384
	ds_read_b128 v[192:195], v150 offset:17408
	ds_read_b128 v[196:199], v150 offset:18432
	ds_read_b128 v[200:203], v150 offset:19456
	ds_read_b128 v[204:207], v150 offset:20480
	ds_read_b128 v[208:211], v150 offset:21504
	ds_read_b128 v[212:215], v150 offset:22528
	ds_read_b128 v[216:219], v150 offset:23552
	global_load_lds_dwordx4 v[220:221], off
	s_add_i32 m0, s79, 0x2000
	s_add_u32 s88, s62, 0x40000
	v_lshl_add_u64 v[222:223], s[62:63], 0, v[134:135]
	s_addc_u32 s89, s63, 0
	s_add_i32 s79, s82, s68
	global_load_lds_dwordx4 v[222:223], off
	v_lshl_add_u64 v[224:225], s[88:89], 0, v[130:131]
	s_mov_b32 m0, s79
	v_lshl_add_u64 v[226:227], s[64:65], 0, v[132:133]
	global_load_lds_dwordx4 v[224:225], off
	v_lshl_add_u64 v[224:225], s[88:89], 0, v[134:135]
	s_add_i32 m0, s79, 0x2000
	s_nop 0
	global_load_lds_dwordx4 v[224:225], off
	v_lshl_add_u64 v[224:225], s[64:65], 0, v[128:129]
	s_mov_b32 m0, s69
	s_nop 0
	global_load_lds_dwordx4 v[224:225], off
	s_mov_b32 m0, s70
	s_nop 0
	global_load_lds_dwordx4 v[226:227], off
	s_waitcnt vmcnt(8)
	s_waitcnt lgkmcnt(0)
	s_barrier
	s_setprio 1
	s_waitcnt lgkmcnt(0)
	v_mfma_f32_16x16x32_bf16 v[92:95], v[152:155], v[188:191], v[92:95]
	v_mfma_f32_16x16x32_bf16 v[92:95], v[156:159], v[192:195], v[92:95]
	v_mfma_f32_16x16x32_bf16 v[88:91], v[160:163], v[188:191], v[88:91]
	v_mfma_f32_16x16x32_bf16 v[88:91], v[164:167], v[192:195], v[88:91]
	v_mfma_f32_16x16x32_bf16 v[84:87], v[152:155], v[196:199], v[84:87]
	v_mfma_f32_16x16x32_bf16 v[84:87], v[156:159], v[200:203], v[84:87]
	v_mfma_f32_16x16x32_bf16 v[80:83], v[160:163], v[196:199], v[80:83]
	v_mfma_f32_16x16x32_bf16 v[80:83], v[164:167], v[200:203], v[80:83]
	v_mfma_f32_16x16x32_bf16 v[72:75], v[152:155], v[204:207], v[72:75]
	v_mfma_f32_16x16x32_bf16 v[72:75], v[156:159], v[208:211], v[72:75]
	v_mfma_f32_16x16x32_bf16 v[64:67], v[160:163], v[204:207], v[64:67]
	v_mfma_f32_16x16x32_bf16 v[64:67], v[164:167], v[208:211], v[64:67]
	v_mfma_f32_16x16x32_bf16 v[56:59], v[152:155], v[212:215], v[56:59]
	v_mfma_f32_16x16x32_bf16 v[56:59], v[156:159], v[216:219], v[56:59]
	v_mfma_f32_16x16x32_bf16 v[48:51], v[160:163], v[212:215], v[48:51]
	v_mfma_f32_16x16x32_bf16 v[48:51], v[164:167], v[216:219], v[48:51]
	s_setprio 0
	s_setprio 1
	v_mfma_f32_16x16x32_bf16 v[28:31], v[168:171], v[188:191], v[28:31]
	v_mfma_f32_16x16x32_bf16 v[28:31], v[172:175], v[192:195], v[28:31]
	v_mfma_f32_16x16x32_bf16 v[24:27], v[176:179], v[188:191], v[24:27]
	v_mfma_f32_16x16x32_bf16 v[24:27], v[184:187], v[192:195], v[24:27]
	v_mfma_f32_16x16x32_bf16 v[20:23], v[168:171], v[196:199], v[20:23]
	v_mfma_f32_16x16x32_bf16 v[20:23], v[172:175], v[200:203], v[20:23]
	v_mfma_f32_16x16x32_bf16 v[16:19], v[176:179], v[196:199], v[16:19]
	v_mfma_f32_16x16x32_bf16 v[16:19], v[184:187], v[200:203], v[16:19]
	v_mfma_f32_16x16x32_bf16 v[12:15], v[168:171], v[204:207], v[12:15]
	v_mfma_f32_16x16x32_bf16 v[12:15], v[172:175], v[208:211], v[12:15]
	v_mfma_f32_16x16x32_bf16 v[8:11], v[176:179], v[204:207], v[8:11]
	v_mfma_f32_16x16x32_bf16 v[8:11], v[184:187], v[208:211], v[8:11]
	v_mfma_f32_16x16x32_bf16 v[4:7], v[168:171], v[212:215], v[4:7]
	v_mfma_f32_16x16x32_bf16 v[4:7], v[172:175], v[216:219], v[4:7]
	v_mfma_f32_16x16x32_bf16 v[0:3], v[176:179], v[212:215], v[0:3]
	v_mfma_f32_16x16x32_bf16 v[0:3], v[184:187], v[216:219], v[0:3]
	s_setprio 0
	s_barrier
.Lmid_gemm6:
	s_add_i32 s79, 0, 0x18000
	v_add_u32_e32 v151, s79, v147
	s_add_i32 s88, 0, 0x1c000
	ds_read_b128 v[152:155], v151
	ds_read_b128 v[156:159], v151 offset:1024
	ds_read_b128 v[160:163], v151 offset:2048
	ds_read_b128 v[164:167], v151 offset:3072
	v_add_u32_e32 v151, s88, v147
	ds_read_b128 v[168:171], v151
	ds_read_b128 v[172:175], v151 offset:1024
	ds_read_b128 v[176:179], v151 offset:2048
	ds_read_b128 v[184:187], v151 offset:3072
	s_add_u32 s64, s64, 0x40000
	s_addc_u32 s65, s65, 0
	s_mov_b32 m0, s71
	v_lshl_add_u64 v[228:229], s[64:65], 0, v[128:129]
	ds_read_b128 v[188:191], v150 offset:32768
	ds_read_b128 v[192:195], v150 offset:33792
	ds_read_b128 v[196:199], v150 offset:34816
	ds_read_b128 v[200:203], v150 offset:35840
	ds_read_b128 v[204:207], v150 offset:36864
	ds_read_b128 v[208:211], v150 offset:37888
	ds_read_b128 v[212:215], v150 offset:38912
	ds_read_b128 v[216:219], v150 offset:39936
	global_load_lds_dwordx4 v[228:229], off
	v_lshl_add_u64 v[228:229], s[64:65], 0, v[132:133]
	s_mov_b32 m0, s72
	s_nop 0
	global_load_lds_dwordx4 v[228:229], off
	s_waitcnt vmcnt(8)
	s_waitcnt lgkmcnt(0)
	s_barrier
	s_setprio 1
	s_waitcnt lgkmcnt(0)
	v_mfma_f32_16x16x32_bf16 v[124:127], v[152:155], v[188:191], v[124:127]
	v_mfma_f32_16x16x32_bf16 v[124:127], v[156:159], v[192:195], v[124:127]
	v_mfma_f32_16x16x32_bf16 v[120:123], v[160:163], v[188:191], v[120:123]
	v_mfma_f32_16x16x32_bf16 v[120:123], v[164:167], v[192:195], v[120:123]
	v_mfma_f32_16x16x32_bf16 v[116:119], v[152:155], v[196:199], v[116:119]
	v_mfma_f32_16x16x32_bf16 v[116:119], v[156:159], v[200:203], v[116:119]
	v_mfma_f32_16x16x32_bf16 v[112:115], v[160:163], v[196:199], v[112:115]
	v_mfma_f32_16x16x32_bf16 v[112:115], v[164:167], v[200:203], v[112:115]
	v_mfma_f32_16x16x32_bf16 v[108:111], v[152:155], v[204:207], v[108:111]
	v_mfma_f32_16x16x32_bf16 v[108:111], v[156:159], v[208:211], v[108:111]
	v_mfma_f32_16x16x32_bf16 v[104:107], v[160:163], v[204:207], v[104:107]
	v_mfma_f32_16x16x32_bf16 v[104:107], v[164:167], v[208:211], v[104:107]
	v_mfma_f32_16x16x32_bf16 v[100:103], v[152:155], v[212:215], v[100:103]
	v_mfma_f32_16x16x32_bf16 v[100:103], v[156:159], v[216:219], v[100:103]
	v_mfma_f32_16x16x32_bf16 v[96:99], v[160:163], v[212:215], v[96:99]
	v_mfma_f32_16x16x32_bf16 v[96:99], v[164:167], v[216:219], v[96:99]
	s_setprio 0
	s_setprio 1
	v_mfma_f32_16x16x32_bf16 v[76:79], v[168:171], v[188:191], v[76:79]
	v_mfma_f32_16x16x32_bf16 v[76:79], v[172:175], v[192:195], v[76:79]
	v_mfma_f32_16x16x32_bf16 v[68:71], v[176:179], v[188:191], v[68:71]
	v_mfma_f32_16x16x32_bf16 v[68:71], v[184:187], v[192:195], v[68:71]
	v_mfma_f32_16x16x32_bf16 v[60:63], v[168:171], v[196:199], v[60:63]
	v_mfma_f32_16x16x32_bf16 v[60:63], v[172:175], v[200:203], v[60:63]
	v_mfma_f32_16x16x32_bf16 v[52:55], v[176:179], v[196:199], v[52:55]
	v_mfma_f32_16x16x32_bf16 v[52:55], v[184:187], v[200:203], v[52:55]
	v_mfma_f32_16x16x32_bf16 v[44:47], v[168:171], v[204:207], v[44:47]
	v_mfma_f32_16x16x32_bf16 v[44:47], v[172:175], v[208:211], v[44:47]
	v_mfma_f32_16x16x32_bf16 v[40:43], v[176:179], v[204:207], v[40:43]
	v_mfma_f32_16x16x32_bf16 v[40:43], v[184:187], v[208:211], v[40:43]
	v_mfma_f32_16x16x32_bf16 v[36:39], v[168:171], v[212:215], v[36:39]
	v_mfma_f32_16x16x32_bf16 v[36:39], v[172:175], v[216:219], v[36:39]
	v_mfma_f32_16x16x32_bf16 v[32:35], v[176:179], v[212:215], v[32:35]
	v_mfma_f32_16x16x32_bf16 v[32:35], v[184:187], v[216:219], v[32:35]
	s_setprio 0
	s_barrier
	s_add_i32 s64, s79, s68
	v_lshl_add_u64 v[220:221], v[220:221], 0, s[12:13]
	s_mov_b32 m0, s64
	ds_read_b128 v[188:191], v150 offset:49152
	ds_read_b128 v[192:195], v150 offset:50176
	ds_read_b128 v[196:199], v150 offset:51200
	ds_read_b128 v[200:203], v150 offset:52224
	ds_read_b128 v[204:207], v150 offset:53248
	ds_read_b128 v[208:211], v150 offset:54272
	ds_read_b128 v[212:215], v150 offset:55296
	ds_read_b128 v[216:219], v150 offset:56320
	global_load_lds_dwordx4 v[220:221], off
	s_add_i32 m0, s64, 0x2000
	s_add_u32 s62, s62, 0x40080
	v_lshl_add_u64 v[220:221], v[222:223], 0, s[12:13]
	s_addc_u32 s63, s63, 0
	s_add_i32 s64, s88, s68
	global_load_lds_dwordx4 v[220:221], off
	v_lshl_add_u64 v[220:221], s[62:63], 0, v[130:131]
	s_mov_b32 m0, s64
	s_nop 0
	global_load_lds_dwordx4 v[220:221], off
	v_lshl_add_u64 v[220:221], s[62:63], 0, v[134:135]
	s_add_i32 m0, s64, 0x2000
	s_nop 0
	global_load_lds_dwordx4 v[220:221], off
	v_lshl_add_u64 v[220:221], v[224:225], 0, s[12:13]
	s_mov_b32 m0, s75
	s_nop 0
	global_load_lds_dwordx4 v[220:221], off
	v_lshl_add_u64 v[220:221], v[226:227], 0, s[12:13]
	s_mov_b32 m0, s76
	s_nop 0
	global_load_lds_dwordx4 v[220:221], off
	s_waitcnt vmcnt(8)
	s_waitcnt lgkmcnt(0)
	s_barrier
	s_setprio 1
	s_waitcnt lgkmcnt(0)
	v_mfma_f32_16x16x32_bf16 v[92:95], v[152:155], v[188:191], v[92:95]
	v_mfma_f32_16x16x32_bf16 v[92:95], v[156:159], v[192:195], v[92:95]
	v_mfma_f32_16x16x32_bf16 v[88:91], v[160:163], v[188:191], v[88:91]
	v_mfma_f32_16x16x32_bf16 v[88:91], v[164:167], v[192:195], v[88:91]
	v_mfma_f32_16x16x32_bf16 v[84:87], v[152:155], v[196:199], v[84:87]
	v_mfma_f32_16x16x32_bf16 v[84:87], v[156:159], v[200:203], v[84:87]
	v_mfma_f32_16x16x32_bf16 v[80:83], v[160:163], v[196:199], v[80:83]
	v_mfma_f32_16x16x32_bf16 v[80:83], v[164:167], v[200:203], v[80:83]
	v_mfma_f32_16x16x32_bf16 v[72:75], v[152:155], v[204:207], v[72:75]
	v_mfma_f32_16x16x32_bf16 v[72:75], v[156:159], v[208:211], v[72:75]
	v_mfma_f32_16x16x32_bf16 v[64:67], v[160:163], v[204:207], v[64:67]
	v_mfma_f32_16x16x32_bf16 v[64:67], v[164:167], v[208:211], v[64:67]
	v_mfma_f32_16x16x32_bf16 v[56:59], v[152:155], v[212:215], v[56:59]
	v_mfma_f32_16x16x32_bf16 v[56:59], v[156:159], v[216:219], v[56:59]
	v_mfma_f32_16x16x32_bf16 v[48:51], v[160:163], v[212:215], v[48:51]
	v_mfma_f32_16x16x32_bf16 v[48:51], v[164:167], v[216:219], v[48:51]
	s_setprio 0
	s_setprio 1
	v_mfma_f32_16x16x32_bf16 v[28:31], v[168:171], v[188:191], v[28:31]
	v_mfma_f32_16x16x32_bf16 v[28:31], v[172:175], v[192:195], v[28:31]
	v_mfma_f32_16x16x32_bf16 v[24:27], v[176:179], v[188:191], v[24:27]
	v_mfma_f32_16x16x32_bf16 v[24:27], v[184:187], v[192:195], v[24:27]
	v_mfma_f32_16x16x32_bf16 v[20:23], v[168:171], v[196:199], v[20:23]
	v_mfma_f32_16x16x32_bf16 v[20:23], v[172:175], v[200:203], v[20:23]
	v_mfma_f32_16x16x32_bf16 v[16:19], v[176:179], v[196:199], v[16:19]
	v_mfma_f32_16x16x32_bf16 v[16:19], v[184:187], v[200:203], v[16:19]
	v_mfma_f32_16x16x32_bf16 v[12:15], v[168:171], v[204:207], v[12:15]
	v_mfma_f32_16x16x32_bf16 v[12:15], v[172:175], v[208:211], v[12:15]
	v_mfma_f32_16x16x32_bf16 v[8:11], v[176:179], v[204:207], v[8:11]
	v_mfma_f32_16x16x32_bf16 v[8:11], v[184:187], v[208:211], v[8:11]
	v_mfma_f32_16x16x32_bf16 v[4:7], v[168:171], v[212:215], v[4:7]
	v_mfma_f32_16x16x32_bf16 v[4:7], v[172:175], v[216:219], v[4:7]
	v_mfma_f32_16x16x32_bf16 v[0:3], v[176:179], v[212:215], v[0:3]
	v_mfma_f32_16x16x32_bf16 v[0:3], v[184:187], v[216:219], v[0:3]
	s_setprio 0
	s_barrier
	s_add_i32 s87, s87, 2
	s_add_u32 s60, s60, 0x100
	s_addc_u32 s61, s61, 0
	s_add_u32 s85, s85, 0x100
	s_addc_u32 s86, s86, 0
	s_cmp_gt_u32 s87, 13
	s_cbranch_scc0 .LBB0_935
	s_and_b64 vcc, exec, s[16:17]
	s_cbranch_vccz .LBB0_938
	s_barrier

.LBB0_950:
	s_ashr_i32 s37, s36, 31
	s_lshl_b64 s[44:45], s[36:37], 19
	s_add_u32 s44, s80, s44
	s_addc_u32 s45, s81, s45
	s_and_b64 s[46:47], s[10:11], exec
	s_cselect_b32 s37, s45, s53
	s_cselect_b32 s72, s44, s52
	s_ashr_i32 s19, s18, 31
	s_lshl_b64 s[46:47], s[18:19], 19
	s_add_u32 s46, s58, s46
	s_addc_u32 s47, s59, s47
	s_and_b64 s[56:57], s[10:11], exec
	s_cselect_b32 s19, s47, s55
	s_cselect_b32 s73, s46, s54
	s_add_u32 s52, s52, 0x40080
	s_addc_u32 s53, s53, 0
	s_add_u32 s74, s54, 0x100
	s_addc_u32 s75, s55, 0
	s_mov_b32 s76, -2
	ds_read_b128 v[140:143], v147
	ds_read_b128 v[150:153], v147 offset:1024
	ds_read_b128 v[154:157], v147 offset:2048
	ds_read_b128 v[158:161], v147 offset:3072
	ds_read_b128 v[162:165], v148
	ds_read_b128 v[166:169], v148 offset:1024
	ds_read_b128 v[170:173], v148 offset:2048
	ds_read_b128 v[174:177], v148 offset:3072
	s_add_u32 s54, s52, 0xfffc0080
	s_addc_u32 s55, s53, -1
	s_cmp_eq_u32 s76, 12
	s_cselect_b32 s57, s37, s55
	s_cselect_b32 s56, s72, s54
	s_cselect_b32 s55, s19, s75
	s_cselect_b32 s54, s73, s74
	v_lshl_add_u64 v[178:179], s[52:53], 0, v[132:133]
	s_add_i32 m0, s49, 0xc000
	ds_read_b128 v[184:187], v149
	ds_read_b128 v[188:191], v149 offset:1024
	ds_read_b128 v[192:195], v149 offset:2048
	ds_read_b128 v[196:199], v149 offset:3072
	ds_read_b128 v[200:203], v149 offset:4096
	ds_read_b128 v[204:207], v149 offset:5120
	ds_read_b128 v[208:211], v149 offset:6144
	ds_read_b128 v[212:215], v149 offset:7168
	global_load_lds_dwordx4 v[178:179], off
	v_lshl_add_u64 v[178:179], s[52:53], 0, v[134:135]
	s_add_i32 m0, s49, 0xe000
	s_nop 0
	global_load_lds_dwordx4 v[178:179], off
	s_waitcnt vmcnt(8)
	s_waitcnt lgkmcnt(0)
	s_barrier
	s_setprio 1
	s_waitcnt lgkmcnt(0)
	v_mfma_f32_16x16x32_bf16 v[124:127], v[140:143], v[184:187], 0
	v_mfma_f32_16x16x32_bf16 v[124:127], v[150:153], v[188:191], v[124:127]
	v_mfma_f32_16x16x32_bf16 v[120:123], v[154:157], v[184:187], 0
	v_mfma_f32_16x16x32_bf16 v[120:123], v[158:161], v[188:191], v[120:123]
	v_mfma_f32_16x16x32_bf16 v[108:111], v[140:143], v[192:195], 0
	v_mfma_f32_16x16x32_bf16 v[108:111], v[150:153], v[196:199], v[108:111]
	v_mfma_f32_16x16x32_bf16 v[104:107], v[154:157], v[192:195], 0
	v_mfma_f32_16x16x32_bf16 v[104:107], v[158:161], v[196:199], v[104:107]
	v_mfma_f32_16x16x32_bf16 v[92:95], v[140:143], v[200:203], 0
	v_mfma_f32_16x16x32_bf16 v[92:95], v[150:153], v[204:207], v[92:95]
	v_mfma_f32_16x16x32_bf16 v[88:91], v[154:157], v[200:203], 0
	v_mfma_f32_16x16x32_bf16 v[88:91], v[158:161], v[204:207], v[88:91]
	v_mfma_f32_16x16x32_bf16 v[76:79], v[140:143], v[208:211], 0
	v_mfma_f32_16x16x32_bf16 v[76:79], v[150:153], v[212:215], v[76:79]
	v_mfma_f32_16x16x32_bf16 v[72:75], v[154:157], v[208:211], 0
	v_mfma_f32_16x16x32_bf16 v[72:75], v[158:161], v[212:215], v[72:75]
	s_setprio 0
	s_setprio 1
	v_mfma_f32_16x16x32_bf16 v[116:119], v[162:165], v[184:187], 0
	v_mfma_f32_16x16x32_bf16 v[116:119], v[166:169], v[188:191], v[116:119]
	v_mfma_f32_16x16x32_bf16 v[112:115], v[170:173], v[184:187], 0
	v_mfma_f32_16x16x32_bf16 v[112:115], v[174:177], v[188:191], v[112:115]
	v_mfma_f32_16x16x32_bf16 v[100:103], v[162:165], v[192:195], 0
	v_mfma_f32_16x16x32_bf16 v[100:103], v[166:169], v[196:199], v[100:103]
	v_mfma_f32_16x16x32_bf16 v[96:99], v[170:173], v[192:195], 0
	v_mfma_f32_16x16x32_bf16 v[96:99], v[174:177], v[196:199], v[96:99]
	v_mfma_f32_16x16x32_bf16 v[84:87], v[162:165], v[200:203], 0
	v_mfma_f32_16x16x32_bf16 v[84:87], v[166:169], v[204:207], v[84:87]
	v_mfma_f32_16x16x32_bf16 v[80:83], v[170:173], v[200:203], 0
	v_mfma_f32_16x16x32_bf16 v[80:83], v[174:177], v[204:207], v[80:83]
	v_mfma_f32_16x16x32_bf16 v[68:71], v[162:165], v[208:211], 0
	v_mfma_f32_16x16x32_bf16 v[68:71], v[166:169], v[212:215], v[68:71]
	v_mfma_f32_16x16x32_bf16 v[64:67], v[170:173], v[208:211], 0
	v_mfma_f32_16x16x32_bf16 v[64:67], v[174:177], v[212:215], v[64:67]
	s_setprio 0
	s_barrier
	s_add_i32 s77, s68, s60
	v_lshl_add_u64 v[178:179], s[54:55], 0, v[130:131]
	s_mov_b32 m0, s77
	ds_read_b128 v[184:187], v149 offset:16384
	ds_read_b128 v[188:191], v149 offset:17408
	ds_read_b128 v[192:195], v149 offset:18432
	ds_read_b128 v[196:199], v149 offset:19456
	ds_read_b128 v[200:203], v149 offset:20480
	ds_read_b128 v[204:207], v149 offset:21504
	ds_read_b128 v[208:211], v149 offset:22528
	ds_read_b128 v[212:215], v149 offset:23552
	global_load_lds_dwordx4 v[178:179], off
	s_add_i32 m0, s77, 0x2000
	s_add_u32 s82, s54, 0x40000
	v_lshl_add_u64 v[216:217], s[54:55], 0, v[128:129]
	s_addc_u32 s83, s55, 0
	s_add_i32 s77, s69, s60
	global_load_lds_dwordx4 v[216:217], off
	v_lshl_add_u64 v[218:219], s[82:83], 0, v[130:131]
	s_mov_b32 m0, s77
	v_lshl_add_u64 v[220:221], s[56:57], 0, v[128:129]
	global_load_lds_dwordx4 v[218:219], off
	v_lshl_add_u64 v[218:219], s[82:83], 0, v[128:129]
	s_add_i32 m0, s77, 0x2000
	s_nop 0
	global_load_lds_dwordx4 v[218:219], off
	v_lshl_add_u64 v[218:219], s[56:57], 0, v[130:131]
	s_mov_b32 m0, s49
	s_nop 0
	global_load_lds_dwordx4 v[218:219], off
	s_mov_b32 m0, s62
	s_nop 0
	global_load_lds_dwordx4 v[220:221], off
	s_waitcnt vmcnt(8)
	s_waitcnt lgkmcnt(0)
	s_barrier
	s_setprio 1
	s_waitcnt lgkmcnt(0)
	v_mfma_f32_16x16x32_bf16 v[60:63], v[140:143], v[184:187], 0
	v_mfma_f32_16x16x32_bf16 v[60:63], v[150:153], v[188:191], v[60:63]
	v_mfma_f32_16x16x32_bf16 v[56:59], v[154:157], v[184:187], 0
	v_mfma_f32_16x16x32_bf16 v[56:59], v[158:161], v[188:191], v[56:59]
	v_mfma_f32_16x16x32_bf16 v[44:47], v[140:143], v[192:195], 0
	v_mfma_f32_16x16x32_bf16 v[44:47], v[150:153], v[196:199], v[44:47]
	v_mfma_f32_16x16x32_bf16 v[40:43], v[154:157], v[192:195], 0
	v_mfma_f32_16x16x32_bf16 v[40:43], v[158:161], v[196:199], v[40:43]
	v_mfma_f32_16x16x32_bf16 v[28:31], v[140:143], v[200:203], 0
	v_mfma_f32_16x16x32_bf16 v[28:31], v[150:153], v[204:207], v[28:31]
	v_mfma_f32_16x16x32_bf16 v[24:27], v[154:157], v[200:203], 0
	v_mfma_f32_16x16x32_bf16 v[24:27], v[158:161], v[204:207], v[24:27]
	v_mfma_f32_16x16x32_bf16 v[12:15], v[140:143], v[208:211], 0
	v_mfma_f32_16x16x32_bf16 v[12:15], v[150:153], v[212:215], v[12:15]
	v_mfma_f32_16x16x32_bf16 v[8:11], v[154:157], v[208:211], 0
	v_mfma_f32_16x16x32_bf16 v[8:11], v[158:161], v[212:215], v[8:11]
	s_setprio 0
	s_setprio 1
	v_mfma_f32_16x16x32_bf16 v[52:55], v[162:165], v[184:187], 0
	v_mfma_f32_16x16x32_bf16 v[52:55], v[166:169], v[188:191], v[52:55]
	v_mfma_f32_16x16x32_bf16 v[48:51], v[170:173], v[184:187], 0
	v_mfma_f32_16x16x32_bf16 v[48:51], v[174:177], v[188:191], v[48:51]
	v_mfma_f32_16x16x32_bf16 v[36:39], v[162:165], v[192:195], 0
	v_mfma_f32_16x16x32_bf16 v[36:39], v[166:169], v[196:199], v[36:39]
	v_mfma_f32_16x16x32_bf16 v[32:35], v[170:173], v[192:195], 0
	v_mfma_f32_16x16x32_bf16 v[32:35], v[174:177], v[196:199], v[32:35]
	v_mfma_f32_16x16x32_bf16 v[20:23], v[162:165], v[200:203], 0
	v_mfma_f32_16x16x32_bf16 v[20:23], v[166:169], v[204:207], v[20:23]
	v_mfma_f32_16x16x32_bf16 v[16:19], v[170:173], v[200:203], 0
	v_mfma_f32_16x16x32_bf16 v[16:19], v[174:177], v[204:207], v[16:19]
	v_mfma_f32_16x16x32_bf16 v[4:7], v[162:165], v[208:211], 0
	v_mfma_f32_16x16x32_bf16 v[4:7], v[166:169], v[212:215], v[4:7]
	v_mfma_f32_16x16x32_bf16 v[0:3], v[170:173], v[208:211], 0
	v_mfma_f32_16x16x32_bf16 v[0:3], v[174:177], v[212:215], v[0:3]
	s_setprio 0
	s_barrier
	s_branch .Lmid_gemm7
.LBB0_951:
	ds_read_b128 v[140:143], v147
	ds_read_b128 v[150:153], v147 offset:1024
	ds_read_b128 v[154:157], v147 offset:2048
	ds_read_b128 v[158:161], v147 offset:3072
	ds_read_b128 v[162:165], v148
	ds_read_b128 v[166:169], v148 offset:1024
	ds_read_b128 v[170:173], v148 offset:2048
	ds_read_b128 v[174:177], v148 offset:3072
	s_add_u32 s54, s52, 0xfffc0080
	s_addc_u32 s55, s53, -1
	s_cmp_eq_u32 s76, 12
	s_cselect_b32 s57, s37, s55
	s_cselect_b32 s56, s72, s54
	s_cselect_b32 s55, s19, s75
	s_cselect_b32 s54, s73, s74
	v_lshl_add_u64 v[178:179], s[52:53], 0, v[132:133]
	s_add_i32 m0, s49, 0xc000
	ds_read_b128 v[184:187], v149
	ds_read_b128 v[188:191], v149 offset:1024
	ds_read_b128 v[192:195], v149 offset:2048
	ds_read_b128 v[196:199], v149 offset:3072
	ds_read_b128 v[200:203], v149 offset:4096
	ds_read_b128 v[204:207], v149 offset:5120
	ds_read_b128 v[208:211], v149 offset:6144
	ds_read_b128 v[212:215], v149 offset:7168
	global_load_lds_dwordx4 v[178:179], off
	v_lshl_add_u64 v[178:179], s[52:53], 0, v[134:135]
	s_add_i32 m0, s49, 0xe000
	s_nop 0
	global_load_lds_dwordx4 v[178:179], off
	s_waitcnt vmcnt(8)
	s_waitcnt lgkmcnt(0)
	s_barrier
	s_setprio 1
	s_waitcnt lgkmcnt(0)
	v_mfma_f32_16x16x32_bf16 v[124:127], v[140:143], v[184:187], v[124:127]
	v_mfma_f32_16x16x32_bf16 v[124:127], v[150:153], v[188:191], v[124:127]
	v_mfma_f32_16x16x32_bf16 v[120:123], v[154:157], v[184:187], v[120:123]
	v_mfma_f32_16x16x32_bf16 v[120:123], v[158:161], v[188:191], v[120:123]
	v_mfma_f32_16x16x32_bf16 v[108:111], v[140:143], v[192:195], v[108:111]
	v_mfma_f32_16x16x32_bf16 v[108:111], v[150:153], v[196:199], v[108:111]
	v_mfma_f32_16x16x32_bf16 v[104:107], v[154:157], v[192:195], v[104:107]
	v_mfma_f32_16x16x32_bf16 v[104:107], v[158:161], v[196:199], v[104:107]
	v_mfma_f32_16x16x32_bf16 v[92:95], v[140:143], v[200:203], v[92:95]
	v_mfma_f32_16x16x32_bf16 v[92:95], v[150:153], v[204:207], v[92:95]
	v_mfma_f32_16x16x32_bf16 v[88:91], v[154:157], v[200:203], v[88:91]
	v_mfma_f32_16x16x32_bf16 v[88:91], v[158:161], v[204:207], v[88:91]
	v_mfma_f32_16x16x32_bf16 v[76:79], v[140:143], v[208:211], v[76:79]
	v_mfma_f32_16x16x32_bf16 v[76:79], v[150:153], v[212:215], v[76:79]
	v_mfma_f32_16x16x32_bf16 v[72:75], v[154:157], v[208:211], v[72:75]
	v_mfma_f32_16x16x32_bf16 v[72:75], v[158:161], v[212:215], v[72:75]
	s_setprio 0
	s_setprio 1
	v_mfma_f32_16x16x32_bf16 v[116:119], v[162:165], v[184:187], v[116:119]
	v_mfma_f32_16x16x32_bf16 v[116:119], v[166:169], v[188:191], v[116:119]
	v_mfma_f32_16x16x32_bf16 v[112:115], v[170:173], v[184:187], v[112:115]
	v_mfma_f32_16x16x32_bf16 v[112:115], v[174:177], v[188:191], v[112:115]
	v_mfma_f32_16x16x32_bf16 v[100:103], v[162:165], v[192:195], v[100:103]
	v_mfma_f32_16x16x32_bf16 v[100:103], v[166:169], v[196:199], v[100:103]
	v_mfma_f32_16x16x32_bf16 v[96:99], v[170:173], v[192:195], v[96:99]
	v_mfma_f32_16x16x32_bf16 v[96:99], v[174:177], v[196:199], v[96:99]
	v_mfma_f32_16x16x32_bf16 v[84:87], v[162:165], v[200:203], v[84:87]
	v_mfma_f32_16x16x32_bf16 v[84:87], v[166:169], v[204:207], v[84:87]
	v_mfma_f32_16x16x32_bf16 v[80:83], v[170:173], v[200:203], v[80:83]
	v_mfma_f32_16x16x32_bf16 v[80:83], v[174:177], v[204:207], v[80:83]
	v_mfma_f32_16x16x32_bf16 v[68:71], v[162:165], v[208:211], v[68:71]
	v_mfma_f32_16x16x32_bf16 v[68:71], v[166:169], v[212:215], v[68:71]
	v_mfma_f32_16x16x32_bf16 v[64:67], v[170:173], v[208:211], v[64:67]
	v_mfma_f32_16x16x32_bf16 v[64:67], v[174:177], v[212:215], v[64:67]
	s_setprio 0
	s_barrier
	s_add_i32 s77, s68, s60
	v_lshl_add_u64 v[178:179], s[54:55], 0, v[130:131]
	s_mov_b32 m0, s77
	ds_read_b128 v[184:187], v149 offset:16384
	ds_read_b128 v[188:191], v149 offset:17408
	ds_read_b128 v[192:195], v149 offset:18432
	ds_read_b128 v[196:199], v149 offset:19456
	ds_read_b128 v[200:203], v149 offset:20480
	ds_read_b128 v[204:207], v149 offset:21504
	ds_read_b128 v[208:211], v149 offset:22528
	ds_read_b128 v[212:215], v149 offset:23552
	global_load_lds_dwordx4 v[178:179], off
	s_add_i32 m0, s77, 0x2000
	s_add_u32 s82, s54, 0x40000
	v_lshl_add_u64 v[216:217], s[54:55], 0, v[128:129]
	s_addc_u32 s83, s55, 0
	s_add_i32 s77, s69, s60
	global_load_lds_dwordx4 v[216:217], off
	v_lshl_add_u64 v[218:219], s[82:83], 0, v[130:131]
	s_mov_b32 m0, s77
	v_lshl_add_u64 v[220:221], s[56:57], 0, v[128:129]
	global_load_lds_dwordx4 v[218:219], off
	v_lshl_add_u64 v[218:219], s[82:83], 0, v[128:129]
	s_add_i32 m0, s77, 0x2000
	s_nop 0
	global_load_lds_dwordx4 v[218:219], off
	v_lshl_add_u64 v[218:219], s[56:57], 0, v[130:131]
	s_mov_b32 m0, s49
	s_nop 0
	global_load_lds_dwordx4 v[218:219], off
	s_mov_b32 m0, s62
	s_nop 0
	global_load_lds_dwordx4 v[220:221], off
	s_waitcnt vmcnt(8)
	s_waitcnt lgkmcnt(0)
	s_barrier
	s_setprio 1
	s_waitcnt lgkmcnt(0)
	v_mfma_f32_16x16x32_bf16 v[60:63], v[140:143], v[184:187], v[60:63]
	v_mfma_f32_16x16x32_bf16 v[60:63], v[150:153], v[188:191], v[60:63]
	v_mfma_f32_16x16x32_bf16 v[56:59], v[154:157], v[184:187], v[56:59]
	v_mfma_f32_16x16x32_bf16 v[56:59], v[158:161], v[188:191], v[56:59]
	v_mfma_f32_16x16x32_bf16 v[44:47], v[140:143], v[192:195], v[44:47]
	v_mfma_f32_16x16x32_bf16 v[44:47], v[150:153], v[196:199], v[44:47]
	v_mfma_f32_16x16x32_bf16 v[40:43], v[154:157], v[192:195], v[40:43]
	v_mfma_f32_16x16x32_bf16 v[40:43], v[158:161], v[196:199], v[40:43]
	v_mfma_f32_16x16x32_bf16 v[28:31], v[140:143], v[200:203], v[28:31]
	v_mfma_f32_16x16x32_bf16 v[28:31], v[150:153], v[204:207], v[28:31]
	v_mfma_f32_16x16x32_bf16 v[24:27], v[154:157], v[200:203], v[24:27]
	v_mfma_f32_16x16x32_bf16 v[24:27], v[158:161], v[204:207], v[24:27]
	v_mfma_f32_16x16x32_bf16 v[12:15], v[140:143], v[208:211], v[12:15]
	v_mfma_f32_16x16x32_bf16 v[12:15], v[150:153], v[212:215], v[12:15]
	v_mfma_f32_16x16x32_bf16 v[8:11], v[154:157], v[208:211], v[8:11]
	v_mfma_f32_16x16x32_bf16 v[8:11], v[158:161], v[212:215], v[8:11]
	s_setprio 0
	s_setprio 1
	v_mfma_f32_16x16x32_bf16 v[52:55], v[162:165], v[184:187], v[52:55]
	v_mfma_f32_16x16x32_bf16 v[52:55], v[166:169], v[188:191], v[52:55]
	v_mfma_f32_16x16x32_bf16 v[48:51], v[170:173], v[184:187], v[48:51]
	v_mfma_f32_16x16x32_bf16 v[48:51], v[174:177], v[188:191], v[48:51]
	v_mfma_f32_16x16x32_bf16 v[36:39], v[162:165], v[192:195], v[36:39]
	v_mfma_f32_16x16x32_bf16 v[36:39], v[166:169], v[196:199], v[36:39]
	v_mfma_f32_16x16x32_bf16 v[32:35], v[170:173], v[192:195], v[32:35]
	v_mfma_f32_16x16x32_bf16 v[32:35], v[174:177], v[196:199], v[32:35]
	v_mfma_f32_16x16x32_bf16 v[20:23], v[162:165], v[200:203], v[20:23]
	v_mfma_f32_16x16x32_bf16 v[20:23], v[166:169], v[204:207], v[20:23]
	v_mfma_f32_16x16x32_bf16 v[16:19], v[170:173], v[200:203], v[16:19]
	v_mfma_f32_16x16x32_bf16 v[16:19], v[174:177], v[204:207], v[16:19]
	v_mfma_f32_16x16x32_bf16 v[4:7], v[162:165], v[208:211], v[4:7]
	v_mfma_f32_16x16x32_bf16 v[4:7], v[166:169], v[212:215], v[4:7]
	v_mfma_f32_16x16x32_bf16 v[0:3], v[170:173], v[208:211], v[0:3]
	v_mfma_f32_16x16x32_bf16 v[0:3], v[174:177], v[212:215], v[0:3]
	s_setprio 0
	s_barrier
.Lmid_gemm7:
	s_add_i32 s77, 0, 0x18000
	s_add_i32 s79, 0, 0x1c000
	v_add_u32_e32 v158, s77, v145
	v_add_u32_e32 v174, s79, v145
	ds_read_b128 v[140:143], v158
	ds_read_b128 v[150:153], v158 offset:1024
	ds_read_b128 v[154:157], v158 offset:2048
	ds_read_b128 v[158:161], v158 offset:3072
	ds_read_b128 v[162:165], v174
	ds_read_b128 v[166:169], v174 offset:1024
	ds_read_b128 v[170:173], v174 offset:2048
	ds_read_b128 v[174:177], v174 offset:3072
	s_add_u32 s56, s56, 0x40000
	s_addc_u32 s57, s57, 0
	s_mov_b32 m0, s63
	v_lshl_add_u64 v[222:223], s[56:57], 0, v[130:131]
	ds_read_b128 v[184:187], v149 offset:32768
	ds_read_b128 v[188:191], v149 offset:33792
	ds_read_b128 v[192:195], v149 offset:34816
	ds_read_b128 v[196:199], v149 offset:35840
	ds_read_b128 v[200:203], v149 offset:36864
	ds_read_b128 v[204:207], v149 offset:37888
	ds_read_b128 v[208:211], v149 offset:38912
	ds_read_b128 v[212:215], v149 offset:39936
	global_load_lds_dwordx4 v[222:223], off
	v_lshl_add_u64 v[222:223], s[56:57], 0, v[128:129]
	s_mov_b32 m0, s64
	s_nop 0
	global_load_lds_dwordx4 v[222:223], off
	s_waitcnt vmcnt(8)
	s_waitcnt lgkmcnt(0)
	s_barrier
	s_setprio 1
	s_waitcnt lgkmcnt(0)
	v_mfma_f32_16x16x32_bf16 v[124:127], v[140:143], v[184:187], v[124:127]
	v_mfma_f32_16x16x32_bf16 v[124:127], v[150:153], v[188:191], v[124:127]
	v_mfma_f32_16x16x32_bf16 v[120:123], v[154:157], v[184:187], v[120:123]
	v_mfma_f32_16x16x32_bf16 v[120:123], v[158:161], v[188:191], v[120:123]
	v_mfma_f32_16x16x32_bf16 v[108:111], v[140:143], v[192:195], v[108:111]
	v_mfma_f32_16x16x32_bf16 v[108:111], v[150:153], v[196:199], v[108:111]
	v_mfma_f32_16x16x32_bf16 v[104:107], v[154:157], v[192:195], v[104:107]
	v_mfma_f32_16x16x32_bf16 v[104:107], v[158:161], v[196:199], v[104:107]
	v_mfma_f32_16x16x32_bf16 v[92:95], v[140:143], v[200:203], v[92:95]
	v_mfma_f32_16x16x32_bf16 v[92:95], v[150:153], v[204:207], v[92:95]
	v_mfma_f32_16x16x32_bf16 v[88:91], v[154:157], v[200:203], v[88:91]
	v_mfma_f32_16x16x32_bf16 v[88:91], v[158:161], v[204:207], v[88:91]
	v_mfma_f32_16x16x32_bf16 v[76:79], v[140:143], v[208:211], v[76:79]
	v_mfma_f32_16x16x32_bf16 v[76:79], v[150:153], v[212:215], v[76:79]
	v_mfma_f32_16x16x32_bf16 v[72:75], v[154:157], v[208:211], v[72:75]
	v_mfma_f32_16x16x32_bf16 v[72:75], v[158:161], v[212:215], v[72:75]
	s_setprio 0
	s_setprio 1
	v_mfma_f32_16x16x32_bf16 v[116:119], v[162:165], v[184:187], v[116:119]
	v_mfma_f32_16x16x32_bf16 v[116:119], v[166:169], v[188:191], v[116:119]
	v_mfma_f32_16x16x32_bf16 v[112:115], v[170:173], v[184:187], v[112:115]
	v_mfma_f32_16x16x32_bf16 v[112:115], v[174:177], v[188:191], v[112:115]
	v_mfma_f32_16x16x32_bf16 v[100:103], v[162:165], v[192:195], v[100:103]
	v_mfma_f32_16x16x32_bf16 v[100:103], v[166:169], v[196:199], v[100:103]
	v_mfma_f32_16x16x32_bf16 v[96:99], v[170:173], v[192:195], v[96:99]
	v_mfma_f32_16x16x32_bf16 v[96:99], v[174:177], v[196:199], v[96:99]
	v_mfma_f32_16x16x32_bf16 v[84:87], v[162:165], v[200:203], v[84:87]
	v_mfma_f32_16x16x32_bf16 v[84:87], v[166:169], v[204:207], v[84:87]
	v_mfma_f32_16x16x32_bf16 v[80:83], v[170:173], v[200:203], v[80:83]
	v_mfma_f32_16x16x32_bf16 v[80:83], v[174:177], v[204:207], v[80:83]
	v_mfma_f32_16x16x32_bf16 v[68:71], v[162:165], v[208:211], v[68:71]
	v_mfma_f32_16x16x32_bf16 v[68:71], v[166:169], v[212:215], v[68:71]
	v_mfma_f32_16x16x32_bf16 v[64:67], v[170:173], v[208:211], v[64:67]
	v_mfma_f32_16x16x32_bf16 v[64:67], v[174:177], v[212:215], v[64:67]
	s_setprio 0
	s_barrier
	s_add_i32 s56, s77, s60
	v_lshl_add_u64 v[178:179], v[178:179], 0, s[12:13]
	s_mov_b32 m0, s56
	ds_read_b128 v[184:187], v149 offset:49152
	ds_read_b128 v[188:191], v149 offset:50176
	ds_read_b128 v[192:195], v149 offset:51200
	ds_read_b128 v[196:199], v149 offset:52224
	ds_read_b128 v[200:203], v149 offset:53248
	ds_read_b128 v[204:207], v149 offset:54272
	ds_read_b128 v[208:211], v149 offset:55296
	ds_read_b128 v[212:215], v149 offset:56320
	global_load_lds_dwordx4 v[178:179], off
	s_add_i32 m0, s56, 0x2000
	s_add_u32 s54, s54, 0x40080
	v_lshl_add_u64 v[178:179], v[216:217], 0, s[12:13]
	s_addc_u32 s55, s55, 0
	s_add_i32 s56, s79, s60
	global_load_lds_dwordx4 v[178:179], off
	v_lshl_add_u64 v[178:179], s[54:55], 0, v[130:131]
	s_mov_b32 m0, s56
	s_nop 0
	global_load_lds_dwordx4 v[178:179], off
	v_lshl_add_u64 v[178:179], s[54:55], 0, v[128:129]
	s_add_i32 m0, s56, 0x2000
	s_nop 0
	global_load_lds_dwordx4 v[178:179], off
	v_lshl_add_u64 v[178:179], v[218:219], 0, s[12:13]
	s_mov_b32 m0, s66
	s_nop 0
	global_load_lds_dwordx4 v[178:179], off
	v_lshl_add_u64 v[178:179], v[220:221], 0, s[12:13]
	s_mov_b32 m0, s67
	s_nop 0
	global_load_lds_dwordx4 v[178:179], off
	s_waitcnt vmcnt(8)
	s_waitcnt lgkmcnt(0)
	s_barrier
	s_setprio 1
	s_waitcnt lgkmcnt(0)
	v_mfma_f32_16x16x32_bf16 v[60:63], v[140:143], v[184:187], v[60:63]
	v_mfma_f32_16x16x32_bf16 v[60:63], v[150:153], v[188:191], v[60:63]
	v_mfma_f32_16x16x32_bf16 v[56:59], v[154:157], v[184:187], v[56:59]
	v_mfma_f32_16x16x32_bf16 v[56:59], v[158:161], v[188:191], v[56:59]
	v_mfma_f32_16x16x32_bf16 v[44:47], v[140:143], v[192:195], v[44:47]
	v_mfma_f32_16x16x32_bf16 v[44:47], v[150:153], v[196:199], v[44:47]
	v_mfma_f32_16x16x32_bf16 v[40:43], v[154:157], v[192:195], v[40:43]
	v_mfma_f32_16x16x32_bf16 v[40:43], v[158:161], v[196:199], v[40:43]
	v_mfma_f32_16x16x32_bf16 v[28:31], v[140:143], v[200:203], v[28:31]
	v_mfma_f32_16x16x32_bf16 v[28:31], v[150:153], v[204:207], v[28:31]
	v_mfma_f32_16x16x32_bf16 v[24:27], v[154:157], v[200:203], v[24:27]
	v_mfma_f32_16x16x32_bf16 v[24:27], v[158:161], v[204:207], v[24:27]
	v_mfma_f32_16x16x32_bf16 v[12:15], v[140:143], v[208:211], v[12:15]
	v_mfma_f32_16x16x32_bf16 v[12:15], v[150:153], v[212:215], v[12:15]
	v_mfma_f32_16x16x32_bf16 v[8:11], v[154:157], v[208:211], v[8:11]
	v_mfma_f32_16x16x32_bf16 v[8:11], v[158:161], v[212:215], v[8:11]
	s_setprio 0
	s_setprio 1
	v_mfma_f32_16x16x32_bf16 v[52:55], v[162:165], v[184:187], v[52:55]
	v_mfma_f32_16x16x32_bf16 v[52:55], v[166:169], v[188:191], v[52:55]
	v_mfma_f32_16x16x32_bf16 v[48:51], v[170:173], v[184:187], v[48:51]
	v_mfma_f32_16x16x32_bf16 v[48:51], v[174:177], v[188:191], v[48:51]
	v_mfma_f32_16x16x32_bf16 v[36:39], v[162:165], v[192:195], v[36:39]
	v_mfma_f32_16x16x32_bf16 v[36:39], v[166:169], v[196:199], v[36:39]
	v_mfma_f32_16x16x32_bf16 v[32:35], v[170:173], v[192:195], v[32:35]
	v_mfma_f32_16x16x32_bf16 v[32:35], v[174:177], v[196:199], v[32:35]
	v_mfma_f32_16x16x32_bf16 v[20:23], v[162:165], v[200:203], v[20:23]
	v_mfma_f32_16x16x32_bf16 v[20:23], v[166:169], v[204:207], v[20:23]
	v_mfma_f32_16x16x32_bf16 v[16:19], v[170:173], v[200:203], v[16:19]
	v_mfma_f32_16x16x32_bf16 v[16:19], v[174:177], v[204:207], v[16:19]
	v_mfma_f32_16x16x32_bf16 v[4:7], v[162:165], v[208:211], v[4:7]
	v_mfma_f32_16x16x32_bf16 v[4:7], v[166:169], v[212:215], v[4:7]
	v_mfma_f32_16x16x32_bf16 v[0:3], v[170:173], v[208:211], v[0:3]
	v_mfma_f32_16x16x32_bf16 v[0:3], v[174:177], v[212:215], v[0:3]
	s_setprio 0
	s_barrier
	s_add_i32 s76, s76, 2
	s_add_u32 s52, s52, 0x100
	s_addc_u32 s53, s53, 0
	s_add_u32 s74, s74, 0x100
	s_addc_u32 s75, s75, 0
	s_cmp_gt_u32 s76, 13
	s_cbranch_scc0 .LBB0_951
	s_and_b64 vcc, exec, s[16:17]
	s_cbranch_vccz .LBB0_954
	s_barrier

.LBB0_1030:
	s_add_u32 s86, s56, 0x100
	s_addc_u32 s87, s57, 0
	s_mov_b32 s88, -2
	ds_read_b128 v[152:155], v149
	ds_read_b128 v[156:159], v149 offset:1024
	ds_read_b128 v[160:163], v149 offset:2048
	ds_read_b128 v[164:167], v149 offset:3072
	ds_read_b128 v[168:171], v150
	ds_read_b128 v[172:175], v150 offset:1024
	ds_read_b128 v[176:179], v150 offset:2048
	ds_read_b128 v[184:187], v150 offset:3072
	s_add_u32 s56, s54, 0x100
	s_addc_u32 s57, s55, 0
	s_cmp_eq_u32 s88, 40
	s_cselect_b32 s61, s13, s57
	s_cselect_b32 s60, s12, s56
	s_cselect_b32 s59, s53, s87
	s_cselect_b32 s58, s52, s86
	v_lshl_add_u64 v[144:145], s[54:55], 0, v[136:137]
	s_add_i32 m0, s65, 0xc000
	ds_read_b128 v[188:191], v151
	ds_read_b128 v[192:195], v151 offset:1024
	ds_read_b128 v[196:199], v151 offset:2048
	ds_read_b128 v[200:203], v151 offset:3072
	ds_read_b128 v[204:207], v151 offset:4096
	ds_read_b128 v[208:211], v151 offset:5120
	ds_read_b128 v[212:215], v151 offset:6144
	ds_read_b128 v[216:219], v151 offset:7168
	global_load_lds_dwordx4 v[144:145], off
	v_lshl_add_u64 v[144:145], s[54:55], 0, v[138:139]
	s_add_i32 m0, s65, 0xe000
	s_nop 0
	global_load_lds_dwordx4 v[144:145], off
	s_waitcnt vmcnt(8)
	s_waitcnt lgkmcnt(0)
	s_barrier
	s_setprio 1
	s_waitcnt lgkmcnt(0)
	v_mfma_f32_16x16x32_bf16 v[124:127], v[152:155], v[188:191], 0
	v_mfma_f32_16x16x32_bf16 v[124:127], v[156:159], v[192:195], v[124:127]
	v_mfma_f32_16x16x32_bf16 v[120:123], v[160:163], v[188:191], 0
	v_mfma_f32_16x16x32_bf16 v[120:123], v[164:167], v[192:195], v[120:123]
	v_mfma_f32_16x16x32_bf16 v[116:119], v[152:155], v[196:199], 0
	v_mfma_f32_16x16x32_bf16 v[116:119], v[156:159], v[200:203], v[116:119]
	v_mfma_f32_16x16x32_bf16 v[108:111], v[160:163], v[196:199], 0
	v_mfma_f32_16x16x32_bf16 v[108:111], v[164:167], v[200:203], v[108:111]
	v_mfma_f32_16x16x32_bf16 v[100:103], v[152:155], v[204:207], 0
	v_mfma_f32_16x16x32_bf16 v[100:103], v[156:159], v[208:211], v[100:103]
	v_mfma_f32_16x16x32_bf16 v[92:95], v[160:163], v[204:207], 0
	v_mfma_f32_16x16x32_bf16 v[92:95], v[164:167], v[208:211], v[92:95]
	v_mfma_f32_16x16x32_bf16 v[84:87], v[152:155], v[212:215], 0
	v_mfma_f32_16x16x32_bf16 v[84:87], v[156:159], v[216:219], v[84:87]
	v_mfma_f32_16x16x32_bf16 v[76:79], v[160:163], v[212:215], 0
	v_mfma_f32_16x16x32_bf16 v[76:79], v[164:167], v[216:219], v[76:79]
	s_setprio 0
	s_setprio 1
	v_mfma_f32_16x16x32_bf16 v[112:115], v[168:171], v[188:191], 0
	v_mfma_f32_16x16x32_bf16 v[112:115], v[172:175], v[192:195], v[112:115]
	v_mfma_f32_16x16x32_bf16 v[104:107], v[176:179], v[188:191], 0
	v_mfma_f32_16x16x32_bf16 v[104:107], v[184:187], v[192:195], v[104:107]
	v_mfma_f32_16x16x32_bf16 v[96:99], v[168:171], v[196:199], 0
	v_mfma_f32_16x16x32_bf16 v[96:99], v[172:175], v[200:203], v[96:99]
	v_mfma_f32_16x16x32_bf16 v[88:91], v[176:179], v[196:199], 0
	v_mfma_f32_16x16x32_bf16 v[88:91], v[184:187], v[200:203], v[88:91]
	v_mfma_f32_16x16x32_bf16 v[80:83], v[168:171], v[204:207], 0
	v_mfma_f32_16x16x32_bf16 v[80:83], v[172:175], v[208:211], v[80:83]
	v_mfma_f32_16x16x32_bf16 v[72:75], v[176:179], v[204:207], 0
	v_mfma_f32_16x16x32_bf16 v[72:75], v[184:187], v[208:211], v[72:75]
	v_mfma_f32_16x16x32_bf16 v[68:71], v[168:171], v[212:215], 0
	v_mfma_f32_16x16x32_bf16 v[68:71], v[172:175], v[216:219], v[68:71]
	v_mfma_f32_16x16x32_bf16 v[64:67], v[176:179], v[212:215], 0
	v_mfma_f32_16x16x32_bf16 v[64:67], v[184:187], v[216:219], v[64:67]
	s_setprio 0
	s_barrier
	s_add_i32 s54, s72, s64
	v_lshl_add_u64 v[144:145], s[58:59], 0, v[130:131]
	s_mov_b32 m0, s54
	ds_read_b128 v[188:191], v151 offset:16384
	ds_read_b128 v[192:195], v151 offset:17408
	ds_read_b128 v[196:199], v151 offset:18432
	ds_read_b128 v[200:203], v151 offset:19456
	ds_read_b128 v[204:207], v151 offset:20480
	ds_read_b128 v[208:211], v151 offset:21504
	ds_read_b128 v[212:215], v151 offset:22528
	ds_read_b128 v[216:219], v151 offset:23552
	global_load_lds_dwordx4 v[144:145], off
	s_add_i32 m0, s54, 0x2000
	s_add_u32 s54, s58, 0xb0000
	v_lshl_add_u64 v[220:221], s[58:59], 0, v[134:135]
	s_addc_u32 s55, s59, 0
	s_add_i32 s79, s73, s64
	global_load_lds_dwordx4 v[220:221], off
	v_lshl_add_u64 v[222:223], s[54:55], 0, v[130:131]
	s_mov_b32 m0, s79
	v_lshl_add_u64 v[224:225], s[60:61], 0, v[132:133]
	global_load_lds_dwordx4 v[222:223], off
	v_lshl_add_u64 v[222:223], s[54:55], 0, v[134:135]
	s_add_i32 m0, s79, 0x2000
	s_nop 0
	global_load_lds_dwordx4 v[222:223], off
	v_lshl_add_u64 v[222:223], s[60:61], 0, v[128:129]
	s_mov_b32 m0, s65
	s_nop 0
	global_load_lds_dwordx4 v[222:223], off
	s_mov_b32 m0, s66
	s_nop 0
	global_load_lds_dwordx4 v[224:225], off
	s_waitcnt vmcnt(8)
	s_waitcnt lgkmcnt(0)
	s_barrier
	s_setprio 1
	s_waitcnt lgkmcnt(0)
	v_mfma_f32_16x16x32_bf16 v[60:63], v[152:155], v[188:191], 0
	v_mfma_f32_16x16x32_bf16 v[60:63], v[156:159], v[192:195], v[60:63]
	v_mfma_f32_16x16x32_bf16 v[56:59], v[160:163], v[188:191], 0
	v_mfma_f32_16x16x32_bf16 v[56:59], v[164:167], v[192:195], v[56:59]
	v_mfma_f32_16x16x32_bf16 v[52:55], v[152:155], v[196:199], 0
	v_mfma_f32_16x16x32_bf16 v[52:55], v[156:159], v[200:203], v[52:55]
	v_mfma_f32_16x16x32_bf16 v[44:47], v[160:163], v[196:199], 0
	v_mfma_f32_16x16x32_bf16 v[44:47], v[164:167], v[200:203], v[44:47]
	v_mfma_f32_16x16x32_bf16 v[36:39], v[152:155], v[204:207], 0
	v_mfma_f32_16x16x32_bf16 v[36:39], v[156:159], v[208:211], v[36:39]
	v_mfma_f32_16x16x32_bf16 v[28:31], v[160:163], v[204:207], 0
	v_mfma_f32_16x16x32_bf16 v[28:31], v[164:167], v[208:211], v[28:31]
	v_mfma_f32_16x16x32_bf16 v[20:23], v[152:155], v[212:215], 0
	v_mfma_f32_16x16x32_bf16 v[20:23], v[156:159], v[216:219], v[20:23]
	v_mfma_f32_16x16x32_bf16 v[12:15], v[160:163], v[212:215], 0
	v_mfma_f32_16x16x32_bf16 v[12:15], v[164:167], v[216:219], v[12:15]
	s_setprio 0
	s_setprio 1
	v_mfma_f32_16x16x32_bf16 v[48:51], v[168:171], v[188:191], 0
	v_mfma_f32_16x16x32_bf16 v[48:51], v[172:175], v[192:195], v[48:51]
	v_mfma_f32_16x16x32_bf16 v[40:43], v[176:179], v[188:191], 0
	v_mfma_f32_16x16x32_bf16 v[40:43], v[184:187], v[192:195], v[40:43]
	v_mfma_f32_16x16x32_bf16 v[32:35], v[168:171], v[196:199], 0
	v_mfma_f32_16x16x32_bf16 v[32:35], v[172:175], v[200:203], v[32:35]
	v_mfma_f32_16x16x32_bf16 v[24:27], v[176:179], v[196:199], 0
	v_mfma_f32_16x16x32_bf16 v[24:27], v[184:187], v[200:203], v[24:27]
	v_mfma_f32_16x16x32_bf16 v[16:19], v[168:171], v[204:207], 0
	v_mfma_f32_16x16x32_bf16 v[16:19], v[172:175], v[208:211], v[16:19]
	v_mfma_f32_16x16x32_bf16 v[8:11], v[176:179], v[204:207], 0
	v_mfma_f32_16x16x32_bf16 v[8:11], v[184:187], v[208:211], v[8:11]
	v_mfma_f32_16x16x32_bf16 v[4:7], v[168:171], v[212:215], 0
	v_mfma_f32_16x16x32_bf16 v[4:7], v[172:175], v[216:219], v[4:7]
	v_mfma_f32_16x16x32_bf16 v[0:3], v[176:179], v[212:215], 0
	v_mfma_f32_16x16x32_bf16 v[0:3], v[184:187], v[216:219], v[0:3]
	s_setprio 0
	s_barrier
	s_branch .Lmid_gemm8
.LBB0_1031:
	ds_read_b128 v[152:155], v149
	ds_read_b128 v[156:159], v149 offset:1024
	ds_read_b128 v[160:163], v149 offset:2048
	ds_read_b128 v[164:167], v149 offset:3072
	ds_read_b128 v[168:171], v150
	ds_read_b128 v[172:175], v150 offset:1024
	ds_read_b128 v[176:179], v150 offset:2048
	ds_read_b128 v[184:187], v150 offset:3072
	s_add_u32 s56, s54, 0x100
	s_addc_u32 s57, s55, 0
	s_cmp_eq_u32 s88, 40
	s_cselect_b32 s61, s13, s57
	s_cselect_b32 s60, s12, s56
	s_cselect_b32 s59, s53, s87
	s_cselect_b32 s58, s52, s86
	v_lshl_add_u64 v[144:145], s[54:55], 0, v[136:137]
	s_add_i32 m0, s65, 0xc000
	ds_read_b128 v[188:191], v151
	ds_read_b128 v[192:195], v151 offset:1024
	ds_read_b128 v[196:199], v151 offset:2048
	ds_read_b128 v[200:203], v151 offset:3072
	ds_read_b128 v[204:207], v151 offset:4096
	ds_read_b128 v[208:211], v151 offset:5120
	ds_read_b128 v[212:215], v151 offset:6144
	ds_read_b128 v[216:219], v151 offset:7168
	global_load_lds_dwordx4 v[144:145], off
	v_lshl_add_u64 v[144:145], s[54:55], 0, v[138:139]
	s_add_i32 m0, s65, 0xe000
	s_nop 0
	global_load_lds_dwordx4 v[144:145], off
	s_waitcnt vmcnt(8)
	s_waitcnt lgkmcnt(0)
	s_barrier
	s_setprio 1
	s_waitcnt lgkmcnt(0)
	v_mfma_f32_16x16x32_bf16 v[124:127], v[152:155], v[188:191], v[124:127]
	v_mfma_f32_16x16x32_bf16 v[124:127], v[156:159], v[192:195], v[124:127]
	v_mfma_f32_16x16x32_bf16 v[120:123], v[160:163], v[188:191], v[120:123]
	v_mfma_f32_16x16x32_bf16 v[120:123], v[164:167], v[192:195], v[120:123]
	v_mfma_f32_16x16x32_bf16 v[116:119], v[152:155], v[196:199], v[116:119]
	v_mfma_f32_16x16x32_bf16 v[116:119], v[156:159], v[200:203], v[116:119]
	v_mfma_f32_16x16x32_bf16 v[108:111], v[160:163], v[196:199], v[108:111]
	v_mfma_f32_16x16x32_bf16 v[108:111], v[164:167], v[200:203], v[108:111]
	v_mfma_f32_16x16x32_bf16 v[100:103], v[152:155], v[204:207], v[100:103]
	v_mfma_f32_16x16x32_bf16 v[100:103], v[156:159], v[208:211], v[100:103]
	v_mfma_f32_16x16x32_bf16 v[92:95], v[160:163], v[204:207], v[92:95]
	v_mfma_f32_16x16x32_bf16 v[92:95], v[164:167], v[208:211], v[92:95]
	v_mfma_f32_16x16x32_bf16 v[84:87], v[152:155], v[212:215], v[84:87]
	v_mfma_f32_16x16x32_bf16 v[84:87], v[156:159], v[216:219], v[84:87]
	v_mfma_f32_16x16x32_bf16 v[76:79], v[160:163], v[212:215], v[76:79]
	v_mfma_f32_16x16x32_bf16 v[76:79], v[164:167], v[216:219], v[76:79]
	s_setprio 0
	s_setprio 1
	v_mfma_f32_16x16x32_bf16 v[112:115], v[168:171], v[188:191], v[112:115]
	v_mfma_f32_16x16x32_bf16 v[112:115], v[172:175], v[192:195], v[112:115]
	v_mfma_f32_16x16x32_bf16 v[104:107], v[176:179], v[188:191], v[104:107]
	v_mfma_f32_16x16x32_bf16 v[104:107], v[184:187], v[192:195], v[104:107]
	v_mfma_f32_16x16x32_bf16 v[96:99], v[168:171], v[196:199], v[96:99]
	v_mfma_f32_16x16x32_bf16 v[96:99], v[172:175], v[200:203], v[96:99]
	v_mfma_f32_16x16x32_bf16 v[88:91], v[176:179], v[196:199], v[88:91]
	v_mfma_f32_16x16x32_bf16 v[88:91], v[184:187], v[200:203], v[88:91]
	v_mfma_f32_16x16x32_bf16 v[80:83], v[168:171], v[204:207], v[80:83]
	v_mfma_f32_16x16x32_bf16 v[80:83], v[172:175], v[208:211], v[80:83]
	v_mfma_f32_16x16x32_bf16 v[72:75], v[176:179], v[204:207], v[72:75]
	v_mfma_f32_16x16x32_bf16 v[72:75], v[184:187], v[208:211], v[72:75]
	v_mfma_f32_16x16x32_bf16 v[68:71], v[168:171], v[212:215], v[68:71]
	v_mfma_f32_16x16x32_bf16 v[68:71], v[172:175], v[216:219], v[68:71]
	v_mfma_f32_16x16x32_bf16 v[64:67], v[176:179], v[212:215], v[64:67]
	v_mfma_f32_16x16x32_bf16 v[64:67], v[184:187], v[216:219], v[64:67]
	s_setprio 0
	s_barrier
	s_add_i32 s54, s72, s64
	v_lshl_add_u64 v[144:145], s[58:59], 0, v[130:131]
	s_mov_b32 m0, s54
	ds_read_b128 v[188:191], v151 offset:16384
	ds_read_b128 v[192:195], v151 offset:17408
	ds_read_b128 v[196:199], v151 offset:18432
	ds_read_b128 v[200:203], v151 offset:19456
	ds_read_b128 v[204:207], v151 offset:20480
	ds_read_b128 v[208:211], v151 offset:21504
	ds_read_b128 v[212:215], v151 offset:22528
	ds_read_b128 v[216:219], v151 offset:23552
	global_load_lds_dwordx4 v[144:145], off
	s_add_i32 m0, s54, 0x2000
	s_add_u32 s54, s58, 0xb0000
	v_lshl_add_u64 v[220:221], s[58:59], 0, v[134:135]
	s_addc_u32 s55, s59, 0
	s_add_i32 s79, s73, s64
	global_load_lds_dwordx4 v[220:221], off
	v_lshl_add_u64 v[222:223], s[54:55], 0, v[130:131]
	s_mov_b32 m0, s79
	v_lshl_add_u64 v[224:225], s[60:61], 0, v[132:133]
	global_load_lds_dwordx4 v[222:223], off
	v_lshl_add_u64 v[222:223], s[54:55], 0, v[134:135]
	s_add_i32 m0, s79, 0x2000
	s_nop 0
	global_load_lds_dwordx4 v[222:223], off
	v_lshl_add_u64 v[222:223], s[60:61], 0, v[128:129]
	s_mov_b32 m0, s65
	s_nop 0
	global_load_lds_dwordx4 v[222:223], off
	s_mov_b32 m0, s66
	s_nop 0
	global_load_lds_dwordx4 v[224:225], off
	s_waitcnt vmcnt(8)
	s_waitcnt lgkmcnt(0)
	s_barrier
	s_setprio 1
	s_waitcnt lgkmcnt(0)
	v_mfma_f32_16x16x32_bf16 v[60:63], v[152:155], v[188:191], v[60:63]
	v_mfma_f32_16x16x32_bf16 v[60:63], v[156:159], v[192:195], v[60:63]
	v_mfma_f32_16x16x32_bf16 v[56:59], v[160:163], v[188:191], v[56:59]
	v_mfma_f32_16x16x32_bf16 v[56:59], v[164:167], v[192:195], v[56:59]
	v_mfma_f32_16x16x32_bf16 v[52:55], v[152:155], v[196:199], v[52:55]
	v_mfma_f32_16x16x32_bf16 v[52:55], v[156:159], v[200:203], v[52:55]
	v_mfma_f32_16x16x32_bf16 v[44:47], v[160:163], v[196:199], v[44:47]
	v_mfma_f32_16x16x32_bf16 v[44:47], v[164:167], v[200:203], v[44:47]
	v_mfma_f32_16x16x32_bf16 v[36:39], v[152:155], v[204:207], v[36:39]
	v_mfma_f32_16x16x32_bf16 v[36:39], v[156:159], v[208:211], v[36:39]
	v_mfma_f32_16x16x32_bf16 v[28:31], v[160:163], v[204:207], v[28:31]
	v_mfma_f32_16x16x32_bf16 v[28:31], v[164:167], v[208:211], v[28:31]
	v_mfma_f32_16x16x32_bf16 v[20:23], v[152:155], v[212:215], v[20:23]
	v_mfma_f32_16x16x32_bf16 v[20:23], v[156:159], v[216:219], v[20:23]
	v_mfma_f32_16x16x32_bf16 v[12:15], v[160:163], v[212:215], v[12:15]
	v_mfma_f32_16x16x32_bf16 v[12:15], v[164:167], v[216:219], v[12:15]
	s_setprio 0
	s_setprio 1
	v_mfma_f32_16x16x32_bf16 v[48:51], v[168:171], v[188:191], v[48:51]
	v_mfma_f32_16x16x32_bf16 v[48:51], v[172:175], v[192:195], v[48:51]
	v_mfma_f32_16x16x32_bf16 v[40:43], v[176:179], v[188:191], v[40:43]
	v_mfma_f32_16x16x32_bf16 v[40:43], v[184:187], v[192:195], v[40:43]
	v_mfma_f32_16x16x32_bf16 v[32:35], v[168:171], v[196:199], v[32:35]
	v_mfma_f32_16x16x32_bf16 v[32:35], v[172:175], v[200:203], v[32:35]
	v_mfma_f32_16x16x32_bf16 v[24:27], v[176:179], v[196:199], v[24:27]
	v_mfma_f32_16x16x32_bf16 v[24:27], v[184:187], v[200:203], v[24:27]
	v_mfma_f32_16x16x32_bf16 v[16:19], v[168:171], v[204:207], v[16:19]
	v_mfma_f32_16x16x32_bf16 v[16:19], v[172:175], v[208:211], v[16:19]
	v_mfma_f32_16x16x32_bf16 v[8:11], v[176:179], v[204:207], v[8:11]
	v_mfma_f32_16x16x32_bf16 v[8:11], v[184:187], v[208:211], v[8:11]
	v_mfma_f32_16x16x32_bf16 v[4:7], v[168:171], v[212:215], v[4:7]
	v_mfma_f32_16x16x32_bf16 v[4:7], v[172:175], v[216:219], v[4:7]
	v_mfma_f32_16x16x32_bf16 v[0:3], v[176:179], v[212:215], v[0:3]
	v_mfma_f32_16x16x32_bf16 v[0:3], v[184:187], v[216:219], v[0:3]
	s_setprio 0
	s_barrier
.Lmid_gemm8:
	s_add_i32 s79, 0, 0x18000
	s_add_i32 s89, 0, 0x1c000
	v_add_u32_e32 v164, s79, v147
	v_add_u32_e32 v181, s89, v147
	ds_read_b128 v[152:155], v164
	ds_read_b128 v[156:159], v164 offset:1024
	ds_read_b128 v[160:163], v164 offset:2048
	ds_read_b128 v[164:167], v164 offset:3072
	ds_read_b128 v[168:171], v181
	ds_read_b128 v[172:175], v181 offset:1024
	ds_read_b128 v[176:179], v181 offset:2048
	ds_read_b128 v[184:187], v181 offset:3072
	s_add_u32 s54, s60, 0xb0000
	s_addc_u32 s55, s61, 0
	s_mov_b32 m0, s67
	v_lshl_add_u64 v[226:227], s[54:55], 0, v[128:129]
	ds_read_b128 v[188:191], v151 offset:32768
	ds_read_b128 v[192:195], v151 offset:33792
	ds_read_b128 v[196:199], v151 offset:34816
	ds_read_b128 v[200:203], v151 offset:35840
	ds_read_b128 v[204:207], v151 offset:36864
	ds_read_b128 v[208:211], v151 offset:37888
	ds_read_b128 v[212:215], v151 offset:38912
	ds_read_b128 v[216:219], v151 offset:39936
	global_load_lds_dwordx4 v[226:227], off
	v_lshl_add_u64 v[226:227], s[54:55], 0, v[132:133]
	s_mov_b32 m0, s68
	s_nop 0
	global_load_lds_dwordx4 v[226:227], off
	s_waitcnt vmcnt(8)
	s_waitcnt lgkmcnt(0)
	s_barrier
	s_setprio 1
	s_waitcnt lgkmcnt(0)
	v_mfma_f32_16x16x32_bf16 v[124:127], v[152:155], v[188:191], v[124:127]
	v_mfma_f32_16x16x32_bf16 v[124:127], v[156:159], v[192:195], v[124:127]
	v_mfma_f32_16x16x32_bf16 v[120:123], v[160:163], v[188:191], v[120:123]
	v_mfma_f32_16x16x32_bf16 v[120:123], v[164:167], v[192:195], v[120:123]
	v_mfma_f32_16x16x32_bf16 v[116:119], v[152:155], v[196:199], v[116:119]
	v_mfma_f32_16x16x32_bf16 v[116:119], v[156:159], v[200:203], v[116:119]
	v_mfma_f32_16x16x32_bf16 v[108:111], v[160:163], v[196:199], v[108:111]
	v_mfma_f32_16x16x32_bf16 v[108:111], v[164:167], v[200:203], v[108:111]
	v_mfma_f32_16x16x32_bf16 v[100:103], v[152:155], v[204:207], v[100:103]
	v_mfma_f32_16x16x32_bf16 v[100:103], v[156:159], v[208:211], v[100:103]
	v_mfma_f32_16x16x32_bf16 v[92:95], v[160:163], v[204:207], v[92:95]
	v_mfma_f32_16x16x32_bf16 v[92:95], v[164:167], v[208:211], v[92:95]
	v_mfma_f32_16x16x32_bf16 v[84:87], v[152:155], v[212:215], v[84:87]
	v_mfma_f32_16x16x32_bf16 v[84:87], v[156:159], v[216:219], v[84:87]
	v_mfma_f32_16x16x32_bf16 v[76:79], v[160:163], v[212:215], v[76:79]
	v_mfma_f32_16x16x32_bf16 v[76:79], v[164:167], v[216:219], v[76:79]
	s_setprio 0
	s_setprio 1
	v_mfma_f32_16x16x32_bf16 v[112:115], v[168:171], v[188:191], v[112:115]
	v_mfma_f32_16x16x32_bf16 v[112:115], v[172:175], v[192:195], v[112:115]
	v_mfma_f32_16x16x32_bf16 v[104:107], v[176:179], v[188:191], v[104:107]
	v_mfma_f32_16x16x32_bf16 v[104:107], v[184:187], v[192:195], v[104:107]
	v_mfma_f32_16x16x32_bf16 v[96:99], v[168:171], v[196:199], v[96:99]
	v_mfma_f32_16x16x32_bf16 v[96:99], v[172:175], v[200:203], v[96:99]
	v_mfma_f32_16x16x32_bf16 v[88:91], v[176:179], v[196:199], v[88:91]
	v_mfma_f32_16x16x32_bf16 v[88:91], v[184:187], v[200:203], v[88:91]
	v_mfma_f32_16x16x32_bf16 v[80:83], v[168:171], v[204:207], v[80:83]
	v_mfma_f32_16x16x32_bf16 v[80:83], v[172:175], v[208:211], v[80:83]
	v_mfma_f32_16x16x32_bf16 v[72:75], v[176:179], v[204:207], v[72:75]
	v_mfma_f32_16x16x32_bf16 v[72:75], v[184:187], v[208:211], v[72:75]
	v_mfma_f32_16x16x32_bf16 v[68:71], v[168:171], v[212:215], v[68:71]
	v_mfma_f32_16x16x32_bf16 v[68:71], v[172:175], v[216:219], v[68:71]
	v_mfma_f32_16x16x32_bf16 v[64:67], v[176:179], v[212:215], v[64:67]
	v_mfma_f32_16x16x32_bf16 v[64:67], v[184:187], v[216:219], v[64:67]
	s_setprio 0
	s_barrier
	s_add_i32 s54, s79, s64
	v_lshl_add_u64 v[144:145], v[144:145], 0, s[16:17]
	s_mov_b32 m0, s54
	ds_read_b128 v[188:191], v151 offset:49152
	ds_read_b128 v[192:195], v151 offset:50176
	ds_read_b128 v[196:199], v151 offset:51200
	ds_read_b128 v[200:203], v151 offset:52224
	ds_read_b128 v[204:207], v151 offset:53248
	ds_read_b128 v[208:211], v151 offset:54272
	ds_read_b128 v[212:215], v151 offset:55296
	ds_read_b128 v[216:219], v151 offset:56320
	global_load_lds_dwordx4 v[144:145], off
	s_add_i32 m0, s54, 0x2000
	s_add_u32 s54, s58, 0xb0080
	v_lshl_add_u64 v[144:145], v[220:221], 0, s[16:17]
	s_addc_u32 s55, s59, 0
	s_add_i32 s58, s89, s64
	global_load_lds_dwordx4 v[144:145], off
	v_lshl_add_u64 v[144:145], s[54:55], 0, v[130:131]
	s_mov_b32 m0, s58
	s_nop 0
	global_load_lds_dwordx4 v[144:145], off
	v_lshl_add_u64 v[144:145], s[54:55], 0, v[134:135]
	s_add_i32 m0, s58, 0x2000
	s_nop 0
	global_load_lds_dwordx4 v[144:145], off
	v_lshl_add_u64 v[144:145], v[222:223], 0, s[16:17]
	s_mov_b32 m0, s70
	s_nop 0
	global_load_lds_dwordx4 v[144:145], off
	v_lshl_add_u64 v[144:145], v[224:225], 0, s[16:17]
	s_mov_b32 m0, s71
	s_nop 0
	global_load_lds_dwordx4 v[144:145], off
	s_waitcnt vmcnt(8)
	s_waitcnt lgkmcnt(0)
	s_barrier
	s_setprio 1
	s_waitcnt lgkmcnt(0)
	v_mfma_f32_16x16x32_bf16 v[60:63], v[152:155], v[188:191], v[60:63]
	v_mfma_f32_16x16x32_bf16 v[60:63], v[156:159], v[192:195], v[60:63]
	v_mfma_f32_16x16x32_bf16 v[56:59], v[160:163], v[188:191], v[56:59]
	v_mfma_f32_16x16x32_bf16 v[56:59], v[164:167], v[192:195], v[56:59]
	v_mfma_f32_16x16x32_bf16 v[52:55], v[152:155], v[196:199], v[52:55]
	v_mfma_f32_16x16x32_bf16 v[52:55], v[156:159], v[200:203], v[52:55]
	v_mfma_f32_16x16x32_bf16 v[44:47], v[160:163], v[196:199], v[44:47]
	v_mfma_f32_16x16x32_bf16 v[44:47], v[164:167], v[200:203], v[44:47]
	v_mfma_f32_16x16x32_bf16 v[36:39], v[152:155], v[204:207], v[36:39]
	v_mfma_f32_16x16x32_bf16 v[36:39], v[156:159], v[208:211], v[36:39]
	v_mfma_f32_16x16x32_bf16 v[28:31], v[160:163], v[204:207], v[28:31]
	v_mfma_f32_16x16x32_bf16 v[28:31], v[164:167], v[208:211], v[28:31]
	v_mfma_f32_16x16x32_bf16 v[20:23], v[152:155], v[212:215], v[20:23]
	v_mfma_f32_16x16x32_bf16 v[20:23], v[156:159], v[216:219], v[20:23]
	v_mfma_f32_16x16x32_bf16 v[12:15], v[160:163], v[212:215], v[12:15]
	v_mfma_f32_16x16x32_bf16 v[12:15], v[164:167], v[216:219], v[12:15]
	s_setprio 0
	s_setprio 1
	v_mfma_f32_16x16x32_bf16 v[48:51], v[168:171], v[188:191], v[48:51]
	v_mfma_f32_16x16x32_bf16 v[48:51], v[172:175], v[192:195], v[48:51]
	v_mfma_f32_16x16x32_bf16 v[40:43], v[176:179], v[188:191], v[40:43]
	v_mfma_f32_16x16x32_bf16 v[40:43], v[184:187], v[192:195], v[40:43]
	v_mfma_f32_16x16x32_bf16 v[32:35], v[168:171], v[196:199], v[32:35]
	v_mfma_f32_16x16x32_bf16 v[32:35], v[172:175], v[200:203], v[32:35]
	v_mfma_f32_16x16x32_bf16 v[24:27], v[176:179], v[196:199], v[24:27]
	v_mfma_f32_16x16x32_bf16 v[24:27], v[184:187], v[200:203], v[24:27]
	v_mfma_f32_16x16x32_bf16 v[16:19], v[168:171], v[204:207], v[16:19]
	v_mfma_f32_16x16x32_bf16 v[16:19], v[172:175], v[208:211], v[16:19]
	v_mfma_f32_16x16x32_bf16 v[8:11], v[176:179], v[204:207], v[8:11]
	v_mfma_f32_16x16x32_bf16 v[8:11], v[184:187], v[208:211], v[8:11]
	v_mfma_f32_16x16x32_bf16 v[4:7], v[168:171], v[212:215], v[4:7]
	v_mfma_f32_16x16x32_bf16 v[4:7], v[172:175], v[216:219], v[4:7]
	v_mfma_f32_16x16x32_bf16 v[0:3], v[176:179], v[212:215], v[0:3]
	v_mfma_f32_16x16x32_bf16 v[0:3], v[184:187], v[216:219], v[0:3]
	s_setprio 0
	s_barrier
	s_add_i32 s88, s88, 2
	s_add_u32 s86, s86, 0x100
	s_addc_u32 s87, s87, 0
	s_cmp_gt_u32 s88, 41
	s_mov_b64 s[54:55], s[56:57]
	s_cbranch_scc0 .LBB0_1031
	s_and_b64 vcc, exec, s[18:19]
	s_cbranch_vccz .LBB0_1034
	s_barrier

.LBB0_1161:
	s_ashr_i32 s53, s52, 31
	s_lshl_b64 s[54:55], s[52:53], 19
	s_add_u32 s54, s80, s54
	s_addc_u32 s55, s81, s55
	s_and_b64 s[56:57], s[10:11], exec
	s_cselect_b32 s53, s55, s61
	s_cselect_b32 s83, s54, s60
	s_ashr_i32 s49, s48, 31
	s_lshl_b64 s[56:57], s[48:49], 19
	s_add_u32 s56, s66, s56
	s_addc_u32 s57, s67, s57
	s_and_b64 s[64:65], s[10:11], exec
	s_cselect_b32 s49, s57, s63
	s_cselect_b32 s84, s56, s62
	s_add_u32 s60, s60, 0x40080
	s_addc_u32 s61, s61, 0
	s_add_u32 s85, s62, 0x100
	s_addc_u32 s86, s63, 0
	s_mov_b32 s87, -2
	ds_read_b128 v[152:155], v148
	ds_read_b128 v[156:159], v148 offset:1024
	ds_read_b128 v[160:163], v148 offset:2048
	ds_read_b128 v[164:167], v148 offset:3072
	ds_read_b128 v[168:171], v149
	ds_read_b128 v[172:175], v149 offset:1024
	ds_read_b128 v[176:179], v149 offset:2048
	ds_read_b128 v[184:187], v149 offset:3072
	s_add_u32 s62, s60, 0xfffc0080
	s_addc_u32 s63, s61, -1
	s_cmp_eq_u32 s87, 12
	s_cselect_b32 s65, s53, s63
	s_cselect_b32 s64, s83, s62
	s_cselect_b32 s63, s49, s86
	s_cselect_b32 s62, s84, s85
	v_lshl_add_u64 v[220:221], s[60:61], 0, v[138:139]
	s_add_i32 m0, s69, 0xc000
	ds_read_b128 v[188:191], v150
	ds_read_b128 v[192:195], v150 offset:1024
	ds_read_b128 v[196:199], v150 offset:2048
	ds_read_b128 v[200:203], v150 offset:3072
	ds_read_b128 v[204:207], v150 offset:4096
	ds_read_b128 v[208:211], v150 offset:5120
	ds_read_b128 v[212:215], v150 offset:6144
	ds_read_b128 v[216:219], v150 offset:7168
	global_load_lds_dwordx4 v[220:221], off
	v_lshl_add_u64 v[220:221], s[60:61], 0, v[140:141]
	s_add_i32 m0, s69, 0xe000
	s_nop 0
	global_load_lds_dwordx4 v[220:221], off
	s_waitcnt vmcnt(8)
	s_waitcnt lgkmcnt(0)
	s_barrier
	s_setprio 1
	s_waitcnt lgkmcnt(0)
	v_mfma_f32_16x16x32_bf16 v[124:127], v[152:155], v[188:191], 0
	v_mfma_f32_16x16x32_bf16 v[124:127], v[156:159], v[192:195], v[124:127]
	v_mfma_f32_16x16x32_bf16 v[120:123], v[160:163], v[188:191], 0
	v_mfma_f32_16x16x32_bf16 v[120:123], v[164:167], v[192:195], v[120:123]
	v_mfma_f32_16x16x32_bf16 v[116:119], v[152:155], v[196:199], 0
	v_mfma_f32_16x16x32_bf16 v[116:119], v[156:159], v[200:203], v[116:119]
	v_mfma_f32_16x16x32_bf16 v[112:115], v[160:163], v[196:199], 0
	v_mfma_f32_16x16x32_bf16 v[112:115], v[164:167], v[200:203], v[112:115]
	v_mfma_f32_16x16x32_bf16 v[108:111], v[152:155], v[204:207], 0
	v_mfma_f32_16x16x32_bf16 v[108:111], v[156:159], v[208:211], v[108:111]
	v_mfma_f32_16x16x32_bf16 v[104:107], v[160:163], v[204:207], 0
	v_mfma_f32_16x16x32_bf16 v[104:107], v[164:167], v[208:211], v[104:107]
	v_mfma_f32_16x16x32_bf16 v[100:103], v[152:155], v[212:215], 0
	v_mfma_f32_16x16x32_bf16 v[100:103], v[156:159], v[216:219], v[100:103]
	v_mfma_f32_16x16x32_bf16 v[96:99], v[160:163], v[212:215], 0
	v_mfma_f32_16x16x32_bf16 v[96:99], v[164:167], v[216:219], v[96:99]
	s_setprio 0
	s_setprio 1
	v_mfma_f32_16x16x32_bf16 v[68:71], v[168:171], v[188:191], 0
	v_mfma_f32_16x16x32_bf16 v[68:71], v[172:175], v[192:195], v[68:71]
	v_mfma_f32_16x16x32_bf16 v[64:67], v[176:179], v[188:191], 0
	v_mfma_f32_16x16x32_bf16 v[64:67], v[184:187], v[192:195], v[64:67]
	v_mfma_f32_16x16x32_bf16 v[52:55], v[168:171], v[196:199], 0
	v_mfma_f32_16x16x32_bf16 v[52:55], v[172:175], v[200:203], v[52:55]
	v_mfma_f32_16x16x32_bf16 v[48:51], v[176:179], v[196:199], 0
	v_mfma_f32_16x16x32_bf16 v[48:51], v[184:187], v[200:203], v[48:51]
	v_mfma_f32_16x16x32_bf16 v[44:47], v[168:171], v[204:207], 0
	v_mfma_f32_16x16x32_bf16 v[44:47], v[172:175], v[208:211], v[44:47]
	v_mfma_f32_16x16x32_bf16 v[40:43], v[176:179], v[204:207], 0
	v_mfma_f32_16x16x32_bf16 v[40:43], v[184:187], v[208:211], v[40:43]
	v_mfma_f32_16x16x32_bf16 v[36:39], v[168:171], v[212:215], 0
	v_mfma_f32_16x16x32_bf16 v[36:39], v[172:175], v[216:219], v[36:39]
	v_mfma_f32_16x16x32_bf16 v[32:35], v[176:179], v[212:215], 0
	v_mfma_f32_16x16x32_bf16 v[32:35], v[184:187], v[216:219], v[32:35]
	s_setprio 0
	s_barrier
	s_add_i32 s79, s77, s68
	v_lshl_add_u64 v[220:221], s[62:63], 0, v[130:131]
	s_mov_b32 m0, s79
	ds_read_b128 v[188:191], v150 offset:16384
	ds_read_b128 v[192:195], v150 offset:17408
	ds_read_b128 v[196:199], v150 offset:18432
	ds_read_b128 v[200:203], v150 offset:19456
	ds_read_b128 v[204:207], v150 offset:20480
	ds_read_b128 v[208:211], v150 offset:21504
	ds_read_b128 v[212:215], v150 offset:22528
	ds_read_b128 v[216:219], v150 offset:23552
	global_load_lds_dwordx4 v[220:221], off
	s_add_i32 m0, s79, 0x2000
	s_add_u32 s88, s62, 0x40000
	v_lshl_add_u64 v[222:223], s[62:63], 0, v[134:135]
	s_addc_u32 s89, s63, 0
	s_add_i32 s79, s82, s68
	global_load_lds_dwordx4 v[222:223], off
	v_lshl_add_u64 v[224:225], s[88:89], 0, v[130:131]
	s_mov_b32 m0, s79
	v_lshl_add_u64 v[226:227], s[64:65], 0, v[132:133]
	global_load_lds_dwordx4 v[224:225], off
	v_lshl_add_u64 v[224:225], s[88:89], 0, v[134:135]
	s_add_i32 m0, s79, 0x2000
	s_nop 0
	global_load_lds_dwordx4 v[224:225], off
	v_lshl_add_u64 v[224:225], s[64:65], 0, v[128:129]
	s_mov_b32 m0, s69
	s_nop 0
	global_load_lds_dwordx4 v[224:225], off
	s_mov_b32 m0, s70
	s_nop 0
	global_load_lds_dwordx4 v[226:227], off
	s_waitcnt vmcnt(8)
	s_waitcnt lgkmcnt(0)
	s_barrier
	s_setprio 1
	s_waitcnt lgkmcnt(0)
	v_mfma_f32_16x16x32_bf16 v[92:95], v[152:155], v[188:191], 0
	v_mfma_f32_16x16x32_bf16 v[92:95], v[156:159], v[192:195], v[92:95]
	v_mfma_f32_16x16x32_bf16 v[88:91], v[160:163], v[188:191], 0
	v_mfma_f32_16x16x32_bf16 v[88:91], v[164:167], v[192:195], v[88:91]
	v_mfma_f32_16x16x32_bf16 v[84:87], v[152:155], v[196:199], 0
	v_mfma_f32_16x16x32_bf16 v[84:87], v[156:159], v[200:203], v[84:87]
	v_mfma_f32_16x16x32_bf16 v[80:83], v[160:163], v[196:199], 0
	v_mfma_f32_16x16x32_bf16 v[80:83], v[164:167], v[200:203], v[80:83]
	v_mfma_f32_16x16x32_bf16 v[76:79], v[152:155], v[204:207], 0
	v_mfma_f32_16x16x32_bf16 v[76:79], v[156:159], v[208:211], v[76:79]
	v_mfma_f32_16x16x32_bf16 v[72:75], v[160:163], v[204:207], 0
	v_mfma_f32_16x16x32_bf16 v[72:75], v[164:167], v[208:211], v[72:75]
	v_mfma_f32_16x16x32_bf16 v[60:63], v[152:155], v[212:215], 0
	v_mfma_f32_16x16x32_bf16 v[60:63], v[156:159], v[216:219], v[60:63]
	v_mfma_f32_16x16x32_bf16 v[56:59], v[160:163], v[212:215], 0
	v_mfma_f32_16x16x32_bf16 v[56:59], v[164:167], v[216:219], v[56:59]
	s_setprio 0
	s_setprio 1
	v_mfma_f32_16x16x32_bf16 v[28:31], v[168:171], v[188:191], 0
	v_mfma_f32_16x16x32_bf16 v[28:31], v[172:175], v[192:195], v[28:31]
	v_mfma_f32_16x16x32_bf16 v[24:27], v[176:179], v[188:191], 0
	v_mfma_f32_16x16x32_bf16 v[24:27], v[184:187], v[192:195], v[24:27]
	v_mfma_f32_16x16x32_bf16 v[20:23], v[168:171], v[196:199], 0
	v_mfma_f32_16x16x32_bf16 v[20:23], v[172:175], v[200:203], v[20:23]
	v_mfma_f32_16x16x32_bf16 v[16:19], v[176:179], v[196:199], 0
	v_mfma_f32_16x16x32_bf16 v[16:19], v[184:187], v[200:203], v[16:19]
	v_mfma_f32_16x16x32_bf16 v[12:15], v[168:171], v[204:207], 0
	v_mfma_f32_16x16x32_bf16 v[12:15], v[172:175], v[208:211], v[12:15]
	v_mfma_f32_16x16x32_bf16 v[8:11], v[176:179], v[204:207], 0
	v_mfma_f32_16x16x32_bf16 v[8:11], v[184:187], v[208:211], v[8:11]
	v_mfma_f32_16x16x32_bf16 v[4:7], v[168:171], v[212:215], 0
	v_mfma_f32_16x16x32_bf16 v[4:7], v[172:175], v[216:219], v[4:7]
	v_mfma_f32_16x16x32_bf16 v[0:3], v[176:179], v[212:215], 0
	v_mfma_f32_16x16x32_bf16 v[0:3], v[184:187], v[216:219], v[0:3]
	s_setprio 0
	s_barrier
	s_branch .Lmid_gemm9
.LBB0_1162:
	ds_read_b128 v[152:155], v148
	ds_read_b128 v[156:159], v148 offset:1024
	ds_read_b128 v[160:163], v148 offset:2048
	ds_read_b128 v[164:167], v148 offset:3072
	ds_read_b128 v[168:171], v149
	ds_read_b128 v[172:175], v149 offset:1024
	ds_read_b128 v[176:179], v149 offset:2048
	ds_read_b128 v[184:187], v149 offset:3072
	s_add_u32 s62, s60, 0xfffc0080
	s_addc_u32 s63, s61, -1
	s_cmp_eq_u32 s87, 12
	s_cselect_b32 s65, s53, s63
	s_cselect_b32 s64, s83, s62
	s_cselect_b32 s63, s49, s86
	s_cselect_b32 s62, s84, s85
	v_lshl_add_u64 v[220:221], s[60:61], 0, v[138:139]
	s_add_i32 m0, s69, 0xc000
	ds_read_b128 v[188:191], v150
	ds_read_b128 v[192:195], v150 offset:1024
	ds_read_b128 v[196:199], v150 offset:2048
	ds_read_b128 v[200:203], v150 offset:3072
	ds_read_b128 v[204:207], v150 offset:4096
	ds_read_b128 v[208:211], v150 offset:5120
	ds_read_b128 v[212:215], v150 offset:6144
	ds_read_b128 v[216:219], v150 offset:7168
	global_load_lds_dwordx4 v[220:221], off
	v_lshl_add_u64 v[220:221], s[60:61], 0, v[140:141]
	s_add_i32 m0, s69, 0xe000
	s_nop 0
	global_load_lds_dwordx4 v[220:221], off
	s_waitcnt vmcnt(8)
	s_waitcnt lgkmcnt(0)
	s_barrier
	s_setprio 1
	s_waitcnt lgkmcnt(0)
	v_mfma_f32_16x16x32_bf16 v[124:127], v[152:155], v[188:191], v[124:127]
	v_mfma_f32_16x16x32_bf16 v[124:127], v[156:159], v[192:195], v[124:127]
	v_mfma_f32_16x16x32_bf16 v[120:123], v[160:163], v[188:191], v[120:123]
	v_mfma_f32_16x16x32_bf16 v[120:123], v[164:167], v[192:195], v[120:123]
	v_mfma_f32_16x16x32_bf16 v[116:119], v[152:155], v[196:199], v[116:119]
	v_mfma_f32_16x16x32_bf16 v[116:119], v[156:159], v[200:203], v[116:119]
	v_mfma_f32_16x16x32_bf16 v[112:115], v[160:163], v[196:199], v[112:115]
	v_mfma_f32_16x16x32_bf16 v[112:115], v[164:167], v[200:203], v[112:115]
	v_mfma_f32_16x16x32_bf16 v[108:111], v[152:155], v[204:207], v[108:111]
	v_mfma_f32_16x16x32_bf16 v[108:111], v[156:159], v[208:211], v[108:111]
	v_mfma_f32_16x16x32_bf16 v[104:107], v[160:163], v[204:207], v[104:107]
	v_mfma_f32_16x16x32_bf16 v[104:107], v[164:167], v[208:211], v[104:107]
	v_mfma_f32_16x16x32_bf16 v[100:103], v[152:155], v[212:215], v[100:103]
	v_mfma_f32_16x16x32_bf16 v[100:103], v[156:159], v[216:219], v[100:103]
	v_mfma_f32_16x16x32_bf16 v[96:99], v[160:163], v[212:215], v[96:99]
	v_mfma_f32_16x16x32_bf16 v[96:99], v[164:167], v[216:219], v[96:99]
	s_setprio 0
	s_setprio 1
	v_mfma_f32_16x16x32_bf16 v[68:71], v[168:171], v[188:191], v[68:71]
	v_mfma_f32_16x16x32_bf16 v[68:71], v[172:175], v[192:195], v[68:71]
	v_mfma_f32_16x16x32_bf16 v[64:67], v[176:179], v[188:191], v[64:67]
	v_mfma_f32_16x16x32_bf16 v[64:67], v[184:187], v[192:195], v[64:67]
	v_mfma_f32_16x16x32_bf16 v[52:55], v[168:171], v[196:199], v[52:55]
	v_mfma_f32_16x16x32_bf16 v[52:55], v[172:175], v[200:203], v[52:55]
	v_mfma_f32_16x16x32_bf16 v[48:51], v[176:179], v[196:199], v[48:51]
	v_mfma_f32_16x16x32_bf16 v[48:51], v[184:187], v[200:203], v[48:51]
	v_mfma_f32_16x16x32_bf16 v[44:47], v[168:171], v[204:207], v[44:47]
	v_mfma_f32_16x16x32_bf16 v[44:47], v[172:175], v[208:211], v[44:47]
	v_mfma_f32_16x16x32_bf16 v[40:43], v[176:179], v[204:207], v[40:43]
	v_mfma_f32_16x16x32_bf16 v[40:43], v[184:187], v[208:211], v[40:43]
	v_mfma_f32_16x16x32_bf16 v[36:39], v[168:171], v[212:215], v[36:39]
	v_mfma_f32_16x16x32_bf16 v[36:39], v[172:175], v[216:219], v[36:39]
	v_mfma_f32_16x16x32_bf16 v[32:35], v[176:179], v[212:215], v[32:35]
	v_mfma_f32_16x16x32_bf16 v[32:35], v[184:187], v[216:219], v[32:35]
	s_setprio 0
	s_barrier
	s_add_i32 s79, s77, s68
	v_lshl_add_u64 v[220:221], s[62:63], 0, v[130:131]
	s_mov_b32 m0, s79
	ds_read_b128 v[188:191], v150 offset:16384
	ds_read_b128 v[192:195], v150 offset:17408
	ds_read_b128 v[196:199], v150 offset:18432
	ds_read_b128 v[200:203], v150 offset:19456
	ds_read_b128 v[204:207], v150 offset:20480
	ds_read_b128 v[208:211], v150 offset:21504
	ds_read_b128 v[212:215], v150 offset:22528
	ds_read_b128 v[216:219], v150 offset:23552
	global_load_lds_dwordx4 v[220:221], off
	s_add_i32 m0, s79, 0x2000
	s_add_u32 s88, s62, 0x40000
	v_lshl_add_u64 v[222:223], s[62:63], 0, v[134:135]
	s_addc_u32 s89, s63, 0
	s_add_i32 s79, s82, s68
	global_load_lds_dwordx4 v[222:223], off
	v_lshl_add_u64 v[224:225], s[88:89], 0, v[130:131]
	s_mov_b32 m0, s79
	v_lshl_add_u64 v[226:227], s[64:65], 0, v[132:133]
	global_load_lds_dwordx4 v[224:225], off
	v_lshl_add_u64 v[224:225], s[88:89], 0, v[134:135]
	s_add_i32 m0, s79, 0x2000
	s_nop 0
	global_load_lds_dwordx4 v[224:225], off
	v_lshl_add_u64 v[224:225], s[64:65], 0, v[128:129]
	s_mov_b32 m0, s69
	s_nop 0
	global_load_lds_dwordx4 v[224:225], off
	s_mov_b32 m0, s70
	s_nop 0
	global_load_lds_dwordx4 v[226:227], off
	s_waitcnt vmcnt(8)
	s_waitcnt lgkmcnt(0)
	s_barrier
	s_setprio 1
	s_waitcnt lgkmcnt(0)
	v_mfma_f32_16x16x32_bf16 v[92:95], v[152:155], v[188:191], v[92:95]
	v_mfma_f32_16x16x32_bf16 v[92:95], v[156:159], v[192:195], v[92:95]
	v_mfma_f32_16x16x32_bf16 v[88:91], v[160:163], v[188:191], v[88:91]
	v_mfma_f32_16x16x32_bf16 v[88:91], v[164:167], v[192:195], v[88:91]
	v_mfma_f32_16x16x32_bf16 v[84:87], v[152:155], v[196:199], v[84:87]
	v_mfma_f32_16x16x32_bf16 v[84:87], v[156:159], v[200:203], v[84:87]
	v_mfma_f32_16x16x32_bf16 v[80:83], v[160:163], v[196:199], v[80:83]
	v_mfma_f32_16x16x32_bf16 v[80:83], v[164:167], v[200:203], v[80:83]
	v_mfma_f32_16x16x32_bf16 v[76:79], v[152:155], v[204:207], v[76:79]
	v_mfma_f32_16x16x32_bf16 v[76:79], v[156:159], v[208:211], v[76:79]
	v_mfma_f32_16x16x32_bf16 v[72:75], v[160:163], v[204:207], v[72:75]
	v_mfma_f32_16x16x32_bf16 v[72:75], v[164:167], v[208:211], v[72:75]
	v_mfma_f32_16x16x32_bf16 v[60:63], v[152:155], v[212:215], v[60:63]
	v_mfma_f32_16x16x32_bf16 v[60:63], v[156:159], v[216:219], v[60:63]
	v_mfma_f32_16x16x32_bf16 v[56:59], v[160:163], v[212:215], v[56:59]
	v_mfma_f32_16x16x32_bf16 v[56:59], v[164:167], v[216:219], v[56:59]
	s_setprio 0
	s_setprio 1
	v_mfma_f32_16x16x32_bf16 v[28:31], v[168:171], v[188:191], v[28:31]
	v_mfma_f32_16x16x32_bf16 v[28:31], v[172:175], v[192:195], v[28:31]
	v_mfma_f32_16x16x32_bf16 v[24:27], v[176:179], v[188:191], v[24:27]
	v_mfma_f32_16x16x32_bf16 v[24:27], v[184:187], v[192:195], v[24:27]
	v_mfma_f32_16x16x32_bf16 v[20:23], v[168:171], v[196:199], v[20:23]
	v_mfma_f32_16x16x32_bf16 v[20:23], v[172:175], v[200:203], v[20:23]
	v_mfma_f32_16x16x32_bf16 v[16:19], v[176:179], v[196:199], v[16:19]
	v_mfma_f32_16x16x32_bf16 v[16:19], v[184:187], v[200:203], v[16:19]
	v_mfma_f32_16x16x32_bf16 v[12:15], v[168:171], v[204:207], v[12:15]
	v_mfma_f32_16x16x32_bf16 v[12:15], v[172:175], v[208:211], v[12:15]
	v_mfma_f32_16x16x32_bf16 v[8:11], v[176:179], v[204:207], v[8:11]
	v_mfma_f32_16x16x32_bf16 v[8:11], v[184:187], v[208:211], v[8:11]
	v_mfma_f32_16x16x32_bf16 v[4:7], v[168:171], v[212:215], v[4:7]
	v_mfma_f32_16x16x32_bf16 v[4:7], v[172:175], v[216:219], v[4:7]
	v_mfma_f32_16x16x32_bf16 v[0:3], v[176:179], v[212:215], v[0:3]
	v_mfma_f32_16x16x32_bf16 v[0:3], v[184:187], v[216:219], v[0:3]
	s_setprio 0
	s_barrier
.Lmid_gemm9:
	s_add_i32 s79, 0, 0x18000
	s_add_i32 s88, 0, 0x1c000
	v_add_u32_e32 v164, s79, v147
	v_add_u32_e32 v181, s88, v147
	ds_read_b128 v[152:155], v164
	ds_read_b128 v[156:159], v164 offset:1024
	ds_read_b128 v[160:163], v164 offset:2048
	ds_read_b128 v[164:167], v164 offset:3072
	ds_read_b128 v[168:171], v181
	ds_read_b128 v[172:175], v181 offset:1024
	ds_read_b128 v[176:179], v181 offset:2048
	ds_read_b128 v[184:187], v181 offset:3072
	s_add_u32 s64, s64, 0x40000
	s_addc_u32 s65, s65, 0
	s_mov_b32 m0, s71
	v_lshl_add_u64 v[228:229], s[64:65], 0, v[128:129]
	ds_read_b128 v[188:191], v150 offset:32768
	ds_read_b128 v[192:195], v150 offset:33792
	ds_read_b128 v[196:199], v150 offset:34816
	ds_read_b128 v[200:203], v150 offset:35840
	ds_read_b128 v[204:207], v150 offset:36864
	ds_read_b128 v[208:211], v150 offset:37888
	ds_read_b128 v[212:215], v150 offset:38912
	ds_read_b128 v[216:219], v150 offset:39936
	global_load_lds_dwordx4 v[228:229], off
	v_lshl_add_u64 v[228:229], s[64:65], 0, v[132:133]
	s_mov_b32 m0, s72
	s_nop 0
	global_load_lds_dwordx4 v[228:229], off
	s_waitcnt vmcnt(8)
	s_waitcnt lgkmcnt(0)
	s_barrier
	s_setprio 1
	s_waitcnt lgkmcnt(0)
	v_mfma_f32_16x16x32_bf16 v[124:127], v[152:155], v[188:191], v[124:127]
	v_mfma_f32_16x16x32_bf16 v[124:127], v[156:159], v[192:195], v[124:127]
	v_mfma_f32_16x16x32_bf16 v[120:123], v[160:163], v[188:191], v[120:123]
	v_mfma_f32_16x16x32_bf16 v[120:123], v[164:167], v[192:195], v[120:123]
	v_mfma_f32_16x16x32_bf16 v[116:119], v[152:155], v[196:199], v[116:119]
	v_mfma_f32_16x16x32_bf16 v[116:119], v[156:159], v[200:203], v[116:119]
	v_mfma_f32_16x16x32_bf16 v[112:115], v[160:163], v[196:199], v[112:115]
	v_mfma_f32_16x16x32_bf16 v[112:115], v[164:167], v[200:203], v[112:115]
	v_mfma_f32_16x16x32_bf16 v[108:111], v[152:155], v[204:207], v[108:111]
	v_mfma_f32_16x16x32_bf16 v[108:111], v[156:159], v[208:211], v[108:111]
	v_mfma_f32_16x16x32_bf16 v[104:107], v[160:163], v[204:207], v[104:107]
	v_mfma_f32_16x16x32_bf16 v[104:107], v[164:167], v[208:211], v[104:107]
	v_mfma_f32_16x16x32_bf16 v[100:103], v[152:155], v[212:215], v[100:103]
	v_mfma_f32_16x16x32_bf16 v[100:103], v[156:159], v[216:219], v[100:103]
	v_mfma_f32_16x16x32_bf16 v[96:99], v[160:163], v[212:215], v[96:99]
	v_mfma_f32_16x16x32_bf16 v[96:99], v[164:167], v[216:219], v[96:99]
	s_setprio 0
	s_setprio 1
	v_mfma_f32_16x16x32_bf16 v[68:71], v[168:171], v[188:191], v[68:71]
	v_mfma_f32_16x16x32_bf16 v[68:71], v[172:175], v[192:195], v[68:71]
	v_mfma_f32_16x16x32_bf16 v[64:67], v[176:179], v[188:191], v[64:67]
	v_mfma_f32_16x16x32_bf16 v[64:67], v[184:187], v[192:195], v[64:67]
	v_mfma_f32_16x16x32_bf16 v[52:55], v[168:171], v[196:199], v[52:55]
	v_mfma_f32_16x16x32_bf16 v[52:55], v[172:175], v[200:203], v[52:55]
	v_mfma_f32_16x16x32_bf16 v[48:51], v[176:179], v[196:199], v[48:51]
	v_mfma_f32_16x16x32_bf16 v[48:51], v[184:187], v[200:203], v[48:51]
	v_mfma_f32_16x16x32_bf16 v[44:47], v[168:171], v[204:207], v[44:47]
	v_mfma_f32_16x16x32_bf16 v[44:47], v[172:175], v[208:211], v[44:47]
	v_mfma_f32_16x16x32_bf16 v[40:43], v[176:179], v[204:207], v[40:43]
	v_mfma_f32_16x16x32_bf16 v[40:43], v[184:187], v[208:211], v[40:43]
	v_mfma_f32_16x16x32_bf16 v[36:39], v[168:171], v[212:215], v[36:39]
	v_mfma_f32_16x16x32_bf16 v[36:39], v[172:175], v[216:219], v[36:39]
	v_mfma_f32_16x16x32_bf16 v[32:35], v[176:179], v[212:215], v[32:35]
	v_mfma_f32_16x16x32_bf16 v[32:35], v[184:187], v[216:219], v[32:35]
	s_setprio 0
	s_barrier
	s_add_i32 s64, s79, s68
	v_lshl_add_u64 v[220:221], v[220:221], 0, s[12:13]
	s_mov_b32 m0, s64
	ds_read_b128 v[188:191], v150 offset:49152
	ds_read_b128 v[192:195], v150 offset:50176
	ds_read_b128 v[196:199], v150 offset:51200
	ds_read_b128 v[200:203], v150 offset:52224
	ds_read_b128 v[204:207], v150 offset:53248
	ds_read_b128 v[208:211], v150 offset:54272
	ds_read_b128 v[212:215], v150 offset:55296
	ds_read_b128 v[216:219], v150 offset:56320
	global_load_lds_dwordx4 v[220:221], off
	s_add_i32 m0, s64, 0x2000
	s_add_u32 s62, s62, 0x40080
	v_lshl_add_u64 v[220:221], v[222:223], 0, s[12:13]
	s_addc_u32 s63, s63, 0
	s_add_i32 s64, s88, s68
	global_load_lds_dwordx4 v[220:221], off
	v_lshl_add_u64 v[220:221], s[62:63], 0, v[130:131]
	s_mov_b32 m0, s64
	s_nop 0
	global_load_lds_dwordx4 v[220:221], off
	v_lshl_add_u64 v[220:221], s[62:63], 0, v[134:135]
	s_add_i32 m0, s64, 0x2000
	s_nop 0
	global_load_lds_dwordx4 v[220:221], off
	v_lshl_add_u64 v[220:221], v[224:225], 0, s[12:13]
	s_mov_b32 m0, s75
	s_nop 0
	global_load_lds_dwordx4 v[220:221], off
	v_lshl_add_u64 v[220:221], v[226:227], 0, s[12:13]
	s_mov_b32 m0, s76
	s_nop 0
	global_load_lds_dwordx4 v[220:221], off
	s_waitcnt vmcnt(8)
	s_waitcnt lgkmcnt(0)
	s_barrier
	s_setprio 1
	s_waitcnt lgkmcnt(0)
	v_mfma_f32_16x16x32_bf16 v[92:95], v[152:155], v[188:191], v[92:95]
	v_mfma_f32_16x16x32_bf16 v[92:95], v[156:159], v[192:195], v[92:95]
	v_mfma_f32_16x16x32_bf16 v[88:91], v[160:163], v[188:191], v[88:91]
	v_mfma_f32_16x16x32_bf16 v[88:91], v[164:167], v[192:195], v[88:91]
	v_mfma_f32_16x16x32_bf16 v[84:87], v[152:155], v[196:199], v[84:87]
	v_mfma_f32_16x16x32_bf16 v[84:87], v[156:159], v[200:203], v[84:87]
	v_mfma_f32_16x16x32_bf16 v[80:83], v[160:163], v[196:199], v[80:83]
	v_mfma_f32_16x16x32_bf16 v[80:83], v[164:167], v[200:203], v[80:83]
	v_mfma_f32_16x16x32_bf16 v[76:79], v[152:155], v[204:207], v[76:79]
	v_mfma_f32_16x16x32_bf16 v[76:79], v[156:159], v[208:211], v[76:79]
	v_mfma_f32_16x16x32_bf16 v[72:75], v[160:163], v[204:207], v[72:75]
	v_mfma_f32_16x16x32_bf16 v[72:75], v[164:167], v[208:211], v[72:75]
	v_mfma_f32_16x16x32_bf16 v[60:63], v[152:155], v[212:215], v[60:63]
	v_mfma_f32_16x16x32_bf16 v[60:63], v[156:159], v[216:219], v[60:63]
	v_mfma_f32_16x16x32_bf16 v[56:59], v[160:163], v[212:215], v[56:59]
	v_mfma_f32_16x16x32_bf16 v[56:59], v[164:167], v[216:219], v[56:59]
	s_setprio 0
	s_setprio 1
	v_mfma_f32_16x16x32_bf16 v[28:31], v[168:171], v[188:191], v[28:31]
	v_mfma_f32_16x16x32_bf16 v[28:31], v[172:175], v[192:195], v[28:31]
	v_mfma_f32_16x16x32_bf16 v[24:27], v[176:179], v[188:191], v[24:27]
	v_mfma_f32_16x16x32_bf16 v[24:27], v[184:187], v[192:195], v[24:27]
	v_mfma_f32_16x16x32_bf16 v[20:23], v[168:171], v[196:199], v[20:23]
	v_mfma_f32_16x16x32_bf16 v[20:23], v[172:175], v[200:203], v[20:23]
	v_mfma_f32_16x16x32_bf16 v[16:19], v[176:179], v[196:199], v[16:19]
	v_mfma_f32_16x16x32_bf16 v[16:19], v[184:187], v[200:203], v[16:19]
	v_mfma_f32_16x16x32_bf16 v[12:15], v[168:171], v[204:207], v[12:15]
	v_mfma_f32_16x16x32_bf16 v[12:15], v[172:175], v[208:211], v[12:15]
	v_mfma_f32_16x16x32_bf16 v[8:11], v[176:179], v[204:207], v[8:11]
	v_mfma_f32_16x16x32_bf16 v[8:11], v[184:187], v[208:211], v[8:11]
	v_mfma_f32_16x16x32_bf16 v[4:7], v[168:171], v[212:215], v[4:7]
	v_mfma_f32_16x16x32_bf16 v[4:7], v[172:175], v[216:219], v[4:7]
	v_mfma_f32_16x16x32_bf16 v[0:3], v[176:179], v[212:215], v[0:3]
	v_mfma_f32_16x16x32_bf16 v[0:3], v[184:187], v[216:219], v[0:3]
	s_setprio 0
	s_barrier
	s_add_i32 s87, s87, 2
	s_add_u32 s60, s60, 0x100
	s_addc_u32 s61, s61, 0
	s_add_u32 s85, s85, 0x100
	s_addc_u32 s86, s86, 0
	s_cmp_gt_u32 s87, 13
	s_cbranch_scc0 .LBB0_1162
	s_and_b64 vcc, exec, s[16:17]
	s_cbranch_vccz .LBB0_1165
	s_barrier

.LBB0_1310:
	s_ashr_i32 s49, s48, 31
	s_lshl_b64 s[50:51], s[48:49], 19
	s_add_u32 s50, s38, s50
	s_addc_u32 s51, s39, s51
	s_and_b64 s[52:53], s[10:11], exec
	s_cselect_b32 s49, s51, s57
	s_cselect_b32 s82, s50, s56
	s_ashr_i32 s47, s46, 31
	s_lshl_b64 s[52:53], s[46:47], 19
	s_add_u32 s52, s62, s52
	s_addc_u32 s53, s63, s53
	s_and_b64 s[60:61], s[10:11], exec
	s_cselect_b32 s47, s53, s59
	s_cselect_b32 s83, s52, s58
	s_add_u32 s56, s56, 0x40080
	s_addc_u32 s57, s57, 0
	s_add_u32 s84, s58, 0x100
	s_addc_u32 s85, s59, 0
	s_mov_b32 s86, -2
	ds_read_b128 v[152:155], v149
	ds_read_b128 v[156:159], v149 offset:1024
	ds_read_b128 v[160:163], v149 offset:2048
	ds_read_b128 v[164:167], v149 offset:3072
	ds_read_b128 v[168:171], v150
	ds_read_b128 v[172:175], v150 offset:1024
	ds_read_b128 v[176:179], v150 offset:2048
	ds_read_b128 v[184:187], v150 offset:3072
	s_add_u32 s58, s56, 0xfffc0080
	s_addc_u32 s59, s57, -1
	s_cmp_eq_u32 s86, 12
	s_cselect_b32 s61, s49, s59
	s_cselect_b32 s60, s82, s58
	s_cselect_b32 s59, s47, s85
	s_cselect_b32 s58, s83, s84
	v_lshl_add_u64 v[144:145], s[56:57], 0, v[136:137]
	s_add_i32 m0, s55, 0xc000
	ds_read_b128 v[188:191], v151
	ds_read_b128 v[192:195], v151 offset:1024
	ds_read_b128 v[196:199], v151 offset:2048
	ds_read_b128 v[200:203], v151 offset:3072
	ds_read_b128 v[204:207], v151 offset:4096
	ds_read_b128 v[208:211], v151 offset:5120
	ds_read_b128 v[212:215], v151 offset:6144
	ds_read_b128 v[216:219], v151 offset:7168
	global_load_lds_dwordx4 v[144:145], off
	v_lshl_add_u64 v[144:145], s[56:57], 0, v[138:139]
	s_add_i32 m0, s55, 0xe000
	s_nop 0
	global_load_lds_dwordx4 v[144:145], off
	s_waitcnt vmcnt(8)
	s_waitcnt lgkmcnt(0)
	s_barrier
	s_setprio 1
	s_waitcnt lgkmcnt(0)
	v_mfma_f32_16x16x32_bf16 v[124:127], v[152:155], v[188:191], 0
	v_mfma_f32_16x16x32_bf16 v[124:127], v[156:159], v[192:195], v[124:127]
	v_mfma_f32_16x16x32_bf16 v[120:123], v[160:163], v[188:191], 0
	v_mfma_f32_16x16x32_bf16 v[120:123], v[164:167], v[192:195], v[120:123]
	v_mfma_f32_16x16x32_bf16 v[116:119], v[152:155], v[196:199], 0
	v_mfma_f32_16x16x32_bf16 v[116:119], v[156:159], v[200:203], v[116:119]
	v_mfma_f32_16x16x32_bf16 v[108:111], v[160:163], v[196:199], 0
	v_mfma_f32_16x16x32_bf16 v[108:111], v[164:167], v[200:203], v[108:111]
	v_mfma_f32_16x16x32_bf16 v[100:103], v[152:155], v[204:207], 0
	v_mfma_f32_16x16x32_bf16 v[100:103], v[156:159], v[208:211], v[100:103]
	v_mfma_f32_16x16x32_bf16 v[92:95], v[160:163], v[204:207], 0
	v_mfma_f32_16x16x32_bf16 v[92:95], v[164:167], v[208:211], v[92:95]
	v_mfma_f32_16x16x32_bf16 v[84:87], v[152:155], v[212:215], 0
	v_mfma_f32_16x16x32_bf16 v[84:87], v[156:159], v[216:219], v[84:87]
	v_mfma_f32_16x16x32_bf16 v[76:79], v[160:163], v[212:215], 0
	v_mfma_f32_16x16x32_bf16 v[76:79], v[164:167], v[216:219], v[76:79]
	s_setprio 0
	s_setprio 1
	v_mfma_f32_16x16x32_bf16 v[112:115], v[168:171], v[188:191], 0
	v_mfma_f32_16x16x32_bf16 v[112:115], v[172:175], v[192:195], v[112:115]
	v_mfma_f32_16x16x32_bf16 v[104:107], v[176:179], v[188:191], 0
	v_mfma_f32_16x16x32_bf16 v[104:107], v[184:187], v[192:195], v[104:107]
	v_mfma_f32_16x16x32_bf16 v[96:99], v[168:171], v[196:199], 0
	v_mfma_f32_16x16x32_bf16 v[96:99], v[172:175], v[200:203], v[96:99]
	v_mfma_f32_16x16x32_bf16 v[88:91], v[176:179], v[196:199], 0
	v_mfma_f32_16x16x32_bf16 v[88:91], v[184:187], v[200:203], v[88:91]
	v_mfma_f32_16x16x32_bf16 v[80:83], v[168:171], v[204:207], 0
	v_mfma_f32_16x16x32_bf16 v[80:83], v[172:175], v[208:211], v[80:83]
	v_mfma_f32_16x16x32_bf16 v[72:75], v[176:179], v[204:207], 0
	v_mfma_f32_16x16x32_bf16 v[72:75], v[184:187], v[208:211], v[72:75]
	v_mfma_f32_16x16x32_bf16 v[68:71], v[168:171], v[212:215], 0
	v_mfma_f32_16x16x32_bf16 v[68:71], v[172:175], v[216:219], v[68:71]
	v_mfma_f32_16x16x32_bf16 v[64:67], v[176:179], v[212:215], 0
	v_mfma_f32_16x16x32_bf16 v[64:67], v[184:187], v[216:219], v[64:67]
	s_setprio 0
	s_barrier
	s_add_i32 s79, s71, s64
	v_lshl_add_u64 v[144:145], s[58:59], 0, v[130:131]
	s_mov_b32 m0, s79
	ds_read_b128 v[188:191], v151 offset:16384
	ds_read_b128 v[192:195], v151 offset:17408
	ds_read_b128 v[196:199], v151 offset:18432
	ds_read_b128 v[200:203], v151 offset:19456
	ds_read_b128 v[204:207], v151 offset:20480
	ds_read_b128 v[208:211], v151 offset:21504
	ds_read_b128 v[212:215], v151 offset:22528
	ds_read_b128 v[216:219], v151 offset:23552
	global_load_lds_dwordx4 v[144:145], off
	s_add_i32 m0, s79, 0x2000
	s_add_u32 s88, s58, 0x40000
	v_lshl_add_u64 v[220:221], s[58:59], 0, v[134:135]
	s_addc_u32 s89, s59, 0
	s_add_i32 s79, s72, s64
	global_load_lds_dwordx4 v[220:221], off
	v_lshl_add_u64 v[222:223], s[88:89], 0, v[130:131]
	s_mov_b32 m0, s79
	v_lshl_add_u64 v[224:225], s[60:61], 0, v[132:133]
	global_load_lds_dwordx4 v[222:223], off
	v_lshl_add_u64 v[222:223], s[88:89], 0, v[134:135]
	s_add_i32 m0, s79, 0x2000
	s_nop 0
	global_load_lds_dwordx4 v[222:223], off
	v_lshl_add_u64 v[222:223], s[60:61], 0, v[128:129]
	s_mov_b32 m0, s55
	s_nop 0
	global_load_lds_dwordx4 v[222:223], off
	s_mov_b32 m0, s65
	s_nop 0
	global_load_lds_dwordx4 v[224:225], off
	s_waitcnt vmcnt(8)
	s_waitcnt lgkmcnt(0)
	s_barrier
	s_setprio 1
	s_waitcnt lgkmcnt(0)
	v_mfma_f32_16x16x32_bf16 v[60:63], v[152:155], v[188:191], 0
	v_mfma_f32_16x16x32_bf16 v[60:63], v[156:159], v[192:195], v[60:63]
	v_mfma_f32_16x16x32_bf16 v[56:59], v[160:163], v[188:191], 0
	v_mfma_f32_16x16x32_bf16 v[56:59], v[164:167], v[192:195], v[56:59]
	v_mfma_f32_16x16x32_bf16 v[52:55], v[152:155], v[196:199], 0
	v_mfma_f32_16x16x32_bf16 v[52:55], v[156:159], v[200:203], v[52:55]
	v_mfma_f32_16x16x32_bf16 v[44:47], v[160:163], v[196:199], 0
	v_mfma_f32_16x16x32_bf16 v[44:47], v[164:167], v[200:203], v[44:47]
	v_mfma_f32_16x16x32_bf16 v[36:39], v[152:155], v[204:207], 0
	v_mfma_f32_16x16x32_bf16 v[36:39], v[156:159], v[208:211], v[36:39]
	v_mfma_f32_16x16x32_bf16 v[28:31], v[160:163], v[204:207], 0
	v_mfma_f32_16x16x32_bf16 v[28:31], v[164:167], v[208:211], v[28:31]
	v_mfma_f32_16x16x32_bf16 v[20:23], v[152:155], v[212:215], 0
	v_mfma_f32_16x16x32_bf16 v[20:23], v[156:159], v[216:219], v[20:23]
	v_mfma_f32_16x16x32_bf16 v[12:15], v[160:163], v[212:215], 0
	v_mfma_f32_16x16x32_bf16 v[12:15], v[164:167], v[216:219], v[12:15]
	s_setprio 0
	s_setprio 1
	v_mfma_f32_16x16x32_bf16 v[48:51], v[168:171], v[188:191], 0
	v_mfma_f32_16x16x32_bf16 v[48:51], v[172:175], v[192:195], v[48:51]
	v_mfma_f32_16x16x32_bf16 v[40:43], v[176:179], v[188:191], 0
	v_mfma_f32_16x16x32_bf16 v[40:43], v[184:187], v[192:195], v[40:43]
	v_mfma_f32_16x16x32_bf16 v[32:35], v[168:171], v[196:199], 0
	v_mfma_f32_16x16x32_bf16 v[32:35], v[172:175], v[200:203], v[32:35]
	v_mfma_f32_16x16x32_bf16 v[24:27], v[176:179], v[196:199], 0
	v_mfma_f32_16x16x32_bf16 v[24:27], v[184:187], v[200:203], v[24:27]
	v_mfma_f32_16x16x32_bf16 v[16:19], v[168:171], v[204:207], 0
	v_mfma_f32_16x16x32_bf16 v[16:19], v[172:175], v[208:211], v[16:19]
	v_mfma_f32_16x16x32_bf16 v[8:11], v[176:179], v[204:207], 0
	v_mfma_f32_16x16x32_bf16 v[8:11], v[184:187], v[208:211], v[8:11]
	v_mfma_f32_16x16x32_bf16 v[4:7], v[168:171], v[212:215], 0
	v_mfma_f32_16x16x32_bf16 v[4:7], v[172:175], v[216:219], v[4:7]
	v_mfma_f32_16x16x32_bf16 v[0:3], v[176:179], v[212:215], 0
	v_mfma_f32_16x16x32_bf16 v[0:3], v[184:187], v[216:219], v[0:3]
	s_setprio 0
	s_barrier
	s_branch .Lmid_gemm10
.LBB0_1311:
	ds_read_b128 v[152:155], v149
	ds_read_b128 v[156:159], v149 offset:1024
	ds_read_b128 v[160:163], v149 offset:2048
	ds_read_b128 v[164:167], v149 offset:3072
	ds_read_b128 v[168:171], v150
	ds_read_b128 v[172:175], v150 offset:1024
	ds_read_b128 v[176:179], v150 offset:2048
	ds_read_b128 v[184:187], v150 offset:3072
	s_add_u32 s58, s56, 0xfffc0080
	s_addc_u32 s59, s57, -1
	s_cmp_eq_u32 s86, 12
	s_cselect_b32 s61, s49, s59
	s_cselect_b32 s60, s82, s58
	s_cselect_b32 s59, s47, s85
	s_cselect_b32 s58, s83, s84
	v_lshl_add_u64 v[144:145], s[56:57], 0, v[136:137]
	s_add_i32 m0, s55, 0xc000
	ds_read_b128 v[188:191], v151
	ds_read_b128 v[192:195], v151 offset:1024
	ds_read_b128 v[196:199], v151 offset:2048
	ds_read_b128 v[200:203], v151 offset:3072
	ds_read_b128 v[204:207], v151 offset:4096
	ds_read_b128 v[208:211], v151 offset:5120
	ds_read_b128 v[212:215], v151 offset:6144
	ds_read_b128 v[216:219], v151 offset:7168
	global_load_lds_dwordx4 v[144:145], off
	v_lshl_add_u64 v[144:145], s[56:57], 0, v[138:139]
	s_add_i32 m0, s55, 0xe000
	s_nop 0
	global_load_lds_dwordx4 v[144:145], off
	s_waitcnt vmcnt(8)
	s_waitcnt lgkmcnt(0)
	s_barrier
	s_setprio 1
	s_waitcnt lgkmcnt(0)
	v_mfma_f32_16x16x32_bf16 v[124:127], v[152:155], v[188:191], v[124:127]
	v_mfma_f32_16x16x32_bf16 v[124:127], v[156:159], v[192:195], v[124:127]
	v_mfma_f32_16x16x32_bf16 v[120:123], v[160:163], v[188:191], v[120:123]
	v_mfma_f32_16x16x32_bf16 v[120:123], v[164:167], v[192:195], v[120:123]
	v_mfma_f32_16x16x32_bf16 v[116:119], v[152:155], v[196:199], v[116:119]
	v_mfma_f32_16x16x32_bf16 v[116:119], v[156:159], v[200:203], v[116:119]
	v_mfma_f32_16x16x32_bf16 v[108:111], v[160:163], v[196:199], v[108:111]
	v_mfma_f32_16x16x32_bf16 v[108:111], v[164:167], v[200:203], v[108:111]
	v_mfma_f32_16x16x32_bf16 v[100:103], v[152:155], v[204:207], v[100:103]
	v_mfma_f32_16x16x32_bf16 v[100:103], v[156:159], v[208:211], v[100:103]
	v_mfma_f32_16x16x32_bf16 v[92:95], v[160:163], v[204:207], v[92:95]
	v_mfma_f32_16x16x32_bf16 v[92:95], v[164:167], v[208:211], v[92:95]
	v_mfma_f32_16x16x32_bf16 v[84:87], v[152:155], v[212:215], v[84:87]
	v_mfma_f32_16x16x32_bf16 v[84:87], v[156:159], v[216:219], v[84:87]
	v_mfma_f32_16x16x32_bf16 v[76:79], v[160:163], v[212:215], v[76:79]
	v_mfma_f32_16x16x32_bf16 v[76:79], v[164:167], v[216:219], v[76:79]
	s_setprio 0
	s_setprio 1
	v_mfma_f32_16x16x32_bf16 v[112:115], v[168:171], v[188:191], v[112:115]
	v_mfma_f32_16x16x32_bf16 v[112:115], v[172:175], v[192:195], v[112:115]
	v_mfma_f32_16x16x32_bf16 v[104:107], v[176:179], v[188:191], v[104:107]
	v_mfma_f32_16x16x32_bf16 v[104:107], v[184:187], v[192:195], v[104:107]
	v_mfma_f32_16x16x32_bf16 v[96:99], v[168:171], v[196:199], v[96:99]
	v_mfma_f32_16x16x32_bf16 v[96:99], v[172:175], v[200:203], v[96:99]
	v_mfma_f32_16x16x32_bf16 v[88:91], v[176:179], v[196:199], v[88:91]
	v_mfma_f32_16x16x32_bf16 v[88:91], v[184:187], v[200:203], v[88:91]
	v_mfma_f32_16x16x32_bf16 v[80:83], v[168:171], v[204:207], v[80:83]
	v_mfma_f32_16x16x32_bf16 v[80:83], v[172:175], v[208:211], v[80:83]
	v_mfma_f32_16x16x32_bf16 v[72:75], v[176:179], v[204:207], v[72:75]
	v_mfma_f32_16x16x32_bf16 v[72:75], v[184:187], v[208:211], v[72:75]
	v_mfma_f32_16x16x32_bf16 v[68:71], v[168:171], v[212:215], v[68:71]
	v_mfma_f32_16x16x32_bf16 v[68:71], v[172:175], v[216:219], v[68:71]
	v_mfma_f32_16x16x32_bf16 v[64:67], v[176:179], v[212:215], v[64:67]
	v_mfma_f32_16x16x32_bf16 v[64:67], v[184:187], v[216:219], v[64:67]
	s_setprio 0
	s_barrier
	s_add_i32 s79, s71, s64
	v_lshl_add_u64 v[144:145], s[58:59], 0, v[130:131]
	s_mov_b32 m0, s79
	ds_read_b128 v[188:191], v151 offset:16384
	ds_read_b128 v[192:195], v151 offset:17408
	ds_read_b128 v[196:199], v151 offset:18432
	ds_read_b128 v[200:203], v151 offset:19456
	ds_read_b128 v[204:207], v151 offset:20480
	ds_read_b128 v[208:211], v151 offset:21504
	ds_read_b128 v[212:215], v151 offset:22528
	ds_read_b128 v[216:219], v151 offset:23552
	global_load_lds_dwordx4 v[144:145], off
	s_add_i32 m0, s79, 0x2000
	s_add_u32 s88, s58, 0x40000
	v_lshl_add_u64 v[220:221], s[58:59], 0, v[134:135]
	s_addc_u32 s89, s59, 0
	s_add_i32 s79, s72, s64
	global_load_lds_dwordx4 v[220:221], off
	v_lshl_add_u64 v[222:223], s[88:89], 0, v[130:131]
	s_mov_b32 m0, s79
	v_lshl_add_u64 v[224:225], s[60:61], 0, v[132:133]
	global_load_lds_dwordx4 v[222:223], off
	v_lshl_add_u64 v[222:223], s[88:89], 0, v[134:135]
	s_add_i32 m0, s79, 0x2000
	s_nop 0
	global_load_lds_dwordx4 v[222:223], off
	v_lshl_add_u64 v[222:223], s[60:61], 0, v[128:129]
	s_mov_b32 m0, s55
	s_nop 0
	global_load_lds_dwordx4 v[222:223], off
	s_mov_b32 m0, s65
	s_nop 0
	global_load_lds_dwordx4 v[224:225], off
	s_waitcnt vmcnt(8)
	s_waitcnt lgkmcnt(0)
	s_barrier
	s_setprio 1
	s_waitcnt lgkmcnt(0)
	v_mfma_f32_16x16x32_bf16 v[60:63], v[152:155], v[188:191], v[60:63]
	v_mfma_f32_16x16x32_bf16 v[60:63], v[156:159], v[192:195], v[60:63]
	v_mfma_f32_16x16x32_bf16 v[56:59], v[160:163], v[188:191], v[56:59]
	v_mfma_f32_16x16x32_bf16 v[56:59], v[164:167], v[192:195], v[56:59]
	v_mfma_f32_16x16x32_bf16 v[52:55], v[152:155], v[196:199], v[52:55]
	v_mfma_f32_16x16x32_bf16 v[52:55], v[156:159], v[200:203], v[52:55]
	v_mfma_f32_16x16x32_bf16 v[44:47], v[160:163], v[196:199], v[44:47]
	v_mfma_f32_16x16x32_bf16 v[44:47], v[164:167], v[200:203], v[44:47]
	v_mfma_f32_16x16x32_bf16 v[36:39], v[152:155], v[204:207], v[36:39]
	v_mfma_f32_16x16x32_bf16 v[36:39], v[156:159], v[208:211], v[36:39]
	v_mfma_f32_16x16x32_bf16 v[28:31], v[160:163], v[204:207], v[28:31]
	v_mfma_f32_16x16x32_bf16 v[28:31], v[164:167], v[208:211], v[28:31]
	v_mfma_f32_16x16x32_bf16 v[20:23], v[152:155], v[212:215], v[20:23]
	v_mfma_f32_16x16x32_bf16 v[20:23], v[156:159], v[216:219], v[20:23]
	v_mfma_f32_16x16x32_bf16 v[12:15], v[160:163], v[212:215], v[12:15]
	v_mfma_f32_16x16x32_bf16 v[12:15], v[164:167], v[216:219], v[12:15]
	s_setprio 0
	s_setprio 1
	v_mfma_f32_16x16x32_bf16 v[48:51], v[168:171], v[188:191], v[48:51]
	v_mfma_f32_16x16x32_bf16 v[48:51], v[172:175], v[192:195], v[48:51]
	v_mfma_f32_16x16x32_bf16 v[40:43], v[176:179], v[188:191], v[40:43]
	v_mfma_f32_16x16x32_bf16 v[40:43], v[184:187], v[192:195], v[40:43]
	v_mfma_f32_16x16x32_bf16 v[32:35], v[168:171], v[196:199], v[32:35]
	v_mfma_f32_16x16x32_bf16 v[32:35], v[172:175], v[200:203], v[32:35]
	v_mfma_f32_16x16x32_bf16 v[24:27], v[176:179], v[196:199], v[24:27]
	v_mfma_f32_16x16x32_bf16 v[24:27], v[184:187], v[200:203], v[24:27]
	v_mfma_f32_16x16x32_bf16 v[16:19], v[168:171], v[204:207], v[16:19]
	v_mfma_f32_16x16x32_bf16 v[16:19], v[172:175], v[208:211], v[16:19]
	v_mfma_f32_16x16x32_bf16 v[8:11], v[176:179], v[204:207], v[8:11]
	v_mfma_f32_16x16x32_bf16 v[8:11], v[184:187], v[208:211], v[8:11]
	v_mfma_f32_16x16x32_bf16 v[4:7], v[168:171], v[212:215], v[4:7]
	v_mfma_f32_16x16x32_bf16 v[4:7], v[172:175], v[216:219], v[4:7]
	v_mfma_f32_16x16x32_bf16 v[0:3], v[176:179], v[212:215], v[0:3]
	v_mfma_f32_16x16x32_bf16 v[0:3], v[184:187], v[216:219], v[0:3]
	s_setprio 0
	s_barrier
.Lmid_gemm10:
	s_add_i32 s79, 0, 0x18000
	s_add_i32 s87, 0, 0x1c000
	v_add_u32_e32 v164, s79, v147
	v_add_u32_e32 v181, s87, v147
	ds_read_b128 v[152:155], v164
	ds_read_b128 v[156:159], v164 offset:1024
	ds_read_b128 v[160:163], v164 offset:2048
	ds_read_b128 v[164:167], v164 offset:3072
	ds_read_b128 v[168:171], v181
	ds_read_b128 v[172:175], v181 offset:1024
	ds_read_b128 v[176:179], v181 offset:2048
	ds_read_b128 v[184:187], v181 offset:3072
	s_add_u32 s60, s60, 0x40000
	s_addc_u32 s61, s61, 0
	s_mov_b32 m0, s66
	v_lshl_add_u64 v[226:227], s[60:61], 0, v[128:129]
	ds_read_b128 v[188:191], v151 offset:32768
	ds_read_b128 v[192:195], v151 offset:33792
	ds_read_b128 v[196:199], v151 offset:34816
	ds_read_b128 v[200:203], v151 offset:35840
	ds_read_b128 v[204:207], v151 offset:36864
	ds_read_b128 v[208:211], v151 offset:37888
	ds_read_b128 v[212:215], v151 offset:38912
	ds_read_b128 v[216:219], v151 offset:39936
	global_load_lds_dwordx4 v[226:227], off
	v_lshl_add_u64 v[226:227], s[60:61], 0, v[132:133]
	s_mov_b32 m0, s67
	s_nop 0
	global_load_lds_dwordx4 v[226:227], off
	s_waitcnt vmcnt(8)
	s_waitcnt lgkmcnt(0)
	s_barrier
	s_setprio 1
	s_waitcnt lgkmcnt(0)
	v_mfma_f32_16x16x32_bf16 v[124:127], v[152:155], v[188:191], v[124:127]
	v_mfma_f32_16x16x32_bf16 v[124:127], v[156:159], v[192:195], v[124:127]
	v_mfma_f32_16x16x32_bf16 v[120:123], v[160:163], v[188:191], v[120:123]
	v_mfma_f32_16x16x32_bf16 v[120:123], v[164:167], v[192:195], v[120:123]
	v_mfma_f32_16x16x32_bf16 v[116:119], v[152:155], v[196:199], v[116:119]
	v_mfma_f32_16x16x32_bf16 v[116:119], v[156:159], v[200:203], v[116:119]
	v_mfma_f32_16x16x32_bf16 v[108:111], v[160:163], v[196:199], v[108:111]
	v_mfma_f32_16x16x32_bf16 v[108:111], v[164:167], v[200:203], v[108:111]
	v_mfma_f32_16x16x32_bf16 v[100:103], v[152:155], v[204:207], v[100:103]
	v_mfma_f32_16x16x32_bf16 v[100:103], v[156:159], v[208:211], v[100:103]
	v_mfma_f32_16x16x32_bf16 v[92:95], v[160:163], v[204:207], v[92:95]
	v_mfma_f32_16x16x32_bf16 v[92:95], v[164:167], v[208:211], v[92:95]
	v_mfma_f32_16x16x32_bf16 v[84:87], v[152:155], v[212:215], v[84:87]
	v_mfma_f32_16x16x32_bf16 v[84:87], v[156:159], v[216:219], v[84:87]
	v_mfma_f32_16x16x32_bf16 v[76:79], v[160:163], v[212:215], v[76:79]
	v_mfma_f32_16x16x32_bf16 v[76:79], v[164:167], v[216:219], v[76:79]
	s_setprio 0
	s_setprio 1
	v_mfma_f32_16x16x32_bf16 v[112:115], v[168:171], v[188:191], v[112:115]
	v_mfma_f32_16x16x32_bf16 v[112:115], v[172:175], v[192:195], v[112:115]
	v_mfma_f32_16x16x32_bf16 v[104:107], v[176:179], v[188:191], v[104:107]
	v_mfma_f32_16x16x32_bf16 v[104:107], v[184:187], v[192:195], v[104:107]
	v_mfma_f32_16x16x32_bf16 v[96:99], v[168:171], v[196:199], v[96:99]
	v_mfma_f32_16x16x32_bf16 v[96:99], v[172:175], v[200:203], v[96:99]
	v_mfma_f32_16x16x32_bf16 v[88:91], v[176:179], v[196:199], v[88:91]
	v_mfma_f32_16x16x32_bf16 v[88:91], v[184:187], v[200:203], v[88:91]
	v_mfma_f32_16x16x32_bf16 v[80:83], v[168:171], v[204:207], v[80:83]
	v_mfma_f32_16x16x32_bf16 v[80:83], v[172:175], v[208:211], v[80:83]
	v_mfma_f32_16x16x32_bf16 v[72:75], v[176:179], v[204:207], v[72:75]
	v_mfma_f32_16x16x32_bf16 v[72:75], v[184:187], v[208:211], v[72:75]
	v_mfma_f32_16x16x32_bf16 v[68:71], v[168:171], v[212:215], v[68:71]
	v_mfma_f32_16x16x32_bf16 v[68:71], v[172:175], v[216:219], v[68:71]
	v_mfma_f32_16x16x32_bf16 v[64:67], v[176:179], v[212:215], v[64:67]
	v_mfma_f32_16x16x32_bf16 v[64:67], v[184:187], v[216:219], v[64:67]
	s_setprio 0
	s_barrier
	s_add_i32 s60, s79, s64
	v_lshl_add_u64 v[144:145], v[144:145], 0, s[16:17]
	s_mov_b32 m0, s60
	ds_read_b128 v[188:191], v151 offset:49152
	ds_read_b128 v[192:195], v151 offset:50176
	ds_read_b128 v[196:199], v151 offset:51200
	ds_read_b128 v[200:203], v151 offset:52224
	ds_read_b128 v[204:207], v151 offset:53248
	ds_read_b128 v[208:211], v151 offset:54272
	ds_read_b128 v[212:215], v151 offset:55296
	ds_read_b128 v[216:219], v151 offset:56320
	global_load_lds_dwordx4 v[144:145], off
	s_add_i32 m0, s60, 0x2000
	s_add_u32 s58, s58, 0x40080
	v_lshl_add_u64 v[144:145], v[220:221], 0, s[16:17]
	s_addc_u32 s59, s59, 0
	s_add_i32 s60, s87, s64
	global_load_lds_dwordx4 v[144:145], off
	v_lshl_add_u64 v[144:145], s[58:59], 0, v[130:131]
	s_mov_b32 m0, s60
	s_nop 0
	global_load_lds_dwordx4 v[144:145], off
	v_lshl_add_u64 v[144:145], s[58:59], 0, v[134:135]
	s_add_i32 m0, s60, 0x2000
	s_nop 0
	global_load_lds_dwordx4 v[144:145], off
	v_lshl_add_u64 v[144:145], v[222:223], 0, s[16:17]
	s_mov_b32 m0, s69
	s_nop 0
	global_load_lds_dwordx4 v[144:145], off
	v_lshl_add_u64 v[144:145], v[224:225], 0, s[16:17]
	s_mov_b32 m0, s70
	s_nop 0
	global_load_lds_dwordx4 v[144:145], off
	s_waitcnt vmcnt(8)
	s_waitcnt lgkmcnt(0)
	s_barrier
	s_setprio 1
	s_waitcnt lgkmcnt(0)
	v_mfma_f32_16x16x32_bf16 v[60:63], v[152:155], v[188:191], v[60:63]
	v_mfma_f32_16x16x32_bf16 v[60:63], v[156:159], v[192:195], v[60:63]
	v_mfma_f32_16x16x32_bf16 v[56:59], v[160:163], v[188:191], v[56:59]
	v_mfma_f32_16x16x32_bf16 v[56:59], v[164:167], v[192:195], v[56:59]
	v_mfma_f32_16x16x32_bf16 v[52:55], v[152:155], v[196:199], v[52:55]
	v_mfma_f32_16x16x32_bf16 v[52:55], v[156:159], v[200:203], v[52:55]
	v_mfma_f32_16x16x32_bf16 v[44:47], v[160:163], v[196:199], v[44:47]
	v_mfma_f32_16x16x32_bf16 v[44:47], v[164:167], v[200:203], v[44:47]
	v_mfma_f32_16x16x32_bf16 v[36:39], v[152:155], v[204:207], v[36:39]
	v_mfma_f32_16x16x32_bf16 v[36:39], v[156:159], v[208:211], v[36:39]
	v_mfma_f32_16x16x32_bf16 v[28:31], v[160:163], v[204:207], v[28:31]
	v_mfma_f32_16x16x32_bf16 v[28:31], v[164:167], v[208:211], v[28:31]
	v_mfma_f32_16x16x32_bf16 v[20:23], v[152:155], v[212:215], v[20:23]
	v_mfma_f32_16x16x32_bf16 v[20:23], v[156:159], v[216:219], v[20:23]
	v_mfma_f32_16x16x32_bf16 v[12:15], v[160:163], v[212:215], v[12:15]
	v_mfma_f32_16x16x32_bf16 v[12:15], v[164:167], v[216:219], v[12:15]
	s_setprio 0
	s_setprio 1
	v_mfma_f32_16x16x32_bf16 v[48:51], v[168:171], v[188:191], v[48:51]
	v_mfma_f32_16x16x32_bf16 v[48:51], v[172:175], v[192:195], v[48:51]
	v_mfma_f32_16x16x32_bf16 v[40:43], v[176:179], v[188:191], v[40:43]
	v_mfma_f32_16x16x32_bf16 v[40:43], v[184:187], v[192:195], v[40:43]
	v_mfma_f32_16x16x32_bf16 v[32:35], v[168:171], v[196:199], v[32:35]
	v_mfma_f32_16x16x32_bf16 v[32:35], v[172:175], v[200:203], v[32:35]
	v_mfma_f32_16x16x32_bf16 v[24:27], v[176:179], v[196:199], v[24:27]
	v_mfma_f32_16x16x32_bf16 v[24:27], v[184:187], v[200:203], v[24:27]
	v_mfma_f32_16x16x32_bf16 v[16:19], v[168:171], v[204:207], v[16:19]
	v_mfma_f32_16x16x32_bf16 v[16:19], v[172:175], v[208:211], v[16:19]
	v_mfma_f32_16x16x32_bf16 v[8:11], v[176:179], v[204:207], v[8:11]
	v_mfma_f32_16x16x32_bf16 v[8:11], v[184:187], v[208:211], v[8:11]
	v_mfma_f32_16x16x32_bf16 v[4:7], v[168:171], v[212:215], v[4:7]
	v_mfma_f32_16x16x32_bf16 v[4:7], v[172:175], v[216:219], v[4:7]
	v_mfma_f32_16x16x32_bf16 v[0:3], v[176:179], v[212:215], v[0:3]
	v_mfma_f32_16x16x32_bf16 v[0:3], v[184:187], v[216:219], v[0:3]
	s_setprio 0
	s_barrier
	s_add_i32 s86, s86, 2
	s_add_u32 s56, s56, 0x100
	s_addc_u32 s57, s57, 0
	s_add_u32 s84, s84, 0x100
	s_addc_u32 s85, s85, 0
	s_cmp_gt_u32 s86, 13
	s_cbranch_scc0 .LBB0_1311
	s_and_b64 vcc, exec, s[18:19]
	s_cbranch_vccz .LBB0_1314
	s_barrier

.LBB0_1433:
	s_ashr_i32 s19, s18, 31
	s_lshl_b64 s[30:31], s[18:19], 19
	s_add_u32 s30, s80, s30
	s_addc_u32 s31, s81, s31
	s_and_b64 s[36:37], s[8:9], exec
	s_cselect_b32 s19, s31, s47
	s_cselect_b32 s66, s30, s46
	s_ashr_i32 s17, s16, 31
	s_lshl_b64 s[36:37], s[16:17], 19
	s_add_u32 s36, s52, s36
	s_addc_u32 s37, s53, s37
	s_and_b64 s[50:51], s[8:9], exec
	s_cselect_b32 s17, s37, s49
	s_cselect_b32 s67, s36, s48
	s_add_u32 s46, s46, 0x40080
	s_addc_u32 s47, s47, 0
	s_add_u32 s68, s48, 0x100
	s_addc_u32 s69, s49, 0
	s_mov_b32 s70, -2
	ds_read_b128 v[140:143], v147
	ds_read_b128 v[150:153], v147 offset:1024
	ds_read_b128 v[154:157], v147 offset:2048
	ds_read_b128 v[158:161], v147 offset:3072
	ds_read_b128 v[162:165], v148
	ds_read_b128 v[166:169], v148 offset:1024
	ds_read_b128 v[170:173], v148 offset:2048
	ds_read_b128 v[174:177], v148 offset:3072
	s_add_u32 s48, s46, 0xfffc0080
	s_addc_u32 s49, s47, -1
	s_cmp_eq_u32 s70, 12
	s_cselect_b32 s51, s19, s49
	s_cselect_b32 s50, s66, s48
	s_cselect_b32 s49, s17, s69
	s_cselect_b32 s48, s67, s68
	v_lshl_add_u64 v[178:179], s[46:47], 0, v[132:133]
	s_add_i32 m0, s45, 0xc000
	ds_read_b128 v[184:187], v149
	ds_read_b128 v[188:191], v149 offset:1024
	ds_read_b128 v[192:195], v149 offset:2048
	ds_read_b128 v[196:199], v149 offset:3072
	ds_read_b128 v[200:203], v149 offset:4096
	ds_read_b128 v[204:207], v149 offset:5120
	ds_read_b128 v[208:211], v149 offset:6144
	ds_read_b128 v[212:215], v149 offset:7168
	global_load_lds_dwordx4 v[178:179], off
	v_lshl_add_u64 v[178:179], s[46:47], 0, v[134:135]
	s_add_i32 m0, s45, 0xe000
	s_nop 0
	global_load_lds_dwordx4 v[178:179], off
	s_waitcnt vmcnt(8)
	s_waitcnt lgkmcnt(0)
	s_barrier
	s_setprio 1
	s_waitcnt lgkmcnt(0)
	v_mfma_f32_16x16x32_bf16 v[124:127], v[140:143], v[184:187], 0
	v_mfma_f32_16x16x32_bf16 v[124:127], v[150:153], v[188:191], v[124:127]
	v_mfma_f32_16x16x32_bf16 v[120:123], v[154:157], v[184:187], 0
	v_mfma_f32_16x16x32_bf16 v[120:123], v[158:161], v[188:191], v[120:123]
	v_mfma_f32_16x16x32_bf16 v[108:111], v[140:143], v[192:195], 0
	v_mfma_f32_16x16x32_bf16 v[108:111], v[150:153], v[196:199], v[108:111]
	v_mfma_f32_16x16x32_bf16 v[104:107], v[154:157], v[192:195], 0
	v_mfma_f32_16x16x32_bf16 v[104:107], v[158:161], v[196:199], v[104:107]
	v_mfma_f32_16x16x32_bf16 v[92:95], v[140:143], v[200:203], 0
	v_mfma_f32_16x16x32_bf16 v[92:95], v[150:153], v[204:207], v[92:95]
	v_mfma_f32_16x16x32_bf16 v[88:91], v[154:157], v[200:203], 0
	v_mfma_f32_16x16x32_bf16 v[88:91], v[158:161], v[204:207], v[88:91]
	v_mfma_f32_16x16x32_bf16 v[76:79], v[140:143], v[208:211], 0
	v_mfma_f32_16x16x32_bf16 v[76:79], v[150:153], v[212:215], v[76:79]
	v_mfma_f32_16x16x32_bf16 v[72:75], v[154:157], v[208:211], 0
	v_mfma_f32_16x16x32_bf16 v[72:75], v[158:161], v[212:215], v[72:75]
	s_setprio 0
	s_setprio 1
	v_mfma_f32_16x16x32_bf16 v[116:119], v[162:165], v[184:187], 0
	v_mfma_f32_16x16x32_bf16 v[116:119], v[166:169], v[188:191], v[116:119]
	v_mfma_f32_16x16x32_bf16 v[112:115], v[170:173], v[184:187], 0
	v_mfma_f32_16x16x32_bf16 v[112:115], v[174:177], v[188:191], v[112:115]
	v_mfma_f32_16x16x32_bf16 v[100:103], v[162:165], v[192:195], 0
	v_mfma_f32_16x16x32_bf16 v[100:103], v[166:169], v[196:199], v[100:103]
	v_mfma_f32_16x16x32_bf16 v[96:99], v[170:173], v[192:195], 0
	v_mfma_f32_16x16x32_bf16 v[96:99], v[174:177], v[196:199], v[96:99]
	v_mfma_f32_16x16x32_bf16 v[84:87], v[162:165], v[200:203], 0
	v_mfma_f32_16x16x32_bf16 v[84:87], v[166:169], v[204:207], v[84:87]
	v_mfma_f32_16x16x32_bf16 v[80:83], v[170:173], v[200:203], 0
	v_mfma_f32_16x16x32_bf16 v[80:83], v[174:177], v[204:207], v[80:83]
	v_mfma_f32_16x16x32_bf16 v[68:71], v[162:165], v[208:211], 0
	v_mfma_f32_16x16x32_bf16 v[68:71], v[166:169], v[212:215], v[68:71]
	v_mfma_f32_16x16x32_bf16 v[64:67], v[170:173], v[208:211], 0
	v_mfma_f32_16x16x32_bf16 v[64:67], v[174:177], v[212:215], v[64:67]
	s_setprio 0
	s_barrier
	s_add_i32 s71, s62, s54
	v_lshl_add_u64 v[178:179], s[48:49], 0, v[130:131]
	s_mov_b32 m0, s71
	ds_read_b128 v[184:187], v149 offset:16384
	ds_read_b128 v[188:191], v149 offset:17408
	ds_read_b128 v[192:195], v149 offset:18432
	ds_read_b128 v[196:199], v149 offset:19456
	ds_read_b128 v[200:203], v149 offset:20480
	ds_read_b128 v[204:207], v149 offset:21504
	ds_read_b128 v[208:211], v149 offset:22528
	ds_read_b128 v[212:215], v149 offset:23552
	global_load_lds_dwordx4 v[178:179], off
	s_add_i32 m0, s71, 0x2000
	s_add_u32 s72, s48, 0x40000
	v_lshl_add_u64 v[216:217], s[48:49], 0, v[128:129]
	s_addc_u32 s73, s49, 0
	s_add_i32 s71, s63, s54
	global_load_lds_dwordx4 v[216:217], off
	v_lshl_add_u64 v[218:219], s[72:73], 0, v[130:131]
	s_mov_b32 m0, s71
	v_lshl_add_u64 v[220:221], s[50:51], 0, v[128:129]
	global_load_lds_dwordx4 v[218:219], off
	v_lshl_add_u64 v[218:219], s[72:73], 0, v[128:129]
	s_add_i32 m0, s71, 0x2000
	s_nop 0
	global_load_lds_dwordx4 v[218:219], off
	v_lshl_add_u64 v[218:219], s[50:51], 0, v[130:131]
	s_mov_b32 m0, s45
	s_nop 0
	global_load_lds_dwordx4 v[218:219], off
	s_mov_b32 m0, s56
	s_nop 0
	global_load_lds_dwordx4 v[220:221], off
	s_waitcnt vmcnt(8)
	s_waitcnt lgkmcnt(0)
	s_barrier
	s_setprio 1
	s_waitcnt lgkmcnt(0)
	v_mfma_f32_16x16x32_bf16 v[60:63], v[140:143], v[184:187], 0
	v_mfma_f32_16x16x32_bf16 v[60:63], v[150:153], v[188:191], v[60:63]
	v_mfma_f32_16x16x32_bf16 v[56:59], v[154:157], v[184:187], 0
	v_mfma_f32_16x16x32_bf16 v[56:59], v[158:161], v[188:191], v[56:59]
	v_mfma_f32_16x16x32_bf16 v[44:47], v[140:143], v[192:195], 0
	v_mfma_f32_16x16x32_bf16 v[44:47], v[150:153], v[196:199], v[44:47]
	v_mfma_f32_16x16x32_bf16 v[40:43], v[154:157], v[192:195], 0
	v_mfma_f32_16x16x32_bf16 v[40:43], v[158:161], v[196:199], v[40:43]
	v_mfma_f32_16x16x32_bf16 v[28:31], v[140:143], v[200:203], 0
	v_mfma_f32_16x16x32_bf16 v[28:31], v[150:153], v[204:207], v[28:31]
	v_mfma_f32_16x16x32_bf16 v[24:27], v[154:157], v[200:203], 0
	v_mfma_f32_16x16x32_bf16 v[24:27], v[158:161], v[204:207], v[24:27]
	v_mfma_f32_16x16x32_bf16 v[12:15], v[140:143], v[208:211], 0
	v_mfma_f32_16x16x32_bf16 v[12:15], v[150:153], v[212:215], v[12:15]
	v_mfma_f32_16x16x32_bf16 v[8:11], v[154:157], v[208:211], 0
	v_mfma_f32_16x16x32_bf16 v[8:11], v[158:161], v[212:215], v[8:11]
	s_setprio 0
	s_setprio 1
	v_mfma_f32_16x16x32_bf16 v[52:55], v[162:165], v[184:187], 0
	v_mfma_f32_16x16x32_bf16 v[52:55], v[166:169], v[188:191], v[52:55]
	v_mfma_f32_16x16x32_bf16 v[48:51], v[170:173], v[184:187], 0
	v_mfma_f32_16x16x32_bf16 v[48:51], v[174:177], v[188:191], v[48:51]
	v_mfma_f32_16x16x32_bf16 v[36:39], v[162:165], v[192:195], 0
	v_mfma_f32_16x16x32_bf16 v[36:39], v[166:169], v[196:199], v[36:39]
	v_mfma_f32_16x16x32_bf16 v[32:35], v[170:173], v[192:195], 0
	v_mfma_f32_16x16x32_bf16 v[32:35], v[174:177], v[196:199], v[32:35]
	v_mfma_f32_16x16x32_bf16 v[20:23], v[162:165], v[200:203], 0
	v_mfma_f32_16x16x32_bf16 v[20:23], v[166:169], v[204:207], v[20:23]
	v_mfma_f32_16x16x32_bf16 v[16:19], v[170:173], v[200:203], 0
	v_mfma_f32_16x16x32_bf16 v[16:19], v[174:177], v[204:207], v[16:19]
	v_mfma_f32_16x16x32_bf16 v[4:7], v[162:165], v[208:211], 0
	v_mfma_f32_16x16x32_bf16 v[4:7], v[166:169], v[212:215], v[4:7]
	v_mfma_f32_16x16x32_bf16 v[0:3], v[170:173], v[208:211], 0
	v_mfma_f32_16x16x32_bf16 v[0:3], v[174:177], v[212:215], v[0:3]
	s_setprio 0
	s_barrier
	s_branch .Lmid_gemm11
.LBB0_1434:
	ds_read_b128 v[140:143], v147
	ds_read_b128 v[150:153], v147 offset:1024
	ds_read_b128 v[154:157], v147 offset:2048
	ds_read_b128 v[158:161], v147 offset:3072
	ds_read_b128 v[162:165], v148
	ds_read_b128 v[166:169], v148 offset:1024
	ds_read_b128 v[170:173], v148 offset:2048
	ds_read_b128 v[174:177], v148 offset:3072
	s_add_u32 s48, s46, 0xfffc0080
	s_addc_u32 s49, s47, -1
	s_cmp_eq_u32 s70, 12
	s_cselect_b32 s51, s19, s49
	s_cselect_b32 s50, s66, s48
	s_cselect_b32 s49, s17, s69
	s_cselect_b32 s48, s67, s68
	v_lshl_add_u64 v[178:179], s[46:47], 0, v[132:133]
	s_add_i32 m0, s45, 0xc000
	ds_read_b128 v[184:187], v149
	ds_read_b128 v[188:191], v149 offset:1024
	ds_read_b128 v[192:195], v149 offset:2048
	ds_read_b128 v[196:199], v149 offset:3072
	ds_read_b128 v[200:203], v149 offset:4096
	ds_read_b128 v[204:207], v149 offset:5120
	ds_read_b128 v[208:211], v149 offset:6144
	ds_read_b128 v[212:215], v149 offset:7168
	global_load_lds_dwordx4 v[178:179], off
	v_lshl_add_u64 v[178:179], s[46:47], 0, v[134:135]
	s_add_i32 m0, s45, 0xe000
	s_nop 0
	global_load_lds_dwordx4 v[178:179], off
	s_waitcnt vmcnt(8)
	s_waitcnt lgkmcnt(0)
	s_barrier
	s_setprio 1
	s_waitcnt lgkmcnt(0)
	v_mfma_f32_16x16x32_bf16 v[124:127], v[140:143], v[184:187], v[124:127]
	v_mfma_f32_16x16x32_bf16 v[124:127], v[150:153], v[188:191], v[124:127]
	v_mfma_f32_16x16x32_bf16 v[120:123], v[154:157], v[184:187], v[120:123]
	v_mfma_f32_16x16x32_bf16 v[120:123], v[158:161], v[188:191], v[120:123]
	v_mfma_f32_16x16x32_bf16 v[108:111], v[140:143], v[192:195], v[108:111]
	v_mfma_f32_16x16x32_bf16 v[108:111], v[150:153], v[196:199], v[108:111]
	v_mfma_f32_16x16x32_bf16 v[104:107], v[154:157], v[192:195], v[104:107]
	v_mfma_f32_16x16x32_bf16 v[104:107], v[158:161], v[196:199], v[104:107]
	v_mfma_f32_16x16x32_bf16 v[92:95], v[140:143], v[200:203], v[92:95]
	v_mfma_f32_16x16x32_bf16 v[92:95], v[150:153], v[204:207], v[92:95]
	v_mfma_f32_16x16x32_bf16 v[88:91], v[154:157], v[200:203], v[88:91]
	v_mfma_f32_16x16x32_bf16 v[88:91], v[158:161], v[204:207], v[88:91]
	v_mfma_f32_16x16x32_bf16 v[76:79], v[140:143], v[208:211], v[76:79]
	v_mfma_f32_16x16x32_bf16 v[76:79], v[150:153], v[212:215], v[76:79]
	v_mfma_f32_16x16x32_bf16 v[72:75], v[154:157], v[208:211], v[72:75]
	v_mfma_f32_16x16x32_bf16 v[72:75], v[158:161], v[212:215], v[72:75]
	s_setprio 0
	s_setprio 1
	v_mfma_f32_16x16x32_bf16 v[116:119], v[162:165], v[184:187], v[116:119]
	v_mfma_f32_16x16x32_bf16 v[116:119], v[166:169], v[188:191], v[116:119]
	v_mfma_f32_16x16x32_bf16 v[112:115], v[170:173], v[184:187], v[112:115]
	v_mfma_f32_16x16x32_bf16 v[112:115], v[174:177], v[188:191], v[112:115]
	v_mfma_f32_16x16x32_bf16 v[100:103], v[162:165], v[192:195], v[100:103]
	v_mfma_f32_16x16x32_bf16 v[100:103], v[166:169], v[196:199], v[100:103]
	v_mfma_f32_16x16x32_bf16 v[96:99], v[170:173], v[192:195], v[96:99]
	v_mfma_f32_16x16x32_bf16 v[96:99], v[174:177], v[196:199], v[96:99]
	v_mfma_f32_16x16x32_bf16 v[84:87], v[162:165], v[200:203], v[84:87]
	v_mfma_f32_16x16x32_bf16 v[84:87], v[166:169], v[204:207], v[84:87]
	v_mfma_f32_16x16x32_bf16 v[80:83], v[170:173], v[200:203], v[80:83]
	v_mfma_f32_16x16x32_bf16 v[80:83], v[174:177], v[204:207], v[80:83]
	v_mfma_f32_16x16x32_bf16 v[68:71], v[162:165], v[208:211], v[68:71]
	v_mfma_f32_16x16x32_bf16 v[68:71], v[166:169], v[212:215], v[68:71]
	v_mfma_f32_16x16x32_bf16 v[64:67], v[170:173], v[208:211], v[64:67]
	v_mfma_f32_16x16x32_bf16 v[64:67], v[174:177], v[212:215], v[64:67]
	s_setprio 0
	s_barrier
	s_add_i32 s71, s62, s54
	v_lshl_add_u64 v[178:179], s[48:49], 0, v[130:131]
	s_mov_b32 m0, s71
	ds_read_b128 v[184:187], v149 offset:16384
	ds_read_b128 v[188:191], v149 offset:17408
	ds_read_b128 v[192:195], v149 offset:18432
	ds_read_b128 v[196:199], v149 offset:19456
	ds_read_b128 v[200:203], v149 offset:20480
	ds_read_b128 v[204:207], v149 offset:21504
	ds_read_b128 v[208:211], v149 offset:22528
	ds_read_b128 v[212:215], v149 offset:23552
	global_load_lds_dwordx4 v[178:179], off
	s_add_i32 m0, s71, 0x2000
	s_add_u32 s72, s48, 0x40000
	v_lshl_add_u64 v[216:217], s[48:49], 0, v[128:129]
	s_addc_u32 s73, s49, 0
	s_add_i32 s71, s63, s54
	global_load_lds_dwordx4 v[216:217], off
	v_lshl_add_u64 v[218:219], s[72:73], 0, v[130:131]
	s_mov_b32 m0, s71
	v_lshl_add_u64 v[220:221], s[50:51], 0, v[128:129]
	global_load_lds_dwordx4 v[218:219], off
	v_lshl_add_u64 v[218:219], s[72:73], 0, v[128:129]
	s_add_i32 m0, s71, 0x2000
	s_nop 0
	global_load_lds_dwordx4 v[218:219], off
	v_lshl_add_u64 v[218:219], s[50:51], 0, v[130:131]
	s_mov_b32 m0, s45
	s_nop 0
	global_load_lds_dwordx4 v[218:219], off
	s_mov_b32 m0, s56
	s_nop 0
	global_load_lds_dwordx4 v[220:221], off
	s_waitcnt vmcnt(8)
	s_waitcnt lgkmcnt(0)
	s_barrier
	s_setprio 1
	s_waitcnt lgkmcnt(0)
	v_mfma_f32_16x16x32_bf16 v[60:63], v[140:143], v[184:187], v[60:63]
	v_mfma_f32_16x16x32_bf16 v[60:63], v[150:153], v[188:191], v[60:63]
	v_mfma_f32_16x16x32_bf16 v[56:59], v[154:157], v[184:187], v[56:59]
	v_mfma_f32_16x16x32_bf16 v[56:59], v[158:161], v[188:191], v[56:59]
	v_mfma_f32_16x16x32_bf16 v[44:47], v[140:143], v[192:195], v[44:47]
	v_mfma_f32_16x16x32_bf16 v[44:47], v[150:153], v[196:199], v[44:47]
	v_mfma_f32_16x16x32_bf16 v[40:43], v[154:157], v[192:195], v[40:43]
	v_mfma_f32_16x16x32_bf16 v[40:43], v[158:161], v[196:199], v[40:43]
	v_mfma_f32_16x16x32_bf16 v[28:31], v[140:143], v[200:203], v[28:31]
	v_mfma_f32_16x16x32_bf16 v[28:31], v[150:153], v[204:207], v[28:31]
	v_mfma_f32_16x16x32_bf16 v[24:27], v[154:157], v[200:203], v[24:27]
	v_mfma_f32_16x16x32_bf16 v[24:27], v[158:161], v[204:207], v[24:27]
	v_mfma_f32_16x16x32_bf16 v[12:15], v[140:143], v[208:211], v[12:15]
	v_mfma_f32_16x16x32_bf16 v[12:15], v[150:153], v[212:215], v[12:15]
	v_mfma_f32_16x16x32_bf16 v[8:11], v[154:157], v[208:211], v[8:11]
	v_mfma_f32_16x16x32_bf16 v[8:11], v[158:161], v[212:215], v[8:11]
	s_setprio 0
	s_setprio 1
	v_mfma_f32_16x16x32_bf16 v[52:55], v[162:165], v[184:187], v[52:55]
	v_mfma_f32_16x16x32_bf16 v[52:55], v[166:169], v[188:191], v[52:55]
	v_mfma_f32_16x16x32_bf16 v[48:51], v[170:173], v[184:187], v[48:51]
	v_mfma_f32_16x16x32_bf16 v[48:51], v[174:177], v[188:191], v[48:51]
	v_mfma_f32_16x16x32_bf16 v[36:39], v[162:165], v[192:195], v[36:39]
	v_mfma_f32_16x16x32_bf16 v[36:39], v[166:169], v[196:199], v[36:39]
	v_mfma_f32_16x16x32_bf16 v[32:35], v[170:173], v[192:195], v[32:35]
	v_mfma_f32_16x16x32_bf16 v[32:35], v[174:177], v[196:199], v[32:35]
	v_mfma_f32_16x16x32_bf16 v[20:23], v[162:165], v[200:203], v[20:23]
	v_mfma_f32_16x16x32_bf16 v[20:23], v[166:169], v[204:207], v[20:23]
	v_mfma_f32_16x16x32_bf16 v[16:19], v[170:173], v[200:203], v[16:19]
	v_mfma_f32_16x16x32_bf16 v[16:19], v[174:177], v[204:207], v[16:19]
	v_mfma_f32_16x16x32_bf16 v[4:7], v[162:165], v[208:211], v[4:7]
	v_mfma_f32_16x16x32_bf16 v[4:7], v[166:169], v[212:215], v[4:7]
	v_mfma_f32_16x16x32_bf16 v[0:3], v[170:173], v[208:211], v[0:3]
	v_mfma_f32_16x16x32_bf16 v[0:3], v[174:177], v[212:215], v[0:3]
	s_setprio 0
	s_barrier
.Lmid_gemm11:
	s_add_i32 s71, 0, 0x18000
	s_add_i32 s72, 0, 0x1c000
	v_add_u32_e32 v158, s71, v145
	v_add_u32_e32 v174, s72, v145
	ds_read_b128 v[140:143], v158
	ds_read_b128 v[150:153], v158 offset:1024
	ds_read_b128 v[154:157], v158 offset:2048
	ds_read_b128 v[158:161], v158 offset:3072
	ds_read_b128 v[162:165], v174
	ds_read_b128 v[166:169], v174 offset:1024
	ds_read_b128 v[170:173], v174 offset:2048
	ds_read_b128 v[174:177], v174 offset:3072
	s_add_u32 s50, s50, 0x40000
	s_addc_u32 s51, s51, 0
	s_mov_b32 m0, s57
	v_lshl_add_u64 v[222:223], s[50:51], 0, v[130:131]
	ds_read_b128 v[184:187], v149 offset:32768
	ds_read_b128 v[188:191], v149 offset:33792
	ds_read_b128 v[192:195], v149 offset:34816
	ds_read_b128 v[196:199], v149 offset:35840
	ds_read_b128 v[200:203], v149 offset:36864
	ds_read_b128 v[204:207], v149 offset:37888
	ds_read_b128 v[208:211], v149 offset:38912
	ds_read_b128 v[212:215], v149 offset:39936
	global_load_lds_dwordx4 v[222:223], off
	v_lshl_add_u64 v[222:223], s[50:51], 0, v[128:129]
	s_mov_b32 m0, s58
	s_nop 0
	global_load_lds_dwordx4 v[222:223], off
	s_waitcnt vmcnt(8)
	s_waitcnt lgkmcnt(0)
	s_barrier
	s_setprio 1
	s_waitcnt lgkmcnt(0)
	v_mfma_f32_16x16x32_bf16 v[124:127], v[140:143], v[184:187], v[124:127]
	v_mfma_f32_16x16x32_bf16 v[124:127], v[150:153], v[188:191], v[124:127]
	v_mfma_f32_16x16x32_bf16 v[120:123], v[154:157], v[184:187], v[120:123]
	v_mfma_f32_16x16x32_bf16 v[120:123], v[158:161], v[188:191], v[120:123]
	v_mfma_f32_16x16x32_bf16 v[108:111], v[140:143], v[192:195], v[108:111]
	v_mfma_f32_16x16x32_bf16 v[108:111], v[150:153], v[196:199], v[108:111]
	v_mfma_f32_16x16x32_bf16 v[104:107], v[154:157], v[192:195], v[104:107]
	v_mfma_f32_16x16x32_bf16 v[104:107], v[158:161], v[196:199], v[104:107]
	v_mfma_f32_16x16x32_bf16 v[92:95], v[140:143], v[200:203], v[92:95]
	v_mfma_f32_16x16x32_bf16 v[92:95], v[150:153], v[204:207], v[92:95]
	v_mfma_f32_16x16x32_bf16 v[88:91], v[154:157], v[200:203], v[88:91]
	v_mfma_f32_16x16x32_bf16 v[88:91], v[158:161], v[204:207], v[88:91]
	v_mfma_f32_16x16x32_bf16 v[76:79], v[140:143], v[208:211], v[76:79]
	v_mfma_f32_16x16x32_bf16 v[76:79], v[150:153], v[212:215], v[76:79]
	v_mfma_f32_16x16x32_bf16 v[72:75], v[154:157], v[208:211], v[72:75]
	v_mfma_f32_16x16x32_bf16 v[72:75], v[158:161], v[212:215], v[72:75]
	s_setprio 0
	s_setprio 1
	v_mfma_f32_16x16x32_bf16 v[116:119], v[162:165], v[184:187], v[116:119]
	v_mfma_f32_16x16x32_bf16 v[116:119], v[166:169], v[188:191], v[116:119]
	v_mfma_f32_16x16x32_bf16 v[112:115], v[170:173], v[184:187], v[112:115]
	v_mfma_f32_16x16x32_bf16 v[112:115], v[174:177], v[188:191], v[112:115]
	v_mfma_f32_16x16x32_bf16 v[100:103], v[162:165], v[192:195], v[100:103]
	v_mfma_f32_16x16x32_bf16 v[100:103], v[166:169], v[196:199], v[100:103]
	v_mfma_f32_16x16x32_bf16 v[96:99], v[170:173], v[192:195], v[96:99]
	v_mfma_f32_16x16x32_bf16 v[96:99], v[174:177], v[196:199], v[96:99]
	v_mfma_f32_16x16x32_bf16 v[84:87], v[162:165], v[200:203], v[84:87]
	v_mfma_f32_16x16x32_bf16 v[84:87], v[166:169], v[204:207], v[84:87]
	v_mfma_f32_16x16x32_bf16 v[80:83], v[170:173], v[200:203], v[80:83]
	v_mfma_f32_16x16x32_bf16 v[80:83], v[174:177], v[204:207], v[80:83]
	v_mfma_f32_16x16x32_bf16 v[68:71], v[162:165], v[208:211], v[68:71]
	v_mfma_f32_16x16x32_bf16 v[68:71], v[166:169], v[212:215], v[68:71]
	v_mfma_f32_16x16x32_bf16 v[64:67], v[170:173], v[208:211], v[64:67]
	v_mfma_f32_16x16x32_bf16 v[64:67], v[174:177], v[212:215], v[64:67]
	s_setprio 0
	s_barrier
	s_add_i32 s50, s71, s54
	v_lshl_add_u64 v[178:179], v[178:179], 0, s[10:11]
	s_mov_b32 m0, s50
	ds_read_b128 v[184:187], v149 offset:49152
	ds_read_b128 v[188:191], v149 offset:50176
	ds_read_b128 v[192:195], v149 offset:51200
	ds_read_b128 v[196:199], v149 offset:52224
	ds_read_b128 v[200:203], v149 offset:53248
	ds_read_b128 v[204:207], v149 offset:54272
	ds_read_b128 v[208:211], v149 offset:55296
	ds_read_b128 v[212:215], v149 offset:56320
	global_load_lds_dwordx4 v[178:179], off
	s_add_i32 m0, s50, 0x2000
	s_add_u32 s48, s48, 0x40080
	v_lshl_add_u64 v[178:179], v[216:217], 0, s[10:11]
	s_addc_u32 s49, s49, 0
	s_add_i32 s50, s72, s54
	global_load_lds_dwordx4 v[178:179], off
	v_lshl_add_u64 v[178:179], s[48:49], 0, v[130:131]
	s_mov_b32 m0, s50
	s_nop 0
	global_load_lds_dwordx4 v[178:179], off
	v_lshl_add_u64 v[178:179], s[48:49], 0, v[128:129]
	s_add_i32 m0, s50, 0x2000
	s_nop 0
	global_load_lds_dwordx4 v[178:179], off
	v_lshl_add_u64 v[178:179], v[218:219], 0, s[10:11]
	s_mov_b32 m0, s60
	s_nop 0
	global_load_lds_dwordx4 v[178:179], off
	v_lshl_add_u64 v[178:179], v[220:221], 0, s[10:11]
	s_mov_b32 m0, s61
	s_nop 0
	global_load_lds_dwordx4 v[178:179], off
	s_waitcnt vmcnt(8)
	s_waitcnt lgkmcnt(0)
	s_barrier
	s_setprio 1
	s_waitcnt lgkmcnt(0)
	v_mfma_f32_16x16x32_bf16 v[60:63], v[140:143], v[184:187], v[60:63]
	v_mfma_f32_16x16x32_bf16 v[60:63], v[150:153], v[188:191], v[60:63]
	v_mfma_f32_16x16x32_bf16 v[56:59], v[154:157], v[184:187], v[56:59]
	v_mfma_f32_16x16x32_bf16 v[56:59], v[158:161], v[188:191], v[56:59]
	v_mfma_f32_16x16x32_bf16 v[44:47], v[140:143], v[192:195], v[44:47]
	v_mfma_f32_16x16x32_bf16 v[44:47], v[150:153], v[196:199], v[44:47]
	v_mfma_f32_16x16x32_bf16 v[40:43], v[154:157], v[192:195], v[40:43]
	v_mfma_f32_16x16x32_bf16 v[40:43], v[158:161], v[196:199], v[40:43]
	v_mfma_f32_16x16x32_bf16 v[28:31], v[140:143], v[200:203], v[28:31]
	v_mfma_f32_16x16x32_bf16 v[28:31], v[150:153], v[204:207], v[28:31]
	v_mfma_f32_16x16x32_bf16 v[24:27], v[154:157], v[200:203], v[24:27]
	v_mfma_f32_16x16x32_bf16 v[24:27], v[158:161], v[204:207], v[24:27]
	v_mfma_f32_16x16x32_bf16 v[12:15], v[140:143], v[208:211], v[12:15]
	v_mfma_f32_16x16x32_bf16 v[12:15], v[150:153], v[212:215], v[12:15]
	v_mfma_f32_16x16x32_bf16 v[8:11], v[154:157], v[208:211], v[8:11]
	v_mfma_f32_16x16x32_bf16 v[8:11], v[158:161], v[212:215], v[8:11]
	s_setprio 0
	s_setprio 1
	v_mfma_f32_16x16x32_bf16 v[52:55], v[162:165], v[184:187], v[52:55]
	v_mfma_f32_16x16x32_bf16 v[52:55], v[166:169], v[188:191], v[52:55]
	v_mfma_f32_16x16x32_bf16 v[48:51], v[170:173], v[184:187], v[48:51]
	v_mfma_f32_16x16x32_bf16 v[48:51], v[174:177], v[188:191], v[48:51]
	v_mfma_f32_16x16x32_bf16 v[36:39], v[162:165], v[192:195], v[36:39]
	v_mfma_f32_16x16x32_bf16 v[36:39], v[166:169], v[196:199], v[36:39]
	v_mfma_f32_16x16x32_bf16 v[32:35], v[170:173], v[192:195], v[32:35]
	v_mfma_f32_16x16x32_bf16 v[32:35], v[174:177], v[196:199], v[32:35]
	v_mfma_f32_16x16x32_bf16 v[20:23], v[162:165], v[200:203], v[20:23]
	v_mfma_f32_16x16x32_bf16 v[20:23], v[166:169], v[204:207], v[20:23]
	v_mfma_f32_16x16x32_bf16 v[16:19], v[170:173], v[200:203], v[16:19]
	v_mfma_f32_16x16x32_bf16 v[16:19], v[174:177], v[204:207], v[16:19]
	v_mfma_f32_16x16x32_bf16 v[4:7], v[162:165], v[208:211], v[4:7]
	v_mfma_f32_16x16x32_bf16 v[4:7], v[166:169], v[212:215], v[4:7]
	v_mfma_f32_16x16x32_bf16 v[0:3], v[170:173], v[208:211], v[0:3]
	v_mfma_f32_16x16x32_bf16 v[0:3], v[174:177], v[212:215], v[0:3]
	s_setprio 0
	s_barrier
	s_add_i32 s70, s70, 2
	s_add_u32 s46, s46, 0x100
	s_addc_u32 s47, s47, 0
	s_add_u32 s68, s68, 0x100
	s_addc_u32 s69, s69, 0
	s_cmp_gt_u32 s70, 13
	s_cbranch_scc0 .LBB0_1434
	s_and_b64 vcc, exec, s[12:13]
	s_cbranch_vccz .LBB0_1437
	s_barrier

.LBB0_1513:
	s_add_u32 s74, s48, 0x100
	s_addc_u32 s75, s49, 0
	s_mov_b32 s76, -2
	ds_read_b128 v[152:155], v149
	ds_read_b128 v[156:159], v149 offset:1024
	ds_read_b128 v[160:163], v149 offset:2048
	ds_read_b128 v[164:167], v149 offset:3072
	ds_read_b128 v[168:171], v150
	ds_read_b128 v[172:175], v150 offset:1024
	ds_read_b128 v[176:179], v150 offset:2048
	ds_read_b128 v[184:187], v150 offset:3072
	s_add_u32 s48, s46, 0x100
	s_addc_u32 s49, s47, 0
	s_cmp_eq_u32 s76, 40
	s_cselect_b32 s53, s9, s49
	s_cselect_b32 s52, s8, s48
	s_cselect_b32 s51, s45, s75
	s_cselect_b32 s50, s44, s74
	v_lshl_add_u64 v[144:145], s[46:47], 0, v[136:137]
	s_add_i32 m0, s57, 0xc000
	ds_read_b128 v[188:191], v151
	ds_read_b128 v[192:195], v151 offset:1024
	ds_read_b128 v[196:199], v151 offset:2048
	ds_read_b128 v[200:203], v151 offset:3072
	ds_read_b128 v[204:207], v151 offset:4096
	ds_read_b128 v[208:211], v151 offset:5120
	ds_read_b128 v[212:215], v151 offset:6144
	ds_read_b128 v[216:219], v151 offset:7168
	global_load_lds_dwordx4 v[144:145], off
	v_lshl_add_u64 v[144:145], s[46:47], 0, v[138:139]
	s_add_i32 m0, s57, 0xe000
	s_nop 0
	global_load_lds_dwordx4 v[144:145], off
	s_waitcnt vmcnt(8)
	s_waitcnt lgkmcnt(0)
	s_barrier
	s_setprio 1
	s_waitcnt lgkmcnt(0)
	v_mfma_f32_16x16x32_bf16 v[124:127], v[152:155], v[188:191], 0
	v_mfma_f32_16x16x32_bf16 v[124:127], v[156:159], v[192:195], v[124:127]
	v_mfma_f32_16x16x32_bf16 v[120:123], v[160:163], v[188:191], 0
	v_mfma_f32_16x16x32_bf16 v[120:123], v[164:167], v[192:195], v[120:123]
	v_mfma_f32_16x16x32_bf16 v[116:119], v[152:155], v[196:199], 0
	v_mfma_f32_16x16x32_bf16 v[116:119], v[156:159], v[200:203], v[116:119]
	v_mfma_f32_16x16x32_bf16 v[108:111], v[160:163], v[196:199], 0
	v_mfma_f32_16x16x32_bf16 v[108:111], v[164:167], v[200:203], v[108:111]
	v_mfma_f32_16x16x32_bf16 v[100:103], v[152:155], v[204:207], 0
	v_mfma_f32_16x16x32_bf16 v[100:103], v[156:159], v[208:211], v[100:103]
	v_mfma_f32_16x16x32_bf16 v[92:95], v[160:163], v[204:207], 0
	v_mfma_f32_16x16x32_bf16 v[92:95], v[164:167], v[208:211], v[92:95]
	v_mfma_f32_16x16x32_bf16 v[84:87], v[152:155], v[212:215], 0
	v_mfma_f32_16x16x32_bf16 v[84:87], v[156:159], v[216:219], v[84:87]
	v_mfma_f32_16x16x32_bf16 v[76:79], v[160:163], v[212:215], 0
	v_mfma_f32_16x16x32_bf16 v[76:79], v[164:167], v[216:219], v[76:79]
	s_setprio 0
	s_setprio 1
	v_mfma_f32_16x16x32_bf16 v[112:115], v[168:171], v[188:191], 0
	v_mfma_f32_16x16x32_bf16 v[112:115], v[172:175], v[192:195], v[112:115]
	v_mfma_f32_16x16x32_bf16 v[104:107], v[176:179], v[188:191], 0
	v_mfma_f32_16x16x32_bf16 v[104:107], v[184:187], v[192:195], v[104:107]
	v_mfma_f32_16x16x32_bf16 v[96:99], v[168:171], v[196:199], 0
	v_mfma_f32_16x16x32_bf16 v[96:99], v[172:175], v[200:203], v[96:99]
	v_mfma_f32_16x16x32_bf16 v[88:91], v[176:179], v[196:199], 0
	v_mfma_f32_16x16x32_bf16 v[88:91], v[184:187], v[200:203], v[88:91]
	v_mfma_f32_16x16x32_bf16 v[80:83], v[168:171], v[204:207], 0
	v_mfma_f32_16x16x32_bf16 v[80:83], v[172:175], v[208:211], v[80:83]
	v_mfma_f32_16x16x32_bf16 v[72:75], v[176:179], v[204:207], 0
	v_mfma_f32_16x16x32_bf16 v[72:75], v[184:187], v[208:211], v[72:75]
	v_mfma_f32_16x16x32_bf16 v[68:71], v[168:171], v[212:215], 0
	v_mfma_f32_16x16x32_bf16 v[68:71], v[172:175], v[216:219], v[68:71]
	v_mfma_f32_16x16x32_bf16 v[64:67], v[176:179], v[212:215], 0
	v_mfma_f32_16x16x32_bf16 v[64:67], v[184:187], v[216:219], v[64:67]
	s_setprio 0
	s_barrier
	s_add_i32 s46, s64, s56
	v_lshl_add_u64 v[144:145], s[50:51], 0, v[130:131]
	s_mov_b32 m0, s46
	ds_read_b128 v[188:191], v151 offset:16384
	ds_read_b128 v[192:195], v151 offset:17408
	ds_read_b128 v[196:199], v151 offset:18432
	ds_read_b128 v[200:203], v151 offset:19456
	ds_read_b128 v[204:207], v151 offset:20480
	ds_read_b128 v[208:211], v151 offset:21504
	ds_read_b128 v[212:215], v151 offset:22528
	ds_read_b128 v[216:219], v151 offset:23552
	global_load_lds_dwordx4 v[144:145], off
	s_add_i32 m0, s46, 0x2000
	s_add_u32 s46, s50, 0xb0000
	v_lshl_add_u64 v[220:221], s[50:51], 0, v[134:135]
	s_addc_u32 s47, s51, 0
	s_add_i32 s77, s65, s56
	global_load_lds_dwordx4 v[220:221], off
	v_lshl_add_u64 v[222:223], s[46:47], 0, v[130:131]
	s_mov_b32 m0, s77
	v_lshl_add_u64 v[224:225], s[52:53], 0, v[132:133]
	global_load_lds_dwordx4 v[222:223], off
	v_lshl_add_u64 v[222:223], s[46:47], 0, v[134:135]
	s_add_i32 m0, s77, 0x2000
	s_nop 0
	global_load_lds_dwordx4 v[222:223], off
	v_lshl_add_u64 v[222:223], s[52:53], 0, v[128:129]
	s_mov_b32 m0, s57
	s_nop 0
	global_load_lds_dwordx4 v[222:223], off
	s_mov_b32 m0, s58
	s_nop 0
	global_load_lds_dwordx4 v[224:225], off
	s_waitcnt vmcnt(8)
	s_waitcnt lgkmcnt(0)
	s_barrier
	s_setprio 1
	s_waitcnt lgkmcnt(0)
	v_mfma_f32_16x16x32_bf16 v[60:63], v[152:155], v[188:191], 0
	v_mfma_f32_16x16x32_bf16 v[60:63], v[156:159], v[192:195], v[60:63]
	v_mfma_f32_16x16x32_bf16 v[56:59], v[160:163], v[188:191], 0
	v_mfma_f32_16x16x32_bf16 v[56:59], v[164:167], v[192:195], v[56:59]
	v_mfma_f32_16x16x32_bf16 v[52:55], v[152:155], v[196:199], 0
	v_mfma_f32_16x16x32_bf16 v[52:55], v[156:159], v[200:203], v[52:55]
	v_mfma_f32_16x16x32_bf16 v[44:47], v[160:163], v[196:199], 0
	v_mfma_f32_16x16x32_bf16 v[44:47], v[164:167], v[200:203], v[44:47]
	v_mfma_f32_16x16x32_bf16 v[36:39], v[152:155], v[204:207], 0
	v_mfma_f32_16x16x32_bf16 v[36:39], v[156:159], v[208:211], v[36:39]
	v_mfma_f32_16x16x32_bf16 v[28:31], v[160:163], v[204:207], 0
	v_mfma_f32_16x16x32_bf16 v[28:31], v[164:167], v[208:211], v[28:31]
	v_mfma_f32_16x16x32_bf16 v[20:23], v[152:155], v[212:215], 0
	v_mfma_f32_16x16x32_bf16 v[20:23], v[156:159], v[216:219], v[20:23]
	v_mfma_f32_16x16x32_bf16 v[12:15], v[160:163], v[212:215], 0
	v_mfma_f32_16x16x32_bf16 v[12:15], v[164:167], v[216:219], v[12:15]
	s_setprio 0
	s_setprio 1
	v_mfma_f32_16x16x32_bf16 v[48:51], v[168:171], v[188:191], 0
	v_mfma_f32_16x16x32_bf16 v[48:51], v[172:175], v[192:195], v[48:51]
	v_mfma_f32_16x16x32_bf16 v[40:43], v[176:179], v[188:191], 0
	v_mfma_f32_16x16x32_bf16 v[40:43], v[184:187], v[192:195], v[40:43]
	v_mfma_f32_16x16x32_bf16 v[32:35], v[168:171], v[196:199], 0
	v_mfma_f32_16x16x32_bf16 v[32:35], v[172:175], v[200:203], v[32:35]
	v_mfma_f32_16x16x32_bf16 v[24:27], v[176:179], v[196:199], 0
	v_mfma_f32_16x16x32_bf16 v[24:27], v[184:187], v[200:203], v[24:27]
	v_mfma_f32_16x16x32_bf16 v[16:19], v[168:171], v[204:207], 0
	v_mfma_f32_16x16x32_bf16 v[16:19], v[172:175], v[208:211], v[16:19]
	v_mfma_f32_16x16x32_bf16 v[8:11], v[176:179], v[204:207], 0
	v_mfma_f32_16x16x32_bf16 v[8:11], v[184:187], v[208:211], v[8:11]
	v_mfma_f32_16x16x32_bf16 v[4:7], v[168:171], v[212:215], 0
	v_mfma_f32_16x16x32_bf16 v[4:7], v[172:175], v[216:219], v[4:7]
	v_mfma_f32_16x16x32_bf16 v[0:3], v[176:179], v[212:215], 0
	v_mfma_f32_16x16x32_bf16 v[0:3], v[184:187], v[216:219], v[0:3]
	s_setprio 0
	s_barrier
	s_branch .Lmid_gemm12
.LBB0_1514:
	ds_read_b128 v[152:155], v149
	ds_read_b128 v[156:159], v149 offset:1024
	ds_read_b128 v[160:163], v149 offset:2048
	ds_read_b128 v[164:167], v149 offset:3072
	ds_read_b128 v[168:171], v150
	ds_read_b128 v[172:175], v150 offset:1024
	ds_read_b128 v[176:179], v150 offset:2048
	ds_read_b128 v[184:187], v150 offset:3072
	s_add_u32 s48, s46, 0x100
	s_addc_u32 s49, s47, 0
	s_cmp_eq_u32 s76, 40
	s_cselect_b32 s53, s9, s49
	s_cselect_b32 s52, s8, s48
	s_cselect_b32 s51, s45, s75
	s_cselect_b32 s50, s44, s74
	v_lshl_add_u64 v[144:145], s[46:47], 0, v[136:137]
	s_add_i32 m0, s57, 0xc000
	ds_read_b128 v[188:191], v151
	ds_read_b128 v[192:195], v151 offset:1024
	ds_read_b128 v[196:199], v151 offset:2048
	ds_read_b128 v[200:203], v151 offset:3072
	ds_read_b128 v[204:207], v151 offset:4096
	ds_read_b128 v[208:211], v151 offset:5120
	ds_read_b128 v[212:215], v151 offset:6144
	ds_read_b128 v[216:219], v151 offset:7168
	global_load_lds_dwordx4 v[144:145], off
	v_lshl_add_u64 v[144:145], s[46:47], 0, v[138:139]
	s_add_i32 m0, s57, 0xe000
	s_nop 0
	global_load_lds_dwordx4 v[144:145], off
	s_waitcnt vmcnt(8)
	s_waitcnt lgkmcnt(0)
	s_barrier
	s_setprio 1
	s_waitcnt lgkmcnt(0)
	v_mfma_f32_16x16x32_bf16 v[124:127], v[152:155], v[188:191], v[124:127]
	v_mfma_f32_16x16x32_bf16 v[124:127], v[156:159], v[192:195], v[124:127]
	v_mfma_f32_16x16x32_bf16 v[120:123], v[160:163], v[188:191], v[120:123]
	v_mfma_f32_16x16x32_bf16 v[120:123], v[164:167], v[192:195], v[120:123]
	v_mfma_f32_16x16x32_bf16 v[116:119], v[152:155], v[196:199], v[116:119]
	v_mfma_f32_16x16x32_bf16 v[116:119], v[156:159], v[200:203], v[116:119]
	v_mfma_f32_16x16x32_bf16 v[108:111], v[160:163], v[196:199], v[108:111]
	v_mfma_f32_16x16x32_bf16 v[108:111], v[164:167], v[200:203], v[108:111]
	v_mfma_f32_16x16x32_bf16 v[100:103], v[152:155], v[204:207], v[100:103]
	v_mfma_f32_16x16x32_bf16 v[100:103], v[156:159], v[208:211], v[100:103]
	v_mfma_f32_16x16x32_bf16 v[92:95], v[160:163], v[204:207], v[92:95]
	v_mfma_f32_16x16x32_bf16 v[92:95], v[164:167], v[208:211], v[92:95]
	v_mfma_f32_16x16x32_bf16 v[84:87], v[152:155], v[212:215], v[84:87]
	v_mfma_f32_16x16x32_bf16 v[84:87], v[156:159], v[216:219], v[84:87]
	v_mfma_f32_16x16x32_bf16 v[76:79], v[160:163], v[212:215], v[76:79]
	v_mfma_f32_16x16x32_bf16 v[76:79], v[164:167], v[216:219], v[76:79]
	s_setprio 0
	s_setprio 1
	v_mfma_f32_16x16x32_bf16 v[112:115], v[168:171], v[188:191], v[112:115]
	v_mfma_f32_16x16x32_bf16 v[112:115], v[172:175], v[192:195], v[112:115]
	v_mfma_f32_16x16x32_bf16 v[104:107], v[176:179], v[188:191], v[104:107]
	v_mfma_f32_16x16x32_bf16 v[104:107], v[184:187], v[192:195], v[104:107]
	v_mfma_f32_16x16x32_bf16 v[96:99], v[168:171], v[196:199], v[96:99]
	v_mfma_f32_16x16x32_bf16 v[96:99], v[172:175], v[200:203], v[96:99]
	v_mfma_f32_16x16x32_bf16 v[88:91], v[176:179], v[196:199], v[88:91]
	v_mfma_f32_16x16x32_bf16 v[88:91], v[184:187], v[200:203], v[88:91]
	v_mfma_f32_16x16x32_bf16 v[80:83], v[168:171], v[204:207], v[80:83]
	v_mfma_f32_16x16x32_bf16 v[80:83], v[172:175], v[208:211], v[80:83]
	v_mfma_f32_16x16x32_bf16 v[72:75], v[176:179], v[204:207], v[72:75]
	v_mfma_f32_16x16x32_bf16 v[72:75], v[184:187], v[208:211], v[72:75]
	v_mfma_f32_16x16x32_bf16 v[68:71], v[168:171], v[212:215], v[68:71]
	v_mfma_f32_16x16x32_bf16 v[68:71], v[172:175], v[216:219], v[68:71]
	v_mfma_f32_16x16x32_bf16 v[64:67], v[176:179], v[212:215], v[64:67]
	v_mfma_f32_16x16x32_bf16 v[64:67], v[184:187], v[216:219], v[64:67]
	s_setprio 0
	s_barrier
	s_add_i32 s46, s64, s56
	v_lshl_add_u64 v[144:145], s[50:51], 0, v[130:131]
	s_mov_b32 m0, s46
	ds_read_b128 v[188:191], v151 offset:16384
	ds_read_b128 v[192:195], v151 offset:17408
	ds_read_b128 v[196:199], v151 offset:18432
	ds_read_b128 v[200:203], v151 offset:19456
	ds_read_b128 v[204:207], v151 offset:20480
	ds_read_b128 v[208:211], v151 offset:21504
	ds_read_b128 v[212:215], v151 offset:22528
	ds_read_b128 v[216:219], v151 offset:23552
	global_load_lds_dwordx4 v[144:145], off
	s_add_i32 m0, s46, 0x2000
	s_add_u32 s46, s50, 0xb0000
	v_lshl_add_u64 v[220:221], s[50:51], 0, v[134:135]
	s_addc_u32 s47, s51, 0
	s_add_i32 s77, s65, s56
	global_load_lds_dwordx4 v[220:221], off
	v_lshl_add_u64 v[222:223], s[46:47], 0, v[130:131]
	s_mov_b32 m0, s77
	v_lshl_add_u64 v[224:225], s[52:53], 0, v[132:133]
	global_load_lds_dwordx4 v[222:223], off
	v_lshl_add_u64 v[222:223], s[46:47], 0, v[134:135]
	s_add_i32 m0, s77, 0x2000
	s_nop 0
	global_load_lds_dwordx4 v[222:223], off
	v_lshl_add_u64 v[222:223], s[52:53], 0, v[128:129]
	s_mov_b32 m0, s57
	s_nop 0
	global_load_lds_dwordx4 v[222:223], off
	s_mov_b32 m0, s58
	s_nop 0
	global_load_lds_dwordx4 v[224:225], off
	s_waitcnt vmcnt(8)
	s_waitcnt lgkmcnt(0)
	s_barrier
	s_setprio 1
	s_waitcnt lgkmcnt(0)
	v_mfma_f32_16x16x32_bf16 v[60:63], v[152:155], v[188:191], v[60:63]
	v_mfma_f32_16x16x32_bf16 v[60:63], v[156:159], v[192:195], v[60:63]
	v_mfma_f32_16x16x32_bf16 v[56:59], v[160:163], v[188:191], v[56:59]
	v_mfma_f32_16x16x32_bf16 v[56:59], v[164:167], v[192:195], v[56:59]
	v_mfma_f32_16x16x32_bf16 v[52:55], v[152:155], v[196:199], v[52:55]
	v_mfma_f32_16x16x32_bf16 v[52:55], v[156:159], v[200:203], v[52:55]
	v_mfma_f32_16x16x32_bf16 v[44:47], v[160:163], v[196:199], v[44:47]
	v_mfma_f32_16x16x32_bf16 v[44:47], v[164:167], v[200:203], v[44:47]
	v_mfma_f32_16x16x32_bf16 v[36:39], v[152:155], v[204:207], v[36:39]
	v_mfma_f32_16x16x32_bf16 v[36:39], v[156:159], v[208:211], v[36:39]
	v_mfma_f32_16x16x32_bf16 v[28:31], v[160:163], v[204:207], v[28:31]
	v_mfma_f32_16x16x32_bf16 v[28:31], v[164:167], v[208:211], v[28:31]
	v_mfma_f32_16x16x32_bf16 v[20:23], v[152:155], v[212:215], v[20:23]
	v_mfma_f32_16x16x32_bf16 v[20:23], v[156:159], v[216:219], v[20:23]
	v_mfma_f32_16x16x32_bf16 v[12:15], v[160:163], v[212:215], v[12:15]
	v_mfma_f32_16x16x32_bf16 v[12:15], v[164:167], v[216:219], v[12:15]
	s_setprio 0
	s_setprio 1
	v_mfma_f32_16x16x32_bf16 v[48:51], v[168:171], v[188:191], v[48:51]
	v_mfma_f32_16x16x32_bf16 v[48:51], v[172:175], v[192:195], v[48:51]
	v_mfma_f32_16x16x32_bf16 v[40:43], v[176:179], v[188:191], v[40:43]
	v_mfma_f32_16x16x32_bf16 v[40:43], v[184:187], v[192:195], v[40:43]
	v_mfma_f32_16x16x32_bf16 v[32:35], v[168:171], v[196:199], v[32:35]
	v_mfma_f32_16x16x32_bf16 v[32:35], v[172:175], v[200:203], v[32:35]
	v_mfma_f32_16x16x32_bf16 v[24:27], v[176:179], v[196:199], v[24:27]
	v_mfma_f32_16x16x32_bf16 v[24:27], v[184:187], v[200:203], v[24:27]
	v_mfma_f32_16x16x32_bf16 v[16:19], v[168:171], v[204:207], v[16:19]
	v_mfma_f32_16x16x32_bf16 v[16:19], v[172:175], v[208:211], v[16:19]
	v_mfma_f32_16x16x32_bf16 v[8:11], v[176:179], v[204:207], v[8:11]
	v_mfma_f32_16x16x32_bf16 v[8:11], v[184:187], v[208:211], v[8:11]
	v_mfma_f32_16x16x32_bf16 v[4:7], v[168:171], v[212:215], v[4:7]
	v_mfma_f32_16x16x32_bf16 v[4:7], v[172:175], v[216:219], v[4:7]
	v_mfma_f32_16x16x32_bf16 v[0:3], v[176:179], v[212:215], v[0:3]
	v_mfma_f32_16x16x32_bf16 v[0:3], v[184:187], v[216:219], v[0:3]
	s_setprio 0
	s_barrier
.Lmid_gemm12:
	s_add_i32 s77, 0, 0x18000
	s_add_i32 s79, 0, 0x1c000
	v_add_u32_e32 v164, s77, v147
	v_add_u32_e32 v181, s79, v147
	ds_read_b128 v[152:155], v164
	ds_read_b128 v[156:159], v164 offset:1024
	ds_read_b128 v[160:163], v164 offset:2048
	ds_read_b128 v[164:167], v164 offset:3072
	ds_read_b128 v[168:171], v181
	ds_read_b128 v[172:175], v181 offset:1024
	ds_read_b128 v[176:179], v181 offset:2048
	ds_read_b128 v[184:187], v181 offset:3072
	s_add_u32 s46, s52, 0xb0000
	s_addc_u32 s47, s53, 0
	s_mov_b32 m0, s59
	v_lshl_add_u64 v[226:227], s[46:47], 0, v[128:129]
	ds_read_b128 v[188:191], v151 offset:32768
	ds_read_b128 v[192:195], v151 offset:33792
	ds_read_b128 v[196:199], v151 offset:34816
	ds_read_b128 v[200:203], v151 offset:35840
	ds_read_b128 v[204:207], v151 offset:36864
	ds_read_b128 v[208:211], v151 offset:37888
	ds_read_b128 v[212:215], v151 offset:38912
	ds_read_b128 v[216:219], v151 offset:39936
	global_load_lds_dwordx4 v[226:227], off
	v_lshl_add_u64 v[226:227], s[46:47], 0, v[132:133]
	s_mov_b32 m0, s60
	s_nop 0
	global_load_lds_dwordx4 v[226:227], off
	s_waitcnt vmcnt(8)
	s_waitcnt lgkmcnt(0)
	s_barrier
	s_setprio 1
	s_waitcnt lgkmcnt(0)
	v_mfma_f32_16x16x32_bf16 v[124:127], v[152:155], v[188:191], v[124:127]
	v_mfma_f32_16x16x32_bf16 v[124:127], v[156:159], v[192:195], v[124:127]
	v_mfma_f32_16x16x32_bf16 v[120:123], v[160:163], v[188:191], v[120:123]
	v_mfma_f32_16x16x32_bf16 v[120:123], v[164:167], v[192:195], v[120:123]
	v_mfma_f32_16x16x32_bf16 v[116:119], v[152:155], v[196:199], v[116:119]
	v_mfma_f32_16x16x32_bf16 v[116:119], v[156:159], v[200:203], v[116:119]
	v_mfma_f32_16x16x32_bf16 v[108:111], v[160:163], v[196:199], v[108:111]
	v_mfma_f32_16x16x32_bf16 v[108:111], v[164:167], v[200:203], v[108:111]
	v_mfma_f32_16x16x32_bf16 v[100:103], v[152:155], v[204:207], v[100:103]
	v_mfma_f32_16x16x32_bf16 v[100:103], v[156:159], v[208:211], v[100:103]
	v_mfma_f32_16x16x32_bf16 v[92:95], v[160:163], v[204:207], v[92:95]
	v_mfma_f32_16x16x32_bf16 v[92:95], v[164:167], v[208:211], v[92:95]
	v_mfma_f32_16x16x32_bf16 v[84:87], v[152:155], v[212:215], v[84:87]
	v_mfma_f32_16x16x32_bf16 v[84:87], v[156:159], v[216:219], v[84:87]
	v_mfma_f32_16x16x32_bf16 v[76:79], v[160:163], v[212:215], v[76:79]
	v_mfma_f32_16x16x32_bf16 v[76:79], v[164:167], v[216:219], v[76:79]
	s_setprio 0
	s_setprio 1
	v_mfma_f32_16x16x32_bf16 v[112:115], v[168:171], v[188:191], v[112:115]
	v_mfma_f32_16x16x32_bf16 v[112:115], v[172:175], v[192:195], v[112:115]
	v_mfma_f32_16x16x32_bf16 v[104:107], v[176:179], v[188:191], v[104:107]
	v_mfma_f32_16x16x32_bf16 v[104:107], v[184:187], v[192:195], v[104:107]
	v_mfma_f32_16x16x32_bf16 v[96:99], v[168:171], v[196:199], v[96:99]
	v_mfma_f32_16x16x32_bf16 v[96:99], v[172:175], v[200:203], v[96:99]
	v_mfma_f32_16x16x32_bf16 v[88:91], v[176:179], v[196:199], v[88:91]
	v_mfma_f32_16x16x32_bf16 v[88:91], v[184:187], v[200:203], v[88:91]
	v_mfma_f32_16x16x32_bf16 v[80:83], v[168:171], v[204:207], v[80:83]
	v_mfma_f32_16x16x32_bf16 v[80:83], v[172:175], v[208:211], v[80:83]
	v_mfma_f32_16x16x32_bf16 v[72:75], v[176:179], v[204:207], v[72:75]
	v_mfma_f32_16x16x32_bf16 v[72:75], v[184:187], v[208:211], v[72:75]
	v_mfma_f32_16x16x32_bf16 v[68:71], v[168:171], v[212:215], v[68:71]
	v_mfma_f32_16x16x32_bf16 v[68:71], v[172:175], v[216:219], v[68:71]
	v_mfma_f32_16x16x32_bf16 v[64:67], v[176:179], v[212:215], v[64:67]
	v_mfma_f32_16x16x32_bf16 v[64:67], v[184:187], v[216:219], v[64:67]
	s_setprio 0
	s_barrier
	s_add_i32 s46, s77, s56
	v_lshl_add_u64 v[144:145], v[144:145], 0, s[10:11]
	s_mov_b32 m0, s46
	ds_read_b128 v[188:191], v151 offset:49152
	ds_read_b128 v[192:195], v151 offset:50176
	ds_read_b128 v[196:199], v151 offset:51200
	ds_read_b128 v[200:203], v151 offset:52224
	ds_read_b128 v[204:207], v151 offset:53248
	ds_read_b128 v[208:211], v151 offset:54272
	ds_read_b128 v[212:215], v151 offset:55296
	ds_read_b128 v[216:219], v151 offset:56320
	global_load_lds_dwordx4 v[144:145], off
	s_add_i32 m0, s46, 0x2000
	s_add_u32 s46, s50, 0xb0080
	v_lshl_add_u64 v[144:145], v[220:221], 0, s[10:11]
	s_addc_u32 s47, s51, 0
	s_add_i32 s50, s79, s56
	global_load_lds_dwordx4 v[144:145], off
	v_lshl_add_u64 v[144:145], s[46:47], 0, v[130:131]
	s_mov_b32 m0, s50
	s_nop 0
	global_load_lds_dwordx4 v[144:145], off
	v_lshl_add_u64 v[144:145], s[46:47], 0, v[134:135]
	s_add_i32 m0, s50, 0x2000
	s_nop 0
	global_load_lds_dwordx4 v[144:145], off
	v_lshl_add_u64 v[144:145], v[222:223], 0, s[10:11]
	s_mov_b32 m0, s62
	s_nop 0
	global_load_lds_dwordx4 v[144:145], off
	v_lshl_add_u64 v[144:145], v[224:225], 0, s[10:11]
	s_mov_b32 m0, s63
	s_nop 0
	global_load_lds_dwordx4 v[144:145], off
	s_waitcnt vmcnt(8)
	s_waitcnt lgkmcnt(0)
	s_barrier
	s_setprio 1
	s_waitcnt lgkmcnt(0)
	v_mfma_f32_16x16x32_bf16 v[60:63], v[152:155], v[188:191], v[60:63]
	v_mfma_f32_16x16x32_bf16 v[60:63], v[156:159], v[192:195], v[60:63]
	v_mfma_f32_16x16x32_bf16 v[56:59], v[160:163], v[188:191], v[56:59]
	v_mfma_f32_16x16x32_bf16 v[56:59], v[164:167], v[192:195], v[56:59]
	v_mfma_f32_16x16x32_bf16 v[52:55], v[152:155], v[196:199], v[52:55]
	v_mfma_f32_16x16x32_bf16 v[52:55], v[156:159], v[200:203], v[52:55]
	v_mfma_f32_16x16x32_bf16 v[44:47], v[160:163], v[196:199], v[44:47]
	v_mfma_f32_16x16x32_bf16 v[44:47], v[164:167], v[200:203], v[44:47]
	v_mfma_f32_16x16x32_bf16 v[36:39], v[152:155], v[204:207], v[36:39]
	v_mfma_f32_16x16x32_bf16 v[36:39], v[156:159], v[208:211], v[36:39]
	v_mfma_f32_16x16x32_bf16 v[28:31], v[160:163], v[204:207], v[28:31]
	v_mfma_f32_16x16x32_bf16 v[28:31], v[164:167], v[208:211], v[28:31]
	v_mfma_f32_16x16x32_bf16 v[20:23], v[152:155], v[212:215], v[20:23]
	v_mfma_f32_16x16x32_bf16 v[20:23], v[156:159], v[216:219], v[20:23]
	v_mfma_f32_16x16x32_bf16 v[12:15], v[160:163], v[212:215], v[12:15]
	v_mfma_f32_16x16x32_bf16 v[12:15], v[164:167], v[216:219], v[12:15]
	s_setprio 0
	s_setprio 1
	v_mfma_f32_16x16x32_bf16 v[48:51], v[168:171], v[188:191], v[48:51]
	v_mfma_f32_16x16x32_bf16 v[48:51], v[172:175], v[192:195], v[48:51]
	v_mfma_f32_16x16x32_bf16 v[40:43], v[176:179], v[188:191], v[40:43]
	v_mfma_f32_16x16x32_bf16 v[40:43], v[184:187], v[192:195], v[40:43]
	v_mfma_f32_16x16x32_bf16 v[32:35], v[168:171], v[196:199], v[32:35]
	v_mfma_f32_16x16x32_bf16 v[32:35], v[172:175], v[200:203], v[32:35]
	v_mfma_f32_16x16x32_bf16 v[24:27], v[176:179], v[196:199], v[24:27]
	v_mfma_f32_16x16x32_bf16 v[24:27], v[184:187], v[200:203], v[24:27]
	v_mfma_f32_16x16x32_bf16 v[16:19], v[168:171], v[204:207], v[16:19]
	v_mfma_f32_16x16x32_bf16 v[16:19], v[172:175], v[208:211], v[16:19]
	v_mfma_f32_16x16x32_bf16 v[8:11], v[176:179], v[204:207], v[8:11]
	v_mfma_f32_16x16x32_bf16 v[8:11], v[184:187], v[208:211], v[8:11]
	v_mfma_f32_16x16x32_bf16 v[4:7], v[168:171], v[212:215], v[4:7]
	v_mfma_f32_16x16x32_bf16 v[4:7], v[172:175], v[216:219], v[4:7]
	v_mfma_f32_16x16x32_bf16 v[0:3], v[176:179], v[212:215], v[0:3]
	v_mfma_f32_16x16x32_bf16 v[0:3], v[184:187], v[216:219], v[0:3]
	s_setprio 0
	s_barrier
	s_add_i32 s76, s76, 2
	s_add_u32 s74, s74, 0x100
	s_addc_u32 s75, s75, 0
	s_cmp_gt_u32 s76, 41
	s_mov_b64 s[46:47], s[48:49]
	s_cbranch_scc0 .LBB0_1514
	s_and_b64 vcc, exec, s[12:13]
	s_cbranch_vccz .LBB0_1517
	s_barrier
